# stack5 + residual epilogue: second column group's gain/bias vector loads issued with the row loads (free regs), extra waits dropped, 7 of 8 row blocks
# speedup vs baseline: 1.0029x; 1.0029x over previous
;     DEVI void operator()(const f32x4 (&acc)[2][2][4][2], const pg8::Unit& u, int wr, int wc, int fr, int fq) const {
;     ...
;                     for (int n = 0; n < 2; ++n) {
;                         const int col = colb + bj * 128 + 4 * n;
;                         f32x4 xv = *(const f32x4*)(zsrc + (size_t)row * DM + col);
;                         if (stin) { const f32x4 gv = *(const f32x4*)(gin + col), bv = *(const f32x4*)(bin + col); xv = (xv - mu) * rs * gv + bv; }
;                         f32x4 zz = ALPHA * xv + acc[ai][bj][m][n];
;                         if (bias) zz += *(const f32x4*)(bias + col);
;                         *(f32x4*)(zdst + (size_t)row * DM + col) = zz;
;                         sum += zz[0] + zz[1] + zz[2] + zz[3]; sq += zz[0] * zz[0] + zz[1] * zz[1] + zz[2] * zz[2] + zz[3] * zz[3];
;                         z[n] = zz;
.LBB0_814:
	global_load_dwordx4 v[116:119], v[122:123], off offset:16
	global_load_dwordx4 v[182:185], v[152:153], off offset:16
	global_load_dwordx4 v[186:189], v[154:155], off offset:16
	s_waitcnt vmcnt(0)
	v_pk_fma_f32 v[110:111], v[114:115], s[26:27], v[110:111] op_sel_hi:[1,0,1]
	v_pk_fma_f32 v[108:109], v[112:113], s[26:27], v[108:109] op_sel_hi:[1,0,1]
	s_and_b64 vcc, exec, s[6:7]
	global_store_dwordx4 v[122:123], v[108:111], off
	s_cbranch_vccnz .LBB0_816
	v_sub_f32_e32 v119, v119, v124
	v_sub_f32_e32 v118, v118, v124
	v_sub_f32_e32 v117, v117, v124
	v_sub_f32_e32 v116, v116, v124
	v_mov_b32_e32 v128, v126
	v_mov_b32_e32 v129, v126
	v_pk_mul_f32 v[116:117], v[126:127], v[116:117]
	v_pk_mul_f32 v[118:119], v[128:129], v[118:119]
	v_pk_fma_f32 v[116:117], v[116:117], v[182:183], v[186:187]
	v_pk_fma_f32 v[118:119], v[118:119], v[184:185], v[188:189]

;     DEVI void operator()(const f32x4 (&acc)[2][2][4][2], const pg8::Unit& u, int wr, int wc, int fr, int fq) const {
;     ...
;                     for (int n = 0; n < 2; ++n) {
;                         const int col = colb + bj * 128 + 4 * n;
;                         f32x4 xv = *(const f32x4*)(zsrc + (size_t)row * DM + col);
;                         if (stin) { const f32x4 gv = *(const f32x4*)(gin + col), bv = *(const f32x4*)(bin + col); xv = (xv - mu) * rs * gv + bv; }
;                         f32x4 zz = ALPHA * xv + acc[ai][bj][m][n];
;                         if (bias) zz += *(const f32x4*)(bias + col);
;                         *(f32x4*)(zdst + (size_t)row * DM + col) = zz;
;                         sum += zz[0] + zz[1] + zz[2] + zz[3]; sq += zz[0] * zz[0] + zz[1] * zz[1] + zz[2] * zz[2] + zz[3] * zz[3];
;                         z[n] = zz;
.LBB0_818:
	global_load_dwordx4 v[112:115], v[122:123], off offset:528
	global_load_dwordx4 v[182:185], v[152:153], off offset:528
	global_load_dwordx4 v[186:189], v[154:155], off offset:528
	s_waitcnt vmcnt(0)
	v_pk_fma_f32 v[102:103], v[118:119], s[26:27], v[102:103] op_sel_hi:[1,0,1]
	v_pk_fma_f32 v[100:101], v[116:117], s[26:27], v[100:101] op_sel_hi:[1,0,1]
	s_and_b64 vcc, exec, s[6:7]
	global_store_dwordx4 v[122:123], v[100:103], off offset:512
	s_cbranch_vccnz .LBB0_820
	v_sub_f32_e32 v113, v113, v124
	v_sub_f32_e32 v112, v112, v124
	v_sub_f32_e32 v115, v115, v124
	v_sub_f32_e32 v114, v114, v124
	v_pk_mul_f32 v[112:113], v[126:127], v[112:113]
	v_mov_b32_e32 v127, v126
	v_pk_mul_f32 v[114:115], v[126:127], v[114:115]
	v_pk_fma_f32 v[112:113], v[112:113], v[182:183], v[186:187]
	v_pk_fma_f32 v[114:115], v[114:115], v[184:185], v[188:189]

;     DEVI void operator()(const f32x4 (&acc)[2][2][4][2], const pg8::Unit& u, int wr, int wc, int fr, int fq) const {
;     ...
;                     for (int n = 0; n < 2; ++n) {
;                         const int col = colb + bj * 128 + 4 * n;
;                         f32x4 xv = *(const f32x4*)(zsrc + (size_t)row * DM + col);
;                         if (stin) { const f32x4 gv = *(const f32x4*)(gin + col), bv = *(const f32x4*)(bin + col); xv = (xv - mu) * rs * gv + bv; }
;                         f32x4 zz = ALPHA * xv + acc[ai][bj][m][n];
;                         if (bias) zz += *(const f32x4*)(bias + col);
;                         *(f32x4*)(zdst + (size_t)row * DM + col) = zz;
;                         sum += zz[0] + zz[1] + zz[2] + zz[3]; sq += zz[0] * zz[0] + zz[1] * zz[1] + zz[2] * zz[2] + zz[3] * zz[3];
;                         z[n] = zz;
.LBB0_827:
	global_load_dwordx4 v[100:103], v[106:107], off offset:16
	global_load_dwordx4 v[182:185], v[152:153], off offset:16
	global_load_dwordx4 v[186:189], v[154:155], off offset:16
	s_waitcnt vmcnt(0)
	v_pk_fma_f32 v[94:95], v[98:99], s[26:27], v[94:95] op_sel_hi:[1,0,1]
	v_pk_fma_f32 v[92:93], v[96:97], s[26:27], v[92:93] op_sel_hi:[1,0,1]
	s_and_b64 vcc, exec, s[6:7]
	global_store_dwordx4 v[106:107], v[92:95], off
	s_cbranch_vccnz .LBB0_829
	v_sub_f32_e32 v103, v103, v108
	v_sub_f32_e32 v102, v102, v108
	v_sub_f32_e32 v101, v101, v108
	v_sub_f32_e32 v100, v100, v108
	v_mov_b32_e32 v116, v110
	v_mov_b32_e32 v117, v110
	v_pk_mul_f32 v[100:101], v[110:111], v[100:101]
	v_pk_mul_f32 v[102:103], v[116:117], v[102:103]
	v_pk_fma_f32 v[100:101], v[100:101], v[182:183], v[186:187]
	v_pk_fma_f32 v[102:103], v[102:103], v[184:185], v[188:189]

;     DEVI void operator()(const f32x4 (&acc)[2][2][4][2], const pg8::Unit& u, int wr, int wc, int fr, int fq) const {
;     ...
;                     for (int n = 0; n < 2; ++n) {
;                         const int col = colb + bj * 128 + 4 * n;
;                         f32x4 xv = *(const f32x4*)(zsrc + (size_t)row * DM + col);
;                         if (stin) { const f32x4 gv = *(const f32x4*)(gin + col), bv = *(const f32x4*)(bin + col); xv = (xv - mu) * rs * gv + bv; }
;                         f32x4 zz = ALPHA * xv + acc[ai][bj][m][n];
;                         if (bias) zz += *(const f32x4*)(bias + col);
;                         *(f32x4*)(zdst + (size_t)row * DM + col) = zz;
;                         sum += zz[0] + zz[1] + zz[2] + zz[3]; sq += zz[0] * zz[0] + zz[1] * zz[1] + zz[2] * zz[2] + zz[3] * zz[3];
;                         z[n] = zz;
.LBB0_831:
	global_load_dwordx4 v[96:99], v[106:107], off offset:528
	global_load_dwordx4 v[182:185], v[152:153], off offset:528
	global_load_dwordx4 v[186:189], v[154:155], off offset:528
	s_waitcnt vmcnt(0)
	v_pk_fma_f32 v[86:87], v[102:103], s[26:27], v[86:87] op_sel_hi:[1,0,1]
	v_pk_fma_f32 v[84:85], v[100:101], s[26:27], v[84:85] op_sel_hi:[1,0,1]
	s_and_b64 vcc, exec, s[6:7]
	global_store_dwordx4 v[106:107], v[84:87], off offset:512
	s_cbranch_vccnz .LBB0_833
	v_sub_f32_e32 v97, v97, v108
	v_sub_f32_e32 v96, v96, v108
	v_sub_f32_e32 v99, v99, v108
	v_sub_f32_e32 v98, v98, v108
	v_pk_mul_f32 v[96:97], v[110:111], v[96:97]
	v_mov_b32_e32 v111, v110
	v_pk_mul_f32 v[98:99], v[110:111], v[98:99]
	v_pk_fma_f32 v[96:97], v[96:97], v[182:183], v[186:187]
	v_pk_fma_f32 v[98:99], v[98:99], v[184:185], v[188:189]

;     DEVI void operator()(const f32x4 (&acc)[2][2][4][2], const pg8::Unit& u, int wr, int wc, int fr, int fq) const {
;     ...
;                     for (int n = 0; n < 2; ++n) {
;                         const int col = colb + bj * 128 + 4 * n;
;                         f32x4 xv = *(const f32x4*)(zsrc + (size_t)row * DM + col);
;                         if (stin) { const f32x4 gv = *(const f32x4*)(gin + col), bv = *(const f32x4*)(bin + col); xv = (xv - mu) * rs * gv + bv; }
;                         f32x4 zz = ALPHA * xv + acc[ai][bj][m][n];
;                         if (bias) zz += *(const f32x4*)(bias + col);
;                         *(f32x4*)(zdst + (size_t)row * DM + col) = zz;
;                         sum += zz[0] + zz[1] + zz[2] + zz[3]; sq += zz[0] * zz[0] + zz[1] * zz[1] + zz[2] * zz[2] + zz[3] * zz[3];
;                         z[n] = zz;
.LBB0_840:
	global_load_dwordx4 v[84:87], v[90:91], off offset:16
	global_load_dwordx4 v[182:185], v[152:153], off offset:16
	global_load_dwordx4 v[186:189], v[154:155], off offset:16
	s_waitcnt vmcnt(0)
	v_pk_fma_f32 v[78:79], v[82:83], s[26:27], v[78:79] op_sel_hi:[1,0,1]
	v_pk_fma_f32 v[76:77], v[80:81], s[26:27], v[76:77] op_sel_hi:[1,0,1]
	s_and_b64 vcc, exec, s[6:7]
	global_store_dwordx4 v[90:91], v[76:79], off
	s_cbranch_vccnz .LBB0_842
	v_sub_f32_e32 v87, v87, v92
	v_sub_f32_e32 v86, v86, v92
	v_sub_f32_e32 v85, v85, v92
	v_sub_f32_e32 v84, v84, v92
	v_mov_b32_e32 v100, v94
	v_mov_b32_e32 v101, v94
	v_pk_mul_f32 v[84:85], v[94:95], v[84:85]
	v_pk_mul_f32 v[86:87], v[100:101], v[86:87]
	v_pk_fma_f32 v[84:85], v[84:85], v[182:183], v[186:187]
	v_pk_fma_f32 v[86:87], v[86:87], v[184:185], v[188:189]

;     DEVI void operator()(const f32x4 (&acc)[2][2][4][2], const pg8::Unit& u, int wr, int wc, int fr, int fq) const {
;     ...
;                     for (int n = 0; n < 2; ++n) {
;                         const int col = colb + bj * 128 + 4 * n;
;                         f32x4 xv = *(const f32x4*)(zsrc + (size_t)row * DM + col);
;                         if (stin) { const f32x4 gv = *(const f32x4*)(gin + col), bv = *(const f32x4*)(bin + col); xv = (xv - mu) * rs * gv + bv; }
;                         f32x4 zz = ALPHA * xv + acc[ai][bj][m][n];
;                         if (bias) zz += *(const f32x4*)(bias + col);
;                         *(f32x4*)(zdst + (size_t)row * DM + col) = zz;
;                         sum += zz[0] + zz[1] + zz[2] + zz[3]; sq += zz[0] * zz[0] + zz[1] * zz[1] + zz[2] * zz[2] + zz[3] * zz[3];
;                         z[n] = zz;
.LBB0_844:
	global_load_dwordx4 v[80:83], v[90:91], off offset:528
	global_load_dwordx4 v[182:185], v[152:153], off offset:528
	global_load_dwordx4 v[186:189], v[154:155], off offset:528
	s_waitcnt vmcnt(0)
	v_pk_fma_f32 v[70:71], v[86:87], s[26:27], v[70:71] op_sel_hi:[1,0,1]
	v_pk_fma_f32 v[68:69], v[84:85], s[26:27], v[68:69] op_sel_hi:[1,0,1]
	s_and_b64 vcc, exec, s[6:7]
	global_store_dwordx4 v[90:91], v[68:71], off offset:512
	s_cbranch_vccnz .LBB0_846
	v_sub_f32_e32 v81, v81, v92
	v_sub_f32_e32 v80, v80, v92
	v_sub_f32_e32 v83, v83, v92
	v_sub_f32_e32 v82, v82, v92
	v_pk_mul_f32 v[80:81], v[94:95], v[80:81]
	v_mov_b32_e32 v95, v94
	v_pk_mul_f32 v[82:83], v[94:95], v[82:83]
	v_pk_fma_f32 v[80:81], v[80:81], v[182:183], v[186:187]
	v_pk_fma_f32 v[82:83], v[82:83], v[184:185], v[188:189]

;     DEVI void operator()(const f32x4 (&acc)[2][2][4][2], const pg8::Unit& u, int wr, int wc, int fr, int fq) const {
;     ...
;                     for (int n = 0; n < 2; ++n) {
;                         const int col = colb + bj * 128 + 4 * n;
;                         f32x4 xv = *(const f32x4*)(zsrc + (size_t)row * DM + col);
;                         if (stin) { const f32x4 gv = *(const f32x4*)(gin + col), bv = *(const f32x4*)(bin + col); xv = (xv - mu) * rs * gv + bv; }
;                         f32x4 zz = ALPHA * xv + acc[ai][bj][m][n];
;                         if (bias) zz += *(const f32x4*)(bias + col);
;                         *(f32x4*)(zdst + (size_t)row * DM + col) = zz;
;                         sum += zz[0] + zz[1] + zz[2] + zz[3]; sq += zz[0] * zz[0] + zz[1] * zz[1] + zz[2] * zz[2] + zz[3] * zz[3];
;                         z[n] = zz;
.LBB0_853:
	global_load_dwordx4 v[68:71], v[74:75], off offset:16
	global_load_dwordx4 v[182:185], v[152:153], off offset:16
	global_load_dwordx4 v[186:189], v[154:155], off offset:16
	s_waitcnt vmcnt(0)
	v_pk_fma_f32 v[62:63], v[66:67], s[26:27], v[62:63] op_sel_hi:[1,0,1]
	v_pk_fma_f32 v[60:61], v[64:65], s[26:27], v[60:61] op_sel_hi:[1,0,1]
	s_and_b64 vcc, exec, s[6:7]
	global_store_dwordx4 v[74:75], v[60:63], off
	s_cbranch_vccnz .LBB0_855
	v_sub_f32_e32 v71, v71, v76
	v_sub_f32_e32 v70, v70, v76
	v_sub_f32_e32 v69, v69, v76
	v_sub_f32_e32 v68, v68, v76
	v_mov_b32_e32 v84, v78
	v_mov_b32_e32 v85, v78
	v_pk_mul_f32 v[68:69], v[78:79], v[68:69]
	v_pk_mul_f32 v[70:71], v[84:85], v[70:71]
	v_pk_fma_f32 v[68:69], v[68:69], v[182:183], v[186:187]
	v_pk_fma_f32 v[70:71], v[70:71], v[184:185], v[188:189]

;     DEVI void operator()(const f32x4 (&acc)[2][2][4][2], const pg8::Unit& u, int wr, int wc, int fr, int fq) const {
;     ...
;                     for (int n = 0; n < 2; ++n) {
;                         const int col = colb + bj * 128 + 4 * n;
;                         f32x4 xv = *(const f32x4*)(zsrc + (size_t)row * DM + col);
;                         if (stin) { const f32x4 gv = *(const f32x4*)(gin + col), bv = *(const f32x4*)(bin + col); xv = (xv - mu) * rs * gv + bv; }
;                         f32x4 zz = ALPHA * xv + acc[ai][bj][m][n];
;                         if (bias) zz += *(const f32x4*)(bias + col);
;                         *(f32x4*)(zdst + (size_t)row * DM + col) = zz;
;                         sum += zz[0] + zz[1] + zz[2] + zz[3]; sq += zz[0] * zz[0] + zz[1] * zz[1] + zz[2] * zz[2] + zz[3] * zz[3];
;                         z[n] = zz;
.LBB0_857:
	global_load_dwordx4 v[64:67], v[74:75], off offset:528
	global_load_dwordx4 v[182:185], v[152:153], off offset:528
	global_load_dwordx4 v[186:189], v[154:155], off offset:528
	s_waitcnt vmcnt(0)
	v_pk_fma_f32 v[54:55], v[70:71], s[26:27], v[54:55] op_sel_hi:[1,0,1]
	v_pk_fma_f32 v[52:53], v[68:69], s[26:27], v[52:53] op_sel_hi:[1,0,1]
	s_and_b64 vcc, exec, s[6:7]
	global_store_dwordx4 v[74:75], v[52:55], off offset:512
	s_cbranch_vccnz .LBB0_859
	v_sub_f32_e32 v65, v65, v76
	v_sub_f32_e32 v64, v64, v76
	v_sub_f32_e32 v67, v67, v76
	v_sub_f32_e32 v66, v66, v76
	v_pk_mul_f32 v[64:65], v[78:79], v[64:65]
	v_mov_b32_e32 v79, v78
	v_pk_mul_f32 v[66:67], v[78:79], v[66:67]
	v_pk_fma_f32 v[64:65], v[64:65], v[182:183], v[186:187]
	v_pk_fma_f32 v[66:67], v[66:67], v[184:185], v[188:189]

;     DEVI void operator()(const f32x4 (&acc)[2][2][4][2], const pg8::Unit& u, int wr, int wc, int fr, int fq) const {
;     ...
;                     for (int n = 0; n < 2; ++n) {
;                         const int col = colb + bj * 128 + 4 * n;
;                         f32x4 xv = *(const f32x4*)(zsrc + (size_t)row * DM + col);
;                         if (stin) { const f32x4 gv = *(const f32x4*)(gin + col), bv = *(const f32x4*)(bin + col); xv = (xv - mu) * rs * gv + bv; }
;                         f32x4 zz = ALPHA * xv + acc[ai][bj][m][n];
;                         if (bias) zz += *(const f32x4*)(bias + col);
;                         *(f32x4*)(zdst + (size_t)row * DM + col) = zz;
;                         sum += zz[0] + zz[1] + zz[2] + zz[3]; sq += zz[0] * zz[0] + zz[1] * zz[1] + zz[2] * zz[2] + zz[3] * zz[3];
;                         z[n] = zz;
.LBB0_866:
	global_load_dwordx4 v[52:55], v[58:59], off offset:16
	global_load_dwordx4 v[182:185], v[152:153], off offset:16
	global_load_dwordx4 v[186:189], v[154:155], off offset:16
	s_waitcnt vmcnt(0)
	v_pk_fma_f32 v[46:47], v[50:51], s[26:27], v[46:47] op_sel_hi:[1,0,1]
	v_pk_fma_f32 v[44:45], v[48:49], s[26:27], v[44:45] op_sel_hi:[1,0,1]
	s_and_b64 vcc, exec, s[6:7]
	global_store_dwordx4 v[58:59], v[44:47], off
	s_cbranch_vccnz .LBB0_868
	v_sub_f32_e32 v55, v55, v60
	v_sub_f32_e32 v54, v54, v60
	v_sub_f32_e32 v53, v53, v60
	v_sub_f32_e32 v52, v52, v60
	v_mov_b32_e32 v68, v62
	v_mov_b32_e32 v69, v62
	v_pk_mul_f32 v[52:53], v[62:63], v[52:53]
	v_pk_mul_f32 v[54:55], v[68:69], v[54:55]
	v_pk_fma_f32 v[52:53], v[52:53], v[182:183], v[186:187]
	v_pk_fma_f32 v[54:55], v[54:55], v[184:185], v[188:189]

;     DEVI void operator()(const f32x4 (&acc)[2][2][4][2], const pg8::Unit& u, int wr, int wc, int fr, int fq) const {
;     ...
;                     for (int n = 0; n < 2; ++n) {
;                         const int col = colb + bj * 128 + 4 * n;
;                         f32x4 xv = *(const f32x4*)(zsrc + (size_t)row * DM + col);
;                         if (stin) { const f32x4 gv = *(const f32x4*)(gin + col), bv = *(const f32x4*)(bin + col); xv = (xv - mu) * rs * gv + bv; }
;                         f32x4 zz = ALPHA * xv + acc[ai][bj][m][n];
;                         if (bias) zz += *(const f32x4*)(bias + col);
;                         *(f32x4*)(zdst + (size_t)row * DM + col) = zz;
;                         sum += zz[0] + zz[1] + zz[2] + zz[3]; sq += zz[0] * zz[0] + zz[1] * zz[1] + zz[2] * zz[2] + zz[3] * zz[3];
;                         z[n] = zz;
.LBB0_870:
	global_load_dwordx4 v[48:51], v[58:59], off offset:528
	global_load_dwordx4 v[182:185], v[152:153], off offset:528
	global_load_dwordx4 v[186:189], v[154:155], off offset:528
	s_waitcnt vmcnt(0)
	v_pk_fma_f32 v[38:39], v[54:55], s[26:27], v[38:39] op_sel_hi:[1,0,1]
	v_pk_fma_f32 v[36:37], v[52:53], s[26:27], v[36:37] op_sel_hi:[1,0,1]
	s_and_b64 vcc, exec, s[6:7]
	global_store_dwordx4 v[58:59], v[36:39], off offset:512
	s_cbranch_vccnz .LBB0_872
	v_sub_f32_e32 v49, v49, v60
	v_sub_f32_e32 v48, v48, v60
	v_sub_f32_e32 v51, v51, v60
	v_sub_f32_e32 v50, v50, v60
	v_pk_mul_f32 v[48:49], v[62:63], v[48:49]
	v_mov_b32_e32 v63, v62
	v_pk_mul_f32 v[50:51], v[62:63], v[50:51]
	v_pk_fma_f32 v[48:49], v[48:49], v[182:183], v[186:187]
	v_pk_fma_f32 v[50:51], v[50:51], v[184:185], v[188:189]

;     DEVI void operator()(const f32x4 (&acc)[2][2][4][2], const pg8::Unit& u, int wr, int wc, int fr, int fq) const {
;     ...
;                     for (int n = 0; n < 2; ++n) {
;                         const int col = colb + bj * 128 + 4 * n;
;                         f32x4 xv = *(const f32x4*)(zsrc + (size_t)row * DM + col);
;                         if (stin) { const f32x4 gv = *(const f32x4*)(gin + col), bv = *(const f32x4*)(bin + col); xv = (xv - mu) * rs * gv + bv; }
;                         f32x4 zz = ALPHA * xv + acc[ai][bj][m][n];
;                         if (bias) zz += *(const f32x4*)(bias + col);
;                         *(f32x4*)(zdst + (size_t)row * DM + col) = zz;
;                         sum += zz[0] + zz[1] + zz[2] + zz[3]; sq += zz[0] * zz[0] + zz[1] * zz[1] + zz[2] * zz[2] + zz[3] * zz[3];
;                         z[n] = zz;
.LBB0_879:
	global_load_dwordx4 v[36:39], v[42:43], off offset:16
	global_load_dwordx4 v[182:185], v[152:153], off offset:16
	global_load_dwordx4 v[186:189], v[154:155], off offset:16
	s_waitcnt vmcnt(0)
	v_pk_fma_f32 v[30:31], v[34:35], s[26:27], v[30:31] op_sel_hi:[1,0,1]
	v_pk_fma_f32 v[28:29], v[32:33], s[26:27], v[28:29] op_sel_hi:[1,0,1]
	s_and_b64 vcc, exec, s[6:7]
	global_store_dwordx4 v[42:43], v[28:31], off
	s_cbranch_vccnz .LBB0_881
	v_sub_f32_e32 v39, v39, v44
	v_sub_f32_e32 v38, v38, v44
	v_sub_f32_e32 v37, v37, v44
	v_sub_f32_e32 v36, v36, v44
	v_mov_b32_e32 v52, v46
	v_mov_b32_e32 v53, v46
	v_pk_mul_f32 v[36:37], v[46:47], v[36:37]
	v_pk_mul_f32 v[38:39], v[52:53], v[38:39]
	v_pk_fma_f32 v[36:37], v[36:37], v[182:183], v[186:187]
	v_pk_fma_f32 v[38:39], v[38:39], v[184:185], v[188:189]

;     DEVI void operator()(const f32x4 (&acc)[2][2][4][2], const pg8::Unit& u, int wr, int wc, int fr, int fq) const {
;     ...
;                     for (int n = 0; n < 2; ++n) {
;                         const int col = colb + bj * 128 + 4 * n;
;                         f32x4 xv = *(const f32x4*)(zsrc + (size_t)row * DM + col);
;                         if (stin) { const f32x4 gv = *(const f32x4*)(gin + col), bv = *(const f32x4*)(bin + col); xv = (xv - mu) * rs * gv + bv; }
;                         f32x4 zz = ALPHA * xv + acc[ai][bj][m][n];
;                         if (bias) zz += *(const f32x4*)(bias + col);
;                         *(f32x4*)(zdst + (size_t)row * DM + col) = zz;
;                         sum += zz[0] + zz[1] + zz[2] + zz[3]; sq += zz[0] * zz[0] + zz[1] * zz[1] + zz[2] * zz[2] + zz[3] * zz[3];
;                         z[n] = zz;
.LBB0_883:
	global_load_dwordx4 v[32:35], v[42:43], off offset:528
	global_load_dwordx4 v[182:185], v[152:153], off offset:528
	global_load_dwordx4 v[186:189], v[154:155], off offset:528
	s_waitcnt vmcnt(0)
	v_pk_fma_f32 v[22:23], v[38:39], s[26:27], v[22:23] op_sel_hi:[1,0,1]
	v_pk_fma_f32 v[20:21], v[36:37], s[26:27], v[20:21] op_sel_hi:[1,0,1]
	s_and_b64 vcc, exec, s[6:7]
	global_store_dwordx4 v[42:43], v[20:23], off offset:512
	s_cbranch_vccnz .LBB0_885
	v_sub_f32_e32 v33, v33, v44
	v_sub_f32_e32 v32, v32, v44
	v_sub_f32_e32 v35, v35, v44
	v_sub_f32_e32 v34, v34, v44
	v_pk_mul_f32 v[32:33], v[46:47], v[32:33]
	v_mov_b32_e32 v47, v46
	v_pk_mul_f32 v[34:35], v[46:47], v[34:35]
	v_pk_fma_f32 v[32:33], v[32:33], v[182:183], v[186:187]
	v_pk_fma_f32 v[34:35], v[34:35], v[184:185], v[188:189]

;     DEVI void operator()(const f32x4 (&acc)[2][2][4][2], const pg8::Unit& u, int wr, int wc, int fr, int fq) const {
;     ...
;                     for (int n = 0; n < 2; ++n) {
;                         const int col = colb + bj * 128 + 4 * n;
;                         f32x4 xv = *(const f32x4*)(zsrc + (size_t)row * DM + col);
;                         if (stin) { const f32x4 gv = *(const f32x4*)(gin + col), bv = *(const f32x4*)(bin + col); xv = (xv - mu) * rs * gv + bv; }
;                         f32x4 zz = ALPHA * xv + acc[ai][bj][m][n];
;                         if (bias) zz += *(const f32x4*)(bias + col);
;                         *(f32x4*)(zdst + (size_t)row * DM + col) = zz;
;                         sum += zz[0] + zz[1] + zz[2] + zz[3]; sq += zz[0] * zz[0] + zz[1] * zz[1] + zz[2] * zz[2] + zz[3] * zz[3];
;                         z[n] = zz;
.LBB0_892:
	global_load_dwordx4 v[20:23], v[26:27], off offset:16
	global_load_dwordx4 v[182:185], v[152:153], off offset:16
	global_load_dwordx4 v[186:189], v[154:155], off offset:16
	s_waitcnt vmcnt(0)
	v_pk_fma_f32 v[14:15], v[18:19], s[26:27], v[14:15] op_sel_hi:[1,0,1]
	v_pk_fma_f32 v[12:13], v[16:17], s[26:27], v[12:13] op_sel_hi:[1,0,1]
	s_and_b64 vcc, exec, s[6:7]
	global_store_dwordx4 v[26:27], v[12:15], off
	s_cbranch_vccnz .LBB0_894
	v_sub_f32_e32 v23, v23, v28
	v_sub_f32_e32 v22, v22, v28
	v_sub_f32_e32 v21, v21, v28
	v_sub_f32_e32 v20, v20, v28
	v_mov_b32_e32 v36, v30
	v_mov_b32_e32 v37, v30
	v_pk_mul_f32 v[20:21], v[30:31], v[20:21]
	v_pk_mul_f32 v[22:23], v[36:37], v[22:23]
	v_pk_fma_f32 v[20:21], v[20:21], v[182:183], v[186:187]
	v_pk_fma_f32 v[22:23], v[22:23], v[184:185], v[188:189]

;     DEVI void operator()(const f32x4 (&acc)[2][2][4][2], const pg8::Unit& u, int wr, int wc, int fr, int fq) const {
;     ...
;                     for (int n = 0; n < 2; ++n) {
;                         const int col = colb + bj * 128 + 4 * n;
;                         f32x4 xv = *(const f32x4*)(zsrc + (size_t)row * DM + col);
;                         if (stin) { const f32x4 gv = *(const f32x4*)(gin + col), bv = *(const f32x4*)(bin + col); xv = (xv - mu) * rs * gv + bv; }
;                         f32x4 zz = ALPHA * xv + acc[ai][bj][m][n];
;                         if (bias) zz += *(const f32x4*)(bias + col);
;                         *(f32x4*)(zdst + (size_t)row * DM + col) = zz;
;                         sum += zz[0] + zz[1] + zz[2] + zz[3]; sq += zz[0] * zz[0] + zz[1] * zz[1] + zz[2] * zz[2] + zz[3] * zz[3];
;                         z[n] = zz;
.LBB0_896:
	global_load_dwordx4 v[16:19], v[26:27], off offset:528
	global_load_dwordx4 v[182:185], v[152:153], off offset:528
	global_load_dwordx4 v[186:189], v[154:155], off offset:528
	s_waitcnt vmcnt(0)
	v_pk_fma_f32 v[6:7], v[22:23], s[26:27], v[6:7] op_sel_hi:[1,0,1]
	v_pk_fma_f32 v[4:5], v[20:21], s[26:27], v[4:5] op_sel_hi:[1,0,1]
	s_and_b64 vcc, exec, s[6:7]
	global_store_dwordx4 v[26:27], v[4:7], off offset:512
	s_cbranch_vccnz .LBB0_898
	v_sub_f32_e32 v17, v17, v28
	v_sub_f32_e32 v16, v16, v28
	v_sub_f32_e32 v19, v19, v28
	v_sub_f32_e32 v18, v18, v28
	v_pk_mul_f32 v[16:17], v[30:31], v[16:17]
	v_mov_b32_e32 v31, v30
	v_pk_mul_f32 v[18:19], v[30:31], v[18:19]
	v_pk_fma_f32 v[16:17], v[16:17], v[182:183], v[186:187]
	v_pk_fma_f32 v[18:19], v[18:19], v[184:185], v[188:189]

; DEVI unsigned pk2(float lo, float hi) { unsigned r; asm("v_cvt_pk_bf16_f32 %0, %1, %2" : "=v"(r) : "v"(lo), "v"(hi)); return r; }
;     DEVI void operator()(const f32x4 (&acc)[2][2][4][2], const pg8::Unit& u, int wr, int wc, int fr, int fq) const {
;     ...
;                 const int row = row0 + ai * 128 + m * 16; float mu, rs; row_stats(stin, row, mu, rs);
;                 float sum = 0.f, sq = 0.f;
; #pragma unroll
;                 for (int bj = 0; bj < 2; ++bj) {
;                     f32x4 z[2];
; #pragma unroll
;                     for (int n = 0; n < 2; ++n) {
;                         const int col = colb + bj * 128 + 4 * n;
;                         f32x4 xv = *(const f32x4*)(zsrc + (size_t)row * DM + col);
;                         if (stin) { const f32x4 gv = *(const f32x4*)(gin + col), bv = *(const f32x4*)(bin + col); xv = (xv - mu) * rs * gv + bv; }
;                         f32x4 zz = ALPHA * xv + acc[ai][bj][m][n];
;                         if (bias) zz += *(const f32x4*)(bias + col);
;                         *(f32x4*)(zdst + (size_t)row * DM + col) = zz;
;                         sum += zz[0] + zz[1] + zz[2] + zz[3]; sq += zz[0] * zz[0] + zz[1] * zz[1] + zz[2] * zz[2] + zz[3] * zz[3];
;                         z[n] = zz;
;                     }
;                     u32x4 o; o.x = pk2(z[0][0], z[0][1]); o.y = pk2(z[0][2], z[0][3]); o.z = pk2(z[1][0], z[1][1]); o.w = pk2(z[1][2], z[1][3]);
;                     if (zb) *(u32x4*)(zb + (size_t)row * DM + colb + bj * 128) = o;
;                 }
;                 sum += __shfl_xor(sum, 16); sq += __shfl_xor(sq, 16);
;                 sum += __shfl_xor(sum, 32); sq += __shfl_xor(sq, 32);
;                 if (fq == 0) { atomicAdd(stout + 2 * (size_t)row, sum); atomicAdd(stout + 2 * (size_t)row + 1, sq); }
.LBB0_1331:
	s_or_b64 exec, exec, s[30:31]
	v_or_b32_e32 v126, 16, v150
	v_ashrrev_i32_e32 v127, 31, v126
	v_lshlrev_b64 v[112:113], 3, v[126:127]
	s_waitcnt lgkmcnt(0)
	v_lshl_add_u64 v[114:115], s[6:7], 0, v[112:113]
	flat_load_dwordx2 v[160:161], v[114:115]
	v_lshlrev_b64 v[114:115], 12, v[126:127]
	v_lshl_add_u64 v[114:115], s[46:47], 0, v[114:115]
	v_lshl_add_u64 v[114:115], v[148:149], 2, v[114:115]
	global_load_dwordx4 v[122:125], v[114:115], off
	global_load_dwordx4 v[156:159], v[144:145], off
	global_load_dwordx4 v[170:173], v[146:147], off
	global_load_dwordx4 v[174:177], v[152:153], off
	global_load_dwordx4 v[178:181], v[114:115], off offset:16
	v_lshlrev_b64 v[126:127], 11, v[126:127]
	v_lshl_add_u64 v[126:127], s[10:11], 0, v[126:127]
	v_lshl_add_u64 v[126:127], v[148:149], 1, v[126:127]
	global_load_dwordx4 v[196:199], v[144:145], off offset:16
	global_load_dwordx4 v[200:203], v[146:147], off offset:16
	global_load_dwordx4 v[204:207], v[154:155], off
	s_waitcnt vmcnt(0) lgkmcnt(0)
	v_pk_mul_f32 v[160:161], v[160:161], s[18:19] op_sel:[1,0] op_sel_hi:[0,0]
	v_fma_f32 v151, -v161, v161, v160
	v_max_f32_e32 v151, 0, v151
	v_add_f32_e32 v151, 0x3727c5ac, v151
	v_mul_f32_e32 v160, 0x4b800000, v151
	v_cmp_gt_f32_e32 vcc, s64, v151
	v_sub_f32_e32 v125, v125, v161
	v_sub_f32_e32 v124, v124, v161
	v_cndmask_b32_e32 v151, v151, v160, vcc
	v_rsq_f32_e32 v151, v151
	v_sub_f32_e32 v123, v123, v161
	v_sub_f32_e32 v122, v122, v161
	v_mul_f32_e32 v160, 0x45800000, v151
	v_cndmask_b32_e32 v160, v151, v160, vcc
	v_pk_mul_f32 v[122:123], v[122:123], v[160:161] op_sel_hi:[1,0]
	v_pk_mul_f32 v[124:125], v[124:125], v[160:161] op_sel_hi:[1,0]
	v_pk_fma_f32 v[122:123], v[156:157], v[122:123], v[170:171]
	v_pk_fma_f32 v[124:125], v[158:159], v[124:125], v[172:173]
	v_pk_fma_f32 v[108:109], v[122:123], s[20:21], v[108:109] op_sel_hi:[1,0,1]
	v_pk_fma_f32 v[110:111], v[124:125], s[20:21], v[110:111] op_sel_hi:[1,0,1]
	v_pk_add_f32 v[108:109], v[174:175], v[108:109]
	v_pk_add_f32 v[110:111], v[176:177], v[110:111]
	global_store_dwordx4 v[114:115], v[108:111], off
	v_sub_f32_e32 v175, v181, v161
	v_sub_f32_e32 v174, v180, v161
	v_sub_f32_e32 v177, v179, v161
	v_sub_f32_e32 v176, v178, v161
	v_pk_mul_f32 v[176:177], v[176:177], v[160:161] op_sel_hi:[1,0]
	v_pk_mul_f32 v[178:179], v[174:175], v[160:161] op_sel_hi:[1,0]
	v_cvt_pk_bf16_f32 v174, v108, v109
	v_cvt_pk_bf16_f32 v175, v110, v111
	v_add_f32_e32 v151, v108, v109
	v_mul_f32_e32 v109, v109, v109
	v_fmac_f32_e32 v109, v108, v108
	v_add_f32_e32 v151, v110, v151
	v_fmac_f32_e32 v109, v110, v110
	v_add_f32_e32 v108, v111, v151
	v_add_f32_e32 v108, 0, v108
	v_fmac_f32_e32 v109, v111, v111
	v_pk_fma_f32 v[124:125], v[198:199], v[178:179], v[202:203]
	v_pk_fma_f32 v[122:123], v[196:197], v[176:177], v[200:201]
	v_pk_fma_f32 v[106:107], v[124:125], s[20:21], v[106:107] op_sel_hi:[1,0,1]
	v_pk_fma_f32 v[104:105], v[122:123], s[20:21], v[104:105] op_sel_hi:[1,0,1]
	v_pk_add_f32 v[106:107], v[206:207], v[106:107]
	v_pk_add_f32 v[104:105], v[204:205], v[104:105]
	global_store_dwordx4 v[114:115], v[104:107], off offset:16
	v_cvt_pk_bf16_f32 v176, v104, v105
	v_cvt_pk_bf16_f32 v177, v106, v107
	flat_store_dwordx4 v[126:127], v[174:177]
	global_load_dwordx4 v[122:125], v[114:115], off offset:512
	global_load_dwordx4 v[156:159], v[144:145], off offset:512
	global_load_dwordx4 v[170:173], v[146:147], off offset:512
	s_nop 0
	global_load_dwordx4 v[174:177], v[120:121], off
	global_load_dwordx4 v[178:181], v[114:115], off offset:528
	v_add_f32_e32 v110, v104, v105
	v_mul_f32_e32 v105, v105, v105
	v_fmac_f32_e32 v105, v104, v104
	v_add_f32_e32 v110, v106, v110
	v_fmac_f32_e32 v105, v106, v106
	v_add_f32_e32 v104, v107, v110
	v_fmac_f32_e32 v105, v107, v107
	v_add_f32_e32 v108, v104, v108
	v_add_f32_e32 v109, v109, v105
	global_load_dwordx4 v[196:199], v[144:145], off offset:528
	global_load_dwordx4 v[200:203], v[146:147], off offset:528
	global_load_dwordx4 v[204:207], v[116:117], off
	s_waitcnt vmcnt(0)
	v_sub_f32_e32 v125, v125, v161
	v_sub_f32_e32 v124, v124, v161
	v_sub_f32_e32 v123, v123, v161
	v_sub_f32_e32 v122, v122, v161
	v_pk_mul_f32 v[122:123], v[160:161], v[122:123] op_sel_hi:[0,1]
	v_pk_mul_f32 v[124:125], v[160:161], v[124:125] op_sel_hi:[0,1]
	v_pk_fma_f32 v[124:125], v[158:159], v[124:125], v[172:173]
	v_pk_fma_f32 v[122:123], v[156:157], v[122:123], v[170:171]
	v_pk_fma_f32 v[102:103], v[124:125], s[20:21], v[102:103] op_sel_hi:[1,0,1]
	v_pk_fma_f32 v[100:101], v[122:123], s[20:21], v[100:101] op_sel_hi:[1,0,1]
	v_pk_add_f32 v[102:103], v[176:177], v[102:103]
	v_pk_add_f32 v[100:101], v[174:175], v[100:101]
	global_store_dwordx4 v[114:115], v[100:103], off offset:512
	v_sub_f32_e32 v107, v179, v161
	v_sub_f32_e32 v106, v178, v161
	v_sub_f32_e32 v105, v181, v161
	v_sub_f32_e32 v104, v180, v161
	v_pk_mul_f32 v[106:107], v[160:161], v[106:107] op_sel_hi:[0,1]
	v_pk_mul_f32 v[104:105], v[160:161], v[104:105] op_sel_hi:[0,1]
	v_mul_f32_e32 v111, v101, v101
	v_add_f32_e32 v110, v100, v101
	v_fmac_f32_e32 v111, v100, v100
	v_add_f32_e32 v110, v102, v110
	v_fmac_f32_e32 v111, v102, v102
	v_add_f32_e32 v110, v103, v110
	v_fmac_f32_e32 v111, v103, v103
	v_add_f32_e32 v108, v108, v110
	v_add_f32_e32 v109, v109, v111
	v_cvt_pk_bf16_f32 v100, v100, v101
	v_cvt_pk_bf16_f32 v101, v102, v103
	v_pk_fma_f32 v[106:107], v[196:197], v[106:107], v[200:201]
	v_pk_fma_f32 v[104:105], v[198:199], v[104:105], v[202:203]
	v_pk_fma_f32 v[96:97], v[106:107], s[20:21], v[96:97] op_sel_hi:[1,0,1]
	v_pk_fma_f32 v[98:99], v[104:105], s[20:21], v[98:99] op_sel_hi:[1,0,1]
	v_pk_add_f32 v[104:105], v[204:205], v[96:97]
	v_pk_add_f32 v[106:107], v[206:207], v[98:99]
	v_mul_f32_e32 v97, v105, v105
	v_add_f32_e32 v96, v104, v105
	v_fmac_f32_e32 v97, v104, v104
	v_add_f32_e32 v96, v106, v96
	v_fmac_f32_e32 v97, v106, v106
	v_add_f32_e32 v96, v107, v96
	v_fmac_f32_e32 v97, v107, v107
	v_add_f32_e32 v96, v108, v96
	v_add_f32_e32 v97, v109, v97
	ds_bpermute_b32 v98, v118, v96
	ds_bpermute_b32 v99, v118, v97
	global_store_dwordx4 v[114:115], v[104:107], off offset:528
	v_cvt_pk_bf16_f32 v102, v104, v105
	v_cvt_pk_bf16_f32 v103, v106, v107
	s_waitcnt lgkmcnt(0)
	v_add_f32_e32 v96, v96, v98
	v_add_f32_e32 v97, v97, v99
	ds_bpermute_b32 v98, v119, v96
	ds_bpermute_b32 v99, v119, v97
	flat_store_dwordx4 v[126:127], v[100:103] offset:256
	s_and_saveexec_b64 s[30:31], s[2:3]
	s_cbranch_execz .LBB0_1333
	v_lshl_add_u64 v[100:101], s[8:9], 0, v[112:113]
	s_waitcnt lgkmcnt(0)
	v_add_f32_e32 v96, v96, v98
	v_add_f32_e32 v97, v97, v99
	flat_atomic_add_f32 v[100:101], v96
	flat_atomic_add_f32 v[100:101], v97 offset:4
; DEVI unsigned pk2(float lo, float hi) { unsigned r; asm("v_cvt_pk_bf16_f32 %0, %1, %2" : "=v"(r) : "v"(lo), "v"(hi)); return r; }
;     DEVI void operator()(const f32x4 (&acc)[2][2][4][2], const pg8::Unit& u, int wr, int wc, int fr, int fq) const {
;     ...
;                 const int row = row0 + ai * 128 + m * 16; float mu, rs; row_stats(stin, row, mu, rs);
;                 float sum = 0.f, sq = 0.f;
; #pragma unroll
;                 for (int bj = 0; bj < 2; ++bj) {
;                     f32x4 z[2];
; #pragma unroll
;                     for (int n = 0; n < 2; ++n) {
;                         const int col = colb + bj * 128 + 4 * n;
;                         f32x4 xv = *(const f32x4*)(zsrc + (size_t)row * DM + col);
;                         if (stin) { const f32x4 gv = *(const f32x4*)(gin + col), bv = *(const f32x4*)(bin + col); xv = (xv - mu) * rs * gv + bv; }
;                         f32x4 zz = ALPHA * xv + acc[ai][bj][m][n];
;                         if (bias) zz += *(const f32x4*)(bias + col);
;                         *(f32x4*)(zdst + (size_t)row * DM + col) = zz;
;                         sum += zz[0] + zz[1] + zz[2] + zz[3]; sq += zz[0] * zz[0] + zz[1] * zz[1] + zz[2] * zz[2] + zz[3] * zz[3];
;                         z[n] = zz;
;                     }
;                     u32x4 o; o.x = pk2(z[0][0], z[0][1]); o.y = pk2(z[0][2], z[0][3]); o.z = pk2(z[1][0], z[1][1]); o.w = pk2(z[1][2], z[1][3]);
;                     if (zb) *(u32x4*)(zb + (size_t)row * DM + colb + bj * 128) = o;
;                 }
;                 sum += __shfl_xor(sum, 16); sq += __shfl_xor(sq, 16);
;                 sum += __shfl_xor(sum, 32); sq += __shfl_xor(sq, 32);
;                 if (fq == 0) { atomicAdd(stout + 2 * (size_t)row, sum); atomicAdd(stout + 2 * (size_t)row + 1, sq); }
.LBB0_1333:
	s_or_b64 exec, exec, s[30:31]
	v_or_b32_e32 v126, 32, v150
	v_ashrrev_i32_e32 v127, 31, v126
	v_lshlrev_b64 v[96:97], 3, v[126:127]
	s_waitcnt lgkmcnt(0)
	v_lshl_add_u64 v[98:99], s[6:7], 0, v[96:97]
	flat_load_dwordx2 v[156:157], v[98:99]
	v_lshlrev_b64 v[98:99], 12, v[126:127]
	v_lshl_add_u64 v[98:99], s[46:47], 0, v[98:99]
	v_lshl_add_u64 v[98:99], v[148:149], 2, v[98:99]
	global_load_dwordx4 v[100:103], v[98:99], off
	global_load_dwordx4 v[104:107], v[144:145], off
	global_load_dwordx4 v[108:111], v[146:147], off
	global_load_dwordx4 v[112:115], v[152:153], off
	global_load_dwordx4 v[122:125], v[98:99], off offset:16
	global_load_dwordx4 v[196:199], v[144:145], off offset:16
	global_load_dwordx4 v[200:203], v[146:147], off offset:16
	global_load_dwordx4 v[204:207], v[154:155], off
	s_waitcnt vmcnt(0) lgkmcnt(0)
	v_pk_mul_f32 v[156:157], v[156:157], s[18:19] op_sel:[1,0] op_sel_hi:[0,0]
	v_fma_f32 v151, -v157, v157, v156
	v_max_f32_e32 v151, 0, v151
	v_add_f32_e32 v151, 0x3727c5ac, v151
	v_mul_f32_e32 v156, 0x4b800000, v151
	v_cmp_gt_f32_e32 vcc, s64, v151
	v_sub_f32_e32 v103, v103, v157
	v_sub_f32_e32 v102, v102, v157
	v_cndmask_b32_e32 v151, v151, v156, vcc
	v_rsq_f32_e32 v151, v151
	v_sub_f32_e32 v101, v101, v157
	v_sub_f32_e32 v100, v100, v157
	v_mul_f32_e32 v156, 0x45800000, v151
	v_cndmask_b32_e32 v156, v151, v156, vcc
	v_pk_mul_f32 v[100:101], v[100:101], v[156:157] op_sel_hi:[1,0]
	v_pk_mul_f32 v[102:103], v[102:103], v[156:157] op_sel_hi:[1,0]
	v_pk_fma_f32 v[100:101], v[104:105], v[100:101], v[108:109]
	v_pk_fma_f32 v[102:103], v[106:107], v[102:103], v[110:111]
	v_pk_fma_f32 v[92:93], v[100:101], s[20:21], v[92:93] op_sel_hi:[1,0,1]
	v_pk_fma_f32 v[94:95], v[102:103], s[20:21], v[94:95] op_sel_hi:[1,0,1]
	v_pk_add_f32 v[92:93], v[112:113], v[92:93]
	v_pk_add_f32 v[94:95], v[114:115], v[94:95]
	global_store_dwordx4 v[98:99], v[92:95], off
	v_lshlrev_b64 v[112:113], 11, v[126:127]
	v_lshl_add_u64 v[112:113], s[10:11], 0, v[112:113]
	v_lshl_add_u64 v[126:127], v[148:149], 1, v[112:113]
	v_sub_f32_e32 v113, v125, v157
	v_sub_f32_e32 v112, v124, v157
	v_sub_f32_e32 v115, v123, v157
	v_sub_f32_e32 v114, v122, v157
	v_pk_mul_f32 v[114:115], v[114:115], v[156:157] op_sel_hi:[1,0]
	v_pk_mul_f32 v[122:123], v[112:113], v[156:157] op_sel_hi:[1,0]
	v_cvt_pk_bf16_f32 v112, v92, v93
	v_cvt_pk_bf16_f32 v113, v94, v95
	v_pk_fma_f32 v[100:101], v[196:197], v[114:115], v[200:201]
	v_pk_fma_f32 v[102:103], v[198:199], v[122:123], v[202:203]
	v_pk_fma_f32 v[88:89], v[100:101], s[20:21], v[88:89] op_sel_hi:[1,0,1]
	v_pk_fma_f32 v[90:91], v[102:103], s[20:21], v[90:91] op_sel_hi:[1,0,1]
	v_pk_add_f32 v[88:89], v[204:205], v[88:89]
	v_pk_add_f32 v[90:91], v[206:207], v[90:91]
	global_store_dwordx4 v[98:99], v[88:91], off offset:16
	v_cvt_pk_bf16_f32 v114, v88, v89
	v_cvt_pk_bf16_f32 v115, v90, v91
	flat_store_dwordx4 v[126:127], v[112:115]
	global_load_dwordx4 v[100:103], v[98:99], off offset:512
	global_load_dwordx4 v[104:107], v[144:145], off offset:512
	global_load_dwordx4 v[108:111], v[146:147], off offset:512
	s_nop 0
	global_load_dwordx4 v[112:115], v[120:121], off
	global_load_dwordx4 v[122:125], v[98:99], off offset:528
	global_load_dwordx4 v[196:199], v[144:145], off offset:528
	global_load_dwordx4 v[200:203], v[146:147], off offset:528
	global_load_dwordx4 v[204:207], v[116:117], off
	s_waitcnt vmcnt(0)
	v_sub_f32_e32 v103, v103, v157
	v_sub_f32_e32 v102, v102, v157
	v_sub_f32_e32 v101, v101, v157
	v_sub_f32_e32 v100, v100, v157
	v_pk_mul_f32 v[100:101], v[156:157], v[100:101] op_sel_hi:[0,1]
	v_pk_mul_f32 v[102:103], v[156:157], v[102:103] op_sel_hi:[0,1]
	v_pk_fma_f32 v[102:103], v[106:107], v[102:103], v[110:111]
	v_pk_fma_f32 v[100:101], v[104:105], v[100:101], v[108:109]
	v_pk_fma_f32 v[86:87], v[102:103], s[20:21], v[86:87] op_sel_hi:[1,0,1]
	v_pk_fma_f32 v[84:85], v[100:101], s[20:21], v[84:85] op_sel_hi:[1,0,1]
	v_pk_add_f32 v[86:87], v[114:115], v[86:87]
	v_pk_add_f32 v[84:85], v[112:113], v[84:85]
	global_store_dwordx4 v[98:99], v[84:87], off offset:512
	v_add_f32_e32 v112, v92, v93
	v_mul_f32_e32 v93, v93, v93
	v_fmac_f32_e32 v93, v92, v92
	v_add_f32_e32 v112, v94, v112
	v_fmac_f32_e32 v93, v94, v94
	v_add_f32_e32 v94, v88, v89
	v_mul_f32_e32 v89, v89, v89
	v_fmac_f32_e32 v89, v88, v88
	v_add_f32_e32 v92, v95, v112
	v_add_f32_e32 v94, v90, v94
	v_fmac_f32_e32 v89, v90, v90
	v_add_f32_e32 v92, 0, v92
	v_fmac_f32_e32 v93, v95, v95
	v_add_f32_e32 v88, v91, v94
	v_fmac_f32_e32 v89, v91, v91
	v_sub_f32_e32 v91, v123, v157
	v_sub_f32_e32 v90, v122, v157
	v_add_f32_e32 v92, v88, v92
	v_add_f32_e32 v93, v93, v89
	v_sub_f32_e32 v89, v125, v157
	v_sub_f32_e32 v88, v124, v157
	v_pk_mul_f32 v[90:91], v[156:157], v[90:91] op_sel_hi:[0,1]
	v_pk_mul_f32 v[88:89], v[156:157], v[88:89] op_sel_hi:[0,1]
	v_mul_f32_e32 v95, v85, v85
	v_add_f32_e32 v94, v84, v85
	v_fmac_f32_e32 v95, v84, v84
	v_add_f32_e32 v94, v86, v94
	v_fmac_f32_e32 v95, v86, v86
	v_add_f32_e32 v94, v87, v94
	v_fmac_f32_e32 v95, v87, v87
	v_add_f32_e32 v92, v92, v94
	v_add_f32_e32 v93, v93, v95
	v_cvt_pk_bf16_f32 v84, v84, v85
	v_cvt_pk_bf16_f32 v85, v86, v87
	v_pk_fma_f32 v[90:91], v[196:197], v[90:91], v[200:201]
	v_pk_fma_f32 v[88:89], v[198:199], v[88:89], v[202:203]
	v_pk_fma_f32 v[80:81], v[90:91], s[20:21], v[80:81] op_sel_hi:[1,0,1]
	v_pk_fma_f32 v[82:83], v[88:89], s[20:21], v[82:83] op_sel_hi:[1,0,1]
	v_pk_add_f32 v[88:89], v[204:205], v[80:81]
	v_pk_add_f32 v[90:91], v[206:207], v[82:83]
	v_mul_f32_e32 v81, v89, v89
	v_add_f32_e32 v80, v88, v89
	v_fmac_f32_e32 v81, v88, v88
	v_add_f32_e32 v80, v90, v80
	v_fmac_f32_e32 v81, v90, v90
	v_add_f32_e32 v80, v91, v80
	v_fmac_f32_e32 v81, v91, v91
	v_add_f32_e32 v80, v92, v80
	v_add_f32_e32 v81, v93, v81
	ds_bpermute_b32 v82, v118, v80
	ds_bpermute_b32 v83, v118, v81
	global_store_dwordx4 v[98:99], v[88:91], off offset:528
	v_cvt_pk_bf16_f32 v86, v88, v89
	v_cvt_pk_bf16_f32 v87, v90, v91
	s_waitcnt lgkmcnt(0)
	v_add_f32_e32 v80, v80, v82
	v_add_f32_e32 v81, v81, v83
	ds_bpermute_b32 v82, v119, v80
	ds_bpermute_b32 v83, v119, v81
	flat_store_dwordx4 v[126:127], v[84:87] offset:256
	s_and_saveexec_b64 s[30:31], s[2:3]
	s_cbranch_execz .LBB0_1335
	v_lshl_add_u64 v[84:85], s[8:9], 0, v[96:97]
	s_waitcnt lgkmcnt(0)
	v_add_f32_e32 v80, v80, v82
	v_add_f32_e32 v81, v81, v83
	flat_atomic_add_f32 v[84:85], v80
	flat_atomic_add_f32 v[84:85], v81 offset:4
; DEVI unsigned pk2(float lo, float hi) { unsigned r; asm("v_cvt_pk_bf16_f32 %0, %1, %2" : "=v"(r) : "v"(lo), "v"(hi)); return r; }
;     DEVI void operator()(const f32x4 (&acc)[2][2][4][2], const pg8::Unit& u, int wr, int wc, int fr, int fq) const {
;     ...
;                 const int row = row0 + ai * 128 + m * 16; float mu, rs; row_stats(stin, row, mu, rs);
;                 float sum = 0.f, sq = 0.f;
; #pragma unroll
;                 for (int bj = 0; bj < 2; ++bj) {
;                     f32x4 z[2];
; #pragma unroll
;                     for (int n = 0; n < 2; ++n) {
;                         const int col = colb + bj * 128 + 4 * n;
;                         f32x4 xv = *(const f32x4*)(zsrc + (size_t)row * DM + col);
;                         if (stin) { const f32x4 gv = *(const f32x4*)(gin + col), bv = *(const f32x4*)(bin + col); xv = (xv - mu) * rs * gv + bv; }
;                         f32x4 zz = ALPHA * xv + acc[ai][bj][m][n];
;                         if (bias) zz += *(const f32x4*)(bias + col);
;                         *(f32x4*)(zdst + (size_t)row * DM + col) = zz;
;                         sum += zz[0] + zz[1] + zz[2] + zz[3]; sq += zz[0] * zz[0] + zz[1] * zz[1] + zz[2] * zz[2] + zz[3] * zz[3];
;                         z[n] = zz;
;                     }
;                     u32x4 o; o.x = pk2(z[0][0], z[0][1]); o.y = pk2(z[0][2], z[0][3]); o.z = pk2(z[1][0], z[1][1]); o.w = pk2(z[1][2], z[1][3]);
;                     if (zb) *(u32x4*)(zb + (size_t)row * DM + colb + bj * 128) = o;
;                 }
;                 sum += __shfl_xor(sum, 16); sq += __shfl_xor(sq, 16);
;                 sum += __shfl_xor(sum, 32); sq += __shfl_xor(sq, 32);
;                 if (fq == 0) { atomicAdd(stout + 2 * (size_t)row, sum); atomicAdd(stout + 2 * (size_t)row + 1, sq); }
.LBB0_1335:
	s_or_b64 exec, exec, s[30:31]
	v_or_b32_e32 v104, 48, v150
	v_ashrrev_i32_e32 v105, 31, v104
	v_lshlrev_b64 v[80:81], 3, v[104:105]
	s_waitcnt lgkmcnt(0)
	v_lshl_add_u64 v[82:83], s[6:7], 0, v[80:81]
	flat_load_dwordx2 v[106:107], v[82:83]
	v_lshlrev_b64 v[82:83], 12, v[104:105]
	v_lshl_add_u64 v[82:83], s[46:47], 0, v[82:83]
	v_lshl_add_u64 v[82:83], v[148:149], 2, v[82:83]
	global_load_dwordx4 v[84:87], v[82:83], off
	global_load_dwordx4 v[88:91], v[144:145], off
	global_load_dwordx4 v[92:95], v[146:147], off
	global_load_dwordx4 v[96:99], v[152:153], off
	global_load_dwordx4 v[100:103], v[82:83], off offset:16
	global_load_dwordx4 v[196:199], v[144:145], off offset:16
	global_load_dwordx4 v[200:203], v[146:147], off offset:16
	global_load_dwordx4 v[204:207], v[154:155], off
	s_waitcnt vmcnt(0) lgkmcnt(0)
	v_pk_mul_f32 v[106:107], v[106:107], s[18:19] op_sel:[1,0] op_sel_hi:[0,0]
	v_fma_f32 v106, -v107, v107, v106
	v_max_f32_e32 v106, 0, v106
	v_add_f32_e32 v106, 0x3727c5ac, v106
	v_mul_f32_e32 v108, 0x4b800000, v106
	v_cmp_gt_f32_e32 vcc, s64, v106
	v_sub_f32_e32 v87, v87, v107
	v_sub_f32_e32 v86, v86, v107
	v_cndmask_b32_e32 v106, v106, v108, vcc
	v_rsq_f32_e32 v106, v106
	v_sub_f32_e32 v85, v85, v107
	v_sub_f32_e32 v84, v84, v107
	v_mul_f32_e32 v108, 0x45800000, v106
	v_cndmask_b32_e32 v106, v106, v108, vcc
	v_pk_mul_f32 v[84:85], v[84:85], v[106:107] op_sel_hi:[1,0]
	v_pk_mul_f32 v[86:87], v[86:87], v[106:107] op_sel_hi:[1,0]
	v_pk_fma_f32 v[84:85], v[88:89], v[84:85], v[92:93]
	v_pk_fma_f32 v[86:87], v[90:91], v[86:87], v[94:95]
	v_pk_fma_f32 v[76:77], v[84:85], s[20:21], v[76:77] op_sel_hi:[1,0,1]
	v_pk_fma_f32 v[78:79], v[86:87], s[20:21], v[78:79] op_sel_hi:[1,0,1]
	v_pk_add_f32 v[76:77], v[96:97], v[76:77]
	v_pk_add_f32 v[78:79], v[98:99], v[78:79]
	global_store_dwordx4 v[82:83], v[76:79], off
	v_lshlrev_b64 v[96:97], 11, v[104:105]
	v_lshl_add_u64 v[96:97], s[10:11], 0, v[96:97]
	v_lshl_add_u64 v[104:105], v[148:149], 1, v[96:97]
	v_sub_f32_e32 v97, v103, v107
	v_sub_f32_e32 v96, v102, v107
	v_sub_f32_e32 v99, v101, v107
	v_sub_f32_e32 v98, v100, v107
	v_pk_mul_f32 v[98:99], v[98:99], v[106:107] op_sel_hi:[1,0]
	v_pk_mul_f32 v[100:101], v[96:97], v[106:107] op_sel_hi:[1,0]
	v_cvt_pk_bf16_f32 v96, v76, v77
	v_cvt_pk_bf16_f32 v97, v78, v79
	v_pk_fma_f32 v[84:85], v[196:197], v[98:99], v[200:201]
	v_pk_fma_f32 v[86:87], v[198:199], v[100:101], v[202:203]
	v_pk_fma_f32 v[72:73], v[84:85], s[20:21], v[72:73] op_sel_hi:[1,0,1]
	v_pk_fma_f32 v[74:75], v[86:87], s[20:21], v[74:75] op_sel_hi:[1,0,1]
	v_pk_add_f32 v[72:73], v[204:205], v[72:73]
	v_pk_add_f32 v[74:75], v[206:207], v[74:75]
	global_store_dwordx4 v[82:83], v[72:75], off offset:16
	v_cvt_pk_bf16_f32 v98, v72, v73
	v_cvt_pk_bf16_f32 v99, v74, v75
	flat_store_dwordx4 v[104:105], v[96:99]
	global_load_dwordx4 v[84:87], v[82:83], off offset:512
	global_load_dwordx4 v[88:91], v[144:145], off offset:512
	global_load_dwordx4 v[92:95], v[146:147], off offset:512
	s_nop 0
	global_load_dwordx4 v[96:99], v[120:121], off
	global_load_dwordx4 v[100:103], v[82:83], off offset:528
	global_load_dwordx4 v[196:199], v[144:145], off offset:528
	global_load_dwordx4 v[200:203], v[146:147], off offset:528
	global_load_dwordx4 v[204:207], v[116:117], off
	s_waitcnt vmcnt(0)
	v_sub_f32_e32 v87, v87, v107
	v_sub_f32_e32 v86, v86, v107
	v_sub_f32_e32 v85, v85, v107
	v_sub_f32_e32 v84, v84, v107
	v_pk_mul_f32 v[84:85], v[106:107], v[84:85] op_sel_hi:[0,1]
	v_pk_mul_f32 v[86:87], v[106:107], v[86:87] op_sel_hi:[0,1]
	v_pk_fma_f32 v[86:87], v[90:91], v[86:87], v[94:95]
	v_pk_fma_f32 v[84:85], v[88:89], v[84:85], v[92:93]
	v_pk_fma_f32 v[70:71], v[86:87], s[20:21], v[70:71] op_sel_hi:[1,0,1]
	v_pk_fma_f32 v[68:69], v[84:85], s[20:21], v[68:69] op_sel_hi:[1,0,1]
	v_pk_add_f32 v[70:71], v[98:99], v[70:71]
	v_pk_add_f32 v[68:69], v[96:97], v[68:69]
	global_store_dwordx4 v[82:83], v[68:71], off offset:512
	v_add_f32_e32 v96, v76, v77
	v_mul_f32_e32 v77, v77, v77
	v_fmac_f32_e32 v77, v76, v76
	v_add_f32_e32 v96, v78, v96
	v_fmac_f32_e32 v77, v78, v78
	v_add_f32_e32 v78, v72, v73
	v_mul_f32_e32 v73, v73, v73
	v_fmac_f32_e32 v73, v72, v72
	v_add_f32_e32 v76, v79, v96
	v_add_f32_e32 v78, v74, v78
	v_fmac_f32_e32 v73, v74, v74
	v_add_f32_e32 v76, 0, v76
	v_fmac_f32_e32 v77, v79, v79
	v_add_f32_e32 v72, v75, v78
	v_fmac_f32_e32 v73, v75, v75
	v_sub_f32_e32 v75, v101, v107
	v_sub_f32_e32 v74, v100, v107
	v_add_f32_e32 v76, v72, v76
	v_add_f32_e32 v77, v77, v73
	v_sub_f32_e32 v73, v103, v107
	v_sub_f32_e32 v72, v102, v107
	v_pk_mul_f32 v[74:75], v[106:107], v[74:75] op_sel_hi:[0,1]
	v_pk_mul_f32 v[72:73], v[106:107], v[72:73] op_sel_hi:[0,1]
	v_mul_f32_e32 v79, v69, v69
	v_add_f32_e32 v78, v68, v69
	v_fmac_f32_e32 v79, v68, v68
	v_add_f32_e32 v78, v70, v78
	v_fmac_f32_e32 v79, v70, v70
	v_add_f32_e32 v78, v71, v78
	v_fmac_f32_e32 v79, v71, v71
	v_add_f32_e32 v76, v76, v78
	v_add_f32_e32 v77, v77, v79
	v_cvt_pk_bf16_f32 v68, v68, v69
	v_cvt_pk_bf16_f32 v69, v70, v71
	v_pk_fma_f32 v[74:75], v[196:197], v[74:75], v[200:201]
	v_pk_fma_f32 v[72:73], v[198:199], v[72:73], v[202:203]
	v_pk_fma_f32 v[64:65], v[74:75], s[20:21], v[64:65] op_sel_hi:[1,0,1]
	v_pk_fma_f32 v[66:67], v[72:73], s[20:21], v[66:67] op_sel_hi:[1,0,1]
	v_pk_add_f32 v[72:73], v[204:205], v[64:65]
	v_pk_add_f32 v[74:75], v[206:207], v[66:67]
	v_mul_f32_e32 v65, v73, v73
	v_add_f32_e32 v64, v72, v73
	v_fmac_f32_e32 v65, v72, v72
	v_add_f32_e32 v64, v74, v64
	v_fmac_f32_e32 v65, v74, v74
	v_add_f32_e32 v64, v75, v64
	v_fmac_f32_e32 v65, v75, v75
	v_add_f32_e32 v64, v76, v64
	v_add_f32_e32 v65, v77, v65
	ds_bpermute_b32 v66, v118, v64
	ds_bpermute_b32 v67, v118, v65
	global_store_dwordx4 v[82:83], v[72:75], off offset:528
	v_cvt_pk_bf16_f32 v70, v72, v73
	v_cvt_pk_bf16_f32 v71, v74, v75
	s_waitcnt lgkmcnt(0)
	v_add_f32_e32 v64, v64, v66
	v_add_f32_e32 v65, v65, v67
	ds_bpermute_b32 v66, v119, v64
	ds_bpermute_b32 v67, v119, v65
	flat_store_dwordx4 v[104:105], v[68:71] offset:256
	s_and_saveexec_b64 s[30:31], s[2:3]
	s_cbranch_execz .LBB0_1337
	v_lshl_add_u64 v[68:69], s[8:9], 0, v[80:81]
	s_waitcnt lgkmcnt(0)
	v_add_f32_e32 v64, v64, v66
	v_add_f32_e32 v65, v65, v67
	flat_atomic_add_f32 v[68:69], v64
	flat_atomic_add_f32 v[68:69], v65 offset:4
; DEVI unsigned pk2(float lo, float hi) { unsigned r; asm("v_cvt_pk_bf16_f32 %0, %1, %2" : "=v"(r) : "v"(lo), "v"(hi)); return r; }
; DEVI void row_stats(const float* stats, int row, float& mu, float& rs) {
;     if (stats) { const float2 st = *(const float2*)(stats + 2 * (size_t)row); mu = st.x * (1.0f / 1024.0f); const float var = st.y * (1.0f / 1024.0f) - mu * mu; rs = rsqrtf(fmaxf(var, 0.f) + LN_EPS); }
;     DEVI void operator()(const f32x4 (&acc)[2][2][4][2], const pg8::Unit& u, int wr, int wc, int fr, int fq) const {
;     ...
;                 const int row = row0 + ai * 128 + m * 16; float mu, rs; row_stats(stin, row, mu, rs);
;                 float sum = 0.f, sq = 0.f;
; #pragma unroll
;                 for (int bj = 0; bj < 2; ++bj) {
;                     f32x4 z[2];
; #pragma unroll
;                     for (int n = 0; n < 2; ++n) {
;                         const int col = colb + bj * 128 + 4 * n;
;                         f32x4 xv = *(const f32x4*)(zsrc + (size_t)row * DM + col);
;                         if (stin) { const f32x4 gv = *(const f32x4*)(gin + col), bv = *(const f32x4*)(bin + col); xv = (xv - mu) * rs * gv + bv; }
;                         f32x4 zz = ALPHA * xv + acc[ai][bj][m][n];
;                         if (bias) zz += *(const f32x4*)(bias + col);
;                         *(f32x4*)(zdst + (size_t)row * DM + col) = zz;
;                         sum += zz[0] + zz[1] + zz[2] + zz[3]; sq += zz[0] * zz[0] + zz[1] * zz[1] + zz[2] * zz[2] + zz[3] * zz[3];
;                         z[n] = zz;
;                     }
;                     u32x4 o; o.x = pk2(z[0][0], z[0][1]); o.y = pk2(z[0][2], z[0][3]); o.z = pk2(z[1][0], z[1][1]); o.w = pk2(z[1][2], z[1][3]);
;                     if (zb) *(u32x4*)(zb + (size_t)row * DM + colb + bj * 128) = o;
;                 }
;                 sum += __shfl_xor(sum, 16); sq += __shfl_xor(sq, 16);
;                 sum += __shfl_xor(sum, 32); sq += __shfl_xor(sq, 32);
;                 if (fq == 0) { atomicAdd(stout + 2 * (size_t)row, sum); atomicAdd(stout + 2 * (size_t)row + 1, sq); }
.LBB0_1337:
	s_or_b64 exec, exec, s[30:31]
	v_add_u32_e32 v88, 0x80, v150
	v_ashrrev_i32_e32 v89, 31, v88
	v_lshlrev_b64 v[64:65], 3, v[88:89]
	s_waitcnt lgkmcnt(0)
	v_lshl_add_u64 v[66:67], s[6:7], 0, v[64:65]
	flat_load_dwordx2 v[90:91], v[66:67]
	v_lshlrev_b64 v[66:67], 12, v[88:89]
	v_lshl_add_u64 v[66:67], s[46:47], 0, v[66:67]
	v_lshl_add_u64 v[66:67], v[148:149], 2, v[66:67]
	global_load_dwordx4 v[68:71], v[66:67], off
	global_load_dwordx4 v[72:75], v[144:145], off
	global_load_dwordx4 v[76:79], v[146:147], off
	global_load_dwordx4 v[80:83], v[152:153], off
	global_load_dwordx4 v[84:87], v[66:67], off offset:16
	global_load_dwordx4 v[196:199], v[144:145], off offset:16
	global_load_dwordx4 v[200:203], v[146:147], off offset:16
	global_load_dwordx4 v[204:207], v[154:155], off
	s_waitcnt vmcnt(0) lgkmcnt(0)
	v_pk_mul_f32 v[90:91], v[90:91], s[18:19] op_sel:[1,0] op_sel_hi:[0,0]
	v_fma_f32 v90, -v91, v91, v90
	v_max_f32_e32 v90, 0, v90
	v_add_f32_e32 v90, 0x3727c5ac, v90
	v_mul_f32_e32 v92, 0x4b800000, v90
	v_cmp_gt_f32_e32 vcc, s64, v90
	v_sub_f32_e32 v71, v71, v91
	v_sub_f32_e32 v70, v70, v91
	v_cndmask_b32_e32 v90, v90, v92, vcc
	v_rsq_f32_e32 v90, v90
	v_sub_f32_e32 v69, v69, v91
	v_sub_f32_e32 v68, v68, v91
	v_mul_f32_e32 v92, 0x45800000, v90
	v_cndmask_b32_e32 v90, v90, v92, vcc
	v_pk_mul_f32 v[68:69], v[68:69], v[90:91] op_sel_hi:[1,0]
	v_pk_mul_f32 v[70:71], v[70:71], v[90:91] op_sel_hi:[1,0]
	v_pk_fma_f32 v[68:69], v[72:73], v[68:69], v[76:77]
	v_pk_fma_f32 v[70:71], v[74:75], v[70:71], v[78:79]
	v_pk_fma_f32 v[60:61], v[68:69], s[20:21], v[60:61] op_sel_hi:[1,0,1]
	v_pk_fma_f32 v[62:63], v[70:71], s[20:21], v[62:63] op_sel_hi:[1,0,1]
	v_pk_add_f32 v[60:61], v[80:81], v[60:61]
	v_pk_add_f32 v[62:63], v[82:83], v[62:63]
	global_store_dwordx4 v[66:67], v[60:63], off
	v_lshlrev_b64 v[80:81], 11, v[88:89]
	v_lshl_add_u64 v[80:81], s[10:11], 0, v[80:81]
	v_lshl_add_u64 v[88:89], v[148:149], 1, v[80:81]
	v_sub_f32_e32 v81, v87, v91
	v_sub_f32_e32 v80, v86, v91
	v_sub_f32_e32 v83, v85, v91
	v_sub_f32_e32 v82, v84, v91
	v_pk_mul_f32 v[82:83], v[82:83], v[90:91] op_sel_hi:[1,0]
	v_pk_mul_f32 v[84:85], v[80:81], v[90:91] op_sel_hi:[1,0]
	v_cvt_pk_bf16_f32 v80, v60, v61
	v_cvt_pk_bf16_f32 v81, v62, v63
	v_pk_fma_f32 v[68:69], v[196:197], v[82:83], v[200:201]
	v_pk_fma_f32 v[70:71], v[198:199], v[84:85], v[202:203]
	v_pk_fma_f32 v[56:57], v[68:69], s[20:21], v[56:57] op_sel_hi:[1,0,1]
	v_pk_fma_f32 v[58:59], v[70:71], s[20:21], v[58:59] op_sel_hi:[1,0,1]
	v_pk_add_f32 v[56:57], v[204:205], v[56:57]
	v_pk_add_f32 v[58:59], v[206:207], v[58:59]
	global_store_dwordx4 v[66:67], v[56:59], off offset:16
	v_cvt_pk_bf16_f32 v82, v56, v57
	v_cvt_pk_bf16_f32 v83, v58, v59
	flat_store_dwordx4 v[88:89], v[80:83]
	global_load_dwordx4 v[68:71], v[66:67], off offset:512
	global_load_dwordx4 v[72:75], v[144:145], off offset:512
	global_load_dwordx4 v[76:79], v[146:147], off offset:512
	s_nop 0
	global_load_dwordx4 v[80:83], v[120:121], off
	global_load_dwordx4 v[84:87], v[66:67], off offset:528
	global_load_dwordx4 v[196:199], v[144:145], off offset:528
	global_load_dwordx4 v[200:203], v[146:147], off offset:528
	global_load_dwordx4 v[204:207], v[116:117], off
	s_waitcnt vmcnt(0)
	v_sub_f32_e32 v71, v71, v91
	v_sub_f32_e32 v70, v70, v91
	v_sub_f32_e32 v69, v69, v91
	v_sub_f32_e32 v68, v68, v91
	v_pk_mul_f32 v[68:69], v[90:91], v[68:69] op_sel_hi:[0,1]
	v_pk_mul_f32 v[70:71], v[90:91], v[70:71] op_sel_hi:[0,1]
	v_pk_fma_f32 v[70:71], v[74:75], v[70:71], v[78:79]
	v_pk_fma_f32 v[68:69], v[72:73], v[68:69], v[76:77]
	v_pk_fma_f32 v[54:55], v[70:71], s[20:21], v[54:55] op_sel_hi:[1,0,1]
	v_pk_fma_f32 v[52:53], v[68:69], s[20:21], v[52:53] op_sel_hi:[1,0,1]
	v_pk_add_f32 v[54:55], v[82:83], v[54:55]
	v_pk_add_f32 v[52:53], v[80:81], v[52:53]
	global_store_dwordx4 v[66:67], v[52:55], off offset:512
	v_add_f32_e32 v80, v60, v61
	v_mul_f32_e32 v61, v61, v61
	v_fmac_f32_e32 v61, v60, v60
	v_add_f32_e32 v80, v62, v80
	v_fmac_f32_e32 v61, v62, v62
	v_add_f32_e32 v62, v56, v57
	v_mul_f32_e32 v57, v57, v57
	v_fmac_f32_e32 v57, v56, v56
	v_add_f32_e32 v60, v63, v80
	v_add_f32_e32 v62, v58, v62
	v_fmac_f32_e32 v57, v58, v58
	v_add_f32_e32 v60, 0, v60
	v_fmac_f32_e32 v61, v63, v63
	v_add_f32_e32 v56, v59, v62
	v_fmac_f32_e32 v57, v59, v59
	v_sub_f32_e32 v59, v85, v91
	v_sub_f32_e32 v58, v84, v91
	v_add_f32_e32 v60, v56, v60
	v_add_f32_e32 v61, v61, v57
	v_sub_f32_e32 v57, v87, v91
	v_sub_f32_e32 v56, v86, v91
	v_pk_mul_f32 v[58:59], v[90:91], v[58:59] op_sel_hi:[0,1]
	v_pk_mul_f32 v[56:57], v[90:91], v[56:57] op_sel_hi:[0,1]
	v_mul_f32_e32 v63, v53, v53
	v_add_f32_e32 v62, v52, v53
	v_fmac_f32_e32 v63, v52, v52
	v_add_f32_e32 v62, v54, v62
	v_fmac_f32_e32 v63, v54, v54
	v_add_f32_e32 v62, v55, v62
	v_fmac_f32_e32 v63, v55, v55
	v_add_f32_e32 v60, v60, v62
	v_add_f32_e32 v61, v61, v63
	v_cvt_pk_bf16_f32 v52, v52, v53
	v_cvt_pk_bf16_f32 v53, v54, v55
	v_pk_fma_f32 v[58:59], v[196:197], v[58:59], v[200:201]
	v_pk_fma_f32 v[56:57], v[198:199], v[56:57], v[202:203]
	v_pk_fma_f32 v[48:49], v[58:59], s[20:21], v[48:49] op_sel_hi:[1,0,1]
	v_pk_fma_f32 v[50:51], v[56:57], s[20:21], v[50:51] op_sel_hi:[1,0,1]
	v_pk_add_f32 v[56:57], v[204:205], v[48:49]
	v_pk_add_f32 v[58:59], v[206:207], v[50:51]
	v_mul_f32_e32 v49, v57, v57
	v_add_f32_e32 v48, v56, v57
	v_fmac_f32_e32 v49, v56, v56
	v_add_f32_e32 v48, v58, v48
	v_fmac_f32_e32 v49, v58, v58
	v_add_f32_e32 v48, v59, v48
	v_fmac_f32_e32 v49, v59, v59
	v_add_f32_e32 v48, v60, v48
	v_add_f32_e32 v49, v61, v49
	ds_bpermute_b32 v50, v118, v48
	ds_bpermute_b32 v51, v118, v49
	global_store_dwordx4 v[66:67], v[56:59], off offset:528
	v_cvt_pk_bf16_f32 v54, v56, v57
	v_cvt_pk_bf16_f32 v55, v58, v59
	s_waitcnt lgkmcnt(0)
	v_add_f32_e32 v48, v48, v50
	v_add_f32_e32 v49, v49, v51
	ds_bpermute_b32 v50, v119, v48
	ds_bpermute_b32 v51, v119, v49
	flat_store_dwordx4 v[88:89], v[52:55] offset:256
	s_and_saveexec_b64 s[30:31], s[2:3]
	s_cbranch_execz .LBB0_1339
	v_lshl_add_u64 v[52:53], s[8:9], 0, v[64:65]
	s_waitcnt lgkmcnt(0)
	v_add_f32_e32 v48, v48, v50
	v_add_f32_e32 v49, v49, v51
	flat_atomic_add_f32 v[52:53], v48
	flat_atomic_add_f32 v[52:53], v49 offset:4
; DEVI unsigned pk2(float lo, float hi) { unsigned r; asm("v_cvt_pk_bf16_f32 %0, %1, %2" : "=v"(r) : "v"(lo), "v"(hi)); return r; }
; DEVI void row_stats(const float* stats, int row, float& mu, float& rs) {
;     if (stats) { const float2 st = *(const float2*)(stats + 2 * (size_t)row); mu = st.x * (1.0f / 1024.0f); const float var = st.y * (1.0f / 1024.0f) - mu * mu; rs = rsqrtf(fmaxf(var, 0.f) + LN_EPS); }
;     DEVI void operator()(const f32x4 (&acc)[2][2][4][2], const pg8::Unit& u, int wr, int wc, int fr, int fq) const {
;     ...
;                 const int row = row0 + ai * 128 + m * 16; float mu, rs; row_stats(stin, row, mu, rs);
;                 float sum = 0.f, sq = 0.f;
; #pragma unroll
;                 for (int bj = 0; bj < 2; ++bj) {
;                     f32x4 z[2];
; #pragma unroll
;                     for (int n = 0; n < 2; ++n) {
;                         const int col = colb + bj * 128 + 4 * n;
;                         f32x4 xv = *(const f32x4*)(zsrc + (size_t)row * DM + col);
;                         if (stin) { const f32x4 gv = *(const f32x4*)(gin + col), bv = *(const f32x4*)(bin + col); xv = (xv - mu) * rs * gv + bv; }
;                         f32x4 zz = ALPHA * xv + acc[ai][bj][m][n];
;                         if (bias) zz += *(const f32x4*)(bias + col);
;                         *(f32x4*)(zdst + (size_t)row * DM + col) = zz;
;                         sum += zz[0] + zz[1] + zz[2] + zz[3]; sq += zz[0] * zz[0] + zz[1] * zz[1] + zz[2] * zz[2] + zz[3] * zz[3];
;                         z[n] = zz;
;                     }
;                     u32x4 o; o.x = pk2(z[0][0], z[0][1]); o.y = pk2(z[0][2], z[0][3]); o.z = pk2(z[1][0], z[1][1]); o.w = pk2(z[1][2], z[1][3]);
;                     if (zb) *(u32x4*)(zb + (size_t)row * DM + colb + bj * 128) = o;
;                 }
;                 sum += __shfl_xor(sum, 16); sq += __shfl_xor(sq, 16);
;                 sum += __shfl_xor(sum, 32); sq += __shfl_xor(sq, 32);
;                 if (fq == 0) { atomicAdd(stout + 2 * (size_t)row, sum); atomicAdd(stout + 2 * (size_t)row + 1, sq); }
.LBB0_1339:
	s_or_b64 exec, exec, s[30:31]
	v_add_u32_e32 v72, 0x90, v150
	v_ashrrev_i32_e32 v73, 31, v72
	v_lshlrev_b64 v[48:49], 3, v[72:73]
	s_waitcnt lgkmcnt(0)
	v_lshl_add_u64 v[50:51], s[6:7], 0, v[48:49]
	flat_load_dwordx2 v[74:75], v[50:51]
	v_lshlrev_b64 v[50:51], 12, v[72:73]
	v_lshl_add_u64 v[50:51], s[46:47], 0, v[50:51]
	v_lshl_add_u64 v[50:51], v[148:149], 2, v[50:51]
	global_load_dwordx4 v[52:55], v[50:51], off
	global_load_dwordx4 v[56:59], v[144:145], off
	global_load_dwordx4 v[60:63], v[146:147], off
	global_load_dwordx4 v[64:67], v[152:153], off
	global_load_dwordx4 v[68:71], v[50:51], off offset:16
	global_load_dwordx4 v[196:199], v[144:145], off offset:16
	global_load_dwordx4 v[200:203], v[146:147], off offset:16
	global_load_dwordx4 v[204:207], v[154:155], off
	s_waitcnt vmcnt(0) lgkmcnt(0)
	v_pk_mul_f32 v[74:75], v[74:75], s[18:19] op_sel:[1,0] op_sel_hi:[0,0]
	v_fma_f32 v74, -v75, v75, v74
	v_max_f32_e32 v74, 0, v74
	v_add_f32_e32 v74, 0x3727c5ac, v74
	v_mul_f32_e32 v76, 0x4b800000, v74
	v_cmp_gt_f32_e32 vcc, s64, v74
	v_sub_f32_e32 v55, v55, v75
	v_sub_f32_e32 v54, v54, v75
	v_cndmask_b32_e32 v74, v74, v76, vcc
	v_rsq_f32_e32 v74, v74
	v_sub_f32_e32 v53, v53, v75
	v_sub_f32_e32 v52, v52, v75
	v_mul_f32_e32 v76, 0x45800000, v74
	v_cndmask_b32_e32 v74, v74, v76, vcc
	v_pk_mul_f32 v[52:53], v[52:53], v[74:75] op_sel_hi:[1,0]
	v_pk_mul_f32 v[54:55], v[54:55], v[74:75] op_sel_hi:[1,0]
	v_pk_fma_f32 v[52:53], v[56:57], v[52:53], v[60:61]
	v_pk_fma_f32 v[54:55], v[58:59], v[54:55], v[62:63]
	v_pk_fma_f32 v[44:45], v[52:53], s[20:21], v[44:45] op_sel_hi:[1,0,1]
	v_pk_fma_f32 v[46:47], v[54:55], s[20:21], v[46:47] op_sel_hi:[1,0,1]
	v_pk_add_f32 v[44:45], v[64:65], v[44:45]
	v_pk_add_f32 v[46:47], v[66:67], v[46:47]
	global_store_dwordx4 v[50:51], v[44:47], off
	v_lshlrev_b64 v[64:65], 11, v[72:73]
	v_lshl_add_u64 v[64:65], s[10:11], 0, v[64:65]
	v_lshl_add_u64 v[72:73], v[148:149], 1, v[64:65]
	v_sub_f32_e32 v65, v71, v75
	v_sub_f32_e32 v64, v70, v75
	v_sub_f32_e32 v67, v69, v75
	v_sub_f32_e32 v66, v68, v75
	v_pk_mul_f32 v[66:67], v[66:67], v[74:75] op_sel_hi:[1,0]
	v_pk_mul_f32 v[68:69], v[64:65], v[74:75] op_sel_hi:[1,0]
	v_cvt_pk_bf16_f32 v64, v44, v45
	v_cvt_pk_bf16_f32 v65, v46, v47
	v_pk_fma_f32 v[52:53], v[196:197], v[66:67], v[200:201]
	v_pk_fma_f32 v[54:55], v[198:199], v[68:69], v[202:203]
	v_pk_fma_f32 v[40:41], v[52:53], s[20:21], v[40:41] op_sel_hi:[1,0,1]
	v_pk_fma_f32 v[42:43], v[54:55], s[20:21], v[42:43] op_sel_hi:[1,0,1]
	v_pk_add_f32 v[40:41], v[204:205], v[40:41]
	v_pk_add_f32 v[42:43], v[206:207], v[42:43]
	global_store_dwordx4 v[50:51], v[40:43], off offset:16
	v_cvt_pk_bf16_f32 v66, v40, v41
	v_cvt_pk_bf16_f32 v67, v42, v43
	flat_store_dwordx4 v[72:73], v[64:67]
	global_load_dwordx4 v[52:55], v[50:51], off offset:512
	global_load_dwordx4 v[56:59], v[144:145], off offset:512
	global_load_dwordx4 v[60:63], v[146:147], off offset:512
	s_nop 0
	global_load_dwordx4 v[64:67], v[120:121], off
	global_load_dwordx4 v[68:71], v[50:51], off offset:528
	global_load_dwordx4 v[196:199], v[144:145], off offset:528
	global_load_dwordx4 v[200:203], v[146:147], off offset:528
	global_load_dwordx4 v[204:207], v[116:117], off
	s_waitcnt vmcnt(0)
	v_sub_f32_e32 v55, v55, v75
	v_sub_f32_e32 v54, v54, v75
	v_sub_f32_e32 v53, v53, v75
	v_sub_f32_e32 v52, v52, v75
	v_pk_mul_f32 v[52:53], v[74:75], v[52:53] op_sel_hi:[0,1]
	v_pk_mul_f32 v[54:55], v[74:75], v[54:55] op_sel_hi:[0,1]
	v_pk_fma_f32 v[54:55], v[58:59], v[54:55], v[62:63]
	v_pk_fma_f32 v[52:53], v[56:57], v[52:53], v[60:61]
	v_pk_fma_f32 v[38:39], v[54:55], s[20:21], v[38:39] op_sel_hi:[1,0,1]
	v_pk_fma_f32 v[36:37], v[52:53], s[20:21], v[36:37] op_sel_hi:[1,0,1]
	v_pk_add_f32 v[38:39], v[66:67], v[38:39]
	v_pk_add_f32 v[36:37], v[64:65], v[36:37]
	global_store_dwordx4 v[50:51], v[36:39], off offset:512
	v_add_f32_e32 v64, v44, v45
	v_mul_f32_e32 v45, v45, v45
	v_fmac_f32_e32 v45, v44, v44
	v_add_f32_e32 v64, v46, v64
	v_fmac_f32_e32 v45, v46, v46
	v_add_f32_e32 v46, v40, v41
	v_mul_f32_e32 v41, v41, v41
	v_fmac_f32_e32 v41, v40, v40
	v_add_f32_e32 v44, v47, v64
	v_add_f32_e32 v46, v42, v46
	v_fmac_f32_e32 v41, v42, v42
	v_add_f32_e32 v44, 0, v44
	v_fmac_f32_e32 v45, v47, v47
	v_add_f32_e32 v40, v43, v46
	v_fmac_f32_e32 v41, v43, v43
	v_sub_f32_e32 v43, v69, v75
	v_sub_f32_e32 v42, v68, v75
	v_add_f32_e32 v44, v40, v44
	v_add_f32_e32 v45, v45, v41
	v_sub_f32_e32 v41, v71, v75
	v_sub_f32_e32 v40, v70, v75
	v_pk_mul_f32 v[42:43], v[74:75], v[42:43] op_sel_hi:[0,1]
	v_pk_mul_f32 v[40:41], v[74:75], v[40:41] op_sel_hi:[0,1]
	v_mul_f32_e32 v47, v37, v37
	v_add_f32_e32 v46, v36, v37
	v_fmac_f32_e32 v47, v36, v36
	v_add_f32_e32 v46, v38, v46
	v_fmac_f32_e32 v47, v38, v38
	v_add_f32_e32 v46, v39, v46
	v_fmac_f32_e32 v47, v39, v39
	v_add_f32_e32 v44, v44, v46
	v_add_f32_e32 v45, v45, v47
	v_cvt_pk_bf16_f32 v36, v36, v37
	v_cvt_pk_bf16_f32 v37, v38, v39
	v_pk_fma_f32 v[42:43], v[196:197], v[42:43], v[200:201]
	v_pk_fma_f32 v[40:41], v[198:199], v[40:41], v[202:203]
	v_pk_fma_f32 v[32:33], v[42:43], s[20:21], v[32:33] op_sel_hi:[1,0,1]
	v_pk_fma_f32 v[34:35], v[40:41], s[20:21], v[34:35] op_sel_hi:[1,0,1]
	v_pk_add_f32 v[40:41], v[204:205], v[32:33]
	v_pk_add_f32 v[42:43], v[206:207], v[34:35]
	v_mul_f32_e32 v33, v41, v41
	v_add_f32_e32 v32, v40, v41
	v_fmac_f32_e32 v33, v40, v40
	v_add_f32_e32 v32, v42, v32
	v_fmac_f32_e32 v33, v42, v42
	v_add_f32_e32 v32, v43, v32
	v_fmac_f32_e32 v33, v43, v43
	v_add_f32_e32 v32, v44, v32
	v_add_f32_e32 v33, v45, v33
	ds_bpermute_b32 v34, v118, v32
	ds_bpermute_b32 v35, v118, v33
	global_store_dwordx4 v[50:51], v[40:43], off offset:528
	v_cvt_pk_bf16_f32 v38, v40, v41
	v_cvt_pk_bf16_f32 v39, v42, v43
	s_waitcnt lgkmcnt(0)
	v_add_f32_e32 v32, v32, v34
	v_add_f32_e32 v33, v33, v35
	ds_bpermute_b32 v34, v119, v32
	ds_bpermute_b32 v35, v119, v33
	flat_store_dwordx4 v[72:73], v[36:39] offset:256
	s_and_saveexec_b64 s[30:31], s[2:3]
	s_cbranch_execz .LBB0_1341
	v_lshl_add_u64 v[36:37], s[8:9], 0, v[48:49]
	s_waitcnt lgkmcnt(0)
	v_add_f32_e32 v32, v32, v34
	v_add_f32_e32 v33, v33, v35
	flat_atomic_add_f32 v[36:37], v32
	flat_atomic_add_f32 v[36:37], v33 offset:4
; DEVI unsigned pk2(float lo, float hi) { unsigned r; asm("v_cvt_pk_bf16_f32 %0, %1, %2" : "=v"(r) : "v"(lo), "v"(hi)); return r; }
; DEVI void row_stats(const float* stats, int row, float& mu, float& rs) {
;     if (stats) { const float2 st = *(const float2*)(stats + 2 * (size_t)row); mu = st.x * (1.0f / 1024.0f); const float var = st.y * (1.0f / 1024.0f) - mu * mu; rs = rsqrtf(fmaxf(var, 0.f) + LN_EPS); }
;     DEVI void operator()(const f32x4 (&acc)[2][2][4][2], const pg8::Unit& u, int wr, int wc, int fr, int fq) const {
;     ...
;                 const int row = row0 + ai * 128 + m * 16; float mu, rs; row_stats(stin, row, mu, rs);
;                 float sum = 0.f, sq = 0.f;
; #pragma unroll
;                 for (int bj = 0; bj < 2; ++bj) {
;                     f32x4 z[2];
; #pragma unroll
;                     for (int n = 0; n < 2; ++n) {
;                         const int col = colb + bj * 128 + 4 * n;
;                         f32x4 xv = *(const f32x4*)(zsrc + (size_t)row * DM + col);
;                         if (stin) { const f32x4 gv = *(const f32x4*)(gin + col), bv = *(const f32x4*)(bin + col); xv = (xv - mu) * rs * gv + bv; }
;                         f32x4 zz = ALPHA * xv + acc[ai][bj][m][n];
;                         if (bias) zz += *(const f32x4*)(bias + col);
;                         *(f32x4*)(zdst + (size_t)row * DM + col) = zz;
;                         sum += zz[0] + zz[1] + zz[2] + zz[3]; sq += zz[0] * zz[0] + zz[1] * zz[1] + zz[2] * zz[2] + zz[3] * zz[3];
;                         z[n] = zz;
;                     }
;                     u32x4 o; o.x = pk2(z[0][0], z[0][1]); o.y = pk2(z[0][2], z[0][3]); o.z = pk2(z[1][0], z[1][1]); o.w = pk2(z[1][2], z[1][3]);
;                     if (zb) *(u32x4*)(zb + (size_t)row * DM + colb + bj * 128) = o;
;                 }
;                 sum += __shfl_xor(sum, 16); sq += __shfl_xor(sq, 16);
;                 sum += __shfl_xor(sum, 32); sq += __shfl_xor(sq, 32);
;                 if (fq == 0) { atomicAdd(stout + 2 * (size_t)row, sum); atomicAdd(stout + 2 * (size_t)row + 1, sq); }
.LBB0_1341:
	s_or_b64 exec, exec, s[30:31]
	v_add_u32_e32 v56, 0xa0, v150
	v_ashrrev_i32_e32 v57, 31, v56
	v_lshlrev_b64 v[32:33], 3, v[56:57]
	s_waitcnt lgkmcnt(0)
	v_lshl_add_u64 v[34:35], s[6:7], 0, v[32:33]
	flat_load_dwordx2 v[58:59], v[34:35]
	v_lshlrev_b64 v[34:35], 12, v[56:57]
	v_lshl_add_u64 v[34:35], s[46:47], 0, v[34:35]
	v_lshl_add_u64 v[34:35], v[148:149], 2, v[34:35]
	global_load_dwordx4 v[36:39], v[34:35], off
	global_load_dwordx4 v[40:43], v[144:145], off
	global_load_dwordx4 v[44:47], v[146:147], off
	global_load_dwordx4 v[48:51], v[152:153], off
	global_load_dwordx4 v[52:55], v[34:35], off offset:16
	global_load_dwordx4 v[196:199], v[144:145], off offset:16
	global_load_dwordx4 v[200:203], v[146:147], off offset:16
	global_load_dwordx4 v[204:207], v[154:155], off
	s_waitcnt vmcnt(0) lgkmcnt(0)
	v_pk_mul_f32 v[58:59], v[58:59], s[18:19] op_sel:[1,0] op_sel_hi:[0,0]
	v_fma_f32 v58, -v59, v59, v58
	v_max_f32_e32 v58, 0, v58
	v_add_f32_e32 v58, 0x3727c5ac, v58
	v_mul_f32_e32 v60, 0x4b800000, v58
	v_cmp_gt_f32_e32 vcc, s64, v58
	v_sub_f32_e32 v39, v39, v59
	v_sub_f32_e32 v38, v38, v59
	v_cndmask_b32_e32 v58, v58, v60, vcc
	v_rsq_f32_e32 v58, v58
	v_sub_f32_e32 v37, v37, v59
	v_sub_f32_e32 v36, v36, v59
	v_mul_f32_e32 v60, 0x45800000, v58
	v_cndmask_b32_e32 v58, v58, v60, vcc
	v_pk_mul_f32 v[36:37], v[36:37], v[58:59] op_sel_hi:[1,0]
	v_pk_mul_f32 v[38:39], v[38:39], v[58:59] op_sel_hi:[1,0]
	v_pk_fma_f32 v[36:37], v[40:41], v[36:37], v[44:45]
	v_pk_fma_f32 v[38:39], v[42:43], v[38:39], v[46:47]
	v_pk_fma_f32 v[28:29], v[36:37], s[20:21], v[28:29] op_sel_hi:[1,0,1]
	v_pk_fma_f32 v[30:31], v[38:39], s[20:21], v[30:31] op_sel_hi:[1,0,1]
	v_pk_add_f32 v[28:29], v[48:49], v[28:29]
	v_pk_add_f32 v[30:31], v[50:51], v[30:31]
	global_store_dwordx4 v[34:35], v[28:31], off
	v_lshlrev_b64 v[48:49], 11, v[56:57]
	v_lshl_add_u64 v[48:49], s[10:11], 0, v[48:49]
	v_lshl_add_u64 v[56:57], v[148:149], 1, v[48:49]
	v_sub_f32_e32 v49, v55, v59
	v_sub_f32_e32 v48, v54, v59
	v_sub_f32_e32 v51, v53, v59
	v_sub_f32_e32 v50, v52, v59
	v_pk_mul_f32 v[50:51], v[50:51], v[58:59] op_sel_hi:[1,0]
	v_pk_mul_f32 v[52:53], v[48:49], v[58:59] op_sel_hi:[1,0]
	v_cvt_pk_bf16_f32 v48, v28, v29
	v_cvt_pk_bf16_f32 v49, v30, v31
	v_pk_fma_f32 v[36:37], v[196:197], v[50:51], v[200:201]
	v_pk_fma_f32 v[38:39], v[198:199], v[52:53], v[202:203]
	v_pk_fma_f32 v[24:25], v[36:37], s[20:21], v[24:25] op_sel_hi:[1,0,1]
	v_pk_fma_f32 v[26:27], v[38:39], s[20:21], v[26:27] op_sel_hi:[1,0,1]
	v_pk_add_f32 v[24:25], v[204:205], v[24:25]
	v_pk_add_f32 v[26:27], v[206:207], v[26:27]
	global_store_dwordx4 v[34:35], v[24:27], off offset:16
	v_cvt_pk_bf16_f32 v50, v24, v25
	v_cvt_pk_bf16_f32 v51, v26, v27
	flat_store_dwordx4 v[56:57], v[48:51]
	global_load_dwordx4 v[36:39], v[34:35], off offset:512
	global_load_dwordx4 v[40:43], v[144:145], off offset:512
	global_load_dwordx4 v[44:47], v[146:147], off offset:512
	s_nop 0
	global_load_dwordx4 v[48:51], v[120:121], off
	global_load_dwordx4 v[52:55], v[34:35], off offset:528
	global_load_dwordx4 v[196:199], v[144:145], off offset:528
	global_load_dwordx4 v[200:203], v[146:147], off offset:528
	global_load_dwordx4 v[204:207], v[116:117], off
	s_waitcnt vmcnt(0)
	v_sub_f32_e32 v39, v39, v59
	v_sub_f32_e32 v38, v38, v59
	v_sub_f32_e32 v37, v37, v59
	v_sub_f32_e32 v36, v36, v59
	v_pk_mul_f32 v[36:37], v[58:59], v[36:37] op_sel_hi:[0,1]
	v_pk_mul_f32 v[38:39], v[58:59], v[38:39] op_sel_hi:[0,1]
	v_pk_fma_f32 v[38:39], v[42:43], v[38:39], v[46:47]
	v_pk_fma_f32 v[36:37], v[40:41], v[36:37], v[44:45]
	v_pk_fma_f32 v[22:23], v[38:39], s[20:21], v[22:23] op_sel_hi:[1,0,1]
	v_pk_fma_f32 v[20:21], v[36:37], s[20:21], v[20:21] op_sel_hi:[1,0,1]
	v_pk_add_f32 v[22:23], v[50:51], v[22:23]
	v_pk_add_f32 v[20:21], v[48:49], v[20:21]
	global_store_dwordx4 v[34:35], v[20:23], off offset:512
	v_add_f32_e32 v48, v28, v29
	v_mul_f32_e32 v29, v29, v29
	v_fmac_f32_e32 v29, v28, v28
	v_add_f32_e32 v48, v30, v48
	v_fmac_f32_e32 v29, v30, v30
	v_add_f32_e32 v30, v24, v25
	v_mul_f32_e32 v25, v25, v25
	v_fmac_f32_e32 v25, v24, v24
	v_add_f32_e32 v28, v31, v48
	v_add_f32_e32 v30, v26, v30
	v_fmac_f32_e32 v25, v26, v26
	v_add_f32_e32 v28, 0, v28
	v_fmac_f32_e32 v29, v31, v31
	v_add_f32_e32 v24, v27, v30
	v_fmac_f32_e32 v25, v27, v27
	v_sub_f32_e32 v27, v53, v59
	v_sub_f32_e32 v26, v52, v59
	v_add_f32_e32 v28, v24, v28
	v_add_f32_e32 v29, v29, v25
	v_sub_f32_e32 v25, v55, v59
	v_sub_f32_e32 v24, v54, v59
	v_pk_mul_f32 v[26:27], v[58:59], v[26:27] op_sel_hi:[0,1]
	v_pk_mul_f32 v[24:25], v[58:59], v[24:25] op_sel_hi:[0,1]
	v_mul_f32_e32 v31, v21, v21
	v_add_f32_e32 v30, v20, v21
	v_fmac_f32_e32 v31, v20, v20
	v_add_f32_e32 v30, v22, v30
	v_fmac_f32_e32 v31, v22, v22
	v_add_f32_e32 v30, v23, v30
	v_fmac_f32_e32 v31, v23, v23
	v_add_f32_e32 v28, v28, v30
	v_add_f32_e32 v29, v29, v31
	v_cvt_pk_bf16_f32 v20, v20, v21
	v_cvt_pk_bf16_f32 v21, v22, v23
	v_pk_fma_f32 v[26:27], v[196:197], v[26:27], v[200:201]
	v_pk_fma_f32 v[24:25], v[198:199], v[24:25], v[202:203]
	v_pk_fma_f32 v[16:17], v[26:27], s[20:21], v[16:17] op_sel_hi:[1,0,1]
	v_pk_fma_f32 v[18:19], v[24:25], s[20:21], v[18:19] op_sel_hi:[1,0,1]
	v_pk_add_f32 v[24:25], v[204:205], v[16:17]
	v_pk_add_f32 v[26:27], v[206:207], v[18:19]
	v_mul_f32_e32 v17, v25, v25
	v_add_f32_e32 v16, v24, v25
	v_fmac_f32_e32 v17, v24, v24
	v_add_f32_e32 v16, v26, v16
	v_fmac_f32_e32 v17, v26, v26
	v_add_f32_e32 v16, v27, v16
	v_fmac_f32_e32 v17, v27, v27
	v_add_f32_e32 v16, v28, v16
	v_add_f32_e32 v17, v29, v17
	ds_bpermute_b32 v18, v118, v16
	ds_bpermute_b32 v19, v118, v17
	global_store_dwordx4 v[34:35], v[24:27], off offset:528
	v_cvt_pk_bf16_f32 v22, v24, v25
	v_cvt_pk_bf16_f32 v23, v26, v27
	s_waitcnt lgkmcnt(0)
	v_add_f32_e32 v16, v16, v18
	v_add_f32_e32 v17, v17, v19
	ds_bpermute_b32 v18, v119, v16
	ds_bpermute_b32 v19, v119, v17
	flat_store_dwordx4 v[56:57], v[20:23] offset:256
	s_and_saveexec_b64 s[30:31], s[2:3]
	s_cbranch_execz .LBB0_1343
	v_lshl_add_u64 v[20:21], s[8:9], 0, v[32:33]
	s_waitcnt lgkmcnt(0)
	v_add_f32_e32 v16, v16, v18
	v_add_f32_e32 v17, v17, v19
	flat_atomic_add_f32 v[20:21], v16
	flat_atomic_add_f32 v[20:21], v17 offset:4
; DEVI unsigned pk2(float lo, float hi) { unsigned r; asm("v_cvt_pk_bf16_f32 %0, %1, %2" : "=v"(r) : "v"(lo), "v"(hi)); return r; }
; DEVI void row_stats(const float* stats, int row, float& mu, float& rs) {
;     if (stats) { const float2 st = *(const float2*)(stats + 2 * (size_t)row); mu = st.x * (1.0f / 1024.0f); const float var = st.y * (1.0f / 1024.0f) - mu * mu; rs = rsqrtf(fmaxf(var, 0.f) + LN_EPS); }
;     DEVI void operator()(const f32x4 (&acc)[2][2][4][2], const pg8::Unit& u, int wr, int wc, int fr, int fq) const {
;     ...
;                 const int row = row0 + ai * 128 + m * 16; float mu, rs; row_stats(stin, row, mu, rs);
;                 float sum = 0.f, sq = 0.f;
; #pragma unroll
;                 for (int bj = 0; bj < 2; ++bj) {
;                     f32x4 z[2];
; #pragma unroll
;                     for (int n = 0; n < 2; ++n) {
;                         const int col = colb + bj * 128 + 4 * n;
;                         f32x4 xv = *(const f32x4*)(zsrc + (size_t)row * DM + col);
;                         if (stin) { const f32x4 gv = *(const f32x4*)(gin + col), bv = *(const f32x4*)(bin + col); xv = (xv - mu) * rs * gv + bv; }
;                         f32x4 zz = ALPHA * xv + acc[ai][bj][m][n];
;                         if (bias) zz += *(const f32x4*)(bias + col);
;                         *(f32x4*)(zdst + (size_t)row * DM + col) = zz;
;                         sum += zz[0] + zz[1] + zz[2] + zz[3]; sq += zz[0] * zz[0] + zz[1] * zz[1] + zz[2] * zz[2] + zz[3] * zz[3];
;                         z[n] = zz;
;                     }
;                     u32x4 o; o.x = pk2(z[0][0], z[0][1]); o.y = pk2(z[0][2], z[0][3]); o.z = pk2(z[1][0], z[1][1]); o.w = pk2(z[1][2], z[1][3]);
;                     if (zb) *(u32x4*)(zb + (size_t)row * DM + colb + bj * 128) = o;
;                 }
;                 sum += __shfl_xor(sum, 16); sq += __shfl_xor(sq, 16);
;                 sum += __shfl_xor(sum, 32); sq += __shfl_xor(sq, 32);
;                 if (fq == 0) { atomicAdd(stout + 2 * (size_t)row, sum); atomicAdd(stout + 2 * (size_t)row + 1, sq); }
.LBB0_1343:
	s_or_b64 exec, exec, s[30:31]
	v_add_u32_e32 v40, 0xb0, v150
	v_ashrrev_i32_e32 v41, 31, v40
	v_lshlrev_b64 v[16:17], 3, v[40:41]
	s_waitcnt lgkmcnt(0)
	v_lshl_add_u64 v[18:19], s[6:7], 0, v[16:17]
	flat_load_dwordx2 v[42:43], v[18:19]
	v_lshlrev_b64 v[18:19], 12, v[40:41]
	v_lshl_add_u64 v[18:19], s[46:47], 0, v[18:19]
	v_lshl_add_u64 v[18:19], v[148:149], 2, v[18:19]
	global_load_dwordx4 v[20:23], v[18:19], off
	global_load_dwordx4 v[24:27], v[144:145], off
	global_load_dwordx4 v[28:31], v[146:147], off
	global_load_dwordx4 v[32:35], v[152:153], off
	global_load_dwordx4 v[36:39], v[18:19], off offset:16
	global_load_dwordx4 v[196:199], v[144:145], off offset:16
	global_load_dwordx4 v[200:203], v[146:147], off offset:16
	global_load_dwordx4 v[204:207], v[154:155], off
	s_waitcnt vmcnt(0) lgkmcnt(0)
	v_pk_mul_f32 v[42:43], v[42:43], s[18:19] op_sel:[1,0] op_sel_hi:[0,0]
	v_fma_f32 v42, -v43, v43, v42
	v_max_f32_e32 v42, 0, v42
	v_add_f32_e32 v42, 0x3727c5ac, v42
	v_mul_f32_e32 v44, 0x4b800000, v42
	v_cmp_gt_f32_e32 vcc, s64, v42
	v_sub_f32_e32 v23, v23, v43
	v_sub_f32_e32 v22, v22, v43
	v_cndmask_b32_e32 v42, v42, v44, vcc
	v_rsq_f32_e32 v42, v42
	v_sub_f32_e32 v21, v21, v43
	v_sub_f32_e32 v20, v20, v43
	v_mul_f32_e32 v44, 0x45800000, v42
	v_cndmask_b32_e32 v42, v42, v44, vcc
	v_pk_mul_f32 v[20:21], v[20:21], v[42:43] op_sel_hi:[1,0]
	v_pk_mul_f32 v[22:23], v[22:23], v[42:43] op_sel_hi:[1,0]
	v_pk_fma_f32 v[20:21], v[24:25], v[20:21], v[28:29]
	v_pk_fma_f32 v[22:23], v[26:27], v[22:23], v[30:31]
	v_pk_fma_f32 v[12:13], v[20:21], s[20:21], v[12:13] op_sel_hi:[1,0,1]
	v_pk_fma_f32 v[14:15], v[22:23], s[20:21], v[14:15] op_sel_hi:[1,0,1]
	v_pk_add_f32 v[12:13], v[32:33], v[12:13]
	v_pk_add_f32 v[14:15], v[34:35], v[14:15]
	global_store_dwordx4 v[18:19], v[12:15], off
	v_lshlrev_b64 v[32:33], 11, v[40:41]
	v_lshl_add_u64 v[32:33], s[10:11], 0, v[32:33]
	v_lshl_add_u64 v[40:41], v[148:149], 1, v[32:33]
	v_sub_f32_e32 v33, v39, v43
	v_sub_f32_e32 v32, v38, v43
	v_sub_f32_e32 v35, v37, v43
	v_sub_f32_e32 v34, v36, v43
	v_pk_mul_f32 v[34:35], v[34:35], v[42:43] op_sel_hi:[1,0]
	v_pk_mul_f32 v[36:37], v[32:33], v[42:43] op_sel_hi:[1,0]
	v_cvt_pk_bf16_f32 v32, v12, v13
	v_cvt_pk_bf16_f32 v33, v14, v15
	v_pk_fma_f32 v[20:21], v[196:197], v[34:35], v[200:201]
	v_pk_fma_f32 v[22:23], v[198:199], v[36:37], v[202:203]
	v_pk_fma_f32 v[8:9], v[20:21], s[20:21], v[8:9] op_sel_hi:[1,0,1]
	v_pk_fma_f32 v[10:11], v[22:23], s[20:21], v[10:11] op_sel_hi:[1,0,1]
	v_pk_add_f32 v[8:9], v[204:205], v[8:9]
	v_pk_add_f32 v[10:11], v[206:207], v[10:11]
	global_store_dwordx4 v[18:19], v[8:11], off offset:16
	v_cvt_pk_bf16_f32 v34, v8, v9
	v_cvt_pk_bf16_f32 v35, v10, v11
	flat_store_dwordx4 v[40:41], v[32:35]
	global_load_dwordx4 v[20:23], v[18:19], off offset:512
	global_load_dwordx4 v[24:27], v[144:145], off offset:512
	global_load_dwordx4 v[28:31], v[146:147], off offset:512
	s_nop 0
	global_load_dwordx4 v[32:35], v[120:121], off
	global_load_dwordx4 v[36:39], v[18:19], off offset:528
	global_load_dwordx4 v[196:199], v[144:145], off offset:528
	global_load_dwordx4 v[200:203], v[146:147], off offset:528
	global_load_dwordx4 v[204:207], v[116:117], off
	s_waitcnt vmcnt(0)
	v_sub_f32_e32 v23, v23, v43
	v_sub_f32_e32 v22, v22, v43
	v_sub_f32_e32 v21, v21, v43
	v_sub_f32_e32 v20, v20, v43
	v_pk_mul_f32 v[20:21], v[42:43], v[20:21] op_sel_hi:[0,1]
	v_pk_mul_f32 v[22:23], v[42:43], v[22:23] op_sel_hi:[0,1]
	v_pk_fma_f32 v[22:23], v[26:27], v[22:23], v[30:31]
	v_pk_fma_f32 v[20:21], v[24:25], v[20:21], v[28:29]
	v_pk_fma_f32 v[6:7], v[22:23], s[20:21], v[6:7] op_sel_hi:[1,0,1]
	v_pk_fma_f32 v[4:5], v[20:21], s[20:21], v[4:5] op_sel_hi:[1,0,1]
	v_pk_add_f32 v[6:7], v[34:35], v[6:7]
	v_pk_add_f32 v[4:5], v[32:33], v[4:5]
	global_store_dwordx4 v[18:19], v[4:7], off offset:512
	v_add_f32_e32 v32, v12, v13
	v_mul_f32_e32 v13, v13, v13
	v_fmac_f32_e32 v13, v12, v12
	v_add_f32_e32 v32, v14, v32
	v_fmac_f32_e32 v13, v14, v14
	v_add_f32_e32 v14, v8, v9
	v_mul_f32_e32 v9, v9, v9
	v_fmac_f32_e32 v9, v8, v8
	v_add_f32_e32 v12, v15, v32
	v_add_f32_e32 v14, v10, v14
	v_fmac_f32_e32 v9, v10, v10
	v_add_f32_e32 v12, 0, v12
	v_fmac_f32_e32 v13, v15, v15
	v_add_f32_e32 v8, v11, v14
	v_fmac_f32_e32 v9, v11, v11
	v_sub_f32_e32 v11, v37, v43
	v_sub_f32_e32 v10, v36, v43
	v_add_f32_e32 v12, v8, v12
	v_add_f32_e32 v13, v13, v9
	v_sub_f32_e32 v9, v39, v43
	v_sub_f32_e32 v8, v38, v43
	v_pk_mul_f32 v[10:11], v[42:43], v[10:11] op_sel_hi:[0,1]
	v_pk_mul_f32 v[8:9], v[42:43], v[8:9] op_sel_hi:[0,1]
	v_mul_f32_e32 v15, v5, v5
	v_add_f32_e32 v14, v4, v5
	v_fmac_f32_e32 v15, v4, v4
	v_add_f32_e32 v14, v6, v14
	v_fmac_f32_e32 v15, v6, v6
	v_add_f32_e32 v14, v7, v14
	v_fmac_f32_e32 v15, v7, v7
	v_add_f32_e32 v12, v12, v14
	v_add_f32_e32 v13, v13, v15
	v_cvt_pk_bf16_f32 v4, v4, v5
	v_cvt_pk_bf16_f32 v5, v6, v7
	v_pk_fma_f32 v[10:11], v[196:197], v[10:11], v[200:201]
	v_pk_fma_f32 v[8:9], v[198:199], v[8:9], v[202:203]
	v_pk_fma_f32 v[0:1], v[10:11], s[20:21], v[0:1] op_sel_hi:[1,0,1]
	v_pk_fma_f32 v[2:3], v[8:9], s[20:21], v[2:3] op_sel_hi:[1,0,1]
	v_pk_add_f32 v[8:9], v[204:205], v[0:1]
	v_pk_add_f32 v[10:11], v[206:207], v[2:3]
	v_mul_f32_e32 v1, v9, v9
	v_add_f32_e32 v0, v8, v9
	v_fmac_f32_e32 v1, v8, v8
	v_add_f32_e32 v0, v10, v0
	v_fmac_f32_e32 v1, v10, v10
	v_add_f32_e32 v0, v11, v0
	v_fmac_f32_e32 v1, v11, v11
	v_add_f32_e32 v0, v12, v0
	v_add_f32_e32 v1, v13, v1
	ds_bpermute_b32 v2, v118, v0
	ds_bpermute_b32 v3, v118, v1
	global_store_dwordx4 v[18:19], v[8:11], off offset:528
	v_cvt_pk_bf16_f32 v6, v8, v9
	v_cvt_pk_bf16_f32 v7, v10, v11
	s_waitcnt lgkmcnt(0)
	v_add_f32_e32 v0, v0, v2
	v_add_f32_e32 v1, v1, v3
	ds_bpermute_b32 v2, v119, v0
	ds_bpermute_b32 v3, v119, v1
	flat_store_dwordx4 v[40:41], v[4:7] offset:256
	s_and_saveexec_b64 s[30:31], s[2:3]
	s_cbranch_execz .LBB0_1345
	v_lshl_add_u64 v[4:5], s[8:9], 0, v[16:17]
	s_waitcnt lgkmcnt(0)
	v_add_f32_e32 v0, v0, v2
	v_add_f32_e32 v1, v1, v3
	flat_atomic_add_f32 v[4:5], v0
	flat_atomic_add_f32 v[4:5], v1 offset:4

; DEVI unsigned pk2(float lo, float hi) { unsigned r; asm("v_cvt_pk_bf16_f32 %0, %1, %2" : "=v"(r) : "v"(lo), "v"(hi)); return r; }
; DEVI void row_stats(const float* stats, int row, float& mu, float& rs) {
;     if (stats) { const float2 st = *(const float2*)(stats + 2 * (size_t)row); mu = st.x * (1.0f / 1024.0f); const float var = st.y * (1.0f / 1024.0f) - mu * mu; rs = rsqrtf(fmaxf(var, 0.f) + LN_EPS); }
;     DEVI void operator()(const f32x4 (&acc)[2][2][4][2], const pg8::Unit& u, int wr, int wc, int fr, int fq) const {
;     ...
;                 const int row = row0 + ai * 128 + m * 16; float mu, rs; row_stats(stin, row, mu, rs);
;                 float sum = 0.f, sq = 0.f;
; #pragma unroll
;                 for (int bj = 0; bj < 2; ++bj) {
;                     f32x4 z[2];
; #pragma unroll
;                     for (int n = 0; n < 2; ++n) {
;                         const int col = colb + bj * 128 + 4 * n;
;                         f32x4 xv = *(const f32x4*)(zsrc + (size_t)row * DM + col);
;                         if (stin) { const f32x4 gv = *(const f32x4*)(gin + col), bv = *(const f32x4*)(bin + col); xv = (xv - mu) * rs * gv + bv; }
;                         f32x4 zz = ALPHA * xv + acc[ai][bj][m][n];
;                         if (bias) zz += *(const f32x4*)(bias + col);
;                         *(f32x4*)(zdst + (size_t)row * DM + col) = zz;
;                         sum += zz[0] + zz[1] + zz[2] + zz[3]; sq += zz[0] * zz[0] + zz[1] * zz[1] + zz[2] * zz[2] + zz[3] * zz[3];
;                         z[n] = zz;
;                     }
;                     u32x4 o; o.x = pk2(z[0][0], z[0][1]); o.y = pk2(z[0][2], z[0][3]); o.z = pk2(z[1][0], z[1][1]); o.w = pk2(z[1][2], z[1][3]);
;                     if (zb) *(u32x4*)(zb + (size_t)row * DM + colb + bj * 128) = o;
;                 }
;                 sum += __shfl_xor(sum, 16); sq += __shfl_xor(sq, 16);
;                 sum += __shfl_xor(sum, 32); sq += __shfl_xor(sq, 32);
;                 if (fq == 0) { atomicAdd(stout + 2 * (size_t)row, sum); atomicAdd(stout + 2 * (size_t)row + 1, sq); }
.LBB0_1540:
	s_or_b64 exec, exec, s[30:31]
	v_or_b32_e32 v118, 16, v154
	v_ashrrev_i32_e32 v119, 31, v118
	v_lshlrev_b64 v[112:113], 3, v[118:119]
	s_waitcnt lgkmcnt(0)
	v_lshl_add_u64 v[114:115], s[12:13], 0, v[112:113]
	flat_load_dwordx2 v[160:161], v[114:115]
	v_lshlrev_b64 v[114:115], 12, v[118:119]
	v_lshl_add_u64 v[114:115], s[46:47], 0, v[114:115]
	v_lshl_add_u64 v[114:115], v[144:145], 2, v[114:115]
	global_load_dwordx4 v[156:159], v[114:115], off
	global_load_dwordx4 v[170:173], v[150:151], off
	global_load_dwordx4 v[174:177], v[152:153], off
	global_load_dwordx4 v[178:181], v[114:115], off offset:16
	v_lshlrev_b64 v[118:119], 11, v[118:119]
	v_lshl_add_u64 v[118:119], s[14:15], 0, v[118:119]
	v_lshl_add_u64 v[118:119], v[144:145], 1, v[118:119]
	global_load_dwordx4 v[196:199], v[146:147], off
	global_load_dwordx4 v[200:203], v[148:149], off
	s_waitcnt vmcnt(0) lgkmcnt(0)
	v_pk_mul_f32 v[160:161], v[160:161], s[24:25] op_sel:[1,0] op_sel_hi:[0,0]
	v_fma_f32 v155, -v161, v161, v160
	v_max_f32_e32 v155, 0, v155
	v_add_f32_e32 v155, 0x3727c5ac, v155
	v_mul_f32_e32 v160, 0x4b800000, v155
	v_cmp_gt_f32_e32 vcc, s61, v155
	v_sub_f32_e32 v157, v157, v161
	v_sub_f32_e32 v156, v156, v161
	v_cndmask_b32_e32 v155, v155, v160, vcc
	v_rsq_f32_e32 v155, v155
	v_sub_f32_e32 v159, v159, v161
	v_sub_f32_e32 v158, v158, v161
	v_mul_f32_e32 v160, 0x45800000, v155
	v_cndmask_b32_e32 v160, v155, v160, vcc
	v_pk_mul_f32 v[158:159], v[158:159], v[160:161] op_sel_hi:[1,0]
	v_pk_mul_f32 v[156:157], v[156:157], v[160:161] op_sel_hi:[1,0]
	v_pk_fma_f32 v[158:159], v[172:173], v[158:159], v[176:177]
	v_pk_fma_f32 v[156:157], v[170:171], v[156:157], v[174:175]
	v_pk_fma_f32 v[110:111], v[158:159], s[26:27], v[110:111] op_sel_hi:[1,0,1]
	v_pk_fma_f32 v[108:109], v[156:157], s[26:27], v[108:109] op_sel_hi:[1,0,1]
	global_store_dwordx4 v[114:115], v[108:111], off
	v_sub_f32_e32 v175, v179, v161
	v_sub_f32_e32 v174, v178, v161
	v_sub_f32_e32 v177, v181, v161
	v_sub_f32_e32 v176, v180, v161
	v_pk_mul_f32 v[176:177], v[176:177], v[160:161] op_sel_hi:[1,0]
	v_pk_mul_f32 v[178:179], v[174:175], v[160:161] op_sel_hi:[1,0]
	v_cvt_pk_bf16_f32 v174, v108, v109
	v_cvt_pk_bf16_f32 v175, v110, v111
	v_add_f32_e32 v155, v108, v109
	v_mul_f32_e32 v109, v109, v109
	v_fmac_f32_e32 v109, v108, v108
	v_add_f32_e32 v155, v110, v155
	v_fmac_f32_e32 v109, v110, v110
	v_add_f32_e32 v108, v111, v155
	v_add_f32_e32 v108, 0, v108
	v_fmac_f32_e32 v109, v111, v111
	v_pk_fma_f32 v[156:157], v[196:197], v[178:179], v[200:201]
	v_pk_fma_f32 v[158:159], v[198:199], v[176:177], v[202:203]
	v_pk_fma_f32 v[104:105], v[156:157], s[26:27], v[104:105] op_sel_hi:[1,0,1]
	v_pk_fma_f32 v[106:107], v[158:159], s[26:27], v[106:107] op_sel_hi:[1,0,1]
	global_store_dwordx4 v[114:115], v[104:107], off offset:16
	v_cvt_pk_bf16_f32 v176, v104, v105
	v_cvt_pk_bf16_f32 v177, v106, v107
	flat_store_dwordx4 v[118:119], v[174:177]
	global_load_dwordx4 v[156:159], v[114:115], off offset:512
	global_load_dwordx4 v[170:173], v[120:121], off
	s_nop 0
	global_load_dwordx4 v[174:177], v[122:123], off
	global_load_dwordx4 v[178:181], v[114:115], off offset:528
	v_add_f32_e32 v110, v104, v105
	v_mul_f32_e32 v105, v105, v105
	v_fmac_f32_e32 v105, v104, v104
	v_add_f32_e32 v110, v106, v110
	v_fmac_f32_e32 v105, v106, v106
	v_add_f32_e32 v104, v107, v110
	v_fmac_f32_e32 v105, v107, v107
	v_add_f32_e32 v108, v104, v108
	v_add_f32_e32 v109, v109, v105
	global_load_dwordx4 v[196:199], v[124:125], off
	global_load_dwordx4 v[200:203], v[126:127], off
	s_waitcnt vmcnt(0)
	v_sub_f32_e32 v157, v157, v161
	v_sub_f32_e32 v156, v156, v161
	v_sub_f32_e32 v159, v159, v161
	v_sub_f32_e32 v158, v158, v161
	v_pk_mul_f32 v[158:159], v[160:161], v[158:159] op_sel_hi:[0,1]
	v_pk_mul_f32 v[156:157], v[160:161], v[156:157] op_sel_hi:[0,1]
	v_pk_fma_f32 v[156:157], v[170:171], v[156:157], v[174:175]
	v_pk_fma_f32 v[158:159], v[172:173], v[158:159], v[176:177]
	v_pk_fma_f32 v[100:101], v[156:157], s[26:27], v[100:101] op_sel_hi:[1,0,1]
	v_pk_fma_f32 v[102:103], v[158:159], s[26:27], v[102:103] op_sel_hi:[1,0,1]
	global_store_dwordx4 v[114:115], v[100:103], off offset:512
	v_sub_f32_e32 v105, v179, v161
	v_sub_f32_e32 v104, v178, v161
	v_pk_mul_f32 v[104:105], v[160:161], v[104:105] op_sel_hi:[0,1]
	v_sub_f32_e32 v107, v181, v161
	v_sub_f32_e32 v106, v180, v161
	v_pk_mul_f32 v[106:107], v[160:161], v[106:107] op_sel_hi:[0,1]
	v_mul_f32_e32 v111, v101, v101
	v_add_f32_e32 v110, v100, v101
	v_fmac_f32_e32 v111, v100, v100
	v_add_f32_e32 v110, v102, v110
	v_fmac_f32_e32 v111, v102, v102
	v_add_f32_e32 v110, v103, v110
	v_fmac_f32_e32 v111, v103, v103
	v_add_f32_e32 v108, v108, v110
	v_add_f32_e32 v109, v109, v111
	v_cvt_pk_bf16_f32 v100, v100, v101
	v_cvt_pk_bf16_f32 v101, v102, v103
	v_pk_fma_f32 v[104:105], v[196:197], v[104:105], v[200:201]
	s_nop 0
	v_pk_fma_f32 v[104:105], v[104:105], s[26:27], v[96:97] op_sel_hi:[1,0,1]
	v_pk_fma_f32 v[106:107], v[198:199], v[106:107], v[202:203]
	v_mul_f32_e32 v97, v105, v105
	v_pk_fma_f32 v[106:107], v[106:107], s[26:27], v[98:99] op_sel_hi:[1,0,1]
	v_add_f32_e32 v96, v104, v105
	v_fmac_f32_e32 v97, v104, v104
	v_add_f32_e32 v96, v106, v96
	v_fmac_f32_e32 v97, v106, v106
	v_add_f32_e32 v96, v107, v96
	v_fmac_f32_e32 v97, v107, v107
	v_add_f32_e32 v96, v108, v96
	v_add_f32_e32 v97, v109, v97
	ds_bpermute_b32 v98, v116, v96
	ds_bpermute_b32 v99, v116, v97
	global_store_dwordx4 v[114:115], v[104:107], off offset:528
	v_cvt_pk_bf16_f32 v102, v104, v105
	v_cvt_pk_bf16_f32 v103, v106, v107
	s_waitcnt lgkmcnt(0)
	v_add_f32_e32 v96, v96, v98
	v_add_f32_e32 v97, v97, v99
	ds_bpermute_b32 v98, v117, v96
	ds_bpermute_b32 v99, v117, v97
	flat_store_dwordx4 v[118:119], v[100:103] offset:256
	s_and_saveexec_b64 s[30:31], s[2:3]
	s_cbranch_execz .LBB0_1542
	v_lshl_add_u64 v[100:101], s[10:11], 0, v[112:113]
	s_waitcnt lgkmcnt(0)
	v_add_f32_e32 v96, v96, v98
	v_add_f32_e32 v97, v97, v99
	flat_atomic_add_f32 v[100:101], v96
	flat_atomic_add_f32 v[100:101], v97 offset:4
; DEVI unsigned pk2(float lo, float hi) { unsigned r; asm("v_cvt_pk_bf16_f32 %0, %1, %2" : "=v"(r) : "v"(lo), "v"(hi)); return r; }
; DEVI void row_stats(const float* stats, int row, float& mu, float& rs) {
;     if (stats) { const float2 st = *(const float2*)(stats + 2 * (size_t)row); mu = st.x * (1.0f / 1024.0f); const float var = st.y * (1.0f / 1024.0f) - mu * mu; rs = rsqrtf(fmaxf(var, 0.f) + LN_EPS); }
;     DEVI void operator()(const f32x4 (&acc)[2][2][4][2], const pg8::Unit& u, int wr, int wc, int fr, int fq) const {
;     ...
;                 const int row = row0 + ai * 128 + m * 16; float mu, rs; row_stats(stin, row, mu, rs);
;                 float sum = 0.f, sq = 0.f;
; #pragma unroll
;                 for (int bj = 0; bj < 2; ++bj) {
;                     f32x4 z[2];
; #pragma unroll
;                     for (int n = 0; n < 2; ++n) {
;                         const int col = colb + bj * 128 + 4 * n;
;                         f32x4 xv = *(const f32x4*)(zsrc + (size_t)row * DM + col);
;                         if (stin) { const f32x4 gv = *(const f32x4*)(gin + col), bv = *(const f32x4*)(bin + col); xv = (xv - mu) * rs * gv + bv; }
;                         f32x4 zz = ALPHA * xv + acc[ai][bj][m][n];
;                         if (bias) zz += *(const f32x4*)(bias + col);
;                         *(f32x4*)(zdst + (size_t)row * DM + col) = zz;
;                         sum += zz[0] + zz[1] + zz[2] + zz[3]; sq += zz[0] * zz[0] + zz[1] * zz[1] + zz[2] * zz[2] + zz[3] * zz[3];
;                         z[n] = zz;
;                     }
;                     u32x4 o; o.x = pk2(z[0][0], z[0][1]); o.y = pk2(z[0][2], z[0][3]); o.z = pk2(z[1][0], z[1][1]); o.w = pk2(z[1][2], z[1][3]);
;                     if (zb) *(u32x4*)(zb + (size_t)row * DM + colb + bj * 128) = o;
;                 }
;                 sum += __shfl_xor(sum, 16); sq += __shfl_xor(sq, 16);
;                 sum += __shfl_xor(sum, 32); sq += __shfl_xor(sq, 32);
;                 if (fq == 0) { atomicAdd(stout + 2 * (size_t)row, sum); atomicAdd(stout + 2 * (size_t)row + 1, sq); }
.LBB0_1542:
	s_or_b64 exec, exec, s[30:31]
	v_or_b32_e32 v118, 32, v154
	v_ashrrev_i32_e32 v119, 31, v118
	v_lshlrev_b64 v[96:97], 3, v[118:119]
	s_waitcnt lgkmcnt(0)
	v_lshl_add_u64 v[98:99], s[12:13], 0, v[96:97]
	flat_load_dwordx2 v[156:157], v[98:99]
	v_lshlrev_b64 v[98:99], 12, v[118:119]
	v_lshl_add_u64 v[98:99], s[46:47], 0, v[98:99]
	v_lshl_add_u64 v[98:99], v[144:145], 2, v[98:99]
	global_load_dwordx4 v[100:103], v[98:99], off
	global_load_dwordx4 v[104:107], v[150:151], off
	global_load_dwordx4 v[108:111], v[152:153], off
	global_load_dwordx4 v[112:115], v[98:99], off offset:16
	global_load_dwordx4 v[196:199], v[146:147], off
	global_load_dwordx4 v[200:203], v[148:149], off
	s_waitcnt vmcnt(0) lgkmcnt(0)
	v_pk_mul_f32 v[156:157], v[156:157], s[24:25] op_sel:[1,0] op_sel_hi:[0,0]
	v_fma_f32 v155, -v157, v157, v156
	v_max_f32_e32 v155, 0, v155
	v_add_f32_e32 v155, 0x3727c5ac, v155
	v_mul_f32_e32 v156, 0x4b800000, v155
	v_cmp_gt_f32_e32 vcc, s61, v155
	v_sub_f32_e32 v101, v101, v157
	v_sub_f32_e32 v100, v100, v157
	v_cndmask_b32_e32 v155, v155, v156, vcc
	v_rsq_f32_e32 v155, v155
	v_sub_f32_e32 v103, v103, v157
	v_sub_f32_e32 v102, v102, v157
	v_mul_f32_e32 v156, 0x45800000, v155
	v_cndmask_b32_e32 v156, v155, v156, vcc
	v_pk_mul_f32 v[102:103], v[102:103], v[156:157] op_sel_hi:[1,0]
	v_pk_mul_f32 v[100:101], v[100:101], v[156:157] op_sel_hi:[1,0]
	v_pk_fma_f32 v[102:103], v[106:107], v[102:103], v[110:111]
	v_pk_fma_f32 v[100:101], v[104:105], v[100:101], v[108:109]
	v_pk_fma_f32 v[94:95], v[102:103], s[26:27], v[94:95] op_sel_hi:[1,0,1]
	v_pk_fma_f32 v[92:93], v[100:101], s[26:27], v[92:93] op_sel_hi:[1,0,1]
	global_store_dwordx4 v[98:99], v[92:95], off
	v_lshlrev_b64 v[108:109], 11, v[118:119]
	v_lshl_add_u64 v[108:109], s[14:15], 0, v[108:109]
	v_lshl_add_u64 v[118:119], v[144:145], 1, v[108:109]
	v_sub_f32_e32 v109, v113, v157
	v_sub_f32_e32 v108, v112, v157
	v_sub_f32_e32 v111, v115, v157
	v_sub_f32_e32 v110, v114, v157
	v_pk_mul_f32 v[110:111], v[110:111], v[156:157] op_sel_hi:[1,0]
	v_pk_mul_f32 v[112:113], v[108:109], v[156:157] op_sel_hi:[1,0]
	v_cvt_pk_bf16_f32 v108, v92, v93
	v_cvt_pk_bf16_f32 v109, v94, v95
	v_pk_fma_f32 v[102:103], v[198:199], v[110:111], v[202:203]
	v_pk_fma_f32 v[100:101], v[196:197], v[112:113], v[200:201]
	v_pk_fma_f32 v[90:91], v[102:103], s[26:27], v[90:91] op_sel_hi:[1,0,1]
	v_pk_fma_f32 v[88:89], v[100:101], s[26:27], v[88:89] op_sel_hi:[1,0,1]
	global_store_dwordx4 v[98:99], v[88:91], off offset:16
	v_cvt_pk_bf16_f32 v110, v88, v89
	v_cvt_pk_bf16_f32 v111, v90, v91
	flat_store_dwordx4 v[118:119], v[108:111]
	global_load_dwordx4 v[100:103], v[98:99], off offset:512
	global_load_dwordx4 v[104:107], v[120:121], off
	s_nop 0
	global_load_dwordx4 v[108:111], v[122:123], off
	global_load_dwordx4 v[112:115], v[98:99], off offset:528
	global_load_dwordx4 v[196:199], v[124:125], off
	global_load_dwordx4 v[200:203], v[126:127], off
	s_waitcnt vmcnt(0)
	v_sub_f32_e32 v101, v101, v157
	v_sub_f32_e32 v100, v100, v157
	v_sub_f32_e32 v103, v103, v157
	v_sub_f32_e32 v102, v102, v157
	v_pk_mul_f32 v[102:103], v[156:157], v[102:103] op_sel_hi:[0,1]
	v_pk_mul_f32 v[100:101], v[156:157], v[100:101] op_sel_hi:[0,1]
	v_pk_fma_f32 v[100:101], v[104:105], v[100:101], v[108:109]
	v_pk_fma_f32 v[102:103], v[106:107], v[102:103], v[110:111]
	v_pk_fma_f32 v[84:85], v[100:101], s[26:27], v[84:85] op_sel_hi:[1,0,1]
	v_pk_fma_f32 v[86:87], v[102:103], s[26:27], v[86:87] op_sel_hi:[1,0,1]
	global_store_dwordx4 v[98:99], v[84:87], off offset:512
	v_add_f32_e32 v108, v92, v93
	v_mul_f32_e32 v93, v93, v93
	v_fmac_f32_e32 v93, v92, v92
	v_add_f32_e32 v108, v94, v108
	v_fmac_f32_e32 v93, v94, v94
	v_add_f32_e32 v94, v88, v89
	v_mul_f32_e32 v89, v89, v89
	v_fmac_f32_e32 v89, v88, v88
	v_add_f32_e32 v92, v95, v108
	v_add_f32_e32 v94, v90, v94
	v_fmac_f32_e32 v89, v90, v90
	v_add_f32_e32 v92, 0, v92
	v_fmac_f32_e32 v93, v95, v95
	v_add_f32_e32 v88, v91, v94
	v_fmac_f32_e32 v89, v91, v91
	v_add_f32_e32 v92, v88, v92
	v_add_f32_e32 v93, v93, v89
	v_sub_f32_e32 v89, v113, v157
	v_sub_f32_e32 v88, v112, v157
	v_pk_mul_f32 v[88:89], v[156:157], v[88:89] op_sel_hi:[0,1]
	v_sub_f32_e32 v91, v115, v157
	v_sub_f32_e32 v90, v114, v157
	v_pk_mul_f32 v[90:91], v[156:157], v[90:91] op_sel_hi:[0,1]
	v_mul_f32_e32 v95, v85, v85
	v_add_f32_e32 v94, v84, v85
	v_fmac_f32_e32 v95, v84, v84
	v_add_f32_e32 v94, v86, v94
	v_fmac_f32_e32 v95, v86, v86
	v_add_f32_e32 v94, v87, v94
	v_fmac_f32_e32 v95, v87, v87
	v_add_f32_e32 v92, v92, v94
	v_add_f32_e32 v93, v93, v95
	v_cvt_pk_bf16_f32 v84, v84, v85
	v_cvt_pk_bf16_f32 v85, v86, v87
	v_pk_fma_f32 v[88:89], v[196:197], v[88:89], v[200:201]
	s_nop 0
	v_pk_fma_f32 v[88:89], v[88:89], s[26:27], v[80:81] op_sel_hi:[1,0,1]
	v_pk_fma_f32 v[90:91], v[198:199], v[90:91], v[202:203]
	v_mul_f32_e32 v81, v89, v89
	v_pk_fma_f32 v[90:91], v[90:91], s[26:27], v[82:83] op_sel_hi:[1,0,1]
	v_add_f32_e32 v80, v88, v89
	v_fmac_f32_e32 v81, v88, v88
	v_add_f32_e32 v80, v90, v80
	v_fmac_f32_e32 v81, v90, v90
	v_add_f32_e32 v80, v91, v80
	v_fmac_f32_e32 v81, v91, v91
	v_add_f32_e32 v80, v92, v80
	v_add_f32_e32 v81, v93, v81
	ds_bpermute_b32 v82, v116, v80
	ds_bpermute_b32 v83, v116, v81
	global_store_dwordx4 v[98:99], v[88:91], off offset:528
	v_cvt_pk_bf16_f32 v86, v88, v89
	v_cvt_pk_bf16_f32 v87, v90, v91
	s_waitcnt lgkmcnt(0)
	v_add_f32_e32 v80, v80, v82
	v_add_f32_e32 v81, v81, v83
	ds_bpermute_b32 v82, v117, v80
	ds_bpermute_b32 v83, v117, v81
	flat_store_dwordx4 v[118:119], v[84:87] offset:256
	s_and_saveexec_b64 s[30:31], s[2:3]
	s_cbranch_execz .LBB0_1544
	v_lshl_add_u64 v[84:85], s[10:11], 0, v[96:97]
	s_waitcnt lgkmcnt(0)
	v_add_f32_e32 v80, v80, v82
	v_add_f32_e32 v81, v81, v83
	flat_atomic_add_f32 v[84:85], v80
	flat_atomic_add_f32 v[84:85], v81 offset:4
; DEVI unsigned pk2(float lo, float hi) { unsigned r; asm("v_cvt_pk_bf16_f32 %0, %1, %2" : "=v"(r) : "v"(lo), "v"(hi)); return r; }
; DEVI void row_stats(const float* stats, int row, float& mu, float& rs) {
;     if (stats) { const float2 st = *(const float2*)(stats + 2 * (size_t)row); mu = st.x * (1.0f / 1024.0f); const float var = st.y * (1.0f / 1024.0f) - mu * mu; rs = rsqrtf(fmaxf(var, 0.f) + LN_EPS); }
;     DEVI void operator()(const f32x4 (&acc)[2][2][4][2], const pg8::Unit& u, int wr, int wc, int fr, int fq) const {
;     ...
;                 const int row = row0 + ai * 128 + m * 16; float mu, rs; row_stats(stin, row, mu, rs);
;                 float sum = 0.f, sq = 0.f;
; #pragma unroll
;                 for (int bj = 0; bj < 2; ++bj) {
;                     f32x4 z[2];
; #pragma unroll
;                     for (int n = 0; n < 2; ++n) {
;                         const int col = colb + bj * 128 + 4 * n;
;                         f32x4 xv = *(const f32x4*)(zsrc + (size_t)row * DM + col);
;                         if (stin) { const f32x4 gv = *(const f32x4*)(gin + col), bv = *(const f32x4*)(bin + col); xv = (xv - mu) * rs * gv + bv; }
;                         f32x4 zz = ALPHA * xv + acc[ai][bj][m][n];
;                         if (bias) zz += *(const f32x4*)(bias + col);
;                         *(f32x4*)(zdst + (size_t)row * DM + col) = zz;
;                         sum += zz[0] + zz[1] + zz[2] + zz[3]; sq += zz[0] * zz[0] + zz[1] * zz[1] + zz[2] * zz[2] + zz[3] * zz[3];
;                         z[n] = zz;
;                     }
;                     u32x4 o; o.x = pk2(z[0][0], z[0][1]); o.y = pk2(z[0][2], z[0][3]); o.z = pk2(z[1][0], z[1][1]); o.w = pk2(z[1][2], z[1][3]);
;                     if (zb) *(u32x4*)(zb + (size_t)row * DM + colb + bj * 128) = o;
;                 }
;                 sum += __shfl_xor(sum, 16); sq += __shfl_xor(sq, 16);
;                 sum += __shfl_xor(sum, 32); sq += __shfl_xor(sq, 32);
;                 if (fq == 0) { atomicAdd(stout + 2 * (size_t)row, sum); atomicAdd(stout + 2 * (size_t)row + 1, sq); }
.LBB0_1544:
	s_or_b64 exec, exec, s[30:31]
	v_or_b32_e32 v100, 48, v154
	v_ashrrev_i32_e32 v101, 31, v100
	v_lshlrev_b64 v[80:81], 3, v[100:101]
	s_waitcnt lgkmcnt(0)
	v_lshl_add_u64 v[82:83], s[12:13], 0, v[80:81]
	flat_load_dwordx2 v[102:103], v[82:83]
	v_lshlrev_b64 v[82:83], 12, v[100:101]
	v_lshl_add_u64 v[82:83], s[46:47], 0, v[82:83]
	v_lshl_add_u64 v[82:83], v[144:145], 2, v[82:83]
	global_load_dwordx4 v[84:87], v[82:83], off
	global_load_dwordx4 v[88:91], v[150:151], off
	global_load_dwordx4 v[92:95], v[152:153], off
	global_load_dwordx4 v[96:99], v[82:83], off offset:16
	global_load_dwordx4 v[196:199], v[146:147], off
	global_load_dwordx4 v[200:203], v[148:149], off
	s_waitcnt vmcnt(0) lgkmcnt(0)
	v_pk_mul_f32 v[102:103], v[102:103], s[24:25] op_sel:[1,0] op_sel_hi:[0,0]
	v_fma_f32 v102, -v103, v103, v102
	v_max_f32_e32 v102, 0, v102
	v_add_f32_e32 v102, 0x3727c5ac, v102
	v_mul_f32_e32 v104, 0x4b800000, v102
	v_cmp_gt_f32_e32 vcc, s61, v102
	v_sub_f32_e32 v85, v85, v103
	v_sub_f32_e32 v84, v84, v103
	v_cndmask_b32_e32 v102, v102, v104, vcc
	v_rsq_f32_e32 v102, v102
	v_sub_f32_e32 v87, v87, v103
	v_sub_f32_e32 v86, v86, v103
	v_mul_f32_e32 v104, 0x45800000, v102
	v_cndmask_b32_e32 v102, v102, v104, vcc
	v_pk_mul_f32 v[86:87], v[86:87], v[102:103] op_sel_hi:[1,0]
	v_pk_mul_f32 v[84:85], v[84:85], v[102:103] op_sel_hi:[1,0]
	v_pk_fma_f32 v[86:87], v[90:91], v[86:87], v[94:95]
	v_pk_fma_f32 v[84:85], v[88:89], v[84:85], v[92:93]
	v_pk_fma_f32 v[78:79], v[86:87], s[26:27], v[78:79] op_sel_hi:[1,0,1]
	v_pk_fma_f32 v[76:77], v[84:85], s[26:27], v[76:77] op_sel_hi:[1,0,1]
	global_store_dwordx4 v[82:83], v[76:79], off
	v_lshlrev_b64 v[92:93], 11, v[100:101]
	v_lshl_add_u64 v[92:93], s[14:15], 0, v[92:93]
	v_lshl_add_u64 v[100:101], v[144:145], 1, v[92:93]
	v_sub_f32_e32 v93, v97, v103
	v_sub_f32_e32 v92, v96, v103
	v_sub_f32_e32 v95, v99, v103
	v_sub_f32_e32 v94, v98, v103
	v_pk_mul_f32 v[94:95], v[94:95], v[102:103] op_sel_hi:[1,0]
	v_pk_mul_f32 v[96:97], v[92:93], v[102:103] op_sel_hi:[1,0]
	v_cvt_pk_bf16_f32 v92, v76, v77
	v_cvt_pk_bf16_f32 v93, v78, v79
	v_pk_fma_f32 v[86:87], v[198:199], v[94:95], v[202:203]
	v_pk_fma_f32 v[84:85], v[196:197], v[96:97], v[200:201]
	v_pk_fma_f32 v[74:75], v[86:87], s[26:27], v[74:75] op_sel_hi:[1,0,1]
	v_pk_fma_f32 v[72:73], v[84:85], s[26:27], v[72:73] op_sel_hi:[1,0,1]
	global_store_dwordx4 v[82:83], v[72:75], off offset:16
	v_cvt_pk_bf16_f32 v94, v72, v73
	v_cvt_pk_bf16_f32 v95, v74, v75
	flat_store_dwordx4 v[100:101], v[92:95]
	global_load_dwordx4 v[84:87], v[82:83], off offset:512
	global_load_dwordx4 v[88:91], v[120:121], off
	s_nop 0
	global_load_dwordx4 v[92:95], v[122:123], off
	global_load_dwordx4 v[96:99], v[82:83], off offset:528
	global_load_dwordx4 v[196:199], v[124:125], off
	global_load_dwordx4 v[200:203], v[126:127], off
	s_waitcnt vmcnt(0)
	v_sub_f32_e32 v85, v85, v103
	v_sub_f32_e32 v84, v84, v103
	v_sub_f32_e32 v87, v87, v103
	v_sub_f32_e32 v86, v86, v103
	v_pk_mul_f32 v[86:87], v[102:103], v[86:87] op_sel_hi:[0,1]
	v_pk_mul_f32 v[84:85], v[102:103], v[84:85] op_sel_hi:[0,1]
	v_pk_fma_f32 v[84:85], v[88:89], v[84:85], v[92:93]
	v_pk_fma_f32 v[86:87], v[90:91], v[86:87], v[94:95]
	v_pk_fma_f32 v[68:69], v[84:85], s[26:27], v[68:69] op_sel_hi:[1,0,1]
	v_pk_fma_f32 v[70:71], v[86:87], s[26:27], v[70:71] op_sel_hi:[1,0,1]
	global_store_dwordx4 v[82:83], v[68:71], off offset:512
	v_add_f32_e32 v92, v76, v77
	v_mul_f32_e32 v77, v77, v77
	v_fmac_f32_e32 v77, v76, v76
	v_add_f32_e32 v92, v78, v92
	v_fmac_f32_e32 v77, v78, v78
	v_add_f32_e32 v78, v72, v73
	v_mul_f32_e32 v73, v73, v73
	v_fmac_f32_e32 v73, v72, v72
	v_add_f32_e32 v76, v79, v92
	v_add_f32_e32 v78, v74, v78
	v_fmac_f32_e32 v73, v74, v74
	v_add_f32_e32 v76, 0, v76
	v_fmac_f32_e32 v77, v79, v79
	v_add_f32_e32 v72, v75, v78
	v_fmac_f32_e32 v73, v75, v75
	v_add_f32_e32 v76, v72, v76
	v_add_f32_e32 v77, v77, v73
	v_sub_f32_e32 v73, v97, v103
	v_sub_f32_e32 v72, v96, v103
	v_pk_mul_f32 v[72:73], v[102:103], v[72:73] op_sel_hi:[0,1]
	v_sub_f32_e32 v75, v99, v103
	v_sub_f32_e32 v74, v98, v103
	v_pk_mul_f32 v[74:75], v[102:103], v[74:75] op_sel_hi:[0,1]
	v_mul_f32_e32 v79, v69, v69
	v_add_f32_e32 v78, v68, v69
	v_fmac_f32_e32 v79, v68, v68
	v_add_f32_e32 v78, v70, v78
	v_fmac_f32_e32 v79, v70, v70
	v_add_f32_e32 v78, v71, v78
	v_fmac_f32_e32 v79, v71, v71
	v_add_f32_e32 v76, v76, v78
	v_add_f32_e32 v77, v77, v79
	v_cvt_pk_bf16_f32 v68, v68, v69
	v_cvt_pk_bf16_f32 v69, v70, v71
	v_pk_fma_f32 v[72:73], v[196:197], v[72:73], v[200:201]
	s_nop 0
	v_pk_fma_f32 v[72:73], v[72:73], s[26:27], v[64:65] op_sel_hi:[1,0,1]
	v_pk_fma_f32 v[74:75], v[198:199], v[74:75], v[202:203]
	v_mul_f32_e32 v65, v73, v73
	v_pk_fma_f32 v[74:75], v[74:75], s[26:27], v[66:67] op_sel_hi:[1,0,1]
	v_add_f32_e32 v64, v72, v73
	v_fmac_f32_e32 v65, v72, v72
	v_add_f32_e32 v64, v74, v64
	v_fmac_f32_e32 v65, v74, v74
	v_add_f32_e32 v64, v75, v64
	v_fmac_f32_e32 v65, v75, v75
	v_add_f32_e32 v64, v76, v64
	v_add_f32_e32 v65, v77, v65
	ds_bpermute_b32 v66, v116, v64
	ds_bpermute_b32 v67, v116, v65
	global_store_dwordx4 v[82:83], v[72:75], off offset:528
	v_cvt_pk_bf16_f32 v70, v72, v73
	v_cvt_pk_bf16_f32 v71, v74, v75
	s_waitcnt lgkmcnt(0)
	v_add_f32_e32 v64, v64, v66
	v_add_f32_e32 v65, v65, v67
	ds_bpermute_b32 v66, v117, v64
	ds_bpermute_b32 v67, v117, v65
	flat_store_dwordx4 v[100:101], v[68:71] offset:256
	s_and_saveexec_b64 s[30:31], s[2:3]
	s_cbranch_execz .LBB0_1546
	v_lshl_add_u64 v[68:69], s[10:11], 0, v[80:81]
	s_waitcnt lgkmcnt(0)
	v_add_f32_e32 v64, v64, v66
	v_add_f32_e32 v65, v65, v67
	flat_atomic_add_f32 v[68:69], v64
	flat_atomic_add_f32 v[68:69], v65 offset:4
; DEVI unsigned pk2(float lo, float hi) { unsigned r; asm("v_cvt_pk_bf16_f32 %0, %1, %2" : "=v"(r) : "v"(lo), "v"(hi)); return r; }
; DEVI void row_stats(const float* stats, int row, float& mu, float& rs) {
;     if (stats) { const float2 st = *(const float2*)(stats + 2 * (size_t)row); mu = st.x * (1.0f / 1024.0f); const float var = st.y * (1.0f / 1024.0f) - mu * mu; rs = rsqrtf(fmaxf(var, 0.f) + LN_EPS); }
;     DEVI void operator()(const f32x4 (&acc)[2][2][4][2], const pg8::Unit& u, int wr, int wc, int fr, int fq) const {
;     ...
;                 const int row = row0 + ai * 128 + m * 16; float mu, rs; row_stats(stin, row, mu, rs);
;                 float sum = 0.f, sq = 0.f;
; #pragma unroll
;                 for (int bj = 0; bj < 2; ++bj) {
;                     f32x4 z[2];
; #pragma unroll
;                     for (int n = 0; n < 2; ++n) {
;                         const int col = colb + bj * 128 + 4 * n;
;                         f32x4 xv = *(const f32x4*)(zsrc + (size_t)row * DM + col);
;                         if (stin) { const f32x4 gv = *(const f32x4*)(gin + col), bv = *(const f32x4*)(bin + col); xv = (xv - mu) * rs * gv + bv; }
;                         f32x4 zz = ALPHA * xv + acc[ai][bj][m][n];
;                         if (bias) zz += *(const f32x4*)(bias + col);
;                         *(f32x4*)(zdst + (size_t)row * DM + col) = zz;
;                         sum += zz[0] + zz[1] + zz[2] + zz[3]; sq += zz[0] * zz[0] + zz[1] * zz[1] + zz[2] * zz[2] + zz[3] * zz[3];
;                         z[n] = zz;
;                     }
;                     u32x4 o; o.x = pk2(z[0][0], z[0][1]); o.y = pk2(z[0][2], z[0][3]); o.z = pk2(z[1][0], z[1][1]); o.w = pk2(z[1][2], z[1][3]);
;                     if (zb) *(u32x4*)(zb + (size_t)row * DM + colb + bj * 128) = o;
;                 }
;                 sum += __shfl_xor(sum, 16); sq += __shfl_xor(sq, 16);
;                 sum += __shfl_xor(sum, 32); sq += __shfl_xor(sq, 32);
;                 if (fq == 0) { atomicAdd(stout + 2 * (size_t)row, sum); atomicAdd(stout + 2 * (size_t)row + 1, sq); }
.LBB0_1546:
	s_or_b64 exec, exec, s[30:31]
	v_add_u32_e32 v84, 0x80, v154
	v_ashrrev_i32_e32 v85, 31, v84
	v_lshlrev_b64 v[64:65], 3, v[84:85]
	s_waitcnt lgkmcnt(0)
	v_lshl_add_u64 v[66:67], s[12:13], 0, v[64:65]
	flat_load_dwordx2 v[86:87], v[66:67]
	v_lshlrev_b64 v[66:67], 12, v[84:85]
	v_lshl_add_u64 v[66:67], s[46:47], 0, v[66:67]
	v_lshl_add_u64 v[66:67], v[144:145], 2, v[66:67]
	global_load_dwordx4 v[68:71], v[66:67], off
	global_load_dwordx4 v[72:75], v[150:151], off
	global_load_dwordx4 v[76:79], v[152:153], off
	global_load_dwordx4 v[80:83], v[66:67], off offset:16
	global_load_dwordx4 v[196:199], v[146:147], off
	global_load_dwordx4 v[200:203], v[148:149], off
	s_waitcnt vmcnt(0) lgkmcnt(0)
	v_pk_mul_f32 v[86:87], v[86:87], s[24:25] op_sel:[1,0] op_sel_hi:[0,0]
	v_fma_f32 v86, -v87, v87, v86
	v_max_f32_e32 v86, 0, v86
	v_add_f32_e32 v86, 0x3727c5ac, v86
	v_mul_f32_e32 v88, 0x4b800000, v86
	v_cmp_gt_f32_e32 vcc, s61, v86
	v_sub_f32_e32 v69, v69, v87
	v_sub_f32_e32 v68, v68, v87
	v_cndmask_b32_e32 v86, v86, v88, vcc
	v_rsq_f32_e32 v86, v86
	v_sub_f32_e32 v71, v71, v87
	v_sub_f32_e32 v70, v70, v87
	v_mul_f32_e32 v88, 0x45800000, v86
	v_cndmask_b32_e32 v86, v86, v88, vcc
	v_pk_mul_f32 v[70:71], v[70:71], v[86:87] op_sel_hi:[1,0]
	v_pk_mul_f32 v[68:69], v[68:69], v[86:87] op_sel_hi:[1,0]
	v_pk_fma_f32 v[70:71], v[74:75], v[70:71], v[78:79]
	v_pk_fma_f32 v[68:69], v[72:73], v[68:69], v[76:77]
	v_pk_fma_f32 v[62:63], v[70:71], s[26:27], v[62:63] op_sel_hi:[1,0,1]
	v_pk_fma_f32 v[60:61], v[68:69], s[26:27], v[60:61] op_sel_hi:[1,0,1]
	global_store_dwordx4 v[66:67], v[60:63], off
	v_lshlrev_b64 v[76:77], 11, v[84:85]
	v_lshl_add_u64 v[76:77], s[14:15], 0, v[76:77]
	v_lshl_add_u64 v[84:85], v[144:145], 1, v[76:77]
	v_sub_f32_e32 v77, v81, v87
	v_sub_f32_e32 v76, v80, v87
	v_sub_f32_e32 v79, v83, v87
	v_sub_f32_e32 v78, v82, v87
	v_pk_mul_f32 v[78:79], v[78:79], v[86:87] op_sel_hi:[1,0]
	v_pk_mul_f32 v[80:81], v[76:77], v[86:87] op_sel_hi:[1,0]
	v_cvt_pk_bf16_f32 v76, v60, v61
	v_cvt_pk_bf16_f32 v77, v62, v63
	v_pk_fma_f32 v[70:71], v[198:199], v[78:79], v[202:203]
	v_pk_fma_f32 v[68:69], v[196:197], v[80:81], v[200:201]
	v_pk_fma_f32 v[58:59], v[70:71], s[26:27], v[58:59] op_sel_hi:[1,0,1]
	v_pk_fma_f32 v[56:57], v[68:69], s[26:27], v[56:57] op_sel_hi:[1,0,1]
	global_store_dwordx4 v[66:67], v[56:59], off offset:16
	v_cvt_pk_bf16_f32 v78, v56, v57
	v_cvt_pk_bf16_f32 v79, v58, v59
	flat_store_dwordx4 v[84:85], v[76:79]
	global_load_dwordx4 v[68:71], v[66:67], off offset:512
	global_load_dwordx4 v[72:75], v[120:121], off
	s_nop 0
	global_load_dwordx4 v[76:79], v[122:123], off
	global_load_dwordx4 v[80:83], v[66:67], off offset:528
	global_load_dwordx4 v[196:199], v[124:125], off
	global_load_dwordx4 v[200:203], v[126:127], off
	s_waitcnt vmcnt(0)
	v_sub_f32_e32 v69, v69, v87
	v_sub_f32_e32 v68, v68, v87
	v_sub_f32_e32 v71, v71, v87
	v_sub_f32_e32 v70, v70, v87
	v_pk_mul_f32 v[70:71], v[86:87], v[70:71] op_sel_hi:[0,1]
	v_pk_mul_f32 v[68:69], v[86:87], v[68:69] op_sel_hi:[0,1]
	v_pk_fma_f32 v[68:69], v[72:73], v[68:69], v[76:77]
	v_pk_fma_f32 v[70:71], v[74:75], v[70:71], v[78:79]
	v_pk_fma_f32 v[52:53], v[68:69], s[26:27], v[52:53] op_sel_hi:[1,0,1]
	v_pk_fma_f32 v[54:55], v[70:71], s[26:27], v[54:55] op_sel_hi:[1,0,1]
	global_store_dwordx4 v[66:67], v[52:55], off offset:512
	v_add_f32_e32 v76, v60, v61
	v_mul_f32_e32 v61, v61, v61
	v_fmac_f32_e32 v61, v60, v60
	v_add_f32_e32 v76, v62, v76
	v_fmac_f32_e32 v61, v62, v62
	v_add_f32_e32 v62, v56, v57
	v_mul_f32_e32 v57, v57, v57
	v_fmac_f32_e32 v57, v56, v56
	v_add_f32_e32 v60, v63, v76
	v_add_f32_e32 v62, v58, v62
	v_fmac_f32_e32 v57, v58, v58
	v_add_f32_e32 v60, 0, v60
	v_fmac_f32_e32 v61, v63, v63
	v_add_f32_e32 v56, v59, v62
	v_fmac_f32_e32 v57, v59, v59
	v_add_f32_e32 v60, v56, v60
	v_add_f32_e32 v61, v61, v57
	v_sub_f32_e32 v57, v81, v87
	v_sub_f32_e32 v56, v80, v87
	v_pk_mul_f32 v[56:57], v[86:87], v[56:57] op_sel_hi:[0,1]
	v_sub_f32_e32 v59, v83, v87
	v_sub_f32_e32 v58, v82, v87
	v_pk_mul_f32 v[58:59], v[86:87], v[58:59] op_sel_hi:[0,1]
	v_mul_f32_e32 v63, v53, v53
	v_add_f32_e32 v62, v52, v53
	v_fmac_f32_e32 v63, v52, v52
	v_add_f32_e32 v62, v54, v62
	v_fmac_f32_e32 v63, v54, v54
	v_add_f32_e32 v62, v55, v62
	v_fmac_f32_e32 v63, v55, v55
	v_add_f32_e32 v60, v60, v62
	v_add_f32_e32 v61, v61, v63
	v_cvt_pk_bf16_f32 v52, v52, v53
	v_cvt_pk_bf16_f32 v53, v54, v55
	v_pk_fma_f32 v[56:57], v[196:197], v[56:57], v[200:201]
	s_nop 0
	v_pk_fma_f32 v[56:57], v[56:57], s[26:27], v[48:49] op_sel_hi:[1,0,1]
	v_pk_fma_f32 v[58:59], v[198:199], v[58:59], v[202:203]
	v_mul_f32_e32 v49, v57, v57
	v_pk_fma_f32 v[58:59], v[58:59], s[26:27], v[50:51] op_sel_hi:[1,0,1]
	v_add_f32_e32 v48, v56, v57
	v_fmac_f32_e32 v49, v56, v56
	v_add_f32_e32 v48, v58, v48
	v_fmac_f32_e32 v49, v58, v58
	v_add_f32_e32 v48, v59, v48
	v_fmac_f32_e32 v49, v59, v59
	v_add_f32_e32 v48, v60, v48
	v_add_f32_e32 v49, v61, v49
	ds_bpermute_b32 v50, v116, v48
	ds_bpermute_b32 v51, v116, v49
	global_store_dwordx4 v[66:67], v[56:59], off offset:528
	v_cvt_pk_bf16_f32 v54, v56, v57
	v_cvt_pk_bf16_f32 v55, v58, v59
	s_waitcnt lgkmcnt(0)
	v_add_f32_e32 v48, v48, v50
	v_add_f32_e32 v49, v49, v51
	ds_bpermute_b32 v50, v117, v48
	ds_bpermute_b32 v51, v117, v49
	flat_store_dwordx4 v[84:85], v[52:55] offset:256
	s_and_saveexec_b64 s[30:31], s[2:3]
	s_cbranch_execz .LBB0_1548
	v_lshl_add_u64 v[52:53], s[10:11], 0, v[64:65]
	s_waitcnt lgkmcnt(0)
	v_add_f32_e32 v48, v48, v50
	v_add_f32_e32 v49, v49, v51
	flat_atomic_add_f32 v[52:53], v48
	flat_atomic_add_f32 v[52:53], v49 offset:4
; DEVI unsigned pk2(float lo, float hi) { unsigned r; asm("v_cvt_pk_bf16_f32 %0, %1, %2" : "=v"(r) : "v"(lo), "v"(hi)); return r; }
; DEVI void row_stats(const float* stats, int row, float& mu, float& rs) {
;     if (stats) { const float2 st = *(const float2*)(stats + 2 * (size_t)row); mu = st.x * (1.0f / 1024.0f); const float var = st.y * (1.0f / 1024.0f) - mu * mu; rs = rsqrtf(fmaxf(var, 0.f) + LN_EPS); }
;     DEVI void operator()(const f32x4 (&acc)[2][2][4][2], const pg8::Unit& u, int wr, int wc, int fr, int fq) const {
;     ...
;                 const int row = row0 + ai * 128 + m * 16; float mu, rs; row_stats(stin, row, mu, rs);
;                 float sum = 0.f, sq = 0.f;
; #pragma unroll
;                 for (int bj = 0; bj < 2; ++bj) {
;                     f32x4 z[2];
; #pragma unroll
;                     for (int n = 0; n < 2; ++n) {
;                         const int col = colb + bj * 128 + 4 * n;
;                         f32x4 xv = *(const f32x4*)(zsrc + (size_t)row * DM + col);
;                         if (stin) { const f32x4 gv = *(const f32x4*)(gin + col), bv = *(const f32x4*)(bin + col); xv = (xv - mu) * rs * gv + bv; }
;                         f32x4 zz = ALPHA * xv + acc[ai][bj][m][n];
;                         if (bias) zz += *(const f32x4*)(bias + col);
;                         *(f32x4*)(zdst + (size_t)row * DM + col) = zz;
;                         sum += zz[0] + zz[1] + zz[2] + zz[3]; sq += zz[0] * zz[0] + zz[1] * zz[1] + zz[2] * zz[2] + zz[3] * zz[3];
;                         z[n] = zz;
;                     }
;                     u32x4 o; o.x = pk2(z[0][0], z[0][1]); o.y = pk2(z[0][2], z[0][3]); o.z = pk2(z[1][0], z[1][1]); o.w = pk2(z[1][2], z[1][3]);
;                     if (zb) *(u32x4*)(zb + (size_t)row * DM + colb + bj * 128) = o;
;                 }
;                 sum += __shfl_xor(sum, 16); sq += __shfl_xor(sq, 16);
;                 sum += __shfl_xor(sum, 32); sq += __shfl_xor(sq, 32);
;                 if (fq == 0) { atomicAdd(stout + 2 * (size_t)row, sum); atomicAdd(stout + 2 * (size_t)row + 1, sq); }
.LBB0_1548:
	s_or_b64 exec, exec, s[30:31]
	v_add_u32_e32 v68, 0x90, v154
	v_ashrrev_i32_e32 v69, 31, v68
	v_lshlrev_b64 v[48:49], 3, v[68:69]
	s_waitcnt lgkmcnt(0)
	v_lshl_add_u64 v[50:51], s[12:13], 0, v[48:49]
	flat_load_dwordx2 v[70:71], v[50:51]
	v_lshlrev_b64 v[50:51], 12, v[68:69]
	v_lshl_add_u64 v[50:51], s[46:47], 0, v[50:51]
	v_lshl_add_u64 v[50:51], v[144:145], 2, v[50:51]
	global_load_dwordx4 v[52:55], v[50:51], off
	global_load_dwordx4 v[56:59], v[150:151], off
	global_load_dwordx4 v[60:63], v[152:153], off
	global_load_dwordx4 v[64:67], v[50:51], off offset:16
	global_load_dwordx4 v[196:199], v[146:147], off
	global_load_dwordx4 v[200:203], v[148:149], off
	s_waitcnt vmcnt(0) lgkmcnt(0)
	v_pk_mul_f32 v[70:71], v[70:71], s[24:25] op_sel:[1,0] op_sel_hi:[0,0]
	v_fma_f32 v70, -v71, v71, v70
	v_max_f32_e32 v70, 0, v70
	v_add_f32_e32 v70, 0x3727c5ac, v70
	v_mul_f32_e32 v72, 0x4b800000, v70
	v_cmp_gt_f32_e32 vcc, s61, v70
	v_sub_f32_e32 v53, v53, v71
	v_sub_f32_e32 v52, v52, v71
	v_cndmask_b32_e32 v70, v70, v72, vcc
	v_rsq_f32_e32 v70, v70
	v_sub_f32_e32 v55, v55, v71
	v_sub_f32_e32 v54, v54, v71
	v_mul_f32_e32 v72, 0x45800000, v70
	v_cndmask_b32_e32 v70, v70, v72, vcc
	v_pk_mul_f32 v[54:55], v[54:55], v[70:71] op_sel_hi:[1,0]
	v_pk_mul_f32 v[52:53], v[52:53], v[70:71] op_sel_hi:[1,0]
	v_pk_fma_f32 v[54:55], v[58:59], v[54:55], v[62:63]
	v_pk_fma_f32 v[52:53], v[56:57], v[52:53], v[60:61]
	v_pk_fma_f32 v[46:47], v[54:55], s[26:27], v[46:47] op_sel_hi:[1,0,1]
	v_pk_fma_f32 v[44:45], v[52:53], s[26:27], v[44:45] op_sel_hi:[1,0,1]
	global_store_dwordx4 v[50:51], v[44:47], off
	v_lshlrev_b64 v[60:61], 11, v[68:69]
	v_lshl_add_u64 v[60:61], s[14:15], 0, v[60:61]
	v_lshl_add_u64 v[68:69], v[144:145], 1, v[60:61]
	v_sub_f32_e32 v61, v65, v71
	v_sub_f32_e32 v60, v64, v71
	v_sub_f32_e32 v63, v67, v71
	v_sub_f32_e32 v62, v66, v71
	v_pk_mul_f32 v[62:63], v[62:63], v[70:71] op_sel_hi:[1,0]
	v_pk_mul_f32 v[64:65], v[60:61], v[70:71] op_sel_hi:[1,0]
	v_cvt_pk_bf16_f32 v60, v44, v45
	v_cvt_pk_bf16_f32 v61, v46, v47
	v_pk_fma_f32 v[54:55], v[198:199], v[62:63], v[202:203]
	v_pk_fma_f32 v[52:53], v[196:197], v[64:65], v[200:201]
	v_pk_fma_f32 v[42:43], v[54:55], s[26:27], v[42:43] op_sel_hi:[1,0,1]
	v_pk_fma_f32 v[40:41], v[52:53], s[26:27], v[40:41] op_sel_hi:[1,0,1]
	global_store_dwordx4 v[50:51], v[40:43], off offset:16
	v_cvt_pk_bf16_f32 v62, v40, v41
	v_cvt_pk_bf16_f32 v63, v42, v43
	flat_store_dwordx4 v[68:69], v[60:63]
	global_load_dwordx4 v[52:55], v[50:51], off offset:512
	global_load_dwordx4 v[56:59], v[120:121], off
	s_nop 0
	global_load_dwordx4 v[60:63], v[122:123], off
	global_load_dwordx4 v[64:67], v[50:51], off offset:528
	global_load_dwordx4 v[196:199], v[124:125], off
	global_load_dwordx4 v[200:203], v[126:127], off
	s_waitcnt vmcnt(0)
	v_sub_f32_e32 v53, v53, v71
	v_sub_f32_e32 v52, v52, v71
	v_sub_f32_e32 v55, v55, v71
	v_sub_f32_e32 v54, v54, v71
	v_pk_mul_f32 v[54:55], v[70:71], v[54:55] op_sel_hi:[0,1]
	v_pk_mul_f32 v[52:53], v[70:71], v[52:53] op_sel_hi:[0,1]
	v_pk_fma_f32 v[52:53], v[56:57], v[52:53], v[60:61]
	v_pk_fma_f32 v[54:55], v[58:59], v[54:55], v[62:63]
	v_pk_fma_f32 v[36:37], v[52:53], s[26:27], v[36:37] op_sel_hi:[1,0,1]
	v_pk_fma_f32 v[38:39], v[54:55], s[26:27], v[38:39] op_sel_hi:[1,0,1]
	global_store_dwordx4 v[50:51], v[36:39], off offset:512
	v_add_f32_e32 v60, v44, v45
	v_mul_f32_e32 v45, v45, v45
	v_fmac_f32_e32 v45, v44, v44
	v_add_f32_e32 v60, v46, v60
	v_fmac_f32_e32 v45, v46, v46
	v_add_f32_e32 v46, v40, v41
	v_mul_f32_e32 v41, v41, v41
	v_fmac_f32_e32 v41, v40, v40
	v_add_f32_e32 v44, v47, v60
	v_add_f32_e32 v46, v42, v46
	v_fmac_f32_e32 v41, v42, v42
	v_add_f32_e32 v44, 0, v44
	v_fmac_f32_e32 v45, v47, v47
	v_add_f32_e32 v40, v43, v46
	v_fmac_f32_e32 v41, v43, v43
	v_add_f32_e32 v44, v40, v44
	v_add_f32_e32 v45, v45, v41
	v_sub_f32_e32 v41, v65, v71
	v_sub_f32_e32 v40, v64, v71
	v_pk_mul_f32 v[40:41], v[70:71], v[40:41] op_sel_hi:[0,1]
	v_sub_f32_e32 v43, v67, v71
	v_sub_f32_e32 v42, v66, v71
	v_pk_mul_f32 v[42:43], v[70:71], v[42:43] op_sel_hi:[0,1]
	v_mul_f32_e32 v47, v37, v37
	v_add_f32_e32 v46, v36, v37
	v_fmac_f32_e32 v47, v36, v36
	v_add_f32_e32 v46, v38, v46
	v_fmac_f32_e32 v47, v38, v38
	v_add_f32_e32 v46, v39, v46
	v_fmac_f32_e32 v47, v39, v39
	v_add_f32_e32 v44, v44, v46
	v_add_f32_e32 v45, v45, v47
	v_cvt_pk_bf16_f32 v36, v36, v37
	v_cvt_pk_bf16_f32 v37, v38, v39
	v_pk_fma_f32 v[40:41], v[196:197], v[40:41], v[200:201]
	s_nop 0
	v_pk_fma_f32 v[40:41], v[40:41], s[26:27], v[32:33] op_sel_hi:[1,0,1]
	v_pk_fma_f32 v[42:43], v[198:199], v[42:43], v[202:203]
	v_mul_f32_e32 v33, v41, v41
	v_pk_fma_f32 v[42:43], v[42:43], s[26:27], v[34:35] op_sel_hi:[1,0,1]
	v_add_f32_e32 v32, v40, v41
	v_fmac_f32_e32 v33, v40, v40
	v_add_f32_e32 v32, v42, v32
	v_fmac_f32_e32 v33, v42, v42
	v_add_f32_e32 v32, v43, v32
	v_fmac_f32_e32 v33, v43, v43
	v_add_f32_e32 v32, v44, v32
	v_add_f32_e32 v33, v45, v33
	ds_bpermute_b32 v34, v116, v32
	ds_bpermute_b32 v35, v116, v33
	global_store_dwordx4 v[50:51], v[40:43], off offset:528
	v_cvt_pk_bf16_f32 v38, v40, v41
	v_cvt_pk_bf16_f32 v39, v42, v43
	s_waitcnt lgkmcnt(0)
	v_add_f32_e32 v32, v32, v34
	v_add_f32_e32 v33, v33, v35
	ds_bpermute_b32 v34, v117, v32
	ds_bpermute_b32 v35, v117, v33
	flat_store_dwordx4 v[68:69], v[36:39] offset:256
	s_and_saveexec_b64 s[30:31], s[2:3]
	s_cbranch_execz .LBB0_1550
	v_lshl_add_u64 v[36:37], s[10:11], 0, v[48:49]
	s_waitcnt lgkmcnt(0)
	v_add_f32_e32 v32, v32, v34
	v_add_f32_e32 v33, v33, v35
	flat_atomic_add_f32 v[36:37], v32
	flat_atomic_add_f32 v[36:37], v33 offset:4
; DEVI unsigned pk2(float lo, float hi) { unsigned r; asm("v_cvt_pk_bf16_f32 %0, %1, %2" : "=v"(r) : "v"(lo), "v"(hi)); return r; }
; DEVI void row_stats(const float* stats, int row, float& mu, float& rs) {
;     if (stats) { const float2 st = *(const float2*)(stats + 2 * (size_t)row); mu = st.x * (1.0f / 1024.0f); const float var = st.y * (1.0f / 1024.0f) - mu * mu; rs = rsqrtf(fmaxf(var, 0.f) + LN_EPS); }
;     DEVI void operator()(const f32x4 (&acc)[2][2][4][2], const pg8::Unit& u, int wr, int wc, int fr, int fq) const {
;     ...
;                 const int row = row0 + ai * 128 + m * 16; float mu, rs; row_stats(stin, row, mu, rs);
;                 float sum = 0.f, sq = 0.f;
; #pragma unroll
;                 for (int bj = 0; bj < 2; ++bj) {
;                     f32x4 z[2];
; #pragma unroll
;                     for (int n = 0; n < 2; ++n) {
;                         const int col = colb + bj * 128 + 4 * n;
;                         f32x4 xv = *(const f32x4*)(zsrc + (size_t)row * DM + col);
;                         if (stin) { const f32x4 gv = *(const f32x4*)(gin + col), bv = *(const f32x4*)(bin + col); xv = (xv - mu) * rs * gv + bv; }
;                         f32x4 zz = ALPHA * xv + acc[ai][bj][m][n];
;                         if (bias) zz += *(const f32x4*)(bias + col);
;                         *(f32x4*)(zdst + (size_t)row * DM + col) = zz;
;                         sum += zz[0] + zz[1] + zz[2] + zz[3]; sq += zz[0] * zz[0] + zz[1] * zz[1] + zz[2] * zz[2] + zz[3] * zz[3];
;                         z[n] = zz;
;                     }
;                     u32x4 o; o.x = pk2(z[0][0], z[0][1]); o.y = pk2(z[0][2], z[0][3]); o.z = pk2(z[1][0], z[1][1]); o.w = pk2(z[1][2], z[1][3]);
;                     if (zb) *(u32x4*)(zb + (size_t)row * DM + colb + bj * 128) = o;
;                 }
;                 sum += __shfl_xor(sum, 16); sq += __shfl_xor(sq, 16);
;                 sum += __shfl_xor(sum, 32); sq += __shfl_xor(sq, 32);
;                 if (fq == 0) { atomicAdd(stout + 2 * (size_t)row, sum); atomicAdd(stout + 2 * (size_t)row + 1, sq); }
.LBB0_1550:
	s_or_b64 exec, exec, s[30:31]
	v_add_u32_e32 v52, 0xa0, v154
	v_ashrrev_i32_e32 v53, 31, v52
	v_lshlrev_b64 v[32:33], 3, v[52:53]
	s_waitcnt lgkmcnt(0)
	v_lshl_add_u64 v[34:35], s[12:13], 0, v[32:33]
	flat_load_dwordx2 v[54:55], v[34:35]
	v_lshlrev_b64 v[34:35], 12, v[52:53]
	v_lshl_add_u64 v[34:35], s[46:47], 0, v[34:35]
	v_lshl_add_u64 v[34:35], v[144:145], 2, v[34:35]
	global_load_dwordx4 v[36:39], v[34:35], off
	global_load_dwordx4 v[40:43], v[150:151], off
	global_load_dwordx4 v[44:47], v[152:153], off
	global_load_dwordx4 v[48:51], v[34:35], off offset:16
	global_load_dwordx4 v[196:199], v[146:147], off
	global_load_dwordx4 v[200:203], v[148:149], off
	s_waitcnt vmcnt(0) lgkmcnt(0)
	v_pk_mul_f32 v[54:55], v[54:55], s[24:25] op_sel:[1,0] op_sel_hi:[0,0]
	v_fma_f32 v54, -v55, v55, v54
	v_max_f32_e32 v54, 0, v54
	v_add_f32_e32 v54, 0x3727c5ac, v54
	v_mul_f32_e32 v56, 0x4b800000, v54
	v_cmp_gt_f32_e32 vcc, s61, v54
	v_sub_f32_e32 v37, v37, v55
	v_sub_f32_e32 v36, v36, v55
	v_cndmask_b32_e32 v54, v54, v56, vcc
	v_rsq_f32_e32 v54, v54
	v_sub_f32_e32 v39, v39, v55
	v_sub_f32_e32 v38, v38, v55
	v_mul_f32_e32 v56, 0x45800000, v54
	v_cndmask_b32_e32 v54, v54, v56, vcc
	v_pk_mul_f32 v[38:39], v[38:39], v[54:55] op_sel_hi:[1,0]
	v_pk_mul_f32 v[36:37], v[36:37], v[54:55] op_sel_hi:[1,0]
	v_pk_fma_f32 v[38:39], v[42:43], v[38:39], v[46:47]
	v_pk_fma_f32 v[36:37], v[40:41], v[36:37], v[44:45]
	v_pk_fma_f32 v[30:31], v[38:39], s[26:27], v[30:31] op_sel_hi:[1,0,1]
	v_pk_fma_f32 v[28:29], v[36:37], s[26:27], v[28:29] op_sel_hi:[1,0,1]
	global_store_dwordx4 v[34:35], v[28:31], off
	v_lshlrev_b64 v[44:45], 11, v[52:53]
	v_lshl_add_u64 v[44:45], s[14:15], 0, v[44:45]
	v_lshl_add_u64 v[52:53], v[144:145], 1, v[44:45]
	v_sub_f32_e32 v45, v49, v55
	v_sub_f32_e32 v44, v48, v55
	v_sub_f32_e32 v47, v51, v55
	v_sub_f32_e32 v46, v50, v55
	v_pk_mul_f32 v[46:47], v[46:47], v[54:55] op_sel_hi:[1,0]
	v_pk_mul_f32 v[48:49], v[44:45], v[54:55] op_sel_hi:[1,0]
	v_cvt_pk_bf16_f32 v44, v28, v29
	v_cvt_pk_bf16_f32 v45, v30, v31
	v_pk_fma_f32 v[38:39], v[198:199], v[46:47], v[202:203]
	v_pk_fma_f32 v[36:37], v[196:197], v[48:49], v[200:201]
	v_pk_fma_f32 v[26:27], v[38:39], s[26:27], v[26:27] op_sel_hi:[1,0,1]
	v_pk_fma_f32 v[24:25], v[36:37], s[26:27], v[24:25] op_sel_hi:[1,0,1]
	global_store_dwordx4 v[34:35], v[24:27], off offset:16
	v_cvt_pk_bf16_f32 v46, v24, v25
	v_cvt_pk_bf16_f32 v47, v26, v27
	flat_store_dwordx4 v[52:53], v[44:47]
	global_load_dwordx4 v[36:39], v[34:35], off offset:512
	global_load_dwordx4 v[40:43], v[120:121], off
	s_nop 0
	global_load_dwordx4 v[44:47], v[122:123], off
	global_load_dwordx4 v[48:51], v[34:35], off offset:528
	global_load_dwordx4 v[196:199], v[124:125], off
	global_load_dwordx4 v[200:203], v[126:127], off
	s_waitcnt vmcnt(0)
	v_sub_f32_e32 v37, v37, v55
	v_sub_f32_e32 v36, v36, v55
	v_sub_f32_e32 v39, v39, v55
	v_sub_f32_e32 v38, v38, v55
	v_pk_mul_f32 v[38:39], v[54:55], v[38:39] op_sel_hi:[0,1]
	v_pk_mul_f32 v[36:37], v[54:55], v[36:37] op_sel_hi:[0,1]
	v_pk_fma_f32 v[36:37], v[40:41], v[36:37], v[44:45]
	v_pk_fma_f32 v[38:39], v[42:43], v[38:39], v[46:47]
	v_pk_fma_f32 v[20:21], v[36:37], s[26:27], v[20:21] op_sel_hi:[1,0,1]
	v_pk_fma_f32 v[22:23], v[38:39], s[26:27], v[22:23] op_sel_hi:[1,0,1]
	global_store_dwordx4 v[34:35], v[20:23], off offset:512
	v_add_f32_e32 v44, v28, v29
	v_mul_f32_e32 v29, v29, v29
	v_fmac_f32_e32 v29, v28, v28
	v_add_f32_e32 v44, v30, v44
	v_fmac_f32_e32 v29, v30, v30
	v_add_f32_e32 v30, v24, v25
	v_mul_f32_e32 v25, v25, v25
	v_fmac_f32_e32 v25, v24, v24
	v_add_f32_e32 v28, v31, v44
	v_add_f32_e32 v30, v26, v30
	v_fmac_f32_e32 v25, v26, v26
	v_add_f32_e32 v28, 0, v28
	v_fmac_f32_e32 v29, v31, v31
	v_add_f32_e32 v24, v27, v30
	v_fmac_f32_e32 v25, v27, v27
	v_add_f32_e32 v28, v24, v28
	v_add_f32_e32 v29, v29, v25
	v_sub_f32_e32 v25, v49, v55
	v_sub_f32_e32 v24, v48, v55
	v_pk_mul_f32 v[24:25], v[54:55], v[24:25] op_sel_hi:[0,1]
	v_sub_f32_e32 v27, v51, v55
	v_sub_f32_e32 v26, v50, v55
	v_pk_mul_f32 v[26:27], v[54:55], v[26:27] op_sel_hi:[0,1]
	v_mul_f32_e32 v31, v21, v21
	v_add_f32_e32 v30, v20, v21
	v_fmac_f32_e32 v31, v20, v20
	v_add_f32_e32 v30, v22, v30
	v_fmac_f32_e32 v31, v22, v22
	v_add_f32_e32 v30, v23, v30
	v_fmac_f32_e32 v31, v23, v23
	v_add_f32_e32 v28, v28, v30
	v_add_f32_e32 v29, v29, v31
	v_cvt_pk_bf16_f32 v20, v20, v21
	v_cvt_pk_bf16_f32 v21, v22, v23
	v_pk_fma_f32 v[24:25], v[196:197], v[24:25], v[200:201]
	s_nop 0
	v_pk_fma_f32 v[24:25], v[24:25], s[26:27], v[16:17] op_sel_hi:[1,0,1]
	v_pk_fma_f32 v[26:27], v[198:199], v[26:27], v[202:203]
	v_mul_f32_e32 v17, v25, v25
	v_pk_fma_f32 v[26:27], v[26:27], s[26:27], v[18:19] op_sel_hi:[1,0,1]
	v_add_f32_e32 v16, v24, v25
	v_fmac_f32_e32 v17, v24, v24
	v_add_f32_e32 v16, v26, v16
	v_fmac_f32_e32 v17, v26, v26
	v_add_f32_e32 v16, v27, v16
	v_fmac_f32_e32 v17, v27, v27
	v_add_f32_e32 v16, v28, v16
	v_add_f32_e32 v17, v29, v17
	ds_bpermute_b32 v18, v116, v16
	ds_bpermute_b32 v19, v116, v17
	global_store_dwordx4 v[34:35], v[24:27], off offset:528
	v_cvt_pk_bf16_f32 v22, v24, v25
	v_cvt_pk_bf16_f32 v23, v26, v27
	s_waitcnt lgkmcnt(0)
	v_add_f32_e32 v16, v16, v18
	v_add_f32_e32 v17, v17, v19
	ds_bpermute_b32 v18, v117, v16
	ds_bpermute_b32 v19, v117, v17
	flat_store_dwordx4 v[52:53], v[20:23] offset:256
	s_and_saveexec_b64 s[30:31], s[2:3]
	s_cbranch_execz .LBB0_1552
	v_lshl_add_u64 v[20:21], s[10:11], 0, v[32:33]
	s_waitcnt lgkmcnt(0)
	v_add_f32_e32 v16, v16, v18
	v_add_f32_e32 v17, v17, v19
	flat_atomic_add_f32 v[20:21], v16
	flat_atomic_add_f32 v[20:21], v17 offset:4
; DEVI unsigned pk2(float lo, float hi) { unsigned r; asm("v_cvt_pk_bf16_f32 %0, %1, %2" : "=v"(r) : "v"(lo), "v"(hi)); return r; }
; DEVI void row_stats(const float* stats, int row, float& mu, float& rs) {
;     if (stats) { const float2 st = *(const float2*)(stats + 2 * (size_t)row); mu = st.x * (1.0f / 1024.0f); const float var = st.y * (1.0f / 1024.0f) - mu * mu; rs = rsqrtf(fmaxf(var, 0.f) + LN_EPS); }
;     DEVI void operator()(const f32x4 (&acc)[2][2][4][2], const pg8::Unit& u, int wr, int wc, int fr, int fq) const {
;     ...
;                 const int row = row0 + ai * 128 + m * 16; float mu, rs; row_stats(stin, row, mu, rs);
;                 float sum = 0.f, sq = 0.f;
; #pragma unroll
;                 for (int bj = 0; bj < 2; ++bj) {
;                     f32x4 z[2];
; #pragma unroll
;                     for (int n = 0; n < 2; ++n) {
;                         const int col = colb + bj * 128 + 4 * n;
;                         f32x4 xv = *(const f32x4*)(zsrc + (size_t)row * DM + col);
;                         if (stin) { const f32x4 gv = *(const f32x4*)(gin + col), bv = *(const f32x4*)(bin + col); xv = (xv - mu) * rs * gv + bv; }
;                         f32x4 zz = ALPHA * xv + acc[ai][bj][m][n];
;                         if (bias) zz += *(const f32x4*)(bias + col);
;                         *(f32x4*)(zdst + (size_t)row * DM + col) = zz;
;                         sum += zz[0] + zz[1] + zz[2] + zz[3]; sq += zz[0] * zz[0] + zz[1] * zz[1] + zz[2] * zz[2] + zz[3] * zz[3];
;                         z[n] = zz;
;                     }
;                     u32x4 o; o.x = pk2(z[0][0], z[0][1]); o.y = pk2(z[0][2], z[0][3]); o.z = pk2(z[1][0], z[1][1]); o.w = pk2(z[1][2], z[1][3]);
;                     if (zb) *(u32x4*)(zb + (size_t)row * DM + colb + bj * 128) = o;
;                 }
;                 sum += __shfl_xor(sum, 16); sq += __shfl_xor(sq, 16);
;                 sum += __shfl_xor(sum, 32); sq += __shfl_xor(sq, 32);
;                 if (fq == 0) { atomicAdd(stout + 2 * (size_t)row, sum); atomicAdd(stout + 2 * (size_t)row + 1, sq); }
.LBB0_1552:
	s_or_b64 exec, exec, s[30:31]
	v_add_u32_e32 v36, 0xb0, v154
	v_ashrrev_i32_e32 v37, 31, v36
	v_lshlrev_b64 v[16:17], 3, v[36:37]
	s_waitcnt lgkmcnt(0)
	v_lshl_add_u64 v[18:19], s[12:13], 0, v[16:17]
	flat_load_dwordx2 v[38:39], v[18:19]
	v_lshlrev_b64 v[18:19], 12, v[36:37]
	v_lshl_add_u64 v[18:19], s[46:47], 0, v[18:19]
	v_lshl_add_u64 v[18:19], v[144:145], 2, v[18:19]
	global_load_dwordx4 v[20:23], v[18:19], off
	global_load_dwordx4 v[24:27], v[150:151], off
	global_load_dwordx4 v[28:31], v[152:153], off
	global_load_dwordx4 v[32:35], v[18:19], off offset:16
	global_load_dwordx4 v[196:199], v[146:147], off
	global_load_dwordx4 v[200:203], v[148:149], off
	s_waitcnt vmcnt(0) lgkmcnt(0)
	v_pk_mul_f32 v[38:39], v[38:39], s[24:25] op_sel:[1,0] op_sel_hi:[0,0]
	v_fma_f32 v38, -v39, v39, v38
	v_max_f32_e32 v38, 0, v38
	v_add_f32_e32 v38, 0x3727c5ac, v38
	v_mul_f32_e32 v40, 0x4b800000, v38
	v_cmp_gt_f32_e32 vcc, s61, v38
	v_sub_f32_e32 v21, v21, v39
	v_sub_f32_e32 v20, v20, v39
	v_cndmask_b32_e32 v38, v38, v40, vcc
	v_rsq_f32_e32 v38, v38
	v_sub_f32_e32 v23, v23, v39
	v_sub_f32_e32 v22, v22, v39
	v_mul_f32_e32 v40, 0x45800000, v38
	v_cndmask_b32_e32 v38, v38, v40, vcc
	v_pk_mul_f32 v[22:23], v[22:23], v[38:39] op_sel_hi:[1,0]
	v_pk_mul_f32 v[20:21], v[20:21], v[38:39] op_sel_hi:[1,0]
	v_pk_fma_f32 v[22:23], v[26:27], v[22:23], v[30:31]
	v_pk_fma_f32 v[20:21], v[24:25], v[20:21], v[28:29]
	v_pk_fma_f32 v[14:15], v[22:23], s[26:27], v[14:15] op_sel_hi:[1,0,1]
	v_pk_fma_f32 v[12:13], v[20:21], s[26:27], v[12:13] op_sel_hi:[1,0,1]
	global_store_dwordx4 v[18:19], v[12:15], off
	v_lshlrev_b64 v[28:29], 11, v[36:37]
	v_lshl_add_u64 v[28:29], s[14:15], 0, v[28:29]
	v_lshl_add_u64 v[36:37], v[144:145], 1, v[28:29]
	v_sub_f32_e32 v29, v33, v39
	v_sub_f32_e32 v28, v32, v39
	v_sub_f32_e32 v31, v35, v39
	v_sub_f32_e32 v30, v34, v39
	v_pk_mul_f32 v[30:31], v[30:31], v[38:39] op_sel_hi:[1,0]
	v_pk_mul_f32 v[32:33], v[28:29], v[38:39] op_sel_hi:[1,0]
	v_cvt_pk_bf16_f32 v28, v12, v13
	v_cvt_pk_bf16_f32 v29, v14, v15
	v_pk_fma_f32 v[22:23], v[198:199], v[30:31], v[202:203]
	v_pk_fma_f32 v[20:21], v[196:197], v[32:33], v[200:201]
	v_pk_fma_f32 v[10:11], v[22:23], s[26:27], v[10:11] op_sel_hi:[1,0,1]
	v_pk_fma_f32 v[8:9], v[20:21], s[26:27], v[8:9] op_sel_hi:[1,0,1]
	global_store_dwordx4 v[18:19], v[8:11], off offset:16
	v_cvt_pk_bf16_f32 v30, v8, v9
	v_cvt_pk_bf16_f32 v31, v10, v11
	flat_store_dwordx4 v[36:37], v[28:31]
	global_load_dwordx4 v[20:23], v[18:19], off offset:512
	global_load_dwordx4 v[24:27], v[120:121], off
	s_nop 0
	global_load_dwordx4 v[28:31], v[122:123], off
	global_load_dwordx4 v[32:35], v[18:19], off offset:528
	global_load_dwordx4 v[196:199], v[124:125], off
	global_load_dwordx4 v[200:203], v[126:127], off
	s_waitcnt vmcnt(0)
	v_sub_f32_e32 v21, v21, v39
	v_sub_f32_e32 v20, v20, v39
	v_sub_f32_e32 v23, v23, v39
	v_sub_f32_e32 v22, v22, v39
	v_pk_mul_f32 v[22:23], v[38:39], v[22:23] op_sel_hi:[0,1]
	v_pk_mul_f32 v[20:21], v[38:39], v[20:21] op_sel_hi:[0,1]
	v_pk_fma_f32 v[20:21], v[24:25], v[20:21], v[28:29]
	v_pk_fma_f32 v[22:23], v[26:27], v[22:23], v[30:31]
	v_pk_fma_f32 v[4:5], v[20:21], s[26:27], v[4:5] op_sel_hi:[1,0,1]
	v_pk_fma_f32 v[6:7], v[22:23], s[26:27], v[6:7] op_sel_hi:[1,0,1]
	global_store_dwordx4 v[18:19], v[4:7], off offset:512
	v_add_f32_e32 v28, v12, v13
	v_mul_f32_e32 v13, v13, v13
	v_fmac_f32_e32 v13, v12, v12
	v_add_f32_e32 v28, v14, v28
	v_fmac_f32_e32 v13, v14, v14
	v_add_f32_e32 v14, v8, v9
	v_mul_f32_e32 v9, v9, v9
	v_fmac_f32_e32 v9, v8, v8
	v_add_f32_e32 v12, v15, v28
	v_add_f32_e32 v14, v10, v14
	v_fmac_f32_e32 v9, v10, v10
	v_add_f32_e32 v12, 0, v12
	v_fmac_f32_e32 v13, v15, v15
	v_add_f32_e32 v8, v11, v14
	v_fmac_f32_e32 v9, v11, v11
	v_add_f32_e32 v12, v8, v12
	v_add_f32_e32 v13, v13, v9
	v_sub_f32_e32 v9, v33, v39
	v_sub_f32_e32 v8, v32, v39
	v_pk_mul_f32 v[8:9], v[38:39], v[8:9] op_sel_hi:[0,1]
	v_sub_f32_e32 v11, v35, v39
	v_sub_f32_e32 v10, v34, v39
	v_pk_mul_f32 v[10:11], v[38:39], v[10:11] op_sel_hi:[0,1]
	v_mul_f32_e32 v15, v5, v5
	v_add_f32_e32 v14, v4, v5
	v_fmac_f32_e32 v15, v4, v4
	v_add_f32_e32 v14, v6, v14
	v_fmac_f32_e32 v15, v6, v6
	v_add_f32_e32 v14, v7, v14
	v_fmac_f32_e32 v15, v7, v7
	v_add_f32_e32 v12, v12, v14
	v_add_f32_e32 v13, v13, v15
	v_cvt_pk_bf16_f32 v4, v4, v5
	v_cvt_pk_bf16_f32 v5, v6, v7
	v_pk_fma_f32 v[8:9], v[196:197], v[8:9], v[200:201]
	s_nop 0
	v_pk_fma_f32 v[8:9], v[8:9], s[26:27], v[0:1] op_sel_hi:[1,0,1]
	v_pk_fma_f32 v[10:11], v[198:199], v[10:11], v[202:203]
	v_mul_f32_e32 v1, v9, v9
	v_pk_fma_f32 v[10:11], v[10:11], s[26:27], v[2:3] op_sel_hi:[1,0,1]
	v_add_f32_e32 v0, v8, v9
	v_fmac_f32_e32 v1, v8, v8
	v_add_f32_e32 v0, v10, v0
	v_fmac_f32_e32 v1, v10, v10
	v_add_f32_e32 v0, v11, v0
	v_fmac_f32_e32 v1, v11, v11
	v_add_f32_e32 v0, v12, v0
	v_add_f32_e32 v1, v13, v1
	ds_bpermute_b32 v2, v116, v0
	ds_bpermute_b32 v3, v116, v1
	global_store_dwordx4 v[18:19], v[8:11], off offset:528
	v_cvt_pk_bf16_f32 v6, v8, v9
	v_cvt_pk_bf16_f32 v7, v10, v11
	s_waitcnt lgkmcnt(0)
	v_add_f32_e32 v0, v0, v2
	v_add_f32_e32 v1, v1, v3
	ds_bpermute_b32 v2, v117, v0
	ds_bpermute_b32 v3, v117, v1
	flat_store_dwordx4 v[36:37], v[4:7] offset:256
	s_and_saveexec_b64 s[30:31], s[2:3]
	s_cbranch_execz .LBB0_1554
	v_lshl_add_u64 v[4:5], s[10:11], 0, v[16:17]
	s_waitcnt lgkmcnt(0)
	v_add_f32_e32 v0, v0, v2
	v_add_f32_e32 v1, v1, v3
	flat_atomic_add_f32 v[4:5], v0
	flat_atomic_add_f32 v[4:5], v1 offset:4

; DEVI unsigned pk2(float lo, float hi) { unsigned r; asm("v_cvt_pk_bf16_f32 %0, %1, %2" : "=v"(r) : "v"(lo), "v"(hi)); return r; }
; DEVI void row_stats(const float* stats, int row, float& mu, float& rs) {
;     if (stats) { const float2 st = *(const float2*)(stats + 2 * (size_t)row); mu = st.x * (1.0f / 1024.0f); const float var = st.y * (1.0f / 1024.0f) - mu * mu; rs = rsqrtf(fmaxf(var, 0.f) + LN_EPS); }
;     DEVI void operator()(const f32x4 (&acc)[2][2][4][2], const pg8::Unit& u, int wr, int wc, int fr, int fq) const {
;     ...
;                 const int row = row0 + ai * 128 + m * 16; float mu, rs; row_stats(stin, row, mu, rs);
;                 float sum = 0.f, sq = 0.f;
; #pragma unroll
;                 for (int bj = 0; bj < 2; ++bj) {
;                     f32x4 z[2];
; #pragma unroll
;                     for (int n = 0; n < 2; ++n) {
;                         const int col = colb + bj * 128 + 4 * n;
;                         f32x4 xv = *(const f32x4*)(zsrc + (size_t)row * DM + col);
;                         if (stin) { const f32x4 gv = *(const f32x4*)(gin + col), bv = *(const f32x4*)(bin + col); xv = (xv - mu) * rs * gv + bv; }
;                         f32x4 zz = ALPHA * xv + acc[ai][bj][m][n];
;                         if (bias) zz += *(const f32x4*)(bias + col);
;                         *(f32x4*)(zdst + (size_t)row * DM + col) = zz;
;                         sum += zz[0] + zz[1] + zz[2] + zz[3]; sq += zz[0] * zz[0] + zz[1] * zz[1] + zz[2] * zz[2] + zz[3] * zz[3];
;                         z[n] = zz;
;                     }
;                     u32x4 o; o.x = pk2(z[0][0], z[0][1]); o.y = pk2(z[0][2], z[0][3]); o.z = pk2(z[1][0], z[1][1]); o.w = pk2(z[1][2], z[1][3]);
;                     if (zb) *(u32x4*)(zb + (size_t)row * DM + colb + bj * 128) = o;
;                 }
;                 sum += __shfl_xor(sum, 16); sq += __shfl_xor(sq, 16);
;                 sum += __shfl_xor(sum, 32); sq += __shfl_xor(sq, 32);
;                 if (fq == 0) { atomicAdd(stout + 2 * (size_t)row, sum); atomicAdd(stout + 2 * (size_t)row + 1, sq); }
.LBB0_1985:
	s_or_b64 exec, exec, s[36:37]
	v_or_b32_e32 v166, 16, v154
	v_ashrrev_i32_e32 v167, 31, v166
	v_lshlrev_b64 v[112:113], 3, v[166:167]
	s_waitcnt lgkmcnt(0)
	v_lshl_add_u64 v[114:115], s[6:7], 0, v[112:113]
	flat_load_dwordx2 v[192:193], v[114:115]
	v_lshlrev_b64 v[114:115], 12, v[166:167]
	v_lshl_add_u64 v[114:115], s[46:47], 0, v[114:115]
	v_lshl_add_u64 v[114:115], v[144:145], 2, v[114:115]
	global_load_dwordx4 v[162:165], v[114:115], off
	global_load_dwordx4 v[176:179], v[150:151], off
	global_load_dwordx4 v[180:183], v[152:153], off
	global_load_dwordx4 v[184:187], v[156:157], off
	global_load_dwordx4 v[188:191], v[114:115], off offset:16
	v_lshlrev_b64 v[166:167], 11, v[166:167]
	v_lshl_add_u64 v[166:167], s[10:11], 0, v[166:167]
	v_lshl_add_u64 v[166:167], v[144:145], 1, v[166:167]
	global_load_dwordx4 v[208:211], v[146:147], off
	global_load_dwordx4 v[212:215], v[148:149], off
	global_load_dwordx4 v[250:253], v[124:125], off
	s_waitcnt vmcnt(0) lgkmcnt(0)
	v_pk_mul_f32 v[192:193], v[192:193], s[22:23] op_sel:[1,0] op_sel_hi:[0,0]
	v_fma_f32 v155, -v193, v193, v192
	v_max_f32_e32 v155, 0, v155
	v_add_f32_e32 v155, 0x3727c5ac, v155
	v_mul_f32_e32 v175, 0x4b800000, v155
	v_cmp_gt_f32_e32 vcc, s72, v155
	v_sub_f32_e32 v165, v165, v193
	v_sub_f32_e32 v164, v164, v193
	v_cndmask_b32_e32 v155, v155, v175, vcc
	v_rsq_f32_e32 v155, v155
	v_sub_f32_e32 v163, v163, v193
	v_sub_f32_e32 v162, v162, v193
	v_mul_f32_e32 v175, 0x45800000, v155
	v_cndmask_b32_e32 v192, v155, v175, vcc
	v_pk_mul_f32 v[162:163], v[162:163], v[192:193] op_sel_hi:[1,0]
	v_pk_mul_f32 v[164:165], v[164:165], v[192:193] op_sel_hi:[1,0]
	v_pk_fma_f32 v[162:163], v[176:177], v[162:163], v[180:181]
	v_pk_fma_f32 v[164:165], v[178:179], v[164:165], v[182:183]
	v_pk_fma_f32 v[108:109], v[162:163], s[24:25], v[108:109] op_sel_hi:[1,0,1]
	v_pk_fma_f32 v[110:111], v[164:165], s[24:25], v[110:111] op_sel_hi:[1,0,1]
	v_pk_add_f32 v[108:109], v[184:185], v[108:109]
	v_pk_add_f32 v[110:111], v[186:187], v[110:111]
	global_store_dwordx4 v[114:115], v[108:111], off
	v_sub_f32_e32 v185, v191, v193
	v_sub_f32_e32 v184, v190, v193
	v_sub_f32_e32 v187, v189, v193
	v_sub_f32_e32 v186, v188, v193
	v_pk_mul_f32 v[186:187], v[186:187], v[192:193] op_sel_hi:[1,0]
	v_pk_mul_f32 v[188:189], v[184:185], v[192:193] op_sel_hi:[1,0]
	v_cvt_pk_bf16_f32 v184, v108, v109
	v_cvt_pk_bf16_f32 v185, v110, v111
	v_add_f32_e32 v155, v108, v109
	v_mul_f32_e32 v109, v109, v109
	v_fmac_f32_e32 v109, v108, v108
	v_add_f32_e32 v155, v110, v155
	v_fmac_f32_e32 v109, v110, v110
	v_add_f32_e32 v108, v111, v155
	v_add_f32_e32 v108, 0, v108
	v_fmac_f32_e32 v109, v111, v111
	v_pk_fma_f32 v[164:165], v[210:211], v[188:189], v[214:215]
	v_pk_fma_f32 v[162:163], v[208:209], v[186:187], v[212:213]
	v_pk_fma_f32 v[106:107], v[164:165], s[24:25], v[106:107] op_sel_hi:[1,0,1]
	v_pk_fma_f32 v[104:105], v[162:163], s[24:25], v[104:105] op_sel_hi:[1,0,1]
	v_pk_add_f32 v[106:107], v[252:253], v[106:107]
	v_pk_add_f32 v[104:105], v[250:251], v[104:105]
	global_store_dwordx4 v[114:115], v[104:107], off offset:16
	v_cvt_pk_bf16_f32 v186, v104, v105
	v_cvt_pk_bf16_f32 v187, v106, v107
	flat_store_dwordx4 v[166:167], v[184:187]
	global_load_dwordx4 v[162:165], v[114:115], off offset:512
	global_load_dwordx4 v[176:179], v[126:127], off
	global_load_dwordx4 v[180:183], v[158:159], off
	s_nop 0
	global_load_dwordx4 v[184:187], v[160:161], off
	global_load_dwordx4 v[188:191], v[114:115], off offset:528
	v_add_f32_e32 v110, v104, v105
	v_mul_f32_e32 v105, v105, v105
	v_fmac_f32_e32 v105, v104, v104
	v_add_f32_e32 v110, v106, v110
	v_fmac_f32_e32 v105, v106, v106
	v_add_f32_e32 v104, v107, v110
	v_fmac_f32_e32 v105, v107, v107
	v_add_f32_e32 v108, v104, v108
	v_add_f32_e32 v109, v109, v105
	global_load_dwordx4 v[208:211], v[120:121], off
	global_load_dwordx4 v[212:215], v[122:123], off
	global_load_dwordx4 v[250:253], v[116:117], off
	s_waitcnt vmcnt(0)
	v_sub_f32_e32 v165, v165, v193
	v_sub_f32_e32 v164, v164, v193
	v_sub_f32_e32 v163, v163, v193
	v_sub_f32_e32 v162, v162, v193
	v_pk_mul_f32 v[162:163], v[192:193], v[162:163] op_sel_hi:[0,1]
	v_pk_mul_f32 v[164:165], v[192:193], v[164:165] op_sel_hi:[0,1]
	v_pk_fma_f32 v[164:165], v[178:179], v[164:165], v[182:183]
	v_pk_fma_f32 v[162:163], v[176:177], v[162:163], v[180:181]
	v_pk_fma_f32 v[102:103], v[164:165], s[24:25], v[102:103] op_sel_hi:[1,0,1]
	v_pk_fma_f32 v[100:101], v[162:163], s[24:25], v[100:101] op_sel_hi:[1,0,1]
	v_pk_add_f32 v[102:103], v[186:187], v[102:103]
	v_pk_add_f32 v[100:101], v[184:185], v[100:101]
	global_store_dwordx4 v[114:115], v[100:103], off offset:512
	v_sub_f32_e32 v107, v189, v193
	v_sub_f32_e32 v106, v188, v193
	v_sub_f32_e32 v105, v191, v193
	v_sub_f32_e32 v104, v190, v193
	v_pk_mul_f32 v[106:107], v[192:193], v[106:107] op_sel_hi:[0,1]
	v_pk_mul_f32 v[104:105], v[192:193], v[104:105] op_sel_hi:[0,1]
	v_mul_f32_e32 v111, v101, v101
	v_add_f32_e32 v110, v100, v101
	v_fmac_f32_e32 v111, v100, v100
	v_add_f32_e32 v110, v102, v110
	v_fmac_f32_e32 v111, v102, v102
	v_add_f32_e32 v110, v103, v110
	v_fmac_f32_e32 v111, v103, v103
	v_add_f32_e32 v108, v108, v110
	v_add_f32_e32 v109, v109, v111
	v_cvt_pk_bf16_f32 v100, v100, v101
	v_cvt_pk_bf16_f32 v101, v102, v103
	v_pk_fma_f32 v[106:107], v[208:209], v[106:107], v[212:213]
	v_pk_fma_f32 v[104:105], v[210:211], v[104:105], v[214:215]
	v_pk_fma_f32 v[96:97], v[106:107], s[24:25], v[96:97] op_sel_hi:[1,0,1]
	v_pk_fma_f32 v[98:99], v[104:105], s[24:25], v[98:99] op_sel_hi:[1,0,1]
	v_pk_add_f32 v[104:105], v[250:251], v[96:97]
	v_pk_add_f32 v[106:107], v[252:253], v[98:99]
	v_mul_f32_e32 v97, v105, v105
	v_add_f32_e32 v96, v104, v105
	v_fmac_f32_e32 v97, v104, v104
	v_add_f32_e32 v96, v106, v96
	v_fmac_f32_e32 v97, v106, v106
	v_add_f32_e32 v96, v107, v96
	v_fmac_f32_e32 v97, v107, v107
	v_add_f32_e32 v96, v108, v96
	v_add_f32_e32 v97, v109, v97
	ds_bpermute_b32 v98, v118, v96
	ds_bpermute_b32 v99, v118, v97
	global_store_dwordx4 v[114:115], v[104:107], off offset:528
	v_cvt_pk_bf16_f32 v102, v104, v105
	v_cvt_pk_bf16_f32 v103, v106, v107
	s_waitcnt lgkmcnt(0)
	v_add_f32_e32 v96, v96, v98
	v_add_f32_e32 v97, v97, v99
	ds_bpermute_b32 v98, v119, v96
	ds_bpermute_b32 v99, v119, v97
	flat_store_dwordx4 v[166:167], v[100:103] offset:256
	s_and_saveexec_b64 s[36:37], s[2:3]
	s_cbranch_execz .LBB0_1987
	s_waitcnt lgkmcnt(0)
	v_add_f32_e32 v99, v97, v99
	v_add_f32_e32 v98, v96, v98
	v_lshl_add_u64 v[96:97], s[8:9], 0, v[112:113]
	flat_atomic_add_f32 v[96:97], v98
	flat_atomic_add_f32 v[96:97], v99 offset:4
; DEVI unsigned pk2(float lo, float hi) { unsigned r; asm("v_cvt_pk_bf16_f32 %0, %1, %2" : "=v"(r) : "v"(lo), "v"(hi)); return r; }
; DEVI void row_stats(const float* stats, int row, float& mu, float& rs) {
;     if (stats) { const float2 st = *(const float2*)(stats + 2 * (size_t)row); mu = st.x * (1.0f / 1024.0f); const float var = st.y * (1.0f / 1024.0f) - mu * mu; rs = rsqrtf(fmaxf(var, 0.f) + LN_EPS); }
;     DEVI void operator()(const f32x4 (&acc)[2][2][4][2], const pg8::Unit& u, int wr, int wc, int fr, int fq) const {
;     ...
;                 const int row = row0 + ai * 128 + m * 16; float mu, rs; row_stats(stin, row, mu, rs);
;                 float sum = 0.f, sq = 0.f;
; #pragma unroll
;                 for (int bj = 0; bj < 2; ++bj) {
;                     f32x4 z[2];
; #pragma unroll
;                     for (int n = 0; n < 2; ++n) {
;                         const int col = colb + bj * 128 + 4 * n;
;                         f32x4 xv = *(const f32x4*)(zsrc + (size_t)row * DM + col);
;                         if (stin) { const f32x4 gv = *(const f32x4*)(gin + col), bv = *(const f32x4*)(bin + col); xv = (xv - mu) * rs * gv + bv; }
;                         f32x4 zz = ALPHA * xv + acc[ai][bj][m][n];
;                         if (bias) zz += *(const f32x4*)(bias + col);
;                         *(f32x4*)(zdst + (size_t)row * DM + col) = zz;
;                         sum += zz[0] + zz[1] + zz[2] + zz[3]; sq += zz[0] * zz[0] + zz[1] * zz[1] + zz[2] * zz[2] + zz[3] * zz[3];
;                         z[n] = zz;
;                     }
;                     u32x4 o; o.x = pk2(z[0][0], z[0][1]); o.y = pk2(z[0][2], z[0][3]); o.z = pk2(z[1][0], z[1][1]); o.w = pk2(z[1][2], z[1][3]);
;                     if (zb) *(u32x4*)(zb + (size_t)row * DM + colb + bj * 128) = o;
;                 }
;                 sum += __shfl_xor(sum, 16); sq += __shfl_xor(sq, 16);
;                 sum += __shfl_xor(sum, 32); sq += __shfl_xor(sq, 32);
;                 if (fq == 0) { atomicAdd(stout + 2 * (size_t)row, sum); atomicAdd(stout + 2 * (size_t)row + 1, sq); }
.LBB0_1987:
	s_or_b64 exec, exec, s[36:37]
	v_or_b32_e32 v166, 32, v154
	v_ashrrev_i32_e32 v167, 31, v166
	v_lshlrev_b64 v[96:97], 3, v[166:167]
	s_waitcnt lgkmcnt(0)
	v_lshl_add_u64 v[98:99], s[6:7], 0, v[96:97]
	flat_load_dwordx2 v[176:177], v[98:99]
	v_lshlrev_b64 v[98:99], 12, v[166:167]
	v_lshl_add_u64 v[98:99], s[46:47], 0, v[98:99]
	v_lshl_add_u64 v[98:99], v[144:145], 2, v[98:99]
	global_load_dwordx4 v[100:103], v[98:99], off
	global_load_dwordx4 v[104:107], v[150:151], off
	global_load_dwordx4 v[108:111], v[152:153], off
	global_load_dwordx4 v[112:115], v[156:157], off
	global_load_dwordx4 v[162:165], v[98:99], off offset:16
	global_load_dwordx4 v[208:211], v[146:147], off
	global_load_dwordx4 v[212:215], v[148:149], off
	global_load_dwordx4 v[250:253], v[124:125], off
	s_waitcnt vmcnt(0) lgkmcnt(0)
	v_pk_mul_f32 v[176:177], v[176:177], s[22:23] op_sel:[1,0] op_sel_hi:[0,0]
	v_fma_f32 v155, -v177, v177, v176
	v_max_f32_e32 v155, 0, v155
	v_add_f32_e32 v155, 0x3727c5ac, v155
	v_mul_f32_e32 v175, 0x4b800000, v155
	v_cmp_gt_f32_e32 vcc, s72, v155
	v_sub_f32_e32 v103, v103, v177
	v_sub_f32_e32 v102, v102, v177
	v_cndmask_b32_e32 v155, v155, v175, vcc
	v_rsq_f32_e32 v155, v155
	v_sub_f32_e32 v101, v101, v177
	v_sub_f32_e32 v100, v100, v177
	v_mul_f32_e32 v175, 0x45800000, v155
	v_cndmask_b32_e32 v176, v155, v175, vcc
	v_pk_mul_f32 v[100:101], v[100:101], v[176:177] op_sel_hi:[1,0]
	v_pk_mul_f32 v[102:103], v[102:103], v[176:177] op_sel_hi:[1,0]
	v_pk_fma_f32 v[100:101], v[104:105], v[100:101], v[108:109]
	v_pk_fma_f32 v[102:103], v[106:107], v[102:103], v[110:111]
	v_pk_fma_f32 v[92:93], v[100:101], s[24:25], v[92:93] op_sel_hi:[1,0,1]
	v_pk_fma_f32 v[94:95], v[102:103], s[24:25], v[94:95] op_sel_hi:[1,0,1]
	v_pk_add_f32 v[92:93], v[112:113], v[92:93]
	v_pk_add_f32 v[94:95], v[114:115], v[94:95]
	global_store_dwordx4 v[98:99], v[92:95], off
	v_lshlrev_b64 v[112:113], 11, v[166:167]
	v_lshl_add_u64 v[112:113], s[10:11], 0, v[112:113]
	v_lshl_add_u64 v[166:167], v[144:145], 1, v[112:113]
	v_sub_f32_e32 v113, v165, v177
	v_sub_f32_e32 v112, v164, v177
	v_sub_f32_e32 v115, v163, v177
	v_sub_f32_e32 v114, v162, v177
	v_pk_mul_f32 v[114:115], v[114:115], v[176:177] op_sel_hi:[1,0]
	v_pk_mul_f32 v[162:163], v[112:113], v[176:177] op_sel_hi:[1,0]
	v_cvt_pk_bf16_f32 v112, v92, v93
	v_cvt_pk_bf16_f32 v113, v94, v95
	v_pk_fma_f32 v[100:101], v[208:209], v[114:115], v[212:213]
	v_pk_fma_f32 v[102:103], v[210:211], v[162:163], v[214:215]
	v_pk_fma_f32 v[88:89], v[100:101], s[24:25], v[88:89] op_sel_hi:[1,0,1]
	v_pk_fma_f32 v[90:91], v[102:103], s[24:25], v[90:91] op_sel_hi:[1,0,1]
	v_pk_add_f32 v[88:89], v[250:251], v[88:89]
	v_pk_add_f32 v[90:91], v[252:253], v[90:91]
	global_store_dwordx4 v[98:99], v[88:91], off offset:16
	v_cvt_pk_bf16_f32 v114, v88, v89
	v_cvt_pk_bf16_f32 v115, v90, v91
	flat_store_dwordx4 v[166:167], v[112:115]
	global_load_dwordx4 v[100:103], v[98:99], off offset:512
	global_load_dwordx4 v[104:107], v[126:127], off
	global_load_dwordx4 v[108:111], v[158:159], off
	s_nop 0
	global_load_dwordx4 v[112:115], v[160:161], off
	global_load_dwordx4 v[162:165], v[98:99], off offset:528
	global_load_dwordx4 v[208:211], v[120:121], off
	global_load_dwordx4 v[212:215], v[122:123], off
	global_load_dwordx4 v[250:253], v[116:117], off
	s_waitcnt vmcnt(0)
	v_sub_f32_e32 v103, v103, v177
	v_sub_f32_e32 v102, v102, v177
	v_sub_f32_e32 v101, v101, v177
	v_sub_f32_e32 v100, v100, v177
	v_pk_mul_f32 v[100:101], v[176:177], v[100:101] op_sel_hi:[0,1]
	v_pk_mul_f32 v[102:103], v[176:177], v[102:103] op_sel_hi:[0,1]
	v_pk_fma_f32 v[102:103], v[106:107], v[102:103], v[110:111]
	v_pk_fma_f32 v[100:101], v[104:105], v[100:101], v[108:109]
	v_pk_fma_f32 v[86:87], v[102:103], s[24:25], v[86:87] op_sel_hi:[1,0,1]
	v_pk_fma_f32 v[84:85], v[100:101], s[24:25], v[84:85] op_sel_hi:[1,0,1]
	v_pk_add_f32 v[86:87], v[114:115], v[86:87]
	v_pk_add_f32 v[84:85], v[112:113], v[84:85]
	global_store_dwordx4 v[98:99], v[84:87], off offset:512
	v_add_f32_e32 v112, v92, v93
	v_mul_f32_e32 v93, v93, v93
	v_fmac_f32_e32 v93, v92, v92
	v_add_f32_e32 v112, v94, v112
	v_fmac_f32_e32 v93, v94, v94
	v_add_f32_e32 v94, v88, v89
	v_mul_f32_e32 v89, v89, v89
	v_fmac_f32_e32 v89, v88, v88
	v_add_f32_e32 v92, v95, v112
	v_add_f32_e32 v94, v90, v94
	v_fmac_f32_e32 v89, v90, v90
	v_add_f32_e32 v92, 0, v92
	v_fmac_f32_e32 v93, v95, v95
	v_add_f32_e32 v88, v91, v94
	v_fmac_f32_e32 v89, v91, v91
	v_sub_f32_e32 v91, v163, v177
	v_sub_f32_e32 v90, v162, v177
	v_add_f32_e32 v92, v88, v92
	v_add_f32_e32 v93, v93, v89
	v_sub_f32_e32 v89, v165, v177
	v_sub_f32_e32 v88, v164, v177
	v_pk_mul_f32 v[90:91], v[176:177], v[90:91] op_sel_hi:[0,1]
	v_pk_mul_f32 v[88:89], v[176:177], v[88:89] op_sel_hi:[0,1]
	v_mul_f32_e32 v95, v85, v85
	v_add_f32_e32 v94, v84, v85
	v_fmac_f32_e32 v95, v84, v84
	v_add_f32_e32 v94, v86, v94
	v_fmac_f32_e32 v95, v86, v86
	v_add_f32_e32 v94, v87, v94
	v_fmac_f32_e32 v95, v87, v87
	v_add_f32_e32 v92, v92, v94
	v_add_f32_e32 v93, v93, v95
	v_cvt_pk_bf16_f32 v84, v84, v85
	v_cvt_pk_bf16_f32 v85, v86, v87
	v_pk_fma_f32 v[90:91], v[208:209], v[90:91], v[212:213]
	v_pk_fma_f32 v[88:89], v[210:211], v[88:89], v[214:215]
	v_pk_fma_f32 v[80:81], v[90:91], s[24:25], v[80:81] op_sel_hi:[1,0,1]
	v_pk_fma_f32 v[82:83], v[88:89], s[24:25], v[82:83] op_sel_hi:[1,0,1]
	v_pk_add_f32 v[88:89], v[250:251], v[80:81]
	v_pk_add_f32 v[90:91], v[252:253], v[82:83]
	v_mul_f32_e32 v81, v89, v89
	v_add_f32_e32 v80, v88, v89
	v_fmac_f32_e32 v81, v88, v88
	v_add_f32_e32 v80, v90, v80
	v_fmac_f32_e32 v81, v90, v90
	v_add_f32_e32 v80, v91, v80
	v_fmac_f32_e32 v81, v91, v91
	v_add_f32_e32 v80, v92, v80
	v_add_f32_e32 v81, v93, v81
	ds_bpermute_b32 v82, v118, v80
	ds_bpermute_b32 v83, v118, v81
	global_store_dwordx4 v[98:99], v[88:91], off offset:528
	v_cvt_pk_bf16_f32 v86, v88, v89
	v_cvt_pk_bf16_f32 v87, v90, v91
	s_waitcnt lgkmcnt(0)
	v_add_f32_e32 v80, v80, v82
	v_add_f32_e32 v81, v81, v83
	ds_bpermute_b32 v82, v119, v80
	ds_bpermute_b32 v83, v119, v81
	flat_store_dwordx4 v[166:167], v[84:87] offset:256
	s_and_saveexec_b64 s[36:37], s[2:3]
	s_cbranch_execz .LBB0_1989
	s_waitcnt lgkmcnt(0)
	v_add_f32_e32 v83, v81, v83
	v_add_f32_e32 v82, v80, v82
	v_lshl_add_u64 v[80:81], s[8:9], 0, v[96:97]
	flat_atomic_add_f32 v[80:81], v82
	flat_atomic_add_f32 v[80:81], v83 offset:4
; DEVI unsigned pk2(float lo, float hi) { unsigned r; asm("v_cvt_pk_bf16_f32 %0, %1, %2" : "=v"(r) : "v"(lo), "v"(hi)); return r; }
; DEVI void row_stats(const float* stats, int row, float& mu, float& rs) {
;     if (stats) { const float2 st = *(const float2*)(stats + 2 * (size_t)row); mu = st.x * (1.0f / 1024.0f); const float var = st.y * (1.0f / 1024.0f) - mu * mu; rs = rsqrtf(fmaxf(var, 0.f) + LN_EPS); }
;     DEVI void operator()(const f32x4 (&acc)[2][2][4][2], const pg8::Unit& u, int wr, int wc, int fr, int fq) const {
;     ...
;                 const int row = row0 + ai * 128 + m * 16; float mu, rs; row_stats(stin, row, mu, rs);
;                 float sum = 0.f, sq = 0.f;
; #pragma unroll
;                 for (int bj = 0; bj < 2; ++bj) {
;                     f32x4 z[2];
; #pragma unroll
;                     for (int n = 0; n < 2; ++n) {
;                         const int col = colb + bj * 128 + 4 * n;
;                         f32x4 xv = *(const f32x4*)(zsrc + (size_t)row * DM + col);
;                         if (stin) { const f32x4 gv = *(const f32x4*)(gin + col), bv = *(const f32x4*)(bin + col); xv = (xv - mu) * rs * gv + bv; }
;                         f32x4 zz = ALPHA * xv + acc[ai][bj][m][n];
;                         if (bias) zz += *(const f32x4*)(bias + col);
;                         *(f32x4*)(zdst + (size_t)row * DM + col) = zz;
;                         sum += zz[0] + zz[1] + zz[2] + zz[3]; sq += zz[0] * zz[0] + zz[1] * zz[1] + zz[2] * zz[2] + zz[3] * zz[3];
;                         z[n] = zz;
;                     }
;                     u32x4 o; o.x = pk2(z[0][0], z[0][1]); o.y = pk2(z[0][2], z[0][3]); o.z = pk2(z[1][0], z[1][1]); o.w = pk2(z[1][2], z[1][3]);
;                     if (zb) *(u32x4*)(zb + (size_t)row * DM + colb + bj * 128) = o;
;                 }
;                 sum += __shfl_xor(sum, 16); sq += __shfl_xor(sq, 16);
;                 sum += __shfl_xor(sum, 32); sq += __shfl_xor(sq, 32);
;                 if (fq == 0) { atomicAdd(stout + 2 * (size_t)row, sum); atomicAdd(stout + 2 * (size_t)row + 1, sq); }
.LBB0_1989:
	s_or_b64 exec, exec, s[36:37]
	v_or_b32_e32 v104, 48, v154
	v_ashrrev_i32_e32 v105, 31, v104
	v_lshlrev_b64 v[80:81], 3, v[104:105]
	s_waitcnt lgkmcnt(0)
	v_lshl_add_u64 v[82:83], s[6:7], 0, v[80:81]
	flat_load_dwordx2 v[106:107], v[82:83]
	v_lshlrev_b64 v[82:83], 12, v[104:105]
	v_lshl_add_u64 v[82:83], s[46:47], 0, v[82:83]
	v_lshl_add_u64 v[82:83], v[144:145], 2, v[82:83]
	global_load_dwordx4 v[84:87], v[82:83], off
	global_load_dwordx4 v[88:91], v[150:151], off
	global_load_dwordx4 v[92:95], v[152:153], off
	global_load_dwordx4 v[96:99], v[156:157], off
	global_load_dwordx4 v[100:103], v[82:83], off offset:16
	global_load_dwordx4 v[208:211], v[146:147], off
	global_load_dwordx4 v[212:215], v[148:149], off
	global_load_dwordx4 v[250:253], v[124:125], off
	s_waitcnt vmcnt(0) lgkmcnt(0)
	v_pk_mul_f32 v[106:107], v[106:107], s[22:23] op_sel:[1,0] op_sel_hi:[0,0]
	v_fma_f32 v106, -v107, v107, v106
	v_max_f32_e32 v106, 0, v106
	v_add_f32_e32 v106, 0x3727c5ac, v106
	v_mul_f32_e32 v108, 0x4b800000, v106
	v_cmp_gt_f32_e32 vcc, s72, v106
	v_sub_f32_e32 v87, v87, v107
	v_sub_f32_e32 v86, v86, v107
	v_cndmask_b32_e32 v106, v106, v108, vcc
	v_rsq_f32_e32 v106, v106
	v_sub_f32_e32 v85, v85, v107
	v_sub_f32_e32 v84, v84, v107
	v_mul_f32_e32 v108, 0x45800000, v106
	v_cndmask_b32_e32 v106, v106, v108, vcc
	v_pk_mul_f32 v[84:85], v[84:85], v[106:107] op_sel_hi:[1,0]
	v_pk_mul_f32 v[86:87], v[86:87], v[106:107] op_sel_hi:[1,0]
	v_pk_fma_f32 v[84:85], v[88:89], v[84:85], v[92:93]
	v_pk_fma_f32 v[86:87], v[90:91], v[86:87], v[94:95]
	v_pk_fma_f32 v[76:77], v[84:85], s[24:25], v[76:77] op_sel_hi:[1,0,1]
	v_pk_fma_f32 v[78:79], v[86:87], s[24:25], v[78:79] op_sel_hi:[1,0,1]
	v_pk_add_f32 v[76:77], v[96:97], v[76:77]
	v_pk_add_f32 v[78:79], v[98:99], v[78:79]
	global_store_dwordx4 v[82:83], v[76:79], off
	v_lshlrev_b64 v[96:97], 11, v[104:105]
	v_lshl_add_u64 v[96:97], s[10:11], 0, v[96:97]
	v_lshl_add_u64 v[104:105], v[144:145], 1, v[96:97]
	v_sub_f32_e32 v97, v103, v107
	v_sub_f32_e32 v96, v102, v107
	v_sub_f32_e32 v99, v101, v107
	v_sub_f32_e32 v98, v100, v107
	v_pk_mul_f32 v[98:99], v[98:99], v[106:107] op_sel_hi:[1,0]
	v_pk_mul_f32 v[100:101], v[96:97], v[106:107] op_sel_hi:[1,0]
	v_cvt_pk_bf16_f32 v96, v76, v77
	v_cvt_pk_bf16_f32 v97, v78, v79
	v_pk_fma_f32 v[84:85], v[208:209], v[98:99], v[212:213]
	v_pk_fma_f32 v[86:87], v[210:211], v[100:101], v[214:215]
	v_pk_fma_f32 v[72:73], v[84:85], s[24:25], v[72:73] op_sel_hi:[1,0,1]
	v_pk_fma_f32 v[74:75], v[86:87], s[24:25], v[74:75] op_sel_hi:[1,0,1]
	v_pk_add_f32 v[72:73], v[250:251], v[72:73]
	v_pk_add_f32 v[74:75], v[252:253], v[74:75]
	global_store_dwordx4 v[82:83], v[72:75], off offset:16
	v_cvt_pk_bf16_f32 v98, v72, v73
	v_cvt_pk_bf16_f32 v99, v74, v75
	flat_store_dwordx4 v[104:105], v[96:99]
	global_load_dwordx4 v[84:87], v[82:83], off offset:512
	global_load_dwordx4 v[88:91], v[126:127], off
	global_load_dwordx4 v[92:95], v[158:159], off
	s_nop 0
	global_load_dwordx4 v[96:99], v[160:161], off
	global_load_dwordx4 v[100:103], v[82:83], off offset:528
	global_load_dwordx4 v[208:211], v[120:121], off
	global_load_dwordx4 v[212:215], v[122:123], off
	global_load_dwordx4 v[250:253], v[116:117], off
	s_waitcnt vmcnt(0)
	v_sub_f32_e32 v87, v87, v107
	v_sub_f32_e32 v86, v86, v107
	v_sub_f32_e32 v85, v85, v107
	v_sub_f32_e32 v84, v84, v107
	v_pk_mul_f32 v[84:85], v[106:107], v[84:85] op_sel_hi:[0,1]
	v_pk_mul_f32 v[86:87], v[106:107], v[86:87] op_sel_hi:[0,1]
	v_pk_fma_f32 v[86:87], v[90:91], v[86:87], v[94:95]
	v_pk_fma_f32 v[84:85], v[88:89], v[84:85], v[92:93]
	v_pk_fma_f32 v[70:71], v[86:87], s[24:25], v[70:71] op_sel_hi:[1,0,1]
	v_pk_fma_f32 v[68:69], v[84:85], s[24:25], v[68:69] op_sel_hi:[1,0,1]
	v_pk_add_f32 v[70:71], v[98:99], v[70:71]
	v_pk_add_f32 v[68:69], v[96:97], v[68:69]
	global_store_dwordx4 v[82:83], v[68:71], off offset:512
	v_add_f32_e32 v96, v76, v77
	v_mul_f32_e32 v77, v77, v77
	v_fmac_f32_e32 v77, v76, v76
	v_add_f32_e32 v96, v78, v96
	v_fmac_f32_e32 v77, v78, v78
	v_add_f32_e32 v78, v72, v73
	v_mul_f32_e32 v73, v73, v73
	v_fmac_f32_e32 v73, v72, v72
	v_add_f32_e32 v76, v79, v96
	v_add_f32_e32 v78, v74, v78
	v_fmac_f32_e32 v73, v74, v74
	v_add_f32_e32 v76, 0, v76
	v_fmac_f32_e32 v77, v79, v79
	v_add_f32_e32 v72, v75, v78
	v_fmac_f32_e32 v73, v75, v75
	v_sub_f32_e32 v75, v101, v107
	v_sub_f32_e32 v74, v100, v107
	v_add_f32_e32 v76, v72, v76
	v_add_f32_e32 v77, v77, v73
	v_sub_f32_e32 v73, v103, v107
	v_sub_f32_e32 v72, v102, v107
	v_pk_mul_f32 v[74:75], v[106:107], v[74:75] op_sel_hi:[0,1]
	v_pk_mul_f32 v[72:73], v[106:107], v[72:73] op_sel_hi:[0,1]
	v_mul_f32_e32 v79, v69, v69
	v_add_f32_e32 v78, v68, v69
	v_fmac_f32_e32 v79, v68, v68
	v_add_f32_e32 v78, v70, v78
	v_fmac_f32_e32 v79, v70, v70
	v_add_f32_e32 v78, v71, v78
	v_fmac_f32_e32 v79, v71, v71
	v_add_f32_e32 v76, v76, v78
	v_add_f32_e32 v77, v77, v79
	v_cvt_pk_bf16_f32 v68, v68, v69
	v_cvt_pk_bf16_f32 v69, v70, v71
	v_pk_fma_f32 v[74:75], v[208:209], v[74:75], v[212:213]
	v_pk_fma_f32 v[72:73], v[210:211], v[72:73], v[214:215]
	v_pk_fma_f32 v[64:65], v[74:75], s[24:25], v[64:65] op_sel_hi:[1,0,1]
	v_pk_fma_f32 v[66:67], v[72:73], s[24:25], v[66:67] op_sel_hi:[1,0,1]
	v_pk_add_f32 v[72:73], v[250:251], v[64:65]
	v_pk_add_f32 v[74:75], v[252:253], v[66:67]
	v_mul_f32_e32 v65, v73, v73
	v_add_f32_e32 v64, v72, v73
	v_fmac_f32_e32 v65, v72, v72
	v_add_f32_e32 v64, v74, v64
	v_fmac_f32_e32 v65, v74, v74
	v_add_f32_e32 v64, v75, v64
	v_fmac_f32_e32 v65, v75, v75
	v_add_f32_e32 v64, v76, v64
	v_add_f32_e32 v65, v77, v65
	ds_bpermute_b32 v66, v118, v64
	ds_bpermute_b32 v67, v118, v65
	global_store_dwordx4 v[82:83], v[72:75], off offset:528
	v_cvt_pk_bf16_f32 v70, v72, v73
	v_cvt_pk_bf16_f32 v71, v74, v75
	s_waitcnt lgkmcnt(0)
	v_add_f32_e32 v64, v64, v66
	v_add_f32_e32 v65, v65, v67
	ds_bpermute_b32 v66, v119, v64
	ds_bpermute_b32 v67, v119, v65
	flat_store_dwordx4 v[104:105], v[68:71] offset:256
	s_and_saveexec_b64 s[36:37], s[2:3]
	s_cbranch_execz .LBB0_1991
	s_waitcnt lgkmcnt(0)
	v_add_f32_e32 v67, v65, v67
	v_add_f32_e32 v66, v64, v66
	v_lshl_add_u64 v[64:65], s[8:9], 0, v[80:81]
	flat_atomic_add_f32 v[64:65], v66
	flat_atomic_add_f32 v[64:65], v67 offset:4
; DEVI unsigned pk2(float lo, float hi) { unsigned r; asm("v_cvt_pk_bf16_f32 %0, %1, %2" : "=v"(r) : "v"(lo), "v"(hi)); return r; }
; DEVI void row_stats(const float* stats, int row, float& mu, float& rs) {
;     if (stats) { const float2 st = *(const float2*)(stats + 2 * (size_t)row); mu = st.x * (1.0f / 1024.0f); const float var = st.y * (1.0f / 1024.0f) - mu * mu; rs = rsqrtf(fmaxf(var, 0.f) + LN_EPS); }
;     DEVI void operator()(const f32x4 (&acc)[2][2][4][2], const pg8::Unit& u, int wr, int wc, int fr, int fq) const {
;     ...
;                 const int row = row0 + ai * 128 + m * 16; float mu, rs; row_stats(stin, row, mu, rs);
;                 float sum = 0.f, sq = 0.f;
; #pragma unroll
;                 for (int bj = 0; bj < 2; ++bj) {
;                     f32x4 z[2];
; #pragma unroll
;                     for (int n = 0; n < 2; ++n) {
;                         const int col = colb + bj * 128 + 4 * n;
;                         f32x4 xv = *(const f32x4*)(zsrc + (size_t)row * DM + col);
;                         if (stin) { const f32x4 gv = *(const f32x4*)(gin + col), bv = *(const f32x4*)(bin + col); xv = (xv - mu) * rs * gv + bv; }
;                         f32x4 zz = ALPHA * xv + acc[ai][bj][m][n];
;                         if (bias) zz += *(const f32x4*)(bias + col);
;                         *(f32x4*)(zdst + (size_t)row * DM + col) = zz;
;                         sum += zz[0] + zz[1] + zz[2] + zz[3]; sq += zz[0] * zz[0] + zz[1] * zz[1] + zz[2] * zz[2] + zz[3] * zz[3];
;                         z[n] = zz;
;                     }
;                     u32x4 o; o.x = pk2(z[0][0], z[0][1]); o.y = pk2(z[0][2], z[0][3]); o.z = pk2(z[1][0], z[1][1]); o.w = pk2(z[1][2], z[1][3]);
;                     if (zb) *(u32x4*)(zb + (size_t)row * DM + colb + bj * 128) = o;
;                 }
;                 sum += __shfl_xor(sum, 16); sq += __shfl_xor(sq, 16);
;                 sum += __shfl_xor(sum, 32); sq += __shfl_xor(sq, 32);
;                 if (fq == 0) { atomicAdd(stout + 2 * (size_t)row, sum); atomicAdd(stout + 2 * (size_t)row + 1, sq); }
.LBB0_1991:
	s_or_b64 exec, exec, s[36:37]
	v_add_u32_e32 v88, 0x80, v154
	v_ashrrev_i32_e32 v89, 31, v88
	v_lshlrev_b64 v[64:65], 3, v[88:89]
	s_waitcnt lgkmcnt(0)
	v_lshl_add_u64 v[66:67], s[6:7], 0, v[64:65]
	flat_load_dwordx2 v[90:91], v[66:67]
	v_lshlrev_b64 v[66:67], 12, v[88:89]
	v_lshl_add_u64 v[66:67], s[46:47], 0, v[66:67]
	v_lshl_add_u64 v[66:67], v[144:145], 2, v[66:67]
	global_load_dwordx4 v[68:71], v[66:67], off
	global_load_dwordx4 v[72:75], v[150:151], off
	global_load_dwordx4 v[76:79], v[152:153], off
	global_load_dwordx4 v[80:83], v[156:157], off
	global_load_dwordx4 v[84:87], v[66:67], off offset:16
	global_load_dwordx4 v[208:211], v[146:147], off
	global_load_dwordx4 v[212:215], v[148:149], off
	global_load_dwordx4 v[250:253], v[124:125], off
	s_waitcnt vmcnt(0) lgkmcnt(0)
	v_pk_mul_f32 v[90:91], v[90:91], s[22:23] op_sel:[1,0] op_sel_hi:[0,0]
	v_fma_f32 v90, -v91, v91, v90
	v_max_f32_e32 v90, 0, v90
	v_add_f32_e32 v90, 0x3727c5ac, v90
	v_mul_f32_e32 v92, 0x4b800000, v90
	v_cmp_gt_f32_e32 vcc, s72, v90
	v_sub_f32_e32 v71, v71, v91
	v_sub_f32_e32 v70, v70, v91
	v_cndmask_b32_e32 v90, v90, v92, vcc
	v_rsq_f32_e32 v90, v90
	v_sub_f32_e32 v69, v69, v91
	v_sub_f32_e32 v68, v68, v91
	v_mul_f32_e32 v92, 0x45800000, v90
	v_cndmask_b32_e32 v90, v90, v92, vcc
	v_pk_mul_f32 v[68:69], v[68:69], v[90:91] op_sel_hi:[1,0]
	v_pk_mul_f32 v[70:71], v[70:71], v[90:91] op_sel_hi:[1,0]
	v_pk_fma_f32 v[68:69], v[72:73], v[68:69], v[76:77]
	v_pk_fma_f32 v[70:71], v[74:75], v[70:71], v[78:79]
	v_pk_fma_f32 v[60:61], v[68:69], s[24:25], v[60:61] op_sel_hi:[1,0,1]
	v_pk_fma_f32 v[62:63], v[70:71], s[24:25], v[62:63] op_sel_hi:[1,0,1]
	v_pk_add_f32 v[60:61], v[80:81], v[60:61]
	v_pk_add_f32 v[62:63], v[82:83], v[62:63]
	global_store_dwordx4 v[66:67], v[60:63], off
	v_lshlrev_b64 v[80:81], 11, v[88:89]
	v_lshl_add_u64 v[80:81], s[10:11], 0, v[80:81]
	v_lshl_add_u64 v[88:89], v[144:145], 1, v[80:81]
	v_sub_f32_e32 v81, v87, v91
	v_sub_f32_e32 v80, v86, v91
	v_sub_f32_e32 v83, v85, v91
	v_sub_f32_e32 v82, v84, v91
	v_pk_mul_f32 v[82:83], v[82:83], v[90:91] op_sel_hi:[1,0]
	v_pk_mul_f32 v[84:85], v[80:81], v[90:91] op_sel_hi:[1,0]
	v_cvt_pk_bf16_f32 v80, v60, v61
	v_cvt_pk_bf16_f32 v81, v62, v63
	v_pk_fma_f32 v[68:69], v[208:209], v[82:83], v[212:213]
	v_pk_fma_f32 v[70:71], v[210:211], v[84:85], v[214:215]
	v_pk_fma_f32 v[56:57], v[68:69], s[24:25], v[56:57] op_sel_hi:[1,0,1]
	v_pk_fma_f32 v[58:59], v[70:71], s[24:25], v[58:59] op_sel_hi:[1,0,1]
	v_pk_add_f32 v[56:57], v[250:251], v[56:57]
	v_pk_add_f32 v[58:59], v[252:253], v[58:59]
	global_store_dwordx4 v[66:67], v[56:59], off offset:16
	v_cvt_pk_bf16_f32 v82, v56, v57
	v_cvt_pk_bf16_f32 v83, v58, v59
	flat_store_dwordx4 v[88:89], v[80:83]
	global_load_dwordx4 v[68:71], v[66:67], off offset:512
	global_load_dwordx4 v[72:75], v[126:127], off
	global_load_dwordx4 v[76:79], v[158:159], off
	s_nop 0
	global_load_dwordx4 v[80:83], v[160:161], off
	global_load_dwordx4 v[84:87], v[66:67], off offset:528
	global_load_dwordx4 v[208:211], v[120:121], off
	global_load_dwordx4 v[212:215], v[122:123], off
	global_load_dwordx4 v[250:253], v[116:117], off
	s_waitcnt vmcnt(0)
	v_sub_f32_e32 v71, v71, v91
	v_sub_f32_e32 v70, v70, v91
	v_sub_f32_e32 v69, v69, v91
	v_sub_f32_e32 v68, v68, v91
	v_pk_mul_f32 v[68:69], v[90:91], v[68:69] op_sel_hi:[0,1]
	v_pk_mul_f32 v[70:71], v[90:91], v[70:71] op_sel_hi:[0,1]
	v_pk_fma_f32 v[70:71], v[74:75], v[70:71], v[78:79]
	v_pk_fma_f32 v[68:69], v[72:73], v[68:69], v[76:77]
	v_pk_fma_f32 v[54:55], v[70:71], s[24:25], v[54:55] op_sel_hi:[1,0,1]
	v_pk_fma_f32 v[52:53], v[68:69], s[24:25], v[52:53] op_sel_hi:[1,0,1]
	v_pk_add_f32 v[54:55], v[82:83], v[54:55]
	v_pk_add_f32 v[52:53], v[80:81], v[52:53]
	global_store_dwordx4 v[66:67], v[52:55], off offset:512
	v_add_f32_e32 v80, v60, v61
	v_mul_f32_e32 v61, v61, v61
	v_fmac_f32_e32 v61, v60, v60
	v_add_f32_e32 v80, v62, v80
	v_fmac_f32_e32 v61, v62, v62
	v_add_f32_e32 v62, v56, v57
	v_mul_f32_e32 v57, v57, v57
	v_fmac_f32_e32 v57, v56, v56
	v_add_f32_e32 v60, v63, v80
	v_add_f32_e32 v62, v58, v62
	v_fmac_f32_e32 v57, v58, v58
	v_add_f32_e32 v60, 0, v60
	v_fmac_f32_e32 v61, v63, v63
	v_add_f32_e32 v56, v59, v62
	v_fmac_f32_e32 v57, v59, v59
	v_sub_f32_e32 v59, v85, v91
	v_sub_f32_e32 v58, v84, v91
	v_add_f32_e32 v60, v56, v60
	v_add_f32_e32 v61, v61, v57
	v_sub_f32_e32 v57, v87, v91
	v_sub_f32_e32 v56, v86, v91
	v_pk_mul_f32 v[58:59], v[90:91], v[58:59] op_sel_hi:[0,1]
	v_pk_mul_f32 v[56:57], v[90:91], v[56:57] op_sel_hi:[0,1]
	v_mul_f32_e32 v63, v53, v53
	v_add_f32_e32 v62, v52, v53
	v_fmac_f32_e32 v63, v52, v52
	v_add_f32_e32 v62, v54, v62
	v_fmac_f32_e32 v63, v54, v54
	v_add_f32_e32 v62, v55, v62
	v_fmac_f32_e32 v63, v55, v55
	v_add_f32_e32 v60, v60, v62
	v_add_f32_e32 v61, v61, v63
	v_cvt_pk_bf16_f32 v52, v52, v53
	v_cvt_pk_bf16_f32 v53, v54, v55
	v_pk_fma_f32 v[58:59], v[208:209], v[58:59], v[212:213]
	v_pk_fma_f32 v[56:57], v[210:211], v[56:57], v[214:215]
	v_pk_fma_f32 v[48:49], v[58:59], s[24:25], v[48:49] op_sel_hi:[1,0,1]
	v_pk_fma_f32 v[50:51], v[56:57], s[24:25], v[50:51] op_sel_hi:[1,0,1]
	v_pk_add_f32 v[56:57], v[250:251], v[48:49]
	v_pk_add_f32 v[58:59], v[252:253], v[50:51]
	v_mul_f32_e32 v49, v57, v57
	v_add_f32_e32 v48, v56, v57
	v_fmac_f32_e32 v49, v56, v56
	v_add_f32_e32 v48, v58, v48
	v_fmac_f32_e32 v49, v58, v58
	v_add_f32_e32 v48, v59, v48
	v_fmac_f32_e32 v49, v59, v59
	v_add_f32_e32 v48, v60, v48
	v_add_f32_e32 v49, v61, v49
	ds_bpermute_b32 v50, v118, v48
	ds_bpermute_b32 v51, v118, v49
	global_store_dwordx4 v[66:67], v[56:59], off offset:528
	v_cvt_pk_bf16_f32 v54, v56, v57
	v_cvt_pk_bf16_f32 v55, v58, v59
	s_waitcnt lgkmcnt(0)
	v_add_f32_e32 v48, v48, v50
	v_add_f32_e32 v49, v49, v51
	ds_bpermute_b32 v50, v119, v48
	ds_bpermute_b32 v51, v119, v49
	flat_store_dwordx4 v[88:89], v[52:55] offset:256
	s_and_saveexec_b64 s[36:37], s[2:3]
	s_cbranch_execz .LBB0_1993
	s_waitcnt lgkmcnt(0)
	v_add_f32_e32 v51, v49, v51
	v_add_f32_e32 v50, v48, v50
	v_lshl_add_u64 v[48:49], s[8:9], 0, v[64:65]
	flat_atomic_add_f32 v[48:49], v50
	flat_atomic_add_f32 v[48:49], v51 offset:4
; DEVI unsigned pk2(float lo, float hi) { unsigned r; asm("v_cvt_pk_bf16_f32 %0, %1, %2" : "=v"(r) : "v"(lo), "v"(hi)); return r; }
; DEVI void row_stats(const float* stats, int row, float& mu, float& rs) {
;     if (stats) { const float2 st = *(const float2*)(stats + 2 * (size_t)row); mu = st.x * (1.0f / 1024.0f); const float var = st.y * (1.0f / 1024.0f) - mu * mu; rs = rsqrtf(fmaxf(var, 0.f) + LN_EPS); }
;     DEVI void operator()(const f32x4 (&acc)[2][2][4][2], const pg8::Unit& u, int wr, int wc, int fr, int fq) const {
;     ...
;                 const int row = row0 + ai * 128 + m * 16; float mu, rs; row_stats(stin, row, mu, rs);
;                 float sum = 0.f, sq = 0.f;
; #pragma unroll
;                 for (int bj = 0; bj < 2; ++bj) {
;                     f32x4 z[2];
; #pragma unroll
;                     for (int n = 0; n < 2; ++n) {
;                         const int col = colb + bj * 128 + 4 * n;
;                         f32x4 xv = *(const f32x4*)(zsrc + (size_t)row * DM + col);
;                         if (stin) { const f32x4 gv = *(const f32x4*)(gin + col), bv = *(const f32x4*)(bin + col); xv = (xv - mu) * rs * gv + bv; }
;                         f32x4 zz = ALPHA * xv + acc[ai][bj][m][n];
;                         if (bias) zz += *(const f32x4*)(bias + col);
;                         *(f32x4*)(zdst + (size_t)row * DM + col) = zz;
;                         sum += zz[0] + zz[1] + zz[2] + zz[3]; sq += zz[0] * zz[0] + zz[1] * zz[1] + zz[2] * zz[2] + zz[3] * zz[3];
;                         z[n] = zz;
;                     }
;                     u32x4 o; o.x = pk2(z[0][0], z[0][1]); o.y = pk2(z[0][2], z[0][3]); o.z = pk2(z[1][0], z[1][1]); o.w = pk2(z[1][2], z[1][3]);
;                     if (zb) *(u32x4*)(zb + (size_t)row * DM + colb + bj * 128) = o;
;                 }
;                 sum += __shfl_xor(sum, 16); sq += __shfl_xor(sq, 16);
;                 sum += __shfl_xor(sum, 32); sq += __shfl_xor(sq, 32);
;                 if (fq == 0) { atomicAdd(stout + 2 * (size_t)row, sum); atomicAdd(stout + 2 * (size_t)row + 1, sq); }
.LBB0_1993:
	s_or_b64 exec, exec, s[36:37]
	v_add_u32_e32 v72, 0x90, v154
	v_ashrrev_i32_e32 v73, 31, v72
	v_lshlrev_b64 v[48:49], 3, v[72:73]
	s_waitcnt lgkmcnt(0)
	v_lshl_add_u64 v[50:51], s[6:7], 0, v[48:49]
	flat_load_dwordx2 v[74:75], v[50:51]
	v_lshlrev_b64 v[50:51], 12, v[72:73]
	v_lshl_add_u64 v[50:51], s[46:47], 0, v[50:51]
	v_lshl_add_u64 v[50:51], v[144:145], 2, v[50:51]
	global_load_dwordx4 v[52:55], v[50:51], off
	global_load_dwordx4 v[56:59], v[150:151], off
	global_load_dwordx4 v[60:63], v[152:153], off
	global_load_dwordx4 v[64:67], v[156:157], off
	global_load_dwordx4 v[68:71], v[50:51], off offset:16
	global_load_dwordx4 v[208:211], v[146:147], off
	global_load_dwordx4 v[212:215], v[148:149], off
	global_load_dwordx4 v[250:253], v[124:125], off
	s_waitcnt vmcnt(0) lgkmcnt(0)
	v_pk_mul_f32 v[74:75], v[74:75], s[22:23] op_sel:[1,0] op_sel_hi:[0,0]
	v_fma_f32 v74, -v75, v75, v74
	v_max_f32_e32 v74, 0, v74
	v_add_f32_e32 v74, 0x3727c5ac, v74
	v_mul_f32_e32 v76, 0x4b800000, v74
	v_cmp_gt_f32_e32 vcc, s72, v74
	v_sub_f32_e32 v55, v55, v75
	v_sub_f32_e32 v54, v54, v75
	v_cndmask_b32_e32 v74, v74, v76, vcc
	v_rsq_f32_e32 v74, v74
	v_sub_f32_e32 v53, v53, v75
	v_sub_f32_e32 v52, v52, v75
	v_mul_f32_e32 v76, 0x45800000, v74
	v_cndmask_b32_e32 v74, v74, v76, vcc
	v_pk_mul_f32 v[52:53], v[52:53], v[74:75] op_sel_hi:[1,0]
	v_pk_mul_f32 v[54:55], v[54:55], v[74:75] op_sel_hi:[1,0]
	v_pk_fma_f32 v[52:53], v[56:57], v[52:53], v[60:61]
	v_pk_fma_f32 v[54:55], v[58:59], v[54:55], v[62:63]
	v_pk_fma_f32 v[44:45], v[52:53], s[24:25], v[44:45] op_sel_hi:[1,0,1]
	v_pk_fma_f32 v[46:47], v[54:55], s[24:25], v[46:47] op_sel_hi:[1,0,1]
	v_pk_add_f32 v[44:45], v[64:65], v[44:45]
	v_pk_add_f32 v[46:47], v[66:67], v[46:47]
	global_store_dwordx4 v[50:51], v[44:47], off
	v_lshlrev_b64 v[64:65], 11, v[72:73]
	v_lshl_add_u64 v[64:65], s[10:11], 0, v[64:65]
	v_lshl_add_u64 v[72:73], v[144:145], 1, v[64:65]
	v_sub_f32_e32 v65, v71, v75
	v_sub_f32_e32 v64, v70, v75
	v_sub_f32_e32 v67, v69, v75
	v_sub_f32_e32 v66, v68, v75
	v_pk_mul_f32 v[66:67], v[66:67], v[74:75] op_sel_hi:[1,0]
	v_pk_mul_f32 v[68:69], v[64:65], v[74:75] op_sel_hi:[1,0]
	v_cvt_pk_bf16_f32 v64, v44, v45
	v_cvt_pk_bf16_f32 v65, v46, v47
	v_pk_fma_f32 v[52:53], v[208:209], v[66:67], v[212:213]
	v_pk_fma_f32 v[54:55], v[210:211], v[68:69], v[214:215]
	v_pk_fma_f32 v[40:41], v[52:53], s[24:25], v[40:41] op_sel_hi:[1,0,1]
	v_pk_fma_f32 v[42:43], v[54:55], s[24:25], v[42:43] op_sel_hi:[1,0,1]
	v_pk_add_f32 v[40:41], v[250:251], v[40:41]
	v_pk_add_f32 v[42:43], v[252:253], v[42:43]
	global_store_dwordx4 v[50:51], v[40:43], off offset:16
	v_cvt_pk_bf16_f32 v66, v40, v41
	v_cvt_pk_bf16_f32 v67, v42, v43
	flat_store_dwordx4 v[72:73], v[64:67]
	global_load_dwordx4 v[52:55], v[50:51], off offset:512
	global_load_dwordx4 v[56:59], v[126:127], off
	global_load_dwordx4 v[60:63], v[158:159], off
	s_nop 0
	global_load_dwordx4 v[64:67], v[160:161], off
	global_load_dwordx4 v[68:71], v[50:51], off offset:528
	global_load_dwordx4 v[208:211], v[120:121], off
	global_load_dwordx4 v[212:215], v[122:123], off
	global_load_dwordx4 v[250:253], v[116:117], off
	s_waitcnt vmcnt(0)
	v_sub_f32_e32 v55, v55, v75
	v_sub_f32_e32 v54, v54, v75
	v_sub_f32_e32 v53, v53, v75
	v_sub_f32_e32 v52, v52, v75
	v_pk_mul_f32 v[52:53], v[74:75], v[52:53] op_sel_hi:[0,1]
	v_pk_mul_f32 v[54:55], v[74:75], v[54:55] op_sel_hi:[0,1]
	v_pk_fma_f32 v[54:55], v[58:59], v[54:55], v[62:63]
	v_pk_fma_f32 v[52:53], v[56:57], v[52:53], v[60:61]
	v_pk_fma_f32 v[38:39], v[54:55], s[24:25], v[38:39] op_sel_hi:[1,0,1]
	v_pk_fma_f32 v[36:37], v[52:53], s[24:25], v[36:37] op_sel_hi:[1,0,1]
	v_pk_add_f32 v[38:39], v[66:67], v[38:39]
	v_pk_add_f32 v[36:37], v[64:65], v[36:37]
	global_store_dwordx4 v[50:51], v[36:39], off offset:512
	v_add_f32_e32 v64, v44, v45
	v_mul_f32_e32 v45, v45, v45
	v_fmac_f32_e32 v45, v44, v44
	v_add_f32_e32 v64, v46, v64
	v_fmac_f32_e32 v45, v46, v46
	v_add_f32_e32 v46, v40, v41
	v_mul_f32_e32 v41, v41, v41
	v_fmac_f32_e32 v41, v40, v40
	v_add_f32_e32 v44, v47, v64
	v_add_f32_e32 v46, v42, v46
	v_fmac_f32_e32 v41, v42, v42
	v_add_f32_e32 v44, 0, v44
	v_fmac_f32_e32 v45, v47, v47
	v_add_f32_e32 v40, v43, v46
	v_fmac_f32_e32 v41, v43, v43
	v_sub_f32_e32 v43, v69, v75
	v_sub_f32_e32 v42, v68, v75
	v_add_f32_e32 v44, v40, v44
	v_add_f32_e32 v45, v45, v41
	v_sub_f32_e32 v41, v71, v75
	v_sub_f32_e32 v40, v70, v75
	v_pk_mul_f32 v[42:43], v[74:75], v[42:43] op_sel_hi:[0,1]
	v_pk_mul_f32 v[40:41], v[74:75], v[40:41] op_sel_hi:[0,1]
	v_mul_f32_e32 v47, v37, v37
	v_add_f32_e32 v46, v36, v37
	v_fmac_f32_e32 v47, v36, v36
	v_add_f32_e32 v46, v38, v46
	v_fmac_f32_e32 v47, v38, v38
	v_add_f32_e32 v46, v39, v46
	v_fmac_f32_e32 v47, v39, v39
	v_add_f32_e32 v44, v44, v46
	v_add_f32_e32 v45, v45, v47
	v_cvt_pk_bf16_f32 v36, v36, v37
	v_cvt_pk_bf16_f32 v37, v38, v39
	v_pk_fma_f32 v[42:43], v[208:209], v[42:43], v[212:213]
	v_pk_fma_f32 v[40:41], v[210:211], v[40:41], v[214:215]
	v_pk_fma_f32 v[32:33], v[42:43], s[24:25], v[32:33] op_sel_hi:[1,0,1]
	v_pk_fma_f32 v[34:35], v[40:41], s[24:25], v[34:35] op_sel_hi:[1,0,1]
	v_pk_add_f32 v[40:41], v[250:251], v[32:33]
	v_pk_add_f32 v[42:43], v[252:253], v[34:35]
	v_mul_f32_e32 v33, v41, v41
	v_add_f32_e32 v32, v40, v41
	v_fmac_f32_e32 v33, v40, v40
	v_add_f32_e32 v32, v42, v32
	v_fmac_f32_e32 v33, v42, v42
	v_add_f32_e32 v32, v43, v32
	v_fmac_f32_e32 v33, v43, v43
	v_add_f32_e32 v32, v44, v32
	v_add_f32_e32 v33, v45, v33
	ds_bpermute_b32 v34, v118, v32
	ds_bpermute_b32 v35, v118, v33
	global_store_dwordx4 v[50:51], v[40:43], off offset:528
	v_cvt_pk_bf16_f32 v38, v40, v41
	v_cvt_pk_bf16_f32 v39, v42, v43
	s_waitcnt lgkmcnt(0)
	v_add_f32_e32 v32, v32, v34
	v_add_f32_e32 v33, v33, v35
	ds_bpermute_b32 v34, v119, v32
	ds_bpermute_b32 v35, v119, v33
	flat_store_dwordx4 v[72:73], v[36:39] offset:256
	s_and_saveexec_b64 s[36:37], s[2:3]
	s_cbranch_execz .LBB0_1995
	s_waitcnt lgkmcnt(0)
	v_add_f32_e32 v35, v33, v35
	v_add_f32_e32 v34, v32, v34
	v_lshl_add_u64 v[32:33], s[8:9], 0, v[48:49]
	flat_atomic_add_f32 v[32:33], v34
	flat_atomic_add_f32 v[32:33], v35 offset:4
; DEVI unsigned pk2(float lo, float hi) { unsigned r; asm("v_cvt_pk_bf16_f32 %0, %1, %2" : "=v"(r) : "v"(lo), "v"(hi)); return r; }
; DEVI void row_stats(const float* stats, int row, float& mu, float& rs) {
;     if (stats) { const float2 st = *(const float2*)(stats + 2 * (size_t)row); mu = st.x * (1.0f / 1024.0f); const float var = st.y * (1.0f / 1024.0f) - mu * mu; rs = rsqrtf(fmaxf(var, 0.f) + LN_EPS); }
;     DEVI void operator()(const f32x4 (&acc)[2][2][4][2], const pg8::Unit& u, int wr, int wc, int fr, int fq) const {
;     ...
;                 const int row = row0 + ai * 128 + m * 16; float mu, rs; row_stats(stin, row, mu, rs);
;                 float sum = 0.f, sq = 0.f;
; #pragma unroll
;                 for (int bj = 0; bj < 2; ++bj) {
;                     f32x4 z[2];
; #pragma unroll
;                     for (int n = 0; n < 2; ++n) {
;                         const int col = colb + bj * 128 + 4 * n;
;                         f32x4 xv = *(const f32x4*)(zsrc + (size_t)row * DM + col);
;                         if (stin) { const f32x4 gv = *(const f32x4*)(gin + col), bv = *(const f32x4*)(bin + col); xv = (xv - mu) * rs * gv + bv; }
;                         f32x4 zz = ALPHA * xv + acc[ai][bj][m][n];
;                         if (bias) zz += *(const f32x4*)(bias + col);
;                         *(f32x4*)(zdst + (size_t)row * DM + col) = zz;
;                         sum += zz[0] + zz[1] + zz[2] + zz[3]; sq += zz[0] * zz[0] + zz[1] * zz[1] + zz[2] * zz[2] + zz[3] * zz[3];
;                         z[n] = zz;
;                     }
;                     u32x4 o; o.x = pk2(z[0][0], z[0][1]); o.y = pk2(z[0][2], z[0][3]); o.z = pk2(z[1][0], z[1][1]); o.w = pk2(z[1][2], z[1][3]);
;                     if (zb) *(u32x4*)(zb + (size_t)row * DM + colb + bj * 128) = o;
;                 }
;                 sum += __shfl_xor(sum, 16); sq += __shfl_xor(sq, 16);
;                 sum += __shfl_xor(sum, 32); sq += __shfl_xor(sq, 32);
;                 if (fq == 0) { atomicAdd(stout + 2 * (size_t)row, sum); atomicAdd(stout + 2 * (size_t)row + 1, sq); }
.LBB0_1995:
	s_or_b64 exec, exec, s[36:37]
	v_add_u32_e32 v56, 0xa0, v154
	v_ashrrev_i32_e32 v57, 31, v56
	v_lshlrev_b64 v[32:33], 3, v[56:57]
	s_waitcnt lgkmcnt(0)
	v_lshl_add_u64 v[34:35], s[6:7], 0, v[32:33]
	flat_load_dwordx2 v[58:59], v[34:35]
	v_lshlrev_b64 v[34:35], 12, v[56:57]
	v_lshl_add_u64 v[34:35], s[46:47], 0, v[34:35]
	v_lshl_add_u64 v[34:35], v[144:145], 2, v[34:35]
	global_load_dwordx4 v[36:39], v[34:35], off
	global_load_dwordx4 v[40:43], v[150:151], off
	global_load_dwordx4 v[44:47], v[152:153], off
	global_load_dwordx4 v[48:51], v[156:157], off
	global_load_dwordx4 v[52:55], v[34:35], off offset:16
	global_load_dwordx4 v[208:211], v[146:147], off
	global_load_dwordx4 v[212:215], v[148:149], off
	global_load_dwordx4 v[250:253], v[124:125], off
	s_waitcnt vmcnt(0) lgkmcnt(0)
	v_pk_mul_f32 v[58:59], v[58:59], s[22:23] op_sel:[1,0] op_sel_hi:[0,0]
	v_fma_f32 v58, -v59, v59, v58
	v_max_f32_e32 v58, 0, v58
	v_add_f32_e32 v58, 0x3727c5ac, v58
	v_mul_f32_e32 v60, 0x4b800000, v58
	v_cmp_gt_f32_e32 vcc, s72, v58
	v_sub_f32_e32 v39, v39, v59
	v_sub_f32_e32 v38, v38, v59
	v_cndmask_b32_e32 v58, v58, v60, vcc
	v_rsq_f32_e32 v58, v58
	v_sub_f32_e32 v37, v37, v59
	v_sub_f32_e32 v36, v36, v59
	v_mul_f32_e32 v60, 0x45800000, v58
	v_cndmask_b32_e32 v58, v58, v60, vcc
	v_pk_mul_f32 v[36:37], v[36:37], v[58:59] op_sel_hi:[1,0]
	v_pk_mul_f32 v[38:39], v[38:39], v[58:59] op_sel_hi:[1,0]
	v_pk_fma_f32 v[36:37], v[40:41], v[36:37], v[44:45]
	v_pk_fma_f32 v[38:39], v[42:43], v[38:39], v[46:47]
	v_pk_fma_f32 v[28:29], v[36:37], s[24:25], v[28:29] op_sel_hi:[1,0,1]
	v_pk_fma_f32 v[30:31], v[38:39], s[24:25], v[30:31] op_sel_hi:[1,0,1]
	v_pk_add_f32 v[28:29], v[48:49], v[28:29]
	v_pk_add_f32 v[30:31], v[50:51], v[30:31]
	global_store_dwordx4 v[34:35], v[28:31], off
	v_lshlrev_b64 v[48:49], 11, v[56:57]
	v_lshl_add_u64 v[48:49], s[10:11], 0, v[48:49]
	v_lshl_add_u64 v[56:57], v[144:145], 1, v[48:49]
	v_sub_f32_e32 v49, v55, v59
	v_sub_f32_e32 v48, v54, v59
	v_sub_f32_e32 v51, v53, v59
	v_sub_f32_e32 v50, v52, v59
	v_pk_mul_f32 v[50:51], v[50:51], v[58:59] op_sel_hi:[1,0]
	v_pk_mul_f32 v[52:53], v[48:49], v[58:59] op_sel_hi:[1,0]
	v_cvt_pk_bf16_f32 v48, v28, v29
	v_cvt_pk_bf16_f32 v49, v30, v31
	v_pk_fma_f32 v[36:37], v[208:209], v[50:51], v[212:213]
	v_pk_fma_f32 v[38:39], v[210:211], v[52:53], v[214:215]
	v_pk_fma_f32 v[24:25], v[36:37], s[24:25], v[24:25] op_sel_hi:[1,0,1]
	v_pk_fma_f32 v[26:27], v[38:39], s[24:25], v[26:27] op_sel_hi:[1,0,1]
	v_pk_add_f32 v[24:25], v[250:251], v[24:25]
	v_pk_add_f32 v[26:27], v[252:253], v[26:27]
	global_store_dwordx4 v[34:35], v[24:27], off offset:16
	v_cvt_pk_bf16_f32 v50, v24, v25
	v_cvt_pk_bf16_f32 v51, v26, v27
	flat_store_dwordx4 v[56:57], v[48:51]
	global_load_dwordx4 v[36:39], v[34:35], off offset:512
	global_load_dwordx4 v[40:43], v[126:127], off
	global_load_dwordx4 v[44:47], v[158:159], off
	s_nop 0
	global_load_dwordx4 v[48:51], v[160:161], off
	global_load_dwordx4 v[52:55], v[34:35], off offset:528
	global_load_dwordx4 v[208:211], v[120:121], off
	global_load_dwordx4 v[212:215], v[122:123], off
	global_load_dwordx4 v[250:253], v[116:117], off
	s_waitcnt vmcnt(0)
	v_sub_f32_e32 v39, v39, v59
	v_sub_f32_e32 v38, v38, v59
	v_sub_f32_e32 v37, v37, v59
	v_sub_f32_e32 v36, v36, v59
	v_pk_mul_f32 v[36:37], v[58:59], v[36:37] op_sel_hi:[0,1]
	v_pk_mul_f32 v[38:39], v[58:59], v[38:39] op_sel_hi:[0,1]
	v_pk_fma_f32 v[38:39], v[42:43], v[38:39], v[46:47]
	v_pk_fma_f32 v[36:37], v[40:41], v[36:37], v[44:45]
	v_pk_fma_f32 v[22:23], v[38:39], s[24:25], v[22:23] op_sel_hi:[1,0,1]
	v_pk_fma_f32 v[20:21], v[36:37], s[24:25], v[20:21] op_sel_hi:[1,0,1]
	v_pk_add_f32 v[22:23], v[50:51], v[22:23]
	v_pk_add_f32 v[20:21], v[48:49], v[20:21]
	global_store_dwordx4 v[34:35], v[20:23], off offset:512
	v_add_f32_e32 v48, v28, v29
	v_mul_f32_e32 v29, v29, v29
	v_fmac_f32_e32 v29, v28, v28
	v_add_f32_e32 v48, v30, v48
	v_fmac_f32_e32 v29, v30, v30
	v_add_f32_e32 v30, v24, v25
	v_mul_f32_e32 v25, v25, v25
	v_fmac_f32_e32 v25, v24, v24
	v_add_f32_e32 v28, v31, v48
	v_add_f32_e32 v30, v26, v30
	v_fmac_f32_e32 v25, v26, v26
	v_add_f32_e32 v28, 0, v28
	v_fmac_f32_e32 v29, v31, v31
	v_add_f32_e32 v24, v27, v30
	v_fmac_f32_e32 v25, v27, v27
	v_sub_f32_e32 v27, v53, v59
	v_sub_f32_e32 v26, v52, v59
	v_add_f32_e32 v28, v24, v28
	v_add_f32_e32 v29, v29, v25
	v_sub_f32_e32 v25, v55, v59
	v_sub_f32_e32 v24, v54, v59
	v_pk_mul_f32 v[26:27], v[58:59], v[26:27] op_sel_hi:[0,1]
	v_pk_mul_f32 v[24:25], v[58:59], v[24:25] op_sel_hi:[0,1]
	v_mul_f32_e32 v31, v21, v21
	v_add_f32_e32 v30, v20, v21
	v_fmac_f32_e32 v31, v20, v20
	v_add_f32_e32 v30, v22, v30
	v_fmac_f32_e32 v31, v22, v22
	v_add_f32_e32 v30, v23, v30
	v_fmac_f32_e32 v31, v23, v23
	v_add_f32_e32 v28, v28, v30
	v_add_f32_e32 v29, v29, v31
	v_cvt_pk_bf16_f32 v20, v20, v21
	v_cvt_pk_bf16_f32 v21, v22, v23
	v_pk_fma_f32 v[26:27], v[208:209], v[26:27], v[212:213]
	v_pk_fma_f32 v[24:25], v[210:211], v[24:25], v[214:215]
	v_pk_fma_f32 v[16:17], v[26:27], s[24:25], v[16:17] op_sel_hi:[1,0,1]
	v_pk_fma_f32 v[18:19], v[24:25], s[24:25], v[18:19] op_sel_hi:[1,0,1]
	v_pk_add_f32 v[24:25], v[250:251], v[16:17]
	v_pk_add_f32 v[26:27], v[252:253], v[18:19]
	v_mul_f32_e32 v17, v25, v25
	v_add_f32_e32 v16, v24, v25
	v_fmac_f32_e32 v17, v24, v24
	v_add_f32_e32 v16, v26, v16
	v_fmac_f32_e32 v17, v26, v26
	v_add_f32_e32 v16, v27, v16
	v_fmac_f32_e32 v17, v27, v27
	v_add_f32_e32 v16, v28, v16
	v_add_f32_e32 v17, v29, v17
	ds_bpermute_b32 v18, v118, v16
	ds_bpermute_b32 v19, v118, v17
	global_store_dwordx4 v[34:35], v[24:27], off offset:528
	v_cvt_pk_bf16_f32 v22, v24, v25
	v_cvt_pk_bf16_f32 v23, v26, v27
	s_waitcnt lgkmcnt(0)
	v_add_f32_e32 v16, v16, v18
	v_add_f32_e32 v17, v17, v19
	ds_bpermute_b32 v18, v119, v16
	ds_bpermute_b32 v19, v119, v17
	flat_store_dwordx4 v[56:57], v[20:23] offset:256
	s_and_saveexec_b64 s[36:37], s[2:3]
	s_cbranch_execz .LBB0_1997
	s_waitcnt lgkmcnt(0)
	v_add_f32_e32 v19, v17, v19
	v_add_f32_e32 v18, v16, v18
	v_lshl_add_u64 v[16:17], s[8:9], 0, v[32:33]
	flat_atomic_add_f32 v[16:17], v18
	flat_atomic_add_f32 v[16:17], v19 offset:4
; DEVI unsigned pk2(float lo, float hi) { unsigned r; asm("v_cvt_pk_bf16_f32 %0, %1, %2" : "=v"(r) : "v"(lo), "v"(hi)); return r; }
; DEVI void row_stats(const float* stats, int row, float& mu, float& rs) {
;     if (stats) { const float2 st = *(const float2*)(stats + 2 * (size_t)row); mu = st.x * (1.0f / 1024.0f); const float var = st.y * (1.0f / 1024.0f) - mu * mu; rs = rsqrtf(fmaxf(var, 0.f) + LN_EPS); }
;     DEVI void operator()(const f32x4 (&acc)[2][2][4][2], const pg8::Unit& u, int wr, int wc, int fr, int fq) const {
;     ...
;                 const int row = row0 + ai * 128 + m * 16; float mu, rs; row_stats(stin, row, mu, rs);
;                 float sum = 0.f, sq = 0.f;
; #pragma unroll
;                 for (int bj = 0; bj < 2; ++bj) {
;                     f32x4 z[2];
; #pragma unroll
;                     for (int n = 0; n < 2; ++n) {
;                         const int col = colb + bj * 128 + 4 * n;
;                         f32x4 xv = *(const f32x4*)(zsrc + (size_t)row * DM + col);
;                         if (stin) { const f32x4 gv = *(const f32x4*)(gin + col), bv = *(const f32x4*)(bin + col); xv = (xv - mu) * rs * gv + bv; }
;                         f32x4 zz = ALPHA * xv + acc[ai][bj][m][n];
;                         if (bias) zz += *(const f32x4*)(bias + col);
;                         *(f32x4*)(zdst + (size_t)row * DM + col) = zz;
;                         sum += zz[0] + zz[1] + zz[2] + zz[3]; sq += zz[0] * zz[0] + zz[1] * zz[1] + zz[2] * zz[2] + zz[3] * zz[3];
;                         z[n] = zz;
;                     }
;                     u32x4 o; o.x = pk2(z[0][0], z[0][1]); o.y = pk2(z[0][2], z[0][3]); o.z = pk2(z[1][0], z[1][1]); o.w = pk2(z[1][2], z[1][3]);
;                     if (zb) *(u32x4*)(zb + (size_t)row * DM + colb + bj * 128) = o;
;                 }
;                 sum += __shfl_xor(sum, 16); sq += __shfl_xor(sq, 16);
;                 sum += __shfl_xor(sum, 32); sq += __shfl_xor(sq, 32);
;                 if (fq == 0) { atomicAdd(stout + 2 * (size_t)row, sum); atomicAdd(stout + 2 * (size_t)row + 1, sq); }
.LBB0_1997:
	s_or_b64 exec, exec, s[36:37]
	v_add_u32_e32 v40, 0xb0, v154
	v_ashrrev_i32_e32 v41, 31, v40
	v_lshlrev_b64 v[16:17], 3, v[40:41]
	s_waitcnt lgkmcnt(0)
	v_lshl_add_u64 v[18:19], s[6:7], 0, v[16:17]
	flat_load_dwordx2 v[42:43], v[18:19]
	v_lshlrev_b64 v[18:19], 12, v[40:41]
	v_lshl_add_u64 v[18:19], s[46:47], 0, v[18:19]
	v_lshl_add_u64 v[18:19], v[144:145], 2, v[18:19]
	global_load_dwordx4 v[20:23], v[18:19], off
	global_load_dwordx4 v[24:27], v[150:151], off
	global_load_dwordx4 v[28:31], v[152:153], off
	global_load_dwordx4 v[32:35], v[156:157], off
	global_load_dwordx4 v[36:39], v[18:19], off offset:16
	global_load_dwordx4 v[208:211], v[146:147], off
	global_load_dwordx4 v[212:215], v[148:149], off
	global_load_dwordx4 v[250:253], v[124:125], off
	s_waitcnt vmcnt(0) lgkmcnt(0)
	v_pk_mul_f32 v[42:43], v[42:43], s[22:23] op_sel:[1,0] op_sel_hi:[0,0]
	v_fma_f32 v42, -v43, v43, v42
	v_max_f32_e32 v42, 0, v42
	v_add_f32_e32 v42, 0x3727c5ac, v42
	v_mul_f32_e32 v44, 0x4b800000, v42
	v_cmp_gt_f32_e32 vcc, s72, v42
	v_sub_f32_e32 v23, v23, v43
	v_sub_f32_e32 v22, v22, v43
	v_cndmask_b32_e32 v42, v42, v44, vcc
	v_rsq_f32_e32 v42, v42
	v_sub_f32_e32 v21, v21, v43
	v_sub_f32_e32 v20, v20, v43
	v_mul_f32_e32 v44, 0x45800000, v42
	v_cndmask_b32_e32 v42, v42, v44, vcc
	v_pk_mul_f32 v[20:21], v[20:21], v[42:43] op_sel_hi:[1,0]
	v_pk_mul_f32 v[22:23], v[22:23], v[42:43] op_sel_hi:[1,0]
	v_pk_fma_f32 v[20:21], v[24:25], v[20:21], v[28:29]
	v_pk_fma_f32 v[22:23], v[26:27], v[22:23], v[30:31]
	v_pk_fma_f32 v[12:13], v[20:21], s[24:25], v[12:13] op_sel_hi:[1,0,1]
	v_pk_fma_f32 v[14:15], v[22:23], s[24:25], v[14:15] op_sel_hi:[1,0,1]
	v_pk_add_f32 v[12:13], v[32:33], v[12:13]
	v_pk_add_f32 v[14:15], v[34:35], v[14:15]
	global_store_dwordx4 v[18:19], v[12:15], off
	v_lshlrev_b64 v[32:33], 11, v[40:41]
	v_lshl_add_u64 v[32:33], s[10:11], 0, v[32:33]
	v_lshl_add_u64 v[40:41], v[144:145], 1, v[32:33]
	v_sub_f32_e32 v33, v39, v43
	v_sub_f32_e32 v32, v38, v43
	v_sub_f32_e32 v35, v37, v43
	v_sub_f32_e32 v34, v36, v43
	v_pk_mul_f32 v[34:35], v[34:35], v[42:43] op_sel_hi:[1,0]
	v_pk_mul_f32 v[36:37], v[32:33], v[42:43] op_sel_hi:[1,0]
	v_cvt_pk_bf16_f32 v32, v12, v13
	v_cvt_pk_bf16_f32 v33, v14, v15
	v_pk_fma_f32 v[20:21], v[208:209], v[34:35], v[212:213]
	v_pk_fma_f32 v[22:23], v[210:211], v[36:37], v[214:215]
	v_pk_fma_f32 v[8:9], v[20:21], s[24:25], v[8:9] op_sel_hi:[1,0,1]
	v_pk_fma_f32 v[10:11], v[22:23], s[24:25], v[10:11] op_sel_hi:[1,0,1]
	v_pk_add_f32 v[8:9], v[250:251], v[8:9]
	v_pk_add_f32 v[10:11], v[252:253], v[10:11]
	global_store_dwordx4 v[18:19], v[8:11], off offset:16
	v_cvt_pk_bf16_f32 v34, v8, v9
	v_cvt_pk_bf16_f32 v35, v10, v11
	flat_store_dwordx4 v[40:41], v[32:35]
	global_load_dwordx4 v[20:23], v[18:19], off offset:512
	global_load_dwordx4 v[24:27], v[126:127], off
	global_load_dwordx4 v[28:31], v[158:159], off
	s_nop 0
	global_load_dwordx4 v[32:35], v[160:161], off
	global_load_dwordx4 v[36:39], v[18:19], off offset:528
	global_load_dwordx4 v[208:211], v[120:121], off
	global_load_dwordx4 v[212:215], v[122:123], off
	global_load_dwordx4 v[250:253], v[116:117], off
	s_waitcnt vmcnt(0)
	v_sub_f32_e32 v23, v23, v43
	v_sub_f32_e32 v22, v22, v43
	v_sub_f32_e32 v21, v21, v43
	v_sub_f32_e32 v20, v20, v43
	v_pk_mul_f32 v[20:21], v[42:43], v[20:21] op_sel_hi:[0,1]
	v_pk_mul_f32 v[22:23], v[42:43], v[22:23] op_sel_hi:[0,1]
	v_pk_fma_f32 v[22:23], v[26:27], v[22:23], v[30:31]
	v_pk_fma_f32 v[20:21], v[24:25], v[20:21], v[28:29]
	v_pk_fma_f32 v[6:7], v[22:23], s[24:25], v[6:7] op_sel_hi:[1,0,1]
	v_pk_fma_f32 v[4:5], v[20:21], s[24:25], v[4:5] op_sel_hi:[1,0,1]
	v_pk_add_f32 v[6:7], v[34:35], v[6:7]
	v_pk_add_f32 v[4:5], v[32:33], v[4:5]
	global_store_dwordx4 v[18:19], v[4:7], off offset:512
	v_add_f32_e32 v32, v12, v13
	v_mul_f32_e32 v13, v13, v13
	v_fmac_f32_e32 v13, v12, v12
	v_add_f32_e32 v32, v14, v32
	v_fmac_f32_e32 v13, v14, v14
	v_add_f32_e32 v14, v8, v9
	v_mul_f32_e32 v9, v9, v9
	v_fmac_f32_e32 v9, v8, v8
	v_add_f32_e32 v12, v15, v32
	v_add_f32_e32 v14, v10, v14
	v_fmac_f32_e32 v9, v10, v10
	v_add_f32_e32 v12, 0, v12
	v_fmac_f32_e32 v13, v15, v15
	v_add_f32_e32 v8, v11, v14
	v_fmac_f32_e32 v9, v11, v11
	v_sub_f32_e32 v11, v37, v43
	v_sub_f32_e32 v10, v36, v43
	v_add_f32_e32 v12, v8, v12
	v_add_f32_e32 v13, v13, v9
	v_sub_f32_e32 v9, v39, v43
	v_sub_f32_e32 v8, v38, v43
	v_pk_mul_f32 v[10:11], v[42:43], v[10:11] op_sel_hi:[0,1]
	v_pk_mul_f32 v[8:9], v[42:43], v[8:9] op_sel_hi:[0,1]
	v_mul_f32_e32 v15, v5, v5
	v_add_f32_e32 v14, v4, v5
	v_fmac_f32_e32 v15, v4, v4
	v_add_f32_e32 v14, v6, v14
	v_fmac_f32_e32 v15, v6, v6
	v_add_f32_e32 v14, v7, v14
	v_fmac_f32_e32 v15, v7, v7
	v_add_f32_e32 v12, v12, v14
	v_add_f32_e32 v13, v13, v15
	v_cvt_pk_bf16_f32 v4, v4, v5
	v_cvt_pk_bf16_f32 v5, v6, v7
	v_pk_fma_f32 v[10:11], v[208:209], v[10:11], v[212:213]
	v_pk_fma_f32 v[8:9], v[210:211], v[8:9], v[214:215]
	v_pk_fma_f32 v[0:1], v[10:11], s[24:25], v[0:1] op_sel_hi:[1,0,1]
	v_pk_fma_f32 v[2:3], v[8:9], s[24:25], v[2:3] op_sel_hi:[1,0,1]
	v_pk_add_f32 v[8:9], v[250:251], v[0:1]
	v_pk_add_f32 v[10:11], v[252:253], v[2:3]
	v_mul_f32_e32 v1, v9, v9
	v_add_f32_e32 v0, v8, v9
	v_fmac_f32_e32 v1, v8, v8
	v_add_f32_e32 v0, v10, v0
	v_fmac_f32_e32 v1, v10, v10
	v_add_f32_e32 v0, v11, v0
	v_fmac_f32_e32 v1, v11, v11
	v_add_f32_e32 v0, v12, v0
	v_add_f32_e32 v1, v13, v1
	ds_bpermute_b32 v2, v118, v0
	ds_bpermute_b32 v3, v118, v1
	global_store_dwordx4 v[18:19], v[8:11], off offset:528
	v_cvt_pk_bf16_f32 v6, v8, v9
	v_cvt_pk_bf16_f32 v7, v10, v11
	s_waitcnt lgkmcnt(0)
	v_add_f32_e32 v0, v0, v2
	v_add_f32_e32 v1, v1, v3
	ds_bpermute_b32 v2, v119, v0
	ds_bpermute_b32 v3, v119, v1
	flat_store_dwordx4 v[40:41], v[4:7] offset:256
	s_and_saveexec_b64 s[36:37], s[2:3]
	s_cbranch_execz .LBB0_1999
	s_waitcnt lgkmcnt(0)
	v_add_f32_e32 v3, v1, v3
	v_add_f32_e32 v2, v0, v2
	v_lshl_add_u64 v[0:1], s[8:9], 0, v[16:17]
	flat_atomic_add_f32 v[0:1], v2
	flat_atomic_add_f32 v[0:1], v3 offset:4

; DEVI unsigned pk2(float lo, float hi) { unsigned r; asm("v_cvt_pk_bf16_f32 %0, %1, %2" : "=v"(r) : "v"(lo), "v"(hi)); return r; }
; DEVI void row_stats(const float* stats, int row, float& mu, float& rs) {
;     if (stats) { const float2 st = *(const float2*)(stats + 2 * (size_t)row); mu = st.x * (1.0f / 1024.0f); const float var = st.y * (1.0f / 1024.0f) - mu * mu; rs = rsqrtf(fmaxf(var, 0.f) + LN_EPS); }
;     DEVI void operator()(const f32x4 (&acc)[2][2][4][2], const pg8::Unit& u, int wr, int wc, int fr, int fq) const {
;     ...
;                 const int row = row0 + ai * 128 + m * 16; float mu, rs; row_stats(stin, row, mu, rs);
;                 float sum = 0.f, sq = 0.f;
; #pragma unroll
;                 for (int bj = 0; bj < 2; ++bj) {
;                     f32x4 z[2];
; #pragma unroll
;                     for (int n = 0; n < 2; ++n) {
;                         const int col = colb + bj * 128 + 4 * n;
;                         f32x4 xv = *(const f32x4*)(zsrc + (size_t)row * DM + col);
;                         if (stin) { const f32x4 gv = *(const f32x4*)(gin + col), bv = *(const f32x4*)(bin + col); xv = (xv - mu) * rs * gv + bv; }
;                         f32x4 zz = ALPHA * xv + acc[ai][bj][m][n];
;                         if (bias) zz += *(const f32x4*)(bias + col);
;                         *(f32x4*)(zdst + (size_t)row * DM + col) = zz;
;                         sum += zz[0] + zz[1] + zz[2] + zz[3]; sq += zz[0] * zz[0] + zz[1] * zz[1] + zz[2] * zz[2] + zz[3] * zz[3];
;                         z[n] = zz;
;                     }
;                     u32x4 o; o.x = pk2(z[0][0], z[0][1]); o.y = pk2(z[0][2], z[0][3]); o.z = pk2(z[1][0], z[1][1]); o.w = pk2(z[1][2], z[1][3]);
;                     if (zb) *(u32x4*)(zb + (size_t)row * DM + colb + bj * 128) = o;
;                 }
;                 sum += __shfl_xor(sum, 16); sq += __shfl_xor(sq, 16);
;                 sum += __shfl_xor(sum, 32); sq += __shfl_xor(sq, 32);
;                 if (fq == 0) { atomicAdd(stout + 2 * (size_t)row, sum); atomicAdd(stout + 2 * (size_t)row + 1, sq); }
.LBB0_2194:
	s_or_b64 exec, exec, s[30:31]
	v_or_b32_e32 v118, 16, v154
	v_ashrrev_i32_e32 v119, 31, v118
	v_lshlrev_b64 v[112:113], 3, v[118:119]
	s_waitcnt lgkmcnt(0)
	v_lshl_add_u64 v[114:115], s[12:13], 0, v[112:113]
	flat_load_dwordx2 v[160:161], v[114:115]
	v_lshlrev_b64 v[114:115], 12, v[118:119]
	v_lshl_add_u64 v[114:115], s[46:47], 0, v[114:115]
	v_lshl_add_u64 v[114:115], v[144:145], 2, v[114:115]
	global_load_dwordx4 v[156:159], v[114:115], off
	global_load_dwordx4 v[170:173], v[150:151], off
	global_load_dwordx4 v[174:177], v[152:153], off
	global_load_dwordx4 v[178:181], v[114:115], off offset:16
	v_lshlrev_b64 v[118:119], 11, v[118:119]
	v_lshl_add_u64 v[118:119], s[14:15], 0, v[118:119]
	v_lshl_add_u64 v[118:119], v[144:145], 1, v[118:119]
	global_load_dwordx4 v[196:199], v[146:147], off
	global_load_dwordx4 v[200:203], v[148:149], off
	s_waitcnt vmcnt(0) lgkmcnt(0)
	v_pk_mul_f32 v[160:161], v[160:161], s[24:25] op_sel:[1,0] op_sel_hi:[0,0]
	v_fma_f32 v155, -v161, v161, v160
	v_max_f32_e32 v155, 0, v155
	v_add_f32_e32 v155, 0x3727c5ac, v155
	v_mul_f32_e32 v160, 0x4b800000, v155
	v_cmp_gt_f32_e32 vcc, s61, v155
	v_sub_f32_e32 v157, v157, v161
	v_sub_f32_e32 v156, v156, v161
	v_cndmask_b32_e32 v155, v155, v160, vcc
	v_rsq_f32_e32 v155, v155
	v_sub_f32_e32 v159, v159, v161
	v_sub_f32_e32 v158, v158, v161
	v_mul_f32_e32 v160, 0x45800000, v155
	v_cndmask_b32_e32 v160, v155, v160, vcc
	v_pk_mul_f32 v[158:159], v[158:159], v[160:161] op_sel_hi:[1,0]
	v_pk_mul_f32 v[156:157], v[156:157], v[160:161] op_sel_hi:[1,0]
	v_pk_fma_f32 v[158:159], v[172:173], v[158:159], v[176:177]
	v_pk_fma_f32 v[156:157], v[170:171], v[156:157], v[174:175]
	v_pk_fma_f32 v[110:111], v[158:159], s[26:27], v[110:111] op_sel_hi:[1,0,1]
	v_pk_fma_f32 v[108:109], v[156:157], s[26:27], v[108:109] op_sel_hi:[1,0,1]
	global_store_dwordx4 v[114:115], v[108:111], off
	v_sub_f32_e32 v175, v179, v161
	v_sub_f32_e32 v174, v178, v161
	v_sub_f32_e32 v177, v181, v161
	v_sub_f32_e32 v176, v180, v161
	v_pk_mul_f32 v[176:177], v[176:177], v[160:161] op_sel_hi:[1,0]
	v_pk_mul_f32 v[178:179], v[174:175], v[160:161] op_sel_hi:[1,0]
	v_cvt_pk_bf16_f32 v174, v108, v109
	v_cvt_pk_bf16_f32 v175, v110, v111
	v_add_f32_e32 v155, v108, v109
	v_mul_f32_e32 v109, v109, v109
	v_fmac_f32_e32 v109, v108, v108
	v_add_f32_e32 v155, v110, v155
	v_fmac_f32_e32 v109, v110, v110
	v_add_f32_e32 v108, v111, v155
	v_add_f32_e32 v108, 0, v108
	v_fmac_f32_e32 v109, v111, v111
	v_pk_fma_f32 v[156:157], v[196:197], v[178:179], v[200:201]
	v_pk_fma_f32 v[158:159], v[198:199], v[176:177], v[202:203]
	v_pk_fma_f32 v[104:105], v[156:157], s[26:27], v[104:105] op_sel_hi:[1,0,1]
	v_pk_fma_f32 v[106:107], v[158:159], s[26:27], v[106:107] op_sel_hi:[1,0,1]
	global_store_dwordx4 v[114:115], v[104:107], off offset:16
	v_cvt_pk_bf16_f32 v176, v104, v105
	v_cvt_pk_bf16_f32 v177, v106, v107
	flat_store_dwordx4 v[118:119], v[174:177]
	global_load_dwordx4 v[156:159], v[114:115], off offset:512
	global_load_dwordx4 v[170:173], v[120:121], off
	s_nop 0
	global_load_dwordx4 v[174:177], v[122:123], off
	global_load_dwordx4 v[178:181], v[114:115], off offset:528
	v_add_f32_e32 v110, v104, v105
	v_mul_f32_e32 v105, v105, v105
	v_fmac_f32_e32 v105, v104, v104
	v_add_f32_e32 v110, v106, v110
	v_fmac_f32_e32 v105, v106, v106
	v_add_f32_e32 v104, v107, v110
	v_fmac_f32_e32 v105, v107, v107
	v_add_f32_e32 v108, v104, v108
	v_add_f32_e32 v109, v109, v105
	global_load_dwordx4 v[196:199], v[124:125], off
	global_load_dwordx4 v[200:203], v[126:127], off
	s_waitcnt vmcnt(0)
	v_sub_f32_e32 v157, v157, v161
	v_sub_f32_e32 v156, v156, v161
	v_sub_f32_e32 v159, v159, v161
	v_sub_f32_e32 v158, v158, v161
	v_pk_mul_f32 v[158:159], v[160:161], v[158:159] op_sel_hi:[0,1]
	v_pk_mul_f32 v[156:157], v[160:161], v[156:157] op_sel_hi:[0,1]
	v_pk_fma_f32 v[156:157], v[170:171], v[156:157], v[174:175]
	v_pk_fma_f32 v[158:159], v[172:173], v[158:159], v[176:177]
	v_pk_fma_f32 v[100:101], v[156:157], s[26:27], v[100:101] op_sel_hi:[1,0,1]
	v_pk_fma_f32 v[102:103], v[158:159], s[26:27], v[102:103] op_sel_hi:[1,0,1]
	global_store_dwordx4 v[114:115], v[100:103], off offset:512
	v_sub_f32_e32 v105, v179, v161
	v_sub_f32_e32 v104, v178, v161
	v_pk_mul_f32 v[104:105], v[160:161], v[104:105] op_sel_hi:[0,1]
	v_sub_f32_e32 v107, v181, v161
	v_sub_f32_e32 v106, v180, v161
	v_pk_mul_f32 v[106:107], v[160:161], v[106:107] op_sel_hi:[0,1]
	v_mul_f32_e32 v111, v101, v101
	v_add_f32_e32 v110, v100, v101
	v_fmac_f32_e32 v111, v100, v100
	v_add_f32_e32 v110, v102, v110
	v_fmac_f32_e32 v111, v102, v102
	v_add_f32_e32 v110, v103, v110
	v_fmac_f32_e32 v111, v103, v103
	v_add_f32_e32 v108, v108, v110
	v_add_f32_e32 v109, v109, v111
	v_cvt_pk_bf16_f32 v100, v100, v101
	v_cvt_pk_bf16_f32 v101, v102, v103
	v_pk_fma_f32 v[104:105], v[196:197], v[104:105], v[200:201]
	s_nop 0
	v_pk_fma_f32 v[104:105], v[104:105], s[26:27], v[96:97] op_sel_hi:[1,0,1]
	v_pk_fma_f32 v[106:107], v[198:199], v[106:107], v[202:203]
	v_mul_f32_e32 v97, v105, v105
	v_pk_fma_f32 v[106:107], v[106:107], s[26:27], v[98:99] op_sel_hi:[1,0,1]
	v_add_f32_e32 v96, v104, v105
	v_fmac_f32_e32 v97, v104, v104
	v_add_f32_e32 v96, v106, v96
	v_fmac_f32_e32 v97, v106, v106
	v_add_f32_e32 v96, v107, v96
	v_fmac_f32_e32 v97, v107, v107
	v_add_f32_e32 v96, v108, v96
	v_add_f32_e32 v97, v109, v97
	ds_bpermute_b32 v98, v116, v96
	ds_bpermute_b32 v99, v116, v97
	global_store_dwordx4 v[114:115], v[104:107], off offset:528
	v_cvt_pk_bf16_f32 v102, v104, v105
	v_cvt_pk_bf16_f32 v103, v106, v107
	s_waitcnt lgkmcnt(0)
	v_add_f32_e32 v96, v96, v98
	v_add_f32_e32 v97, v97, v99
	ds_bpermute_b32 v98, v117, v96
	ds_bpermute_b32 v99, v117, v97
	flat_store_dwordx4 v[118:119], v[100:103] offset:256
	s_and_saveexec_b64 s[30:31], s[2:3]
	s_cbranch_execz .LBB0_2196
	s_waitcnt lgkmcnt(0)
	v_add_f32_e32 v99, v97, v99
	v_add_f32_e32 v98, v96, v98
	v_lshl_add_u64 v[96:97], s[10:11], 0, v[112:113]
	flat_atomic_add_f32 v[96:97], v98
	flat_atomic_add_f32 v[96:97], v99 offset:4
; DEVI unsigned pk2(float lo, float hi) { unsigned r; asm("v_cvt_pk_bf16_f32 %0, %1, %2" : "=v"(r) : "v"(lo), "v"(hi)); return r; }
; DEVI void row_stats(const float* stats, int row, float& mu, float& rs) {
;     if (stats) { const float2 st = *(const float2*)(stats + 2 * (size_t)row); mu = st.x * (1.0f / 1024.0f); const float var = st.y * (1.0f / 1024.0f) - mu * mu; rs = rsqrtf(fmaxf(var, 0.f) + LN_EPS); }
;     DEVI void operator()(const f32x4 (&acc)[2][2][4][2], const pg8::Unit& u, int wr, int wc, int fr, int fq) const {
;     ...
;                 const int row = row0 + ai * 128 + m * 16; float mu, rs; row_stats(stin, row, mu, rs);
;                 float sum = 0.f, sq = 0.f;
; #pragma unroll
;                 for (int bj = 0; bj < 2; ++bj) {
;                     f32x4 z[2];
; #pragma unroll
;                     for (int n = 0; n < 2; ++n) {
;                         const int col = colb + bj * 128 + 4 * n;
;                         f32x4 xv = *(const f32x4*)(zsrc + (size_t)row * DM + col);
;                         if (stin) { const f32x4 gv = *(const f32x4*)(gin + col), bv = *(const f32x4*)(bin + col); xv = (xv - mu) * rs * gv + bv; }
;                         f32x4 zz = ALPHA * xv + acc[ai][bj][m][n];
;                         if (bias) zz += *(const f32x4*)(bias + col);
;                         *(f32x4*)(zdst + (size_t)row * DM + col) = zz;
;                         sum += zz[0] + zz[1] + zz[2] + zz[3]; sq += zz[0] * zz[0] + zz[1] * zz[1] + zz[2] * zz[2] + zz[3] * zz[3];
;                         z[n] = zz;
;                     }
;                     u32x4 o; o.x = pk2(z[0][0], z[0][1]); o.y = pk2(z[0][2], z[0][3]); o.z = pk2(z[1][0], z[1][1]); o.w = pk2(z[1][2], z[1][3]);
;                     if (zb) *(u32x4*)(zb + (size_t)row * DM + colb + bj * 128) = o;
;                 }
;                 sum += __shfl_xor(sum, 16); sq += __shfl_xor(sq, 16);
;                 sum += __shfl_xor(sum, 32); sq += __shfl_xor(sq, 32);
;                 if (fq == 0) { atomicAdd(stout + 2 * (size_t)row, sum); atomicAdd(stout + 2 * (size_t)row + 1, sq); }
.LBB0_2196:
	s_or_b64 exec, exec, s[30:31]
	v_or_b32_e32 v118, 32, v154
	v_ashrrev_i32_e32 v119, 31, v118
	v_lshlrev_b64 v[96:97], 3, v[118:119]
	s_waitcnt lgkmcnt(0)
	v_lshl_add_u64 v[98:99], s[12:13], 0, v[96:97]
	flat_load_dwordx2 v[156:157], v[98:99]
	v_lshlrev_b64 v[98:99], 12, v[118:119]
	v_lshl_add_u64 v[98:99], s[46:47], 0, v[98:99]
	v_lshl_add_u64 v[98:99], v[144:145], 2, v[98:99]
	global_load_dwordx4 v[100:103], v[98:99], off
	global_load_dwordx4 v[104:107], v[150:151], off
	global_load_dwordx4 v[108:111], v[152:153], off
	global_load_dwordx4 v[112:115], v[98:99], off offset:16
	global_load_dwordx4 v[196:199], v[146:147], off
	global_load_dwordx4 v[200:203], v[148:149], off
	s_waitcnt vmcnt(0) lgkmcnt(0)
	v_pk_mul_f32 v[156:157], v[156:157], s[24:25] op_sel:[1,0] op_sel_hi:[0,0]
	v_fma_f32 v155, -v157, v157, v156
	v_max_f32_e32 v155, 0, v155
	v_add_f32_e32 v155, 0x3727c5ac, v155
	v_mul_f32_e32 v156, 0x4b800000, v155
	v_cmp_gt_f32_e32 vcc, s61, v155
	v_sub_f32_e32 v101, v101, v157
	v_sub_f32_e32 v100, v100, v157
	v_cndmask_b32_e32 v155, v155, v156, vcc
	v_rsq_f32_e32 v155, v155
	v_sub_f32_e32 v103, v103, v157
	v_sub_f32_e32 v102, v102, v157
	v_mul_f32_e32 v156, 0x45800000, v155
	v_cndmask_b32_e32 v156, v155, v156, vcc
	v_pk_mul_f32 v[102:103], v[102:103], v[156:157] op_sel_hi:[1,0]
	v_pk_mul_f32 v[100:101], v[100:101], v[156:157] op_sel_hi:[1,0]
	v_pk_fma_f32 v[102:103], v[106:107], v[102:103], v[110:111]
	v_pk_fma_f32 v[100:101], v[104:105], v[100:101], v[108:109]
	v_pk_fma_f32 v[94:95], v[102:103], s[26:27], v[94:95] op_sel_hi:[1,0,1]
	v_pk_fma_f32 v[92:93], v[100:101], s[26:27], v[92:93] op_sel_hi:[1,0,1]
	global_store_dwordx4 v[98:99], v[92:95], off
	v_lshlrev_b64 v[108:109], 11, v[118:119]
	v_lshl_add_u64 v[108:109], s[14:15], 0, v[108:109]
	v_lshl_add_u64 v[118:119], v[144:145], 1, v[108:109]
	v_sub_f32_e32 v109, v113, v157
	v_sub_f32_e32 v108, v112, v157
	v_sub_f32_e32 v111, v115, v157
	v_sub_f32_e32 v110, v114, v157
	v_pk_mul_f32 v[110:111], v[110:111], v[156:157] op_sel_hi:[1,0]
	v_pk_mul_f32 v[112:113], v[108:109], v[156:157] op_sel_hi:[1,0]
	v_cvt_pk_bf16_f32 v108, v92, v93
	v_cvt_pk_bf16_f32 v109, v94, v95
	v_pk_fma_f32 v[102:103], v[198:199], v[110:111], v[202:203]
	v_pk_fma_f32 v[100:101], v[196:197], v[112:113], v[200:201]
	v_pk_fma_f32 v[90:91], v[102:103], s[26:27], v[90:91] op_sel_hi:[1,0,1]
	v_pk_fma_f32 v[88:89], v[100:101], s[26:27], v[88:89] op_sel_hi:[1,0,1]
	global_store_dwordx4 v[98:99], v[88:91], off offset:16
	v_cvt_pk_bf16_f32 v110, v88, v89
	v_cvt_pk_bf16_f32 v111, v90, v91
	flat_store_dwordx4 v[118:119], v[108:111]
	global_load_dwordx4 v[100:103], v[98:99], off offset:512
	global_load_dwordx4 v[104:107], v[120:121], off
	s_nop 0
	global_load_dwordx4 v[108:111], v[122:123], off
	global_load_dwordx4 v[112:115], v[98:99], off offset:528
	global_load_dwordx4 v[196:199], v[124:125], off
	global_load_dwordx4 v[200:203], v[126:127], off
	s_waitcnt vmcnt(0)
	v_sub_f32_e32 v101, v101, v157
	v_sub_f32_e32 v100, v100, v157
	v_sub_f32_e32 v103, v103, v157
	v_sub_f32_e32 v102, v102, v157
	v_pk_mul_f32 v[102:103], v[156:157], v[102:103] op_sel_hi:[0,1]
	v_pk_mul_f32 v[100:101], v[156:157], v[100:101] op_sel_hi:[0,1]
	v_pk_fma_f32 v[100:101], v[104:105], v[100:101], v[108:109]
	v_pk_fma_f32 v[102:103], v[106:107], v[102:103], v[110:111]
	v_pk_fma_f32 v[84:85], v[100:101], s[26:27], v[84:85] op_sel_hi:[1,0,1]
	v_pk_fma_f32 v[86:87], v[102:103], s[26:27], v[86:87] op_sel_hi:[1,0,1]
	global_store_dwordx4 v[98:99], v[84:87], off offset:512
	v_add_f32_e32 v108, v92, v93
	v_mul_f32_e32 v93, v93, v93
	v_fmac_f32_e32 v93, v92, v92
	v_add_f32_e32 v108, v94, v108
	v_fmac_f32_e32 v93, v94, v94
	v_add_f32_e32 v94, v88, v89
	v_mul_f32_e32 v89, v89, v89
	v_fmac_f32_e32 v89, v88, v88
	v_add_f32_e32 v92, v95, v108
	v_add_f32_e32 v94, v90, v94
	v_fmac_f32_e32 v89, v90, v90
	v_add_f32_e32 v92, 0, v92
	v_fmac_f32_e32 v93, v95, v95
	v_add_f32_e32 v88, v91, v94
	v_fmac_f32_e32 v89, v91, v91
	v_add_f32_e32 v92, v88, v92
	v_add_f32_e32 v93, v93, v89
	v_sub_f32_e32 v89, v113, v157
	v_sub_f32_e32 v88, v112, v157
	v_pk_mul_f32 v[88:89], v[156:157], v[88:89] op_sel_hi:[0,1]
	v_sub_f32_e32 v91, v115, v157
	v_sub_f32_e32 v90, v114, v157
	v_pk_mul_f32 v[90:91], v[156:157], v[90:91] op_sel_hi:[0,1]
	v_mul_f32_e32 v95, v85, v85
	v_add_f32_e32 v94, v84, v85
	v_fmac_f32_e32 v95, v84, v84
	v_add_f32_e32 v94, v86, v94
	v_fmac_f32_e32 v95, v86, v86
	v_add_f32_e32 v94, v87, v94
	v_fmac_f32_e32 v95, v87, v87
	v_add_f32_e32 v92, v92, v94
	v_add_f32_e32 v93, v93, v95
	v_cvt_pk_bf16_f32 v84, v84, v85
	v_cvt_pk_bf16_f32 v85, v86, v87
	v_pk_fma_f32 v[88:89], v[196:197], v[88:89], v[200:201]
	s_nop 0
	v_pk_fma_f32 v[88:89], v[88:89], s[26:27], v[80:81] op_sel_hi:[1,0,1]
	v_pk_fma_f32 v[90:91], v[198:199], v[90:91], v[202:203]
	v_mul_f32_e32 v81, v89, v89
	v_pk_fma_f32 v[90:91], v[90:91], s[26:27], v[82:83] op_sel_hi:[1,0,1]
	v_add_f32_e32 v80, v88, v89
	v_fmac_f32_e32 v81, v88, v88
	v_add_f32_e32 v80, v90, v80
	v_fmac_f32_e32 v81, v90, v90
	v_add_f32_e32 v80, v91, v80
	v_fmac_f32_e32 v81, v91, v91
	v_add_f32_e32 v80, v92, v80
	v_add_f32_e32 v81, v93, v81
	ds_bpermute_b32 v82, v116, v80
	ds_bpermute_b32 v83, v116, v81
	global_store_dwordx4 v[98:99], v[88:91], off offset:528
	v_cvt_pk_bf16_f32 v86, v88, v89
	v_cvt_pk_bf16_f32 v87, v90, v91
	s_waitcnt lgkmcnt(0)
	v_add_f32_e32 v80, v80, v82
	v_add_f32_e32 v81, v81, v83
	ds_bpermute_b32 v82, v117, v80
	ds_bpermute_b32 v83, v117, v81
	flat_store_dwordx4 v[118:119], v[84:87] offset:256
	s_and_saveexec_b64 s[30:31], s[2:3]
	s_cbranch_execz .LBB0_2198
	s_waitcnt lgkmcnt(0)
	v_add_f32_e32 v83, v81, v83
	v_add_f32_e32 v82, v80, v82
	v_lshl_add_u64 v[80:81], s[10:11], 0, v[96:97]
	flat_atomic_add_f32 v[80:81], v82
	flat_atomic_add_f32 v[80:81], v83 offset:4
; DEVI unsigned pk2(float lo, float hi) { unsigned r; asm("v_cvt_pk_bf16_f32 %0, %1, %2" : "=v"(r) : "v"(lo), "v"(hi)); return r; }
; DEVI void row_stats(const float* stats, int row, float& mu, float& rs) {
;     if (stats) { const float2 st = *(const float2*)(stats + 2 * (size_t)row); mu = st.x * (1.0f / 1024.0f); const float var = st.y * (1.0f / 1024.0f) - mu * mu; rs = rsqrtf(fmaxf(var, 0.f) + LN_EPS); }
;     DEVI void operator()(const f32x4 (&acc)[2][2][4][2], const pg8::Unit& u, int wr, int wc, int fr, int fq) const {
;     ...
;                 const int row = row0 + ai * 128 + m * 16; float mu, rs; row_stats(stin, row, mu, rs);
;                 float sum = 0.f, sq = 0.f;
; #pragma unroll
;                 for (int bj = 0; bj < 2; ++bj) {
;                     f32x4 z[2];
; #pragma unroll
;                     for (int n = 0; n < 2; ++n) {
;                         const int col = colb + bj * 128 + 4 * n;
;                         f32x4 xv = *(const f32x4*)(zsrc + (size_t)row * DM + col);
;                         if (stin) { const f32x4 gv = *(const f32x4*)(gin + col), bv = *(const f32x4*)(bin + col); xv = (xv - mu) * rs * gv + bv; }
;                         f32x4 zz = ALPHA * xv + acc[ai][bj][m][n];
;                         if (bias) zz += *(const f32x4*)(bias + col);
;                         *(f32x4*)(zdst + (size_t)row * DM + col) = zz;
;                         sum += zz[0] + zz[1] + zz[2] + zz[3]; sq += zz[0] * zz[0] + zz[1] * zz[1] + zz[2] * zz[2] + zz[3] * zz[3];
;                         z[n] = zz;
;                     }
;                     u32x4 o; o.x = pk2(z[0][0], z[0][1]); o.y = pk2(z[0][2], z[0][3]); o.z = pk2(z[1][0], z[1][1]); o.w = pk2(z[1][2], z[1][3]);
;                     if (zb) *(u32x4*)(zb + (size_t)row * DM + colb + bj * 128) = o;
;                 }
;                 sum += __shfl_xor(sum, 16); sq += __shfl_xor(sq, 16);
;                 sum += __shfl_xor(sum, 32); sq += __shfl_xor(sq, 32);
;                 if (fq == 0) { atomicAdd(stout + 2 * (size_t)row, sum); atomicAdd(stout + 2 * (size_t)row + 1, sq); }
.LBB0_2198:
	s_or_b64 exec, exec, s[30:31]
	v_or_b32_e32 v100, 48, v154
	v_ashrrev_i32_e32 v101, 31, v100
	v_lshlrev_b64 v[80:81], 3, v[100:101]
	s_waitcnt lgkmcnt(0)
	v_lshl_add_u64 v[82:83], s[12:13], 0, v[80:81]
	flat_load_dwordx2 v[102:103], v[82:83]
	v_lshlrev_b64 v[82:83], 12, v[100:101]
	v_lshl_add_u64 v[82:83], s[46:47], 0, v[82:83]
	v_lshl_add_u64 v[82:83], v[144:145], 2, v[82:83]
	global_load_dwordx4 v[84:87], v[82:83], off
	global_load_dwordx4 v[88:91], v[150:151], off
	global_load_dwordx4 v[92:95], v[152:153], off
	global_load_dwordx4 v[96:99], v[82:83], off offset:16
	global_load_dwordx4 v[196:199], v[146:147], off
	global_load_dwordx4 v[200:203], v[148:149], off
	s_waitcnt vmcnt(0) lgkmcnt(0)
	v_pk_mul_f32 v[102:103], v[102:103], s[24:25] op_sel:[1,0] op_sel_hi:[0,0]
	v_fma_f32 v102, -v103, v103, v102
	v_max_f32_e32 v102, 0, v102
	v_add_f32_e32 v102, 0x3727c5ac, v102
	v_mul_f32_e32 v104, 0x4b800000, v102
	v_cmp_gt_f32_e32 vcc, s61, v102
	v_sub_f32_e32 v85, v85, v103
	v_sub_f32_e32 v84, v84, v103
	v_cndmask_b32_e32 v102, v102, v104, vcc
	v_rsq_f32_e32 v102, v102
	v_sub_f32_e32 v87, v87, v103
	v_sub_f32_e32 v86, v86, v103
	v_mul_f32_e32 v104, 0x45800000, v102
	v_cndmask_b32_e32 v102, v102, v104, vcc
	v_pk_mul_f32 v[86:87], v[86:87], v[102:103] op_sel_hi:[1,0]
	v_pk_mul_f32 v[84:85], v[84:85], v[102:103] op_sel_hi:[1,0]
	v_pk_fma_f32 v[86:87], v[90:91], v[86:87], v[94:95]
	v_pk_fma_f32 v[84:85], v[88:89], v[84:85], v[92:93]
	v_pk_fma_f32 v[78:79], v[86:87], s[26:27], v[78:79] op_sel_hi:[1,0,1]
	v_pk_fma_f32 v[76:77], v[84:85], s[26:27], v[76:77] op_sel_hi:[1,0,1]
	global_store_dwordx4 v[82:83], v[76:79], off
	v_lshlrev_b64 v[92:93], 11, v[100:101]
	v_lshl_add_u64 v[92:93], s[14:15], 0, v[92:93]
	v_lshl_add_u64 v[100:101], v[144:145], 1, v[92:93]
	v_sub_f32_e32 v93, v97, v103
	v_sub_f32_e32 v92, v96, v103
	v_sub_f32_e32 v95, v99, v103
	v_sub_f32_e32 v94, v98, v103
	v_pk_mul_f32 v[94:95], v[94:95], v[102:103] op_sel_hi:[1,0]
	v_pk_mul_f32 v[96:97], v[92:93], v[102:103] op_sel_hi:[1,0]
	v_cvt_pk_bf16_f32 v92, v76, v77
	v_cvt_pk_bf16_f32 v93, v78, v79
	v_pk_fma_f32 v[86:87], v[198:199], v[94:95], v[202:203]
	v_pk_fma_f32 v[84:85], v[196:197], v[96:97], v[200:201]
	v_pk_fma_f32 v[74:75], v[86:87], s[26:27], v[74:75] op_sel_hi:[1,0,1]
	v_pk_fma_f32 v[72:73], v[84:85], s[26:27], v[72:73] op_sel_hi:[1,0,1]
	global_store_dwordx4 v[82:83], v[72:75], off offset:16
	v_cvt_pk_bf16_f32 v94, v72, v73
	v_cvt_pk_bf16_f32 v95, v74, v75
	flat_store_dwordx4 v[100:101], v[92:95]
	global_load_dwordx4 v[84:87], v[82:83], off offset:512
	global_load_dwordx4 v[88:91], v[120:121], off
	s_nop 0
	global_load_dwordx4 v[92:95], v[122:123], off
	global_load_dwordx4 v[96:99], v[82:83], off offset:528
	global_load_dwordx4 v[196:199], v[124:125], off
	global_load_dwordx4 v[200:203], v[126:127], off
	s_waitcnt vmcnt(0)
	v_sub_f32_e32 v85, v85, v103
	v_sub_f32_e32 v84, v84, v103
	v_sub_f32_e32 v87, v87, v103
	v_sub_f32_e32 v86, v86, v103
	v_pk_mul_f32 v[86:87], v[102:103], v[86:87] op_sel_hi:[0,1]
	v_pk_mul_f32 v[84:85], v[102:103], v[84:85] op_sel_hi:[0,1]
	v_pk_fma_f32 v[84:85], v[88:89], v[84:85], v[92:93]
	v_pk_fma_f32 v[86:87], v[90:91], v[86:87], v[94:95]
	v_pk_fma_f32 v[68:69], v[84:85], s[26:27], v[68:69] op_sel_hi:[1,0,1]
	v_pk_fma_f32 v[70:71], v[86:87], s[26:27], v[70:71] op_sel_hi:[1,0,1]
	global_store_dwordx4 v[82:83], v[68:71], off offset:512
	v_add_f32_e32 v92, v76, v77
	v_mul_f32_e32 v77, v77, v77
	v_fmac_f32_e32 v77, v76, v76
	v_add_f32_e32 v92, v78, v92
	v_fmac_f32_e32 v77, v78, v78
	v_add_f32_e32 v78, v72, v73
	v_mul_f32_e32 v73, v73, v73
	v_fmac_f32_e32 v73, v72, v72
	v_add_f32_e32 v76, v79, v92
	v_add_f32_e32 v78, v74, v78
	v_fmac_f32_e32 v73, v74, v74
	v_add_f32_e32 v76, 0, v76
	v_fmac_f32_e32 v77, v79, v79
	v_add_f32_e32 v72, v75, v78
	v_fmac_f32_e32 v73, v75, v75
	v_add_f32_e32 v76, v72, v76
	v_add_f32_e32 v77, v77, v73
	v_sub_f32_e32 v73, v97, v103
	v_sub_f32_e32 v72, v96, v103
	v_pk_mul_f32 v[72:73], v[102:103], v[72:73] op_sel_hi:[0,1]
	v_sub_f32_e32 v75, v99, v103
	v_sub_f32_e32 v74, v98, v103
	v_pk_mul_f32 v[74:75], v[102:103], v[74:75] op_sel_hi:[0,1]
	v_mul_f32_e32 v79, v69, v69
	v_add_f32_e32 v78, v68, v69
	v_fmac_f32_e32 v79, v68, v68
	v_add_f32_e32 v78, v70, v78
	v_fmac_f32_e32 v79, v70, v70
	v_add_f32_e32 v78, v71, v78
	v_fmac_f32_e32 v79, v71, v71
	v_add_f32_e32 v76, v76, v78
	v_add_f32_e32 v77, v77, v79
	v_cvt_pk_bf16_f32 v68, v68, v69
	v_cvt_pk_bf16_f32 v69, v70, v71
	v_pk_fma_f32 v[72:73], v[196:197], v[72:73], v[200:201]
	s_nop 0
	v_pk_fma_f32 v[72:73], v[72:73], s[26:27], v[64:65] op_sel_hi:[1,0,1]
	v_pk_fma_f32 v[74:75], v[198:199], v[74:75], v[202:203]
	v_mul_f32_e32 v65, v73, v73
	v_pk_fma_f32 v[74:75], v[74:75], s[26:27], v[66:67] op_sel_hi:[1,0,1]
	v_add_f32_e32 v64, v72, v73
	v_fmac_f32_e32 v65, v72, v72
	v_add_f32_e32 v64, v74, v64
	v_fmac_f32_e32 v65, v74, v74
	v_add_f32_e32 v64, v75, v64
	v_fmac_f32_e32 v65, v75, v75
	v_add_f32_e32 v64, v76, v64
	v_add_f32_e32 v65, v77, v65
	ds_bpermute_b32 v66, v116, v64
	ds_bpermute_b32 v67, v116, v65
	global_store_dwordx4 v[82:83], v[72:75], off offset:528
	v_cvt_pk_bf16_f32 v70, v72, v73
	v_cvt_pk_bf16_f32 v71, v74, v75
	s_waitcnt lgkmcnt(0)
	v_add_f32_e32 v64, v64, v66
	v_add_f32_e32 v65, v65, v67
	ds_bpermute_b32 v66, v117, v64
	ds_bpermute_b32 v67, v117, v65
	flat_store_dwordx4 v[100:101], v[68:71] offset:256
	s_and_saveexec_b64 s[30:31], s[2:3]
	s_cbranch_execz .LBB0_2200
	s_waitcnt lgkmcnt(0)
	v_add_f32_e32 v67, v65, v67
	v_add_f32_e32 v66, v64, v66
	v_lshl_add_u64 v[64:65], s[10:11], 0, v[80:81]
	flat_atomic_add_f32 v[64:65], v66
	flat_atomic_add_f32 v[64:65], v67 offset:4
; DEVI unsigned pk2(float lo, float hi) { unsigned r; asm("v_cvt_pk_bf16_f32 %0, %1, %2" : "=v"(r) : "v"(lo), "v"(hi)); return r; }
; DEVI void row_stats(const float* stats, int row, float& mu, float& rs) {
;     if (stats) { const float2 st = *(const float2*)(stats + 2 * (size_t)row); mu = st.x * (1.0f / 1024.0f); const float var = st.y * (1.0f / 1024.0f) - mu * mu; rs = rsqrtf(fmaxf(var, 0.f) + LN_EPS); }
;     DEVI void operator()(const f32x4 (&acc)[2][2][4][2], const pg8::Unit& u, int wr, int wc, int fr, int fq) const {
;     ...
;                 const int row = row0 + ai * 128 + m * 16; float mu, rs; row_stats(stin, row, mu, rs);
;                 float sum = 0.f, sq = 0.f;
; #pragma unroll
;                 for (int bj = 0; bj < 2; ++bj) {
;                     f32x4 z[2];
; #pragma unroll
;                     for (int n = 0; n < 2; ++n) {
;                         const int col = colb + bj * 128 + 4 * n;
;                         f32x4 xv = *(const f32x4*)(zsrc + (size_t)row * DM + col);
;                         if (stin) { const f32x4 gv = *(const f32x4*)(gin + col), bv = *(const f32x4*)(bin + col); xv = (xv - mu) * rs * gv + bv; }
;                         f32x4 zz = ALPHA * xv + acc[ai][bj][m][n];
;                         if (bias) zz += *(const f32x4*)(bias + col);
;                         *(f32x4*)(zdst + (size_t)row * DM + col) = zz;
;                         sum += zz[0] + zz[1] + zz[2] + zz[3]; sq += zz[0] * zz[0] + zz[1] * zz[1] + zz[2] * zz[2] + zz[3] * zz[3];
;                         z[n] = zz;
;                     }
;                     u32x4 o; o.x = pk2(z[0][0], z[0][1]); o.y = pk2(z[0][2], z[0][3]); o.z = pk2(z[1][0], z[1][1]); o.w = pk2(z[1][2], z[1][3]);
;                     if (zb) *(u32x4*)(zb + (size_t)row * DM + colb + bj * 128) = o;
;                 }
;                 sum += __shfl_xor(sum, 16); sq += __shfl_xor(sq, 16);
;                 sum += __shfl_xor(sum, 32); sq += __shfl_xor(sq, 32);
;                 if (fq == 0) { atomicAdd(stout + 2 * (size_t)row, sum); atomicAdd(stout + 2 * (size_t)row + 1, sq); }
.LBB0_2200:
	s_or_b64 exec, exec, s[30:31]
	v_add_u32_e32 v84, 0x80, v154
	v_ashrrev_i32_e32 v85, 31, v84
	v_lshlrev_b64 v[64:65], 3, v[84:85]
	s_waitcnt lgkmcnt(0)
	v_lshl_add_u64 v[66:67], s[12:13], 0, v[64:65]
	flat_load_dwordx2 v[86:87], v[66:67]
	v_lshlrev_b64 v[66:67], 12, v[84:85]
	v_lshl_add_u64 v[66:67], s[46:47], 0, v[66:67]
	v_lshl_add_u64 v[66:67], v[144:145], 2, v[66:67]
	global_load_dwordx4 v[68:71], v[66:67], off
	global_load_dwordx4 v[72:75], v[150:151], off
	global_load_dwordx4 v[76:79], v[152:153], off
	global_load_dwordx4 v[80:83], v[66:67], off offset:16
	global_load_dwordx4 v[196:199], v[146:147], off
	global_load_dwordx4 v[200:203], v[148:149], off
	s_waitcnt vmcnt(0) lgkmcnt(0)
	v_pk_mul_f32 v[86:87], v[86:87], s[24:25] op_sel:[1,0] op_sel_hi:[0,0]
	v_fma_f32 v86, -v87, v87, v86
	v_max_f32_e32 v86, 0, v86
	v_add_f32_e32 v86, 0x3727c5ac, v86
	v_mul_f32_e32 v88, 0x4b800000, v86
	v_cmp_gt_f32_e32 vcc, s61, v86
	v_sub_f32_e32 v69, v69, v87
	v_sub_f32_e32 v68, v68, v87
	v_cndmask_b32_e32 v86, v86, v88, vcc
	v_rsq_f32_e32 v86, v86
	v_sub_f32_e32 v71, v71, v87
	v_sub_f32_e32 v70, v70, v87
	v_mul_f32_e32 v88, 0x45800000, v86
	v_cndmask_b32_e32 v86, v86, v88, vcc
	v_pk_mul_f32 v[70:71], v[70:71], v[86:87] op_sel_hi:[1,0]
	v_pk_mul_f32 v[68:69], v[68:69], v[86:87] op_sel_hi:[1,0]
	v_pk_fma_f32 v[70:71], v[74:75], v[70:71], v[78:79]
	v_pk_fma_f32 v[68:69], v[72:73], v[68:69], v[76:77]
	v_pk_fma_f32 v[62:63], v[70:71], s[26:27], v[62:63] op_sel_hi:[1,0,1]
	v_pk_fma_f32 v[60:61], v[68:69], s[26:27], v[60:61] op_sel_hi:[1,0,1]
	global_store_dwordx4 v[66:67], v[60:63], off
	v_lshlrev_b64 v[76:77], 11, v[84:85]
	v_lshl_add_u64 v[76:77], s[14:15], 0, v[76:77]
	v_lshl_add_u64 v[84:85], v[144:145], 1, v[76:77]
	v_sub_f32_e32 v77, v81, v87
	v_sub_f32_e32 v76, v80, v87
	v_sub_f32_e32 v79, v83, v87
	v_sub_f32_e32 v78, v82, v87
	v_pk_mul_f32 v[78:79], v[78:79], v[86:87] op_sel_hi:[1,0]
	v_pk_mul_f32 v[80:81], v[76:77], v[86:87] op_sel_hi:[1,0]
	v_cvt_pk_bf16_f32 v76, v60, v61
	v_cvt_pk_bf16_f32 v77, v62, v63
	v_pk_fma_f32 v[70:71], v[198:199], v[78:79], v[202:203]
	v_pk_fma_f32 v[68:69], v[196:197], v[80:81], v[200:201]
	v_pk_fma_f32 v[58:59], v[70:71], s[26:27], v[58:59] op_sel_hi:[1,0,1]
	v_pk_fma_f32 v[56:57], v[68:69], s[26:27], v[56:57] op_sel_hi:[1,0,1]
	global_store_dwordx4 v[66:67], v[56:59], off offset:16
	v_cvt_pk_bf16_f32 v78, v56, v57
	v_cvt_pk_bf16_f32 v79, v58, v59
	flat_store_dwordx4 v[84:85], v[76:79]
	global_load_dwordx4 v[68:71], v[66:67], off offset:512
	global_load_dwordx4 v[72:75], v[120:121], off
	s_nop 0
	global_load_dwordx4 v[76:79], v[122:123], off
	global_load_dwordx4 v[80:83], v[66:67], off offset:528
	global_load_dwordx4 v[196:199], v[124:125], off
	global_load_dwordx4 v[200:203], v[126:127], off
	s_waitcnt vmcnt(0)
	v_sub_f32_e32 v69, v69, v87
	v_sub_f32_e32 v68, v68, v87
	v_sub_f32_e32 v71, v71, v87
	v_sub_f32_e32 v70, v70, v87
	v_pk_mul_f32 v[70:71], v[86:87], v[70:71] op_sel_hi:[0,1]
	v_pk_mul_f32 v[68:69], v[86:87], v[68:69] op_sel_hi:[0,1]
	v_pk_fma_f32 v[68:69], v[72:73], v[68:69], v[76:77]
	v_pk_fma_f32 v[70:71], v[74:75], v[70:71], v[78:79]
	v_pk_fma_f32 v[52:53], v[68:69], s[26:27], v[52:53] op_sel_hi:[1,0,1]
	v_pk_fma_f32 v[54:55], v[70:71], s[26:27], v[54:55] op_sel_hi:[1,0,1]
	global_store_dwordx4 v[66:67], v[52:55], off offset:512
	v_add_f32_e32 v76, v60, v61
	v_mul_f32_e32 v61, v61, v61
	v_fmac_f32_e32 v61, v60, v60
	v_add_f32_e32 v76, v62, v76
	v_fmac_f32_e32 v61, v62, v62
	v_add_f32_e32 v62, v56, v57
	v_mul_f32_e32 v57, v57, v57
	v_fmac_f32_e32 v57, v56, v56
	v_add_f32_e32 v60, v63, v76
	v_add_f32_e32 v62, v58, v62
	v_fmac_f32_e32 v57, v58, v58
	v_add_f32_e32 v60, 0, v60
	v_fmac_f32_e32 v61, v63, v63
	v_add_f32_e32 v56, v59, v62
	v_fmac_f32_e32 v57, v59, v59
	v_add_f32_e32 v60, v56, v60
	v_add_f32_e32 v61, v61, v57
	v_sub_f32_e32 v57, v81, v87
	v_sub_f32_e32 v56, v80, v87
	v_pk_mul_f32 v[56:57], v[86:87], v[56:57] op_sel_hi:[0,1]
	v_sub_f32_e32 v59, v83, v87
	v_sub_f32_e32 v58, v82, v87
	v_pk_mul_f32 v[58:59], v[86:87], v[58:59] op_sel_hi:[0,1]
	v_mul_f32_e32 v63, v53, v53
	v_add_f32_e32 v62, v52, v53
	v_fmac_f32_e32 v63, v52, v52
	v_add_f32_e32 v62, v54, v62
	v_fmac_f32_e32 v63, v54, v54
	v_add_f32_e32 v62, v55, v62
	v_fmac_f32_e32 v63, v55, v55
	v_add_f32_e32 v60, v60, v62
	v_add_f32_e32 v61, v61, v63
	v_cvt_pk_bf16_f32 v52, v52, v53
	v_cvt_pk_bf16_f32 v53, v54, v55
	v_pk_fma_f32 v[56:57], v[196:197], v[56:57], v[200:201]
	s_nop 0
	v_pk_fma_f32 v[56:57], v[56:57], s[26:27], v[48:49] op_sel_hi:[1,0,1]
	v_pk_fma_f32 v[58:59], v[198:199], v[58:59], v[202:203]
	v_mul_f32_e32 v49, v57, v57
	v_pk_fma_f32 v[58:59], v[58:59], s[26:27], v[50:51] op_sel_hi:[1,0,1]
	v_add_f32_e32 v48, v56, v57
	v_fmac_f32_e32 v49, v56, v56
	v_add_f32_e32 v48, v58, v48
	v_fmac_f32_e32 v49, v58, v58
	v_add_f32_e32 v48, v59, v48
	v_fmac_f32_e32 v49, v59, v59
	v_add_f32_e32 v48, v60, v48
	v_add_f32_e32 v49, v61, v49
	ds_bpermute_b32 v50, v116, v48
	ds_bpermute_b32 v51, v116, v49
	global_store_dwordx4 v[66:67], v[56:59], off offset:528
	v_cvt_pk_bf16_f32 v54, v56, v57
	v_cvt_pk_bf16_f32 v55, v58, v59
	s_waitcnt lgkmcnt(0)
	v_add_f32_e32 v48, v48, v50
	v_add_f32_e32 v49, v49, v51
	ds_bpermute_b32 v50, v117, v48
	ds_bpermute_b32 v51, v117, v49
	flat_store_dwordx4 v[84:85], v[52:55] offset:256
	s_and_saveexec_b64 s[30:31], s[2:3]
	s_cbranch_execz .LBB0_2202
	s_waitcnt lgkmcnt(0)
	v_add_f32_e32 v51, v49, v51
	v_add_f32_e32 v50, v48, v50
	v_lshl_add_u64 v[48:49], s[10:11], 0, v[64:65]
	flat_atomic_add_f32 v[48:49], v50
	flat_atomic_add_f32 v[48:49], v51 offset:4
; DEVI unsigned pk2(float lo, float hi) { unsigned r; asm("v_cvt_pk_bf16_f32 %0, %1, %2" : "=v"(r) : "v"(lo), "v"(hi)); return r; }
; DEVI void row_stats(const float* stats, int row, float& mu, float& rs) {
;     if (stats) { const float2 st = *(const float2*)(stats + 2 * (size_t)row); mu = st.x * (1.0f / 1024.0f); const float var = st.y * (1.0f / 1024.0f) - mu * mu; rs = rsqrtf(fmaxf(var, 0.f) + LN_EPS); }
;     DEVI void operator()(const f32x4 (&acc)[2][2][4][2], const pg8::Unit& u, int wr, int wc, int fr, int fq) const {
;     ...
;                 const int row = row0 + ai * 128 + m * 16; float mu, rs; row_stats(stin, row, mu, rs);
;                 float sum = 0.f, sq = 0.f;
; #pragma unroll
;                 for (int bj = 0; bj < 2; ++bj) {
;                     f32x4 z[2];
; #pragma unroll
;                     for (int n = 0; n < 2; ++n) {
;                         const int col = colb + bj * 128 + 4 * n;
;                         f32x4 xv = *(const f32x4*)(zsrc + (size_t)row * DM + col);
;                         if (stin) { const f32x4 gv = *(const f32x4*)(gin + col), bv = *(const f32x4*)(bin + col); xv = (xv - mu) * rs * gv + bv; }
;                         f32x4 zz = ALPHA * xv + acc[ai][bj][m][n];
;                         if (bias) zz += *(const f32x4*)(bias + col);
;                         *(f32x4*)(zdst + (size_t)row * DM + col) = zz;
;                         sum += zz[0] + zz[1] + zz[2] + zz[3]; sq += zz[0] * zz[0] + zz[1] * zz[1] + zz[2] * zz[2] + zz[3] * zz[3];
;                         z[n] = zz;
;                     }
;                     u32x4 o; o.x = pk2(z[0][0], z[0][1]); o.y = pk2(z[0][2], z[0][3]); o.z = pk2(z[1][0], z[1][1]); o.w = pk2(z[1][2], z[1][3]);
;                     if (zb) *(u32x4*)(zb + (size_t)row * DM + colb + bj * 128) = o;
;                 }
;                 sum += __shfl_xor(sum, 16); sq += __shfl_xor(sq, 16);
;                 sum += __shfl_xor(sum, 32); sq += __shfl_xor(sq, 32);
;                 if (fq == 0) { atomicAdd(stout + 2 * (size_t)row, sum); atomicAdd(stout + 2 * (size_t)row + 1, sq); }
.LBB0_2202:
	s_or_b64 exec, exec, s[30:31]
	v_add_u32_e32 v68, 0x90, v154
	v_ashrrev_i32_e32 v69, 31, v68
	v_lshlrev_b64 v[48:49], 3, v[68:69]
	s_waitcnt lgkmcnt(0)
	v_lshl_add_u64 v[50:51], s[12:13], 0, v[48:49]
	flat_load_dwordx2 v[70:71], v[50:51]
	v_lshlrev_b64 v[50:51], 12, v[68:69]
	v_lshl_add_u64 v[50:51], s[46:47], 0, v[50:51]
	v_lshl_add_u64 v[50:51], v[144:145], 2, v[50:51]
	global_load_dwordx4 v[52:55], v[50:51], off
	global_load_dwordx4 v[56:59], v[150:151], off
	global_load_dwordx4 v[60:63], v[152:153], off
	global_load_dwordx4 v[64:67], v[50:51], off offset:16
	global_load_dwordx4 v[196:199], v[146:147], off
	global_load_dwordx4 v[200:203], v[148:149], off
	s_waitcnt vmcnt(0) lgkmcnt(0)
	v_pk_mul_f32 v[70:71], v[70:71], s[24:25] op_sel:[1,0] op_sel_hi:[0,0]
	v_fma_f32 v70, -v71, v71, v70
	v_max_f32_e32 v70, 0, v70
	v_add_f32_e32 v70, 0x3727c5ac, v70
	v_mul_f32_e32 v72, 0x4b800000, v70
	v_cmp_gt_f32_e32 vcc, s61, v70
	v_sub_f32_e32 v53, v53, v71
	v_sub_f32_e32 v52, v52, v71
	v_cndmask_b32_e32 v70, v70, v72, vcc
	v_rsq_f32_e32 v70, v70
	v_sub_f32_e32 v55, v55, v71
	v_sub_f32_e32 v54, v54, v71
	v_mul_f32_e32 v72, 0x45800000, v70
	v_cndmask_b32_e32 v70, v70, v72, vcc
	v_pk_mul_f32 v[54:55], v[54:55], v[70:71] op_sel_hi:[1,0]
	v_pk_mul_f32 v[52:53], v[52:53], v[70:71] op_sel_hi:[1,0]
	v_pk_fma_f32 v[54:55], v[58:59], v[54:55], v[62:63]
	v_pk_fma_f32 v[52:53], v[56:57], v[52:53], v[60:61]
	v_pk_fma_f32 v[46:47], v[54:55], s[26:27], v[46:47] op_sel_hi:[1,0,1]
	v_pk_fma_f32 v[44:45], v[52:53], s[26:27], v[44:45] op_sel_hi:[1,0,1]
	global_store_dwordx4 v[50:51], v[44:47], off
	v_lshlrev_b64 v[60:61], 11, v[68:69]
	v_lshl_add_u64 v[60:61], s[14:15], 0, v[60:61]
	v_lshl_add_u64 v[68:69], v[144:145], 1, v[60:61]
	v_sub_f32_e32 v61, v65, v71
	v_sub_f32_e32 v60, v64, v71
	v_sub_f32_e32 v63, v67, v71
	v_sub_f32_e32 v62, v66, v71
	v_pk_mul_f32 v[62:63], v[62:63], v[70:71] op_sel_hi:[1,0]
	v_pk_mul_f32 v[64:65], v[60:61], v[70:71] op_sel_hi:[1,0]
	v_cvt_pk_bf16_f32 v60, v44, v45
	v_cvt_pk_bf16_f32 v61, v46, v47
	v_pk_fma_f32 v[54:55], v[198:199], v[62:63], v[202:203]
	v_pk_fma_f32 v[52:53], v[196:197], v[64:65], v[200:201]
	v_pk_fma_f32 v[42:43], v[54:55], s[26:27], v[42:43] op_sel_hi:[1,0,1]
	v_pk_fma_f32 v[40:41], v[52:53], s[26:27], v[40:41] op_sel_hi:[1,0,1]
	global_store_dwordx4 v[50:51], v[40:43], off offset:16
	v_cvt_pk_bf16_f32 v62, v40, v41
	v_cvt_pk_bf16_f32 v63, v42, v43
	flat_store_dwordx4 v[68:69], v[60:63]
	global_load_dwordx4 v[52:55], v[50:51], off offset:512
	global_load_dwordx4 v[56:59], v[120:121], off
	s_nop 0
	global_load_dwordx4 v[60:63], v[122:123], off
	global_load_dwordx4 v[64:67], v[50:51], off offset:528
	global_load_dwordx4 v[196:199], v[124:125], off
	global_load_dwordx4 v[200:203], v[126:127], off
	s_waitcnt vmcnt(0)
	v_sub_f32_e32 v53, v53, v71
	v_sub_f32_e32 v52, v52, v71
	v_sub_f32_e32 v55, v55, v71
	v_sub_f32_e32 v54, v54, v71
	v_pk_mul_f32 v[54:55], v[70:71], v[54:55] op_sel_hi:[0,1]
	v_pk_mul_f32 v[52:53], v[70:71], v[52:53] op_sel_hi:[0,1]
	v_pk_fma_f32 v[52:53], v[56:57], v[52:53], v[60:61]
	v_pk_fma_f32 v[54:55], v[58:59], v[54:55], v[62:63]
	v_pk_fma_f32 v[36:37], v[52:53], s[26:27], v[36:37] op_sel_hi:[1,0,1]
	v_pk_fma_f32 v[38:39], v[54:55], s[26:27], v[38:39] op_sel_hi:[1,0,1]
	global_store_dwordx4 v[50:51], v[36:39], off offset:512
	v_add_f32_e32 v60, v44, v45
	v_mul_f32_e32 v45, v45, v45
	v_fmac_f32_e32 v45, v44, v44
	v_add_f32_e32 v60, v46, v60
	v_fmac_f32_e32 v45, v46, v46
	v_add_f32_e32 v46, v40, v41
	v_mul_f32_e32 v41, v41, v41
	v_fmac_f32_e32 v41, v40, v40
	v_add_f32_e32 v44, v47, v60
	v_add_f32_e32 v46, v42, v46
	v_fmac_f32_e32 v41, v42, v42
	v_add_f32_e32 v44, 0, v44
	v_fmac_f32_e32 v45, v47, v47
	v_add_f32_e32 v40, v43, v46
	v_fmac_f32_e32 v41, v43, v43
	v_add_f32_e32 v44, v40, v44
	v_add_f32_e32 v45, v45, v41
	v_sub_f32_e32 v41, v65, v71
	v_sub_f32_e32 v40, v64, v71
	v_pk_mul_f32 v[40:41], v[70:71], v[40:41] op_sel_hi:[0,1]
	v_sub_f32_e32 v43, v67, v71
	v_sub_f32_e32 v42, v66, v71
	v_pk_mul_f32 v[42:43], v[70:71], v[42:43] op_sel_hi:[0,1]
	v_mul_f32_e32 v47, v37, v37
	v_add_f32_e32 v46, v36, v37
	v_fmac_f32_e32 v47, v36, v36
	v_add_f32_e32 v46, v38, v46
	v_fmac_f32_e32 v47, v38, v38
	v_add_f32_e32 v46, v39, v46
	v_fmac_f32_e32 v47, v39, v39
	v_add_f32_e32 v44, v44, v46
	v_add_f32_e32 v45, v45, v47
	v_cvt_pk_bf16_f32 v36, v36, v37
	v_cvt_pk_bf16_f32 v37, v38, v39
	v_pk_fma_f32 v[40:41], v[196:197], v[40:41], v[200:201]
	s_nop 0
	v_pk_fma_f32 v[40:41], v[40:41], s[26:27], v[32:33] op_sel_hi:[1,0,1]
	v_pk_fma_f32 v[42:43], v[198:199], v[42:43], v[202:203]
	v_mul_f32_e32 v33, v41, v41
	v_pk_fma_f32 v[42:43], v[42:43], s[26:27], v[34:35] op_sel_hi:[1,0,1]
	v_add_f32_e32 v32, v40, v41
	v_fmac_f32_e32 v33, v40, v40
	v_add_f32_e32 v32, v42, v32
	v_fmac_f32_e32 v33, v42, v42
	v_add_f32_e32 v32, v43, v32
	v_fmac_f32_e32 v33, v43, v43
	v_add_f32_e32 v32, v44, v32
	v_add_f32_e32 v33, v45, v33
	ds_bpermute_b32 v34, v116, v32
	ds_bpermute_b32 v35, v116, v33
	global_store_dwordx4 v[50:51], v[40:43], off offset:528
	v_cvt_pk_bf16_f32 v38, v40, v41
	v_cvt_pk_bf16_f32 v39, v42, v43
	s_waitcnt lgkmcnt(0)
	v_add_f32_e32 v32, v32, v34
	v_add_f32_e32 v33, v33, v35
	ds_bpermute_b32 v34, v117, v32
	ds_bpermute_b32 v35, v117, v33
	flat_store_dwordx4 v[68:69], v[36:39] offset:256
	s_and_saveexec_b64 s[30:31], s[2:3]
	s_cbranch_execz .LBB0_2204
	s_waitcnt lgkmcnt(0)
	v_add_f32_e32 v35, v33, v35
	v_add_f32_e32 v34, v32, v34
	v_lshl_add_u64 v[32:33], s[10:11], 0, v[48:49]
	flat_atomic_add_f32 v[32:33], v34
	flat_atomic_add_f32 v[32:33], v35 offset:4
; DEVI unsigned pk2(float lo, float hi) { unsigned r; asm("v_cvt_pk_bf16_f32 %0, %1, %2" : "=v"(r) : "v"(lo), "v"(hi)); return r; }
; DEVI void row_stats(const float* stats, int row, float& mu, float& rs) {
;     if (stats) { const float2 st = *(const float2*)(stats + 2 * (size_t)row); mu = st.x * (1.0f / 1024.0f); const float var = st.y * (1.0f / 1024.0f) - mu * mu; rs = rsqrtf(fmaxf(var, 0.f) + LN_EPS); }
;     DEVI void operator()(const f32x4 (&acc)[2][2][4][2], const pg8::Unit& u, int wr, int wc, int fr, int fq) const {
;     ...
;                 const int row = row0 + ai * 128 + m * 16; float mu, rs; row_stats(stin, row, mu, rs);
;                 float sum = 0.f, sq = 0.f;
; #pragma unroll
;                 for (int bj = 0; bj < 2; ++bj) {
;                     f32x4 z[2];
; #pragma unroll
;                     for (int n = 0; n < 2; ++n) {
;                         const int col = colb + bj * 128 + 4 * n;
;                         f32x4 xv = *(const f32x4*)(zsrc + (size_t)row * DM + col);
;                         if (stin) { const f32x4 gv = *(const f32x4*)(gin + col), bv = *(const f32x4*)(bin + col); xv = (xv - mu) * rs * gv + bv; }
;                         f32x4 zz = ALPHA * xv + acc[ai][bj][m][n];
;                         if (bias) zz += *(const f32x4*)(bias + col);
;                         *(f32x4*)(zdst + (size_t)row * DM + col) = zz;
;                         sum += zz[0] + zz[1] + zz[2] + zz[3]; sq += zz[0] * zz[0] + zz[1] * zz[1] + zz[2] * zz[2] + zz[3] * zz[3];
;                         z[n] = zz;
;                     }
;                     u32x4 o; o.x = pk2(z[0][0], z[0][1]); o.y = pk2(z[0][2], z[0][3]); o.z = pk2(z[1][0], z[1][1]); o.w = pk2(z[1][2], z[1][3]);
;                     if (zb) *(u32x4*)(zb + (size_t)row * DM + colb + bj * 128) = o;
;                 }
;                 sum += __shfl_xor(sum, 16); sq += __shfl_xor(sq, 16);
;                 sum += __shfl_xor(sum, 32); sq += __shfl_xor(sq, 32);
;                 if (fq == 0) { atomicAdd(stout + 2 * (size_t)row, sum); atomicAdd(stout + 2 * (size_t)row + 1, sq); }
.LBB0_2204:
	s_or_b64 exec, exec, s[30:31]
	v_add_u32_e32 v52, 0xa0, v154
	v_ashrrev_i32_e32 v53, 31, v52
	v_lshlrev_b64 v[32:33], 3, v[52:53]
	s_waitcnt lgkmcnt(0)
	v_lshl_add_u64 v[34:35], s[12:13], 0, v[32:33]
	flat_load_dwordx2 v[54:55], v[34:35]
	v_lshlrev_b64 v[34:35], 12, v[52:53]
	v_lshl_add_u64 v[34:35], s[46:47], 0, v[34:35]
	v_lshl_add_u64 v[34:35], v[144:145], 2, v[34:35]
	global_load_dwordx4 v[36:39], v[34:35], off
	global_load_dwordx4 v[40:43], v[150:151], off
	global_load_dwordx4 v[44:47], v[152:153], off
	global_load_dwordx4 v[48:51], v[34:35], off offset:16
	global_load_dwordx4 v[196:199], v[146:147], off
	global_load_dwordx4 v[200:203], v[148:149], off
	s_waitcnt vmcnt(0) lgkmcnt(0)
	v_pk_mul_f32 v[54:55], v[54:55], s[24:25] op_sel:[1,0] op_sel_hi:[0,0]
	v_fma_f32 v54, -v55, v55, v54
	v_max_f32_e32 v54, 0, v54
	v_add_f32_e32 v54, 0x3727c5ac, v54
	v_mul_f32_e32 v56, 0x4b800000, v54
	v_cmp_gt_f32_e32 vcc, s61, v54
	v_sub_f32_e32 v37, v37, v55
	v_sub_f32_e32 v36, v36, v55
	v_cndmask_b32_e32 v54, v54, v56, vcc
	v_rsq_f32_e32 v54, v54
	v_sub_f32_e32 v39, v39, v55
	v_sub_f32_e32 v38, v38, v55
	v_mul_f32_e32 v56, 0x45800000, v54
	v_cndmask_b32_e32 v54, v54, v56, vcc
	v_pk_mul_f32 v[38:39], v[38:39], v[54:55] op_sel_hi:[1,0]
	v_pk_mul_f32 v[36:37], v[36:37], v[54:55] op_sel_hi:[1,0]
	v_pk_fma_f32 v[38:39], v[42:43], v[38:39], v[46:47]
	v_pk_fma_f32 v[36:37], v[40:41], v[36:37], v[44:45]
	v_pk_fma_f32 v[30:31], v[38:39], s[26:27], v[30:31] op_sel_hi:[1,0,1]
	v_pk_fma_f32 v[28:29], v[36:37], s[26:27], v[28:29] op_sel_hi:[1,0,1]
	global_store_dwordx4 v[34:35], v[28:31], off
	v_lshlrev_b64 v[44:45], 11, v[52:53]
	v_lshl_add_u64 v[44:45], s[14:15], 0, v[44:45]
	v_lshl_add_u64 v[52:53], v[144:145], 1, v[44:45]
	v_sub_f32_e32 v45, v49, v55
	v_sub_f32_e32 v44, v48, v55
	v_sub_f32_e32 v47, v51, v55
	v_sub_f32_e32 v46, v50, v55
	v_pk_mul_f32 v[46:47], v[46:47], v[54:55] op_sel_hi:[1,0]
	v_pk_mul_f32 v[48:49], v[44:45], v[54:55] op_sel_hi:[1,0]
	v_cvt_pk_bf16_f32 v44, v28, v29
	v_cvt_pk_bf16_f32 v45, v30, v31
	v_pk_fma_f32 v[38:39], v[198:199], v[46:47], v[202:203]
	v_pk_fma_f32 v[36:37], v[196:197], v[48:49], v[200:201]
	v_pk_fma_f32 v[26:27], v[38:39], s[26:27], v[26:27] op_sel_hi:[1,0,1]
	v_pk_fma_f32 v[24:25], v[36:37], s[26:27], v[24:25] op_sel_hi:[1,0,1]
	global_store_dwordx4 v[34:35], v[24:27], off offset:16
	v_cvt_pk_bf16_f32 v46, v24, v25
	v_cvt_pk_bf16_f32 v47, v26, v27
	flat_store_dwordx4 v[52:53], v[44:47]
	global_load_dwordx4 v[36:39], v[34:35], off offset:512
	global_load_dwordx4 v[40:43], v[120:121], off
	s_nop 0
	global_load_dwordx4 v[44:47], v[122:123], off
	global_load_dwordx4 v[48:51], v[34:35], off offset:528
	global_load_dwordx4 v[196:199], v[124:125], off
	global_load_dwordx4 v[200:203], v[126:127], off
	s_waitcnt vmcnt(0)
	v_sub_f32_e32 v37, v37, v55
	v_sub_f32_e32 v36, v36, v55
	v_sub_f32_e32 v39, v39, v55
	v_sub_f32_e32 v38, v38, v55
	v_pk_mul_f32 v[38:39], v[54:55], v[38:39] op_sel_hi:[0,1]
	v_pk_mul_f32 v[36:37], v[54:55], v[36:37] op_sel_hi:[0,1]
	v_pk_fma_f32 v[36:37], v[40:41], v[36:37], v[44:45]
	v_pk_fma_f32 v[38:39], v[42:43], v[38:39], v[46:47]
	v_pk_fma_f32 v[20:21], v[36:37], s[26:27], v[20:21] op_sel_hi:[1,0,1]
	v_pk_fma_f32 v[22:23], v[38:39], s[26:27], v[22:23] op_sel_hi:[1,0,1]
	global_store_dwordx4 v[34:35], v[20:23], off offset:512
	v_add_f32_e32 v44, v28, v29
	v_mul_f32_e32 v29, v29, v29
	v_fmac_f32_e32 v29, v28, v28
	v_add_f32_e32 v44, v30, v44
	v_fmac_f32_e32 v29, v30, v30
	v_add_f32_e32 v30, v24, v25
	v_mul_f32_e32 v25, v25, v25
	v_fmac_f32_e32 v25, v24, v24
	v_add_f32_e32 v28, v31, v44
	v_add_f32_e32 v30, v26, v30
	v_fmac_f32_e32 v25, v26, v26
	v_add_f32_e32 v28, 0, v28
	v_fmac_f32_e32 v29, v31, v31
	v_add_f32_e32 v24, v27, v30
	v_fmac_f32_e32 v25, v27, v27
	v_add_f32_e32 v28, v24, v28
	v_add_f32_e32 v29, v29, v25
	v_sub_f32_e32 v25, v49, v55
	v_sub_f32_e32 v24, v48, v55
	v_pk_mul_f32 v[24:25], v[54:55], v[24:25] op_sel_hi:[0,1]
	v_sub_f32_e32 v27, v51, v55
	v_sub_f32_e32 v26, v50, v55
	v_pk_mul_f32 v[26:27], v[54:55], v[26:27] op_sel_hi:[0,1]
	v_mul_f32_e32 v31, v21, v21
	v_add_f32_e32 v30, v20, v21
	v_fmac_f32_e32 v31, v20, v20
	v_add_f32_e32 v30, v22, v30
	v_fmac_f32_e32 v31, v22, v22
	v_add_f32_e32 v30, v23, v30
	v_fmac_f32_e32 v31, v23, v23
	v_add_f32_e32 v28, v28, v30
	v_add_f32_e32 v29, v29, v31
	v_cvt_pk_bf16_f32 v20, v20, v21
	v_cvt_pk_bf16_f32 v21, v22, v23
	v_pk_fma_f32 v[24:25], v[196:197], v[24:25], v[200:201]
	s_nop 0
	v_pk_fma_f32 v[24:25], v[24:25], s[26:27], v[16:17] op_sel_hi:[1,0,1]
	v_pk_fma_f32 v[26:27], v[198:199], v[26:27], v[202:203]
	v_mul_f32_e32 v17, v25, v25
	v_pk_fma_f32 v[26:27], v[26:27], s[26:27], v[18:19] op_sel_hi:[1,0,1]
	v_add_f32_e32 v16, v24, v25
	v_fmac_f32_e32 v17, v24, v24
	v_add_f32_e32 v16, v26, v16
	v_fmac_f32_e32 v17, v26, v26
	v_add_f32_e32 v16, v27, v16
	v_fmac_f32_e32 v17, v27, v27
	v_add_f32_e32 v16, v28, v16
	v_add_f32_e32 v17, v29, v17
	ds_bpermute_b32 v18, v116, v16
	ds_bpermute_b32 v19, v116, v17
	global_store_dwordx4 v[34:35], v[24:27], off offset:528
	v_cvt_pk_bf16_f32 v22, v24, v25
	v_cvt_pk_bf16_f32 v23, v26, v27
	s_waitcnt lgkmcnt(0)
	v_add_f32_e32 v16, v16, v18
	v_add_f32_e32 v17, v17, v19
	ds_bpermute_b32 v18, v117, v16
	ds_bpermute_b32 v19, v117, v17
	flat_store_dwordx4 v[52:53], v[20:23] offset:256
	s_and_saveexec_b64 s[30:31], s[2:3]
	s_cbranch_execz .LBB0_2206
	s_waitcnt lgkmcnt(0)
	v_add_f32_e32 v19, v17, v19
	v_add_f32_e32 v18, v16, v18
	v_lshl_add_u64 v[16:17], s[10:11], 0, v[32:33]
	flat_atomic_add_f32 v[16:17], v18
	flat_atomic_add_f32 v[16:17], v19 offset:4
; DEVI unsigned pk2(float lo, float hi) { unsigned r; asm("v_cvt_pk_bf16_f32 %0, %1, %2" : "=v"(r) : "v"(lo), "v"(hi)); return r; }
; DEVI void row_stats(const float* stats, int row, float& mu, float& rs) {
;     if (stats) { const float2 st = *(const float2*)(stats + 2 * (size_t)row); mu = st.x * (1.0f / 1024.0f); const float var = st.y * (1.0f / 1024.0f) - mu * mu; rs = rsqrtf(fmaxf(var, 0.f) + LN_EPS); }
;     DEVI void operator()(const f32x4 (&acc)[2][2][4][2], const pg8::Unit& u, int wr, int wc, int fr, int fq) const {
;     ...
;                 const int row = row0 + ai * 128 + m * 16; float mu, rs; row_stats(stin, row, mu, rs);
;                 float sum = 0.f, sq = 0.f;
; #pragma unroll
;                 for (int bj = 0; bj < 2; ++bj) {
;                     f32x4 z[2];
; #pragma unroll
;                     for (int n = 0; n < 2; ++n) {
;                         const int col = colb + bj * 128 + 4 * n;
;                         f32x4 xv = *(const f32x4*)(zsrc + (size_t)row * DM + col);
;                         if (stin) { const f32x4 gv = *(const f32x4*)(gin + col), bv = *(const f32x4*)(bin + col); xv = (xv - mu) * rs * gv + bv; }
;                         f32x4 zz = ALPHA * xv + acc[ai][bj][m][n];
;                         if (bias) zz += *(const f32x4*)(bias + col);
;                         *(f32x4*)(zdst + (size_t)row * DM + col) = zz;
;                         sum += zz[0] + zz[1] + zz[2] + zz[3]; sq += zz[0] * zz[0] + zz[1] * zz[1] + zz[2] * zz[2] + zz[3] * zz[3];
;                         z[n] = zz;
;                     }
;                     u32x4 o; o.x = pk2(z[0][0], z[0][1]); o.y = pk2(z[0][2], z[0][3]); o.z = pk2(z[1][0], z[1][1]); o.w = pk2(z[1][2], z[1][3]);
;                     if (zb) *(u32x4*)(zb + (size_t)row * DM + colb + bj * 128) = o;
;                 }
;                 sum += __shfl_xor(sum, 16); sq += __shfl_xor(sq, 16);
;                 sum += __shfl_xor(sum, 32); sq += __shfl_xor(sq, 32);
;                 if (fq == 0) { atomicAdd(stout + 2 * (size_t)row, sum); atomicAdd(stout + 2 * (size_t)row + 1, sq); }
.LBB0_2206:
	s_or_b64 exec, exec, s[30:31]
	v_add_u32_e32 v36, 0xb0, v154
	v_ashrrev_i32_e32 v37, 31, v36
	v_lshlrev_b64 v[16:17], 3, v[36:37]
	s_waitcnt lgkmcnt(0)
	v_lshl_add_u64 v[18:19], s[12:13], 0, v[16:17]
	flat_load_dwordx2 v[38:39], v[18:19]
	v_lshlrev_b64 v[18:19], 12, v[36:37]
	v_lshl_add_u64 v[18:19], s[46:47], 0, v[18:19]
	v_lshl_add_u64 v[18:19], v[144:145], 2, v[18:19]
	global_load_dwordx4 v[20:23], v[18:19], off
	global_load_dwordx4 v[24:27], v[150:151], off
	global_load_dwordx4 v[28:31], v[152:153], off
	global_load_dwordx4 v[32:35], v[18:19], off offset:16
	global_load_dwordx4 v[196:199], v[146:147], off
	global_load_dwordx4 v[200:203], v[148:149], off
	s_waitcnt vmcnt(0) lgkmcnt(0)
	v_pk_mul_f32 v[38:39], v[38:39], s[24:25] op_sel:[1,0] op_sel_hi:[0,0]
	v_fma_f32 v38, -v39, v39, v38
	v_max_f32_e32 v38, 0, v38
	v_add_f32_e32 v38, 0x3727c5ac, v38
	v_mul_f32_e32 v40, 0x4b800000, v38
	v_cmp_gt_f32_e32 vcc, s61, v38
	v_sub_f32_e32 v21, v21, v39
	v_sub_f32_e32 v20, v20, v39
	v_cndmask_b32_e32 v38, v38, v40, vcc
	v_rsq_f32_e32 v38, v38
	v_sub_f32_e32 v23, v23, v39
	v_sub_f32_e32 v22, v22, v39
	v_mul_f32_e32 v40, 0x45800000, v38
	v_cndmask_b32_e32 v38, v38, v40, vcc
	v_pk_mul_f32 v[22:23], v[22:23], v[38:39] op_sel_hi:[1,0]
	v_pk_mul_f32 v[20:21], v[20:21], v[38:39] op_sel_hi:[1,0]
	v_pk_fma_f32 v[22:23], v[26:27], v[22:23], v[30:31]
	v_pk_fma_f32 v[20:21], v[24:25], v[20:21], v[28:29]
	v_pk_fma_f32 v[14:15], v[22:23], s[26:27], v[14:15] op_sel_hi:[1,0,1]
	v_pk_fma_f32 v[12:13], v[20:21], s[26:27], v[12:13] op_sel_hi:[1,0,1]
	global_store_dwordx4 v[18:19], v[12:15], off
	v_lshlrev_b64 v[28:29], 11, v[36:37]
	v_lshl_add_u64 v[28:29], s[14:15], 0, v[28:29]
	v_lshl_add_u64 v[36:37], v[144:145], 1, v[28:29]
	v_sub_f32_e32 v29, v33, v39
	v_sub_f32_e32 v28, v32, v39
	v_sub_f32_e32 v31, v35, v39
	v_sub_f32_e32 v30, v34, v39
	v_pk_mul_f32 v[30:31], v[30:31], v[38:39] op_sel_hi:[1,0]
	v_pk_mul_f32 v[32:33], v[28:29], v[38:39] op_sel_hi:[1,0]
	v_cvt_pk_bf16_f32 v28, v12, v13
	v_cvt_pk_bf16_f32 v29, v14, v15
	v_pk_fma_f32 v[22:23], v[198:199], v[30:31], v[202:203]
	v_pk_fma_f32 v[20:21], v[196:197], v[32:33], v[200:201]
	v_pk_fma_f32 v[10:11], v[22:23], s[26:27], v[10:11] op_sel_hi:[1,0,1]
	v_pk_fma_f32 v[8:9], v[20:21], s[26:27], v[8:9] op_sel_hi:[1,0,1]
	global_store_dwordx4 v[18:19], v[8:11], off offset:16
	v_cvt_pk_bf16_f32 v30, v8, v9
	v_cvt_pk_bf16_f32 v31, v10, v11
	flat_store_dwordx4 v[36:37], v[28:31]
	global_load_dwordx4 v[20:23], v[18:19], off offset:512
	global_load_dwordx4 v[24:27], v[120:121], off
	s_nop 0
	global_load_dwordx4 v[28:31], v[122:123], off
	global_load_dwordx4 v[32:35], v[18:19], off offset:528
	global_load_dwordx4 v[196:199], v[124:125], off
	global_load_dwordx4 v[200:203], v[126:127], off
	s_waitcnt vmcnt(0)
	v_sub_f32_e32 v21, v21, v39
	v_sub_f32_e32 v20, v20, v39
	v_sub_f32_e32 v23, v23, v39
	v_sub_f32_e32 v22, v22, v39
	v_pk_mul_f32 v[22:23], v[38:39], v[22:23] op_sel_hi:[0,1]
	v_pk_mul_f32 v[20:21], v[38:39], v[20:21] op_sel_hi:[0,1]
	v_pk_fma_f32 v[20:21], v[24:25], v[20:21], v[28:29]
	v_pk_fma_f32 v[22:23], v[26:27], v[22:23], v[30:31]
	v_pk_fma_f32 v[4:5], v[20:21], s[26:27], v[4:5] op_sel_hi:[1,0,1]
	v_pk_fma_f32 v[6:7], v[22:23], s[26:27], v[6:7] op_sel_hi:[1,0,1]
	global_store_dwordx4 v[18:19], v[4:7], off offset:512
	v_add_f32_e32 v28, v12, v13
	v_mul_f32_e32 v13, v13, v13
	v_fmac_f32_e32 v13, v12, v12
	v_add_f32_e32 v28, v14, v28
	v_fmac_f32_e32 v13, v14, v14
	v_add_f32_e32 v14, v8, v9
	v_mul_f32_e32 v9, v9, v9
	v_fmac_f32_e32 v9, v8, v8
	v_add_f32_e32 v12, v15, v28
	v_add_f32_e32 v14, v10, v14
	v_fmac_f32_e32 v9, v10, v10
	v_add_f32_e32 v12, 0, v12
	v_fmac_f32_e32 v13, v15, v15
	v_add_f32_e32 v8, v11, v14
	v_fmac_f32_e32 v9, v11, v11
	v_add_f32_e32 v12, v8, v12
	v_add_f32_e32 v13, v13, v9
	v_sub_f32_e32 v9, v33, v39
	v_sub_f32_e32 v8, v32, v39
	v_pk_mul_f32 v[8:9], v[38:39], v[8:9] op_sel_hi:[0,1]
	v_sub_f32_e32 v11, v35, v39
	v_sub_f32_e32 v10, v34, v39
	v_pk_mul_f32 v[10:11], v[38:39], v[10:11] op_sel_hi:[0,1]
	v_mul_f32_e32 v15, v5, v5
	v_add_f32_e32 v14, v4, v5
	v_fmac_f32_e32 v15, v4, v4
	v_add_f32_e32 v14, v6, v14
	v_fmac_f32_e32 v15, v6, v6
	v_add_f32_e32 v14, v7, v14
	v_fmac_f32_e32 v15, v7, v7
	v_add_f32_e32 v12, v12, v14
	v_add_f32_e32 v13, v13, v15
	v_cvt_pk_bf16_f32 v4, v4, v5
	v_cvt_pk_bf16_f32 v5, v6, v7
	v_pk_fma_f32 v[8:9], v[196:197], v[8:9], v[200:201]
	s_nop 0
	v_pk_fma_f32 v[8:9], v[8:9], s[26:27], v[0:1] op_sel_hi:[1,0,1]
	v_pk_fma_f32 v[10:11], v[198:199], v[10:11], v[202:203]
	v_mul_f32_e32 v1, v9, v9
	v_pk_fma_f32 v[10:11], v[10:11], s[26:27], v[2:3] op_sel_hi:[1,0,1]
	v_add_f32_e32 v0, v8, v9
	v_fmac_f32_e32 v1, v8, v8
	v_add_f32_e32 v0, v10, v0
	v_fmac_f32_e32 v1, v10, v10
	v_add_f32_e32 v0, v11, v0
	v_fmac_f32_e32 v1, v11, v11
	v_add_f32_e32 v0, v12, v0
	v_add_f32_e32 v1, v13, v1
	ds_bpermute_b32 v2, v116, v0
	ds_bpermute_b32 v3, v116, v1
	global_store_dwordx4 v[18:19], v[8:11], off offset:528
	v_cvt_pk_bf16_f32 v6, v8, v9
	v_cvt_pk_bf16_f32 v7, v10, v11
	s_waitcnt lgkmcnt(0)
	v_add_f32_e32 v0, v0, v2
	v_add_f32_e32 v1, v1, v3
	ds_bpermute_b32 v2, v117, v0
	ds_bpermute_b32 v3, v117, v1
	flat_store_dwordx4 v[36:37], v[4:7] offset:256
	s_and_saveexec_b64 s[30:31], s[2:3]
	s_cbranch_execz .LBB0_2208
	s_waitcnt lgkmcnt(0)
	v_add_f32_e32 v3, v1, v3
	v_add_f32_e32 v2, v0, v2
	v_lshl_add_u64 v[0:1], s[10:11], 0, v[16:17]
	flat_atomic_add_f32 v[0:1], v2
	flat_atomic_add_f32 v[0:1], v3 offset:4

; DEVI unsigned pk2(float lo, float hi) { unsigned r; asm("v_cvt_pk_bf16_f32 %0, %1, %2" : "=v"(r) : "v"(lo), "v"(hi)); return r; }
; DEVI void row_stats(const float* stats, int row, float& mu, float& rs) {
;     if (stats) { const float2 st = *(const float2*)(stats + 2 * (size_t)row); mu = st.x * (1.0f / 1024.0f); const float var = st.y * (1.0f / 1024.0f) - mu * mu; rs = rsqrtf(fmaxf(var, 0.f) + LN_EPS); }
;     DEVI void operator()(const f32x4 (&acc)[2][2][4][2], const pg8::Unit& u, int wr, int wc, int fr, int fq) const {
;     ...
;                 const int row = row0 + ai * 128 + m * 16; float mu, rs; row_stats(stin, row, mu, rs);
;                 float sum = 0.f, sq = 0.f;
; #pragma unroll
;                 for (int bj = 0; bj < 2; ++bj) {
;                     f32x4 z[2];
; #pragma unroll
;                     for (int n = 0; n < 2; ++n) {
;                         const int col = colb + bj * 128 + 4 * n;
;                         f32x4 xv = *(const f32x4*)(zsrc + (size_t)row * DM + col);
;                         if (stin) { const f32x4 gv = *(const f32x4*)(gin + col), bv = *(const f32x4*)(bin + col); xv = (xv - mu) * rs * gv + bv; }
;                         f32x4 zz = ALPHA * xv + acc[ai][bj][m][n];
;                         if (bias) zz += *(const f32x4*)(bias + col);
;                         *(f32x4*)(zdst + (size_t)row * DM + col) = zz;
;                         sum += zz[0] + zz[1] + zz[2] + zz[3]; sq += zz[0] * zz[0] + zz[1] * zz[1] + zz[2] * zz[2] + zz[3] * zz[3];
;                         z[n] = zz;
;                     }
;                     u32x4 o; o.x = pk2(z[0][0], z[0][1]); o.y = pk2(z[0][2], z[0][3]); o.z = pk2(z[1][0], z[1][1]); o.w = pk2(z[1][2], z[1][3]);
;                     if (zb) *(u32x4*)(zb + (size_t)row * DM + colb + bj * 128) = o;
;                 }
;                 sum += __shfl_xor(sum, 16); sq += __shfl_xor(sq, 16);
;                 sum += __shfl_xor(sum, 32); sq += __shfl_xor(sq, 32);
;                 if (fq == 0) { atomicAdd(stout + 2 * (size_t)row, sum); atomicAdd(stout + 2 * (size_t)row + 1, sq); }
.LBB0_2638:
	s_or_b64 exec, exec, s[36:37]
	v_or_b32_e32 v166, 16, v154
	v_ashrrev_i32_e32 v167, 31, v166
	v_lshlrev_b64 v[112:113], 3, v[166:167]
	s_waitcnt lgkmcnt(0)
	v_lshl_add_u64 v[114:115], s[6:7], 0, v[112:113]
	flat_load_dwordx2 v[192:193], v[114:115]
	v_lshlrev_b64 v[114:115], 12, v[166:167]
	v_lshl_add_u64 v[114:115], s[46:47], 0, v[114:115]
	v_lshl_add_u64 v[114:115], v[144:145], 2, v[114:115]
	global_load_dwordx4 v[162:165], v[114:115], off
	global_load_dwordx4 v[176:179], v[150:151], off
	global_load_dwordx4 v[180:183], v[152:153], off
	global_load_dwordx4 v[184:187], v[156:157], off
	global_load_dwordx4 v[188:191], v[114:115], off offset:16
	v_lshlrev_b64 v[166:167], 11, v[166:167]
	v_lshl_add_u64 v[166:167], s[10:11], 0, v[166:167]
	v_lshl_add_u64 v[166:167], v[144:145], 1, v[166:167]
	global_load_dwordx4 v[208:211], v[146:147], off
	global_load_dwordx4 v[212:215], v[148:149], off
	global_load_dwordx4 v[250:253], v[124:125], off
	s_waitcnt vmcnt(0) lgkmcnt(0)
	v_pk_mul_f32 v[192:193], v[192:193], s[22:23] op_sel:[1,0] op_sel_hi:[0,0]
	v_fma_f32 v155, -v193, v193, v192
	v_max_f32_e32 v155, 0, v155
	v_add_f32_e32 v155, 0x3727c5ac, v155
	v_mul_f32_e32 v175, 0x4b800000, v155
	v_cmp_gt_f32_e32 vcc, s64, v155
	v_sub_f32_e32 v165, v165, v193
	v_sub_f32_e32 v164, v164, v193
	v_cndmask_b32_e32 v155, v155, v175, vcc
	v_rsq_f32_e32 v155, v155
	v_sub_f32_e32 v163, v163, v193
	v_sub_f32_e32 v162, v162, v193
	v_mul_f32_e32 v175, 0x45800000, v155
	v_cndmask_b32_e32 v192, v155, v175, vcc
	v_pk_mul_f32 v[162:163], v[162:163], v[192:193] op_sel_hi:[1,0]
	v_pk_mul_f32 v[164:165], v[164:165], v[192:193] op_sel_hi:[1,0]
	v_pk_fma_f32 v[162:163], v[176:177], v[162:163], v[180:181]
	v_pk_fma_f32 v[164:165], v[178:179], v[164:165], v[182:183]
	v_pk_fma_f32 v[108:109], v[162:163], s[24:25], v[108:109] op_sel_hi:[1,0,1]
	v_pk_fma_f32 v[110:111], v[164:165], s[24:25], v[110:111] op_sel_hi:[1,0,1]
	v_pk_add_f32 v[108:109], v[184:185], v[108:109]
	v_pk_add_f32 v[110:111], v[186:187], v[110:111]
	global_store_dwordx4 v[114:115], v[108:111], off
	v_sub_f32_e32 v185, v191, v193
	v_sub_f32_e32 v184, v190, v193
	v_sub_f32_e32 v187, v189, v193
	v_sub_f32_e32 v186, v188, v193
	v_pk_mul_f32 v[186:187], v[186:187], v[192:193] op_sel_hi:[1,0]
	v_pk_mul_f32 v[188:189], v[184:185], v[192:193] op_sel_hi:[1,0]
	v_cvt_pk_bf16_f32 v184, v108, v109
	v_cvt_pk_bf16_f32 v185, v110, v111
	v_add_f32_e32 v155, v108, v109
	v_mul_f32_e32 v109, v109, v109
	v_fmac_f32_e32 v109, v108, v108
	v_add_f32_e32 v155, v110, v155
	v_fmac_f32_e32 v109, v110, v110
	v_add_f32_e32 v108, v111, v155
	v_add_f32_e32 v108, 0, v108
	v_fmac_f32_e32 v109, v111, v111
	v_pk_fma_f32 v[164:165], v[210:211], v[188:189], v[214:215]
	v_pk_fma_f32 v[162:163], v[208:209], v[186:187], v[212:213]
	v_pk_fma_f32 v[106:107], v[164:165], s[24:25], v[106:107] op_sel_hi:[1,0,1]
	v_pk_fma_f32 v[104:105], v[162:163], s[24:25], v[104:105] op_sel_hi:[1,0,1]
	v_pk_add_f32 v[106:107], v[252:253], v[106:107]
	v_pk_add_f32 v[104:105], v[250:251], v[104:105]
	global_store_dwordx4 v[114:115], v[104:107], off offset:16
	v_cvt_pk_bf16_f32 v186, v104, v105
	v_cvt_pk_bf16_f32 v187, v106, v107
	flat_store_dwordx4 v[166:167], v[184:187]
	global_load_dwordx4 v[162:165], v[114:115], off offset:512
	global_load_dwordx4 v[176:179], v[126:127], off
	global_load_dwordx4 v[180:183], v[158:159], off
	s_nop 0
	global_load_dwordx4 v[184:187], v[160:161], off
	global_load_dwordx4 v[188:191], v[114:115], off offset:528
	v_add_f32_e32 v110, v104, v105
	v_mul_f32_e32 v105, v105, v105
	v_fmac_f32_e32 v105, v104, v104
	v_add_f32_e32 v110, v106, v110
	v_fmac_f32_e32 v105, v106, v106
	v_add_f32_e32 v104, v107, v110
	v_fmac_f32_e32 v105, v107, v107
	v_add_f32_e32 v108, v104, v108
	v_add_f32_e32 v109, v109, v105
	global_load_dwordx4 v[208:211], v[120:121], off
	global_load_dwordx4 v[212:215], v[122:123], off
	global_load_dwordx4 v[250:253], v[116:117], off
	s_waitcnt vmcnt(0)
	v_sub_f32_e32 v165, v165, v193
	v_sub_f32_e32 v164, v164, v193
	v_sub_f32_e32 v163, v163, v193
	v_sub_f32_e32 v162, v162, v193
	v_pk_mul_f32 v[162:163], v[192:193], v[162:163] op_sel_hi:[0,1]
	v_pk_mul_f32 v[164:165], v[192:193], v[164:165] op_sel_hi:[0,1]
	v_pk_fma_f32 v[164:165], v[178:179], v[164:165], v[182:183]
	v_pk_fma_f32 v[162:163], v[176:177], v[162:163], v[180:181]
	v_pk_fma_f32 v[102:103], v[164:165], s[24:25], v[102:103] op_sel_hi:[1,0,1]
	v_pk_fma_f32 v[100:101], v[162:163], s[24:25], v[100:101] op_sel_hi:[1,0,1]
	v_pk_add_f32 v[102:103], v[186:187], v[102:103]
	v_pk_add_f32 v[100:101], v[184:185], v[100:101]
	global_store_dwordx4 v[114:115], v[100:103], off offset:512
	v_sub_f32_e32 v107, v189, v193
	v_sub_f32_e32 v106, v188, v193
	v_sub_f32_e32 v105, v191, v193
	v_sub_f32_e32 v104, v190, v193
	v_pk_mul_f32 v[106:107], v[192:193], v[106:107] op_sel_hi:[0,1]
	v_pk_mul_f32 v[104:105], v[192:193], v[104:105] op_sel_hi:[0,1]
	v_mul_f32_e32 v111, v101, v101
	v_add_f32_e32 v110, v100, v101
	v_fmac_f32_e32 v111, v100, v100
	v_add_f32_e32 v110, v102, v110
	v_fmac_f32_e32 v111, v102, v102
	v_add_f32_e32 v110, v103, v110
	v_fmac_f32_e32 v111, v103, v103
	v_add_f32_e32 v108, v108, v110
	v_add_f32_e32 v109, v109, v111
	v_cvt_pk_bf16_f32 v100, v100, v101
	v_cvt_pk_bf16_f32 v101, v102, v103
	v_pk_fma_f32 v[106:107], v[208:209], v[106:107], v[212:213]
	v_pk_fma_f32 v[104:105], v[210:211], v[104:105], v[214:215]
	v_pk_fma_f32 v[96:97], v[106:107], s[24:25], v[96:97] op_sel_hi:[1,0,1]
	v_pk_fma_f32 v[98:99], v[104:105], s[24:25], v[98:99] op_sel_hi:[1,0,1]
	v_pk_add_f32 v[104:105], v[250:251], v[96:97]
	v_pk_add_f32 v[106:107], v[252:253], v[98:99]
	v_mul_f32_e32 v97, v105, v105
	v_add_f32_e32 v96, v104, v105
	v_fmac_f32_e32 v97, v104, v104
	v_add_f32_e32 v96, v106, v96
	v_fmac_f32_e32 v97, v106, v106
	v_add_f32_e32 v96, v107, v96
	v_fmac_f32_e32 v97, v107, v107
	v_add_f32_e32 v96, v108, v96
	v_add_f32_e32 v97, v109, v97
	ds_bpermute_b32 v98, v118, v96
	ds_bpermute_b32 v99, v118, v97
	global_store_dwordx4 v[114:115], v[104:107], off offset:528
	v_cvt_pk_bf16_f32 v102, v104, v105
	v_cvt_pk_bf16_f32 v103, v106, v107
	s_waitcnt lgkmcnt(0)
	v_add_f32_e32 v96, v96, v98
	v_add_f32_e32 v97, v97, v99
	ds_bpermute_b32 v98, v119, v96
	ds_bpermute_b32 v99, v119, v97
	flat_store_dwordx4 v[166:167], v[100:103] offset:256
	s_and_saveexec_b64 s[36:37], s[2:3]
	s_cbranch_execz .LBB0_2640
	v_lshl_add_u64 v[100:101], s[8:9], 0, v[112:113]
	s_waitcnt lgkmcnt(0)
	v_add_f32_e32 v96, v96, v98
	v_add_f32_e32 v97, v97, v99
	flat_atomic_add_f32 v[100:101], v96
	flat_atomic_add_f32 v[100:101], v97 offset:4
; DEVI unsigned pk2(float lo, float hi) { unsigned r; asm("v_cvt_pk_bf16_f32 %0, %1, %2" : "=v"(r) : "v"(lo), "v"(hi)); return r; }
; DEVI void row_stats(const float* stats, int row, float& mu, float& rs) {
;     if (stats) { const float2 st = *(const float2*)(stats + 2 * (size_t)row); mu = st.x * (1.0f / 1024.0f); const float var = st.y * (1.0f / 1024.0f) - mu * mu; rs = rsqrtf(fmaxf(var, 0.f) + LN_EPS); }
;     DEVI void operator()(const f32x4 (&acc)[2][2][4][2], const pg8::Unit& u, int wr, int wc, int fr, int fq) const {
;     ...
;                 const int row = row0 + ai * 128 + m * 16; float mu, rs; row_stats(stin, row, mu, rs);
;                 float sum = 0.f, sq = 0.f;
; #pragma unroll
;                 for (int bj = 0; bj < 2; ++bj) {
;                     f32x4 z[2];
; #pragma unroll
;                     for (int n = 0; n < 2; ++n) {
;                         const int col = colb + bj * 128 + 4 * n;
;                         f32x4 xv = *(const f32x4*)(zsrc + (size_t)row * DM + col);
;                         if (stin) { const f32x4 gv = *(const f32x4*)(gin + col), bv = *(const f32x4*)(bin + col); xv = (xv - mu) * rs * gv + bv; }
;                         f32x4 zz = ALPHA * xv + acc[ai][bj][m][n];
;                         if (bias) zz += *(const f32x4*)(bias + col);
;                         *(f32x4*)(zdst + (size_t)row * DM + col) = zz;
;                         sum += zz[0] + zz[1] + zz[2] + zz[3]; sq += zz[0] * zz[0] + zz[1] * zz[1] + zz[2] * zz[2] + zz[3] * zz[3];
;                         z[n] = zz;
;                     }
;                     u32x4 o; o.x = pk2(z[0][0], z[0][1]); o.y = pk2(z[0][2], z[0][3]); o.z = pk2(z[1][0], z[1][1]); o.w = pk2(z[1][2], z[1][3]);
;                     if (zb) *(u32x4*)(zb + (size_t)row * DM + colb + bj * 128) = o;
;                 }
;                 sum += __shfl_xor(sum, 16); sq += __shfl_xor(sq, 16);
;                 sum += __shfl_xor(sum, 32); sq += __shfl_xor(sq, 32);
;                 if (fq == 0) { atomicAdd(stout + 2 * (size_t)row, sum); atomicAdd(stout + 2 * (size_t)row + 1, sq); }
.LBB0_2640:
	s_or_b64 exec, exec, s[36:37]
	v_or_b32_e32 v166, 32, v154
	v_ashrrev_i32_e32 v167, 31, v166
	v_lshlrev_b64 v[96:97], 3, v[166:167]
	s_waitcnt lgkmcnt(0)
	v_lshl_add_u64 v[98:99], s[6:7], 0, v[96:97]
	flat_load_dwordx2 v[176:177], v[98:99]
	v_lshlrev_b64 v[98:99], 12, v[166:167]
	v_lshl_add_u64 v[98:99], s[46:47], 0, v[98:99]
	v_lshl_add_u64 v[98:99], v[144:145], 2, v[98:99]
	global_load_dwordx4 v[100:103], v[98:99], off
	global_load_dwordx4 v[104:107], v[150:151], off
	global_load_dwordx4 v[108:111], v[152:153], off
	global_load_dwordx4 v[112:115], v[156:157], off
	global_load_dwordx4 v[162:165], v[98:99], off offset:16
	global_load_dwordx4 v[208:211], v[146:147], off
	global_load_dwordx4 v[212:215], v[148:149], off
	global_load_dwordx4 v[250:253], v[124:125], off
	s_waitcnt vmcnt(0) lgkmcnt(0)
	v_pk_mul_f32 v[176:177], v[176:177], s[22:23] op_sel:[1,0] op_sel_hi:[0,0]
	v_fma_f32 v155, -v177, v177, v176
	v_max_f32_e32 v155, 0, v155
	v_add_f32_e32 v155, 0x3727c5ac, v155
	v_mul_f32_e32 v175, 0x4b800000, v155
	v_cmp_gt_f32_e32 vcc, s64, v155
	v_sub_f32_e32 v103, v103, v177
	v_sub_f32_e32 v102, v102, v177
	v_cndmask_b32_e32 v155, v155, v175, vcc
	v_rsq_f32_e32 v155, v155
	v_sub_f32_e32 v101, v101, v177
	v_sub_f32_e32 v100, v100, v177
	v_mul_f32_e32 v175, 0x45800000, v155
	v_cndmask_b32_e32 v176, v155, v175, vcc
	v_pk_mul_f32 v[100:101], v[100:101], v[176:177] op_sel_hi:[1,0]
	v_pk_mul_f32 v[102:103], v[102:103], v[176:177] op_sel_hi:[1,0]
	v_pk_fma_f32 v[100:101], v[104:105], v[100:101], v[108:109]
	v_pk_fma_f32 v[102:103], v[106:107], v[102:103], v[110:111]
	v_pk_fma_f32 v[92:93], v[100:101], s[24:25], v[92:93] op_sel_hi:[1,0,1]
	v_pk_fma_f32 v[94:95], v[102:103], s[24:25], v[94:95] op_sel_hi:[1,0,1]
	v_pk_add_f32 v[92:93], v[112:113], v[92:93]
	v_pk_add_f32 v[94:95], v[114:115], v[94:95]
	global_store_dwordx4 v[98:99], v[92:95], off
	v_lshlrev_b64 v[112:113], 11, v[166:167]
	v_lshl_add_u64 v[112:113], s[10:11], 0, v[112:113]
	v_lshl_add_u64 v[166:167], v[144:145], 1, v[112:113]
	v_sub_f32_e32 v113, v165, v177
	v_sub_f32_e32 v112, v164, v177
	v_sub_f32_e32 v115, v163, v177
	v_sub_f32_e32 v114, v162, v177
	v_pk_mul_f32 v[114:115], v[114:115], v[176:177] op_sel_hi:[1,0]
	v_pk_mul_f32 v[162:163], v[112:113], v[176:177] op_sel_hi:[1,0]
	v_cvt_pk_bf16_f32 v112, v92, v93
	v_cvt_pk_bf16_f32 v113, v94, v95
	v_pk_fma_f32 v[100:101], v[208:209], v[114:115], v[212:213]
	v_pk_fma_f32 v[102:103], v[210:211], v[162:163], v[214:215]
	v_pk_fma_f32 v[88:89], v[100:101], s[24:25], v[88:89] op_sel_hi:[1,0,1]
	v_pk_fma_f32 v[90:91], v[102:103], s[24:25], v[90:91] op_sel_hi:[1,0,1]
	v_pk_add_f32 v[88:89], v[250:251], v[88:89]
	v_pk_add_f32 v[90:91], v[252:253], v[90:91]
	global_store_dwordx4 v[98:99], v[88:91], off offset:16
	v_cvt_pk_bf16_f32 v114, v88, v89
	v_cvt_pk_bf16_f32 v115, v90, v91
	flat_store_dwordx4 v[166:167], v[112:115]
	global_load_dwordx4 v[100:103], v[98:99], off offset:512
	global_load_dwordx4 v[104:107], v[126:127], off
	global_load_dwordx4 v[108:111], v[158:159], off
	s_nop 0
	global_load_dwordx4 v[112:115], v[160:161], off
	global_load_dwordx4 v[162:165], v[98:99], off offset:528
	global_load_dwordx4 v[208:211], v[120:121], off
	global_load_dwordx4 v[212:215], v[122:123], off
	global_load_dwordx4 v[250:253], v[116:117], off
	s_waitcnt vmcnt(0)
	v_sub_f32_e32 v103, v103, v177
	v_sub_f32_e32 v102, v102, v177
	v_sub_f32_e32 v101, v101, v177
	v_sub_f32_e32 v100, v100, v177
	v_pk_mul_f32 v[100:101], v[176:177], v[100:101] op_sel_hi:[0,1]
	v_pk_mul_f32 v[102:103], v[176:177], v[102:103] op_sel_hi:[0,1]
	v_pk_fma_f32 v[102:103], v[106:107], v[102:103], v[110:111]
	v_pk_fma_f32 v[100:101], v[104:105], v[100:101], v[108:109]
	v_pk_fma_f32 v[86:87], v[102:103], s[24:25], v[86:87] op_sel_hi:[1,0,1]
	v_pk_fma_f32 v[84:85], v[100:101], s[24:25], v[84:85] op_sel_hi:[1,0,1]
	v_pk_add_f32 v[86:87], v[114:115], v[86:87]
	v_pk_add_f32 v[84:85], v[112:113], v[84:85]
	global_store_dwordx4 v[98:99], v[84:87], off offset:512
	v_add_f32_e32 v112, v92, v93
	v_mul_f32_e32 v93, v93, v93
	v_fmac_f32_e32 v93, v92, v92
	v_add_f32_e32 v112, v94, v112
	v_fmac_f32_e32 v93, v94, v94
	v_add_f32_e32 v94, v88, v89
	v_mul_f32_e32 v89, v89, v89
	v_fmac_f32_e32 v89, v88, v88
	v_add_f32_e32 v92, v95, v112
	v_add_f32_e32 v94, v90, v94
	v_fmac_f32_e32 v89, v90, v90
	v_add_f32_e32 v92, 0, v92
	v_fmac_f32_e32 v93, v95, v95
	v_add_f32_e32 v88, v91, v94
	v_fmac_f32_e32 v89, v91, v91
	v_sub_f32_e32 v91, v163, v177
	v_sub_f32_e32 v90, v162, v177
	v_add_f32_e32 v92, v88, v92
	v_add_f32_e32 v93, v93, v89
	v_sub_f32_e32 v89, v165, v177
	v_sub_f32_e32 v88, v164, v177
	v_pk_mul_f32 v[90:91], v[176:177], v[90:91] op_sel_hi:[0,1]
	v_pk_mul_f32 v[88:89], v[176:177], v[88:89] op_sel_hi:[0,1]
	v_mul_f32_e32 v95, v85, v85
	v_add_f32_e32 v94, v84, v85
	v_fmac_f32_e32 v95, v84, v84
	v_add_f32_e32 v94, v86, v94
	v_fmac_f32_e32 v95, v86, v86
	v_add_f32_e32 v94, v87, v94
	v_fmac_f32_e32 v95, v87, v87
	v_add_f32_e32 v92, v92, v94
	v_add_f32_e32 v93, v93, v95
	v_cvt_pk_bf16_f32 v84, v84, v85
	v_cvt_pk_bf16_f32 v85, v86, v87
	v_pk_fma_f32 v[90:91], v[208:209], v[90:91], v[212:213]
	v_pk_fma_f32 v[88:89], v[210:211], v[88:89], v[214:215]
	v_pk_fma_f32 v[80:81], v[90:91], s[24:25], v[80:81] op_sel_hi:[1,0,1]
	v_pk_fma_f32 v[82:83], v[88:89], s[24:25], v[82:83] op_sel_hi:[1,0,1]
	v_pk_add_f32 v[88:89], v[250:251], v[80:81]
	v_pk_add_f32 v[90:91], v[252:253], v[82:83]
	v_mul_f32_e32 v81, v89, v89
	v_add_f32_e32 v80, v88, v89
	v_fmac_f32_e32 v81, v88, v88
	v_add_f32_e32 v80, v90, v80
	v_fmac_f32_e32 v81, v90, v90
	v_add_f32_e32 v80, v91, v80
	v_fmac_f32_e32 v81, v91, v91
	v_add_f32_e32 v80, v92, v80
	v_add_f32_e32 v81, v93, v81
	ds_bpermute_b32 v82, v118, v80
	ds_bpermute_b32 v83, v118, v81
	global_store_dwordx4 v[98:99], v[88:91], off offset:528
	v_cvt_pk_bf16_f32 v86, v88, v89
	v_cvt_pk_bf16_f32 v87, v90, v91
	s_waitcnt lgkmcnt(0)
	v_add_f32_e32 v80, v80, v82
	v_add_f32_e32 v81, v81, v83
	ds_bpermute_b32 v82, v119, v80
	ds_bpermute_b32 v83, v119, v81
	flat_store_dwordx4 v[166:167], v[84:87] offset:256
	s_and_saveexec_b64 s[36:37], s[2:3]
	s_cbranch_execz .LBB0_2642
	v_lshl_add_u64 v[84:85], s[8:9], 0, v[96:97]
	s_waitcnt lgkmcnt(0)
	v_add_f32_e32 v80, v80, v82
	v_add_f32_e32 v81, v81, v83
	flat_atomic_add_f32 v[84:85], v80
	flat_atomic_add_f32 v[84:85], v81 offset:4
; DEVI unsigned pk2(float lo, float hi) { unsigned r; asm("v_cvt_pk_bf16_f32 %0, %1, %2" : "=v"(r) : "v"(lo), "v"(hi)); return r; }
; DEVI void row_stats(const float* stats, int row, float& mu, float& rs) {
;     if (stats) { const float2 st = *(const float2*)(stats + 2 * (size_t)row); mu = st.x * (1.0f / 1024.0f); const float var = st.y * (1.0f / 1024.0f) - mu * mu; rs = rsqrtf(fmaxf(var, 0.f) + LN_EPS); }
;     DEVI void operator()(const f32x4 (&acc)[2][2][4][2], const pg8::Unit& u, int wr, int wc, int fr, int fq) const {
;     ...
;                 const int row = row0 + ai * 128 + m * 16; float mu, rs; row_stats(stin, row, mu, rs);
;                 float sum = 0.f, sq = 0.f;
; #pragma unroll
;                 for (int bj = 0; bj < 2; ++bj) {
;                     f32x4 z[2];
; #pragma unroll
;                     for (int n = 0; n < 2; ++n) {
;                         const int col = colb + bj * 128 + 4 * n;
;                         f32x4 xv = *(const f32x4*)(zsrc + (size_t)row * DM + col);
;                         if (stin) { const f32x4 gv = *(const f32x4*)(gin + col), bv = *(const f32x4*)(bin + col); xv = (xv - mu) * rs * gv + bv; }
;                         f32x4 zz = ALPHA * xv + acc[ai][bj][m][n];
;                         if (bias) zz += *(const f32x4*)(bias + col);
;                         *(f32x4*)(zdst + (size_t)row * DM + col) = zz;
;                         sum += zz[0] + zz[1] + zz[2] + zz[3]; sq += zz[0] * zz[0] + zz[1] * zz[1] + zz[2] * zz[2] + zz[3] * zz[3];
;                         z[n] = zz;
;                     }
;                     u32x4 o; o.x = pk2(z[0][0], z[0][1]); o.y = pk2(z[0][2], z[0][3]); o.z = pk2(z[1][0], z[1][1]); o.w = pk2(z[1][2], z[1][3]);
;                     if (zb) *(u32x4*)(zb + (size_t)row * DM + colb + bj * 128) = o;
;                 }
;                 sum += __shfl_xor(sum, 16); sq += __shfl_xor(sq, 16);
;                 sum += __shfl_xor(sum, 32); sq += __shfl_xor(sq, 32);
;                 if (fq == 0) { atomicAdd(stout + 2 * (size_t)row, sum); atomicAdd(stout + 2 * (size_t)row + 1, sq); }
.LBB0_2642:
	s_or_b64 exec, exec, s[36:37]
	v_or_b32_e32 v104, 48, v154
	v_ashrrev_i32_e32 v105, 31, v104
	v_lshlrev_b64 v[80:81], 3, v[104:105]
	s_waitcnt lgkmcnt(0)
	v_lshl_add_u64 v[82:83], s[6:7], 0, v[80:81]
	flat_load_dwordx2 v[106:107], v[82:83]
	v_lshlrev_b64 v[82:83], 12, v[104:105]
	v_lshl_add_u64 v[82:83], s[46:47], 0, v[82:83]
	v_lshl_add_u64 v[82:83], v[144:145], 2, v[82:83]
	global_load_dwordx4 v[84:87], v[82:83], off
	global_load_dwordx4 v[88:91], v[150:151], off
	global_load_dwordx4 v[92:95], v[152:153], off
	global_load_dwordx4 v[96:99], v[156:157], off
	global_load_dwordx4 v[100:103], v[82:83], off offset:16
	global_load_dwordx4 v[208:211], v[146:147], off
	global_load_dwordx4 v[212:215], v[148:149], off
	global_load_dwordx4 v[250:253], v[124:125], off
	s_waitcnt vmcnt(0) lgkmcnt(0)
	v_pk_mul_f32 v[106:107], v[106:107], s[22:23] op_sel:[1,0] op_sel_hi:[0,0]
	v_fma_f32 v106, -v107, v107, v106
	v_max_f32_e32 v106, 0, v106
	v_add_f32_e32 v106, 0x3727c5ac, v106
	v_mul_f32_e32 v108, 0x4b800000, v106
	v_cmp_gt_f32_e32 vcc, s64, v106
	v_sub_f32_e32 v87, v87, v107
	v_sub_f32_e32 v86, v86, v107
	v_cndmask_b32_e32 v106, v106, v108, vcc
	v_rsq_f32_e32 v106, v106
	v_sub_f32_e32 v85, v85, v107
	v_sub_f32_e32 v84, v84, v107
	v_mul_f32_e32 v108, 0x45800000, v106
	v_cndmask_b32_e32 v106, v106, v108, vcc
	v_pk_mul_f32 v[84:85], v[84:85], v[106:107] op_sel_hi:[1,0]
	v_pk_mul_f32 v[86:87], v[86:87], v[106:107] op_sel_hi:[1,0]
	v_pk_fma_f32 v[84:85], v[88:89], v[84:85], v[92:93]
	v_pk_fma_f32 v[86:87], v[90:91], v[86:87], v[94:95]
	v_pk_fma_f32 v[76:77], v[84:85], s[24:25], v[76:77] op_sel_hi:[1,0,1]
	v_pk_fma_f32 v[78:79], v[86:87], s[24:25], v[78:79] op_sel_hi:[1,0,1]
	v_pk_add_f32 v[76:77], v[96:97], v[76:77]
	v_pk_add_f32 v[78:79], v[98:99], v[78:79]
	global_store_dwordx4 v[82:83], v[76:79], off
	v_lshlrev_b64 v[96:97], 11, v[104:105]
	v_lshl_add_u64 v[96:97], s[10:11], 0, v[96:97]
	v_lshl_add_u64 v[104:105], v[144:145], 1, v[96:97]
	v_sub_f32_e32 v97, v103, v107
	v_sub_f32_e32 v96, v102, v107
	v_sub_f32_e32 v99, v101, v107
	v_sub_f32_e32 v98, v100, v107
	v_pk_mul_f32 v[98:99], v[98:99], v[106:107] op_sel_hi:[1,0]
	v_pk_mul_f32 v[100:101], v[96:97], v[106:107] op_sel_hi:[1,0]
	v_cvt_pk_bf16_f32 v96, v76, v77
	v_cvt_pk_bf16_f32 v97, v78, v79
	v_pk_fma_f32 v[84:85], v[208:209], v[98:99], v[212:213]
	v_pk_fma_f32 v[86:87], v[210:211], v[100:101], v[214:215]
	v_pk_fma_f32 v[72:73], v[84:85], s[24:25], v[72:73] op_sel_hi:[1,0,1]
	v_pk_fma_f32 v[74:75], v[86:87], s[24:25], v[74:75] op_sel_hi:[1,0,1]
	v_pk_add_f32 v[72:73], v[250:251], v[72:73]
	v_pk_add_f32 v[74:75], v[252:253], v[74:75]
	global_store_dwordx4 v[82:83], v[72:75], off offset:16
	v_cvt_pk_bf16_f32 v98, v72, v73
	v_cvt_pk_bf16_f32 v99, v74, v75
	flat_store_dwordx4 v[104:105], v[96:99]
	global_load_dwordx4 v[84:87], v[82:83], off offset:512
	global_load_dwordx4 v[88:91], v[126:127], off
	global_load_dwordx4 v[92:95], v[158:159], off
	s_nop 0
	global_load_dwordx4 v[96:99], v[160:161], off
	global_load_dwordx4 v[100:103], v[82:83], off offset:528
	global_load_dwordx4 v[208:211], v[120:121], off
	global_load_dwordx4 v[212:215], v[122:123], off
	global_load_dwordx4 v[250:253], v[116:117], off
	s_waitcnt vmcnt(0)
	v_sub_f32_e32 v87, v87, v107
	v_sub_f32_e32 v86, v86, v107
	v_sub_f32_e32 v85, v85, v107
	v_sub_f32_e32 v84, v84, v107
	v_pk_mul_f32 v[84:85], v[106:107], v[84:85] op_sel_hi:[0,1]
	v_pk_mul_f32 v[86:87], v[106:107], v[86:87] op_sel_hi:[0,1]
	v_pk_fma_f32 v[86:87], v[90:91], v[86:87], v[94:95]
	v_pk_fma_f32 v[84:85], v[88:89], v[84:85], v[92:93]
	v_pk_fma_f32 v[70:71], v[86:87], s[24:25], v[70:71] op_sel_hi:[1,0,1]
	v_pk_fma_f32 v[68:69], v[84:85], s[24:25], v[68:69] op_sel_hi:[1,0,1]
	v_pk_add_f32 v[70:71], v[98:99], v[70:71]
	v_pk_add_f32 v[68:69], v[96:97], v[68:69]
	global_store_dwordx4 v[82:83], v[68:71], off offset:512
	v_add_f32_e32 v96, v76, v77
	v_mul_f32_e32 v77, v77, v77
	v_fmac_f32_e32 v77, v76, v76
	v_add_f32_e32 v96, v78, v96
	v_fmac_f32_e32 v77, v78, v78
	v_add_f32_e32 v78, v72, v73
	v_mul_f32_e32 v73, v73, v73
	v_fmac_f32_e32 v73, v72, v72
	v_add_f32_e32 v76, v79, v96
	v_add_f32_e32 v78, v74, v78
	v_fmac_f32_e32 v73, v74, v74
	v_add_f32_e32 v76, 0, v76
	v_fmac_f32_e32 v77, v79, v79
	v_add_f32_e32 v72, v75, v78
	v_fmac_f32_e32 v73, v75, v75
	v_sub_f32_e32 v75, v101, v107
	v_sub_f32_e32 v74, v100, v107
	v_add_f32_e32 v76, v72, v76
	v_add_f32_e32 v77, v77, v73
	v_sub_f32_e32 v73, v103, v107
	v_sub_f32_e32 v72, v102, v107
	v_pk_mul_f32 v[74:75], v[106:107], v[74:75] op_sel_hi:[0,1]
	v_pk_mul_f32 v[72:73], v[106:107], v[72:73] op_sel_hi:[0,1]
	v_mul_f32_e32 v79, v69, v69
	v_add_f32_e32 v78, v68, v69
	v_fmac_f32_e32 v79, v68, v68
	v_add_f32_e32 v78, v70, v78
	v_fmac_f32_e32 v79, v70, v70
	v_add_f32_e32 v78, v71, v78
	v_fmac_f32_e32 v79, v71, v71
	v_add_f32_e32 v76, v76, v78
	v_add_f32_e32 v77, v77, v79
	v_cvt_pk_bf16_f32 v68, v68, v69
	v_cvt_pk_bf16_f32 v69, v70, v71
	v_pk_fma_f32 v[74:75], v[208:209], v[74:75], v[212:213]
	v_pk_fma_f32 v[72:73], v[210:211], v[72:73], v[214:215]
	v_pk_fma_f32 v[64:65], v[74:75], s[24:25], v[64:65] op_sel_hi:[1,0,1]
	v_pk_fma_f32 v[66:67], v[72:73], s[24:25], v[66:67] op_sel_hi:[1,0,1]
	v_pk_add_f32 v[72:73], v[250:251], v[64:65]
	v_pk_add_f32 v[74:75], v[252:253], v[66:67]
	v_mul_f32_e32 v65, v73, v73
	v_add_f32_e32 v64, v72, v73
	v_fmac_f32_e32 v65, v72, v72
	v_add_f32_e32 v64, v74, v64
	v_fmac_f32_e32 v65, v74, v74
	v_add_f32_e32 v64, v75, v64
	v_fmac_f32_e32 v65, v75, v75
	v_add_f32_e32 v64, v76, v64
	v_add_f32_e32 v65, v77, v65
	ds_bpermute_b32 v66, v118, v64
	ds_bpermute_b32 v67, v118, v65
	global_store_dwordx4 v[82:83], v[72:75], off offset:528
	v_cvt_pk_bf16_f32 v70, v72, v73
	v_cvt_pk_bf16_f32 v71, v74, v75
	s_waitcnt lgkmcnt(0)
	v_add_f32_e32 v64, v64, v66
	v_add_f32_e32 v65, v65, v67
	ds_bpermute_b32 v66, v119, v64
	ds_bpermute_b32 v67, v119, v65
	flat_store_dwordx4 v[104:105], v[68:71] offset:256
	s_and_saveexec_b64 s[36:37], s[2:3]
	s_cbranch_execz .LBB0_2644
	v_lshl_add_u64 v[68:69], s[8:9], 0, v[80:81]
	s_waitcnt lgkmcnt(0)
	v_add_f32_e32 v64, v64, v66
	v_add_f32_e32 v65, v65, v67
	flat_atomic_add_f32 v[68:69], v64
	flat_atomic_add_f32 v[68:69], v65 offset:4
; DEVI unsigned pk2(float lo, float hi) { unsigned r; asm("v_cvt_pk_bf16_f32 %0, %1, %2" : "=v"(r) : "v"(lo), "v"(hi)); return r; }
; DEVI void row_stats(const float* stats, int row, float& mu, float& rs) {
;     if (stats) { const float2 st = *(const float2*)(stats + 2 * (size_t)row); mu = st.x * (1.0f / 1024.0f); const float var = st.y * (1.0f / 1024.0f) - mu * mu; rs = rsqrtf(fmaxf(var, 0.f) + LN_EPS); }
;     DEVI void operator()(const f32x4 (&acc)[2][2][4][2], const pg8::Unit& u, int wr, int wc, int fr, int fq) const {
;     ...
;                 const int row = row0 + ai * 128 + m * 16; float mu, rs; row_stats(stin, row, mu, rs);
;                 float sum = 0.f, sq = 0.f;
; #pragma unroll
;                 for (int bj = 0; bj < 2; ++bj) {
;                     f32x4 z[2];
; #pragma unroll
;                     for (int n = 0; n < 2; ++n) {
;                         const int col = colb + bj * 128 + 4 * n;
;                         f32x4 xv = *(const f32x4*)(zsrc + (size_t)row * DM + col);
;                         if (stin) { const f32x4 gv = *(const f32x4*)(gin + col), bv = *(const f32x4*)(bin + col); xv = (xv - mu) * rs * gv + bv; }
;                         f32x4 zz = ALPHA * xv + acc[ai][bj][m][n];
;                         if (bias) zz += *(const f32x4*)(bias + col);
;                         *(f32x4*)(zdst + (size_t)row * DM + col) = zz;
;                         sum += zz[0] + zz[1] + zz[2] + zz[3]; sq += zz[0] * zz[0] + zz[1] * zz[1] + zz[2] * zz[2] + zz[3] * zz[3];
;                         z[n] = zz;
;                     }
;                     u32x4 o; o.x = pk2(z[0][0], z[0][1]); o.y = pk2(z[0][2], z[0][3]); o.z = pk2(z[1][0], z[1][1]); o.w = pk2(z[1][2], z[1][3]);
;                     if (zb) *(u32x4*)(zb + (size_t)row * DM + colb + bj * 128) = o;
;                 }
;                 sum += __shfl_xor(sum, 16); sq += __shfl_xor(sq, 16);
;                 sum += __shfl_xor(sum, 32); sq += __shfl_xor(sq, 32);
;                 if (fq == 0) { atomicAdd(stout + 2 * (size_t)row, sum); atomicAdd(stout + 2 * (size_t)row + 1, sq); }
.LBB0_2644:
	s_or_b64 exec, exec, s[36:37]
	v_add_u32_e32 v88, 0x80, v154
	v_ashrrev_i32_e32 v89, 31, v88
	v_lshlrev_b64 v[64:65], 3, v[88:89]
	s_waitcnt lgkmcnt(0)
	v_lshl_add_u64 v[66:67], s[6:7], 0, v[64:65]
	flat_load_dwordx2 v[90:91], v[66:67]
	v_lshlrev_b64 v[66:67], 12, v[88:89]
	v_lshl_add_u64 v[66:67], s[46:47], 0, v[66:67]
	v_lshl_add_u64 v[66:67], v[144:145], 2, v[66:67]
	global_load_dwordx4 v[68:71], v[66:67], off
	global_load_dwordx4 v[72:75], v[150:151], off
	global_load_dwordx4 v[76:79], v[152:153], off
	global_load_dwordx4 v[80:83], v[156:157], off
	global_load_dwordx4 v[84:87], v[66:67], off offset:16
	global_load_dwordx4 v[208:211], v[146:147], off
	global_load_dwordx4 v[212:215], v[148:149], off
	global_load_dwordx4 v[250:253], v[124:125], off
	s_waitcnt vmcnt(0) lgkmcnt(0)
	v_pk_mul_f32 v[90:91], v[90:91], s[22:23] op_sel:[1,0] op_sel_hi:[0,0]
	v_fma_f32 v90, -v91, v91, v90
	v_max_f32_e32 v90, 0, v90
	v_add_f32_e32 v90, 0x3727c5ac, v90
	v_mul_f32_e32 v92, 0x4b800000, v90
	v_cmp_gt_f32_e32 vcc, s64, v90
	v_sub_f32_e32 v71, v71, v91
	v_sub_f32_e32 v70, v70, v91
	v_cndmask_b32_e32 v90, v90, v92, vcc
	v_rsq_f32_e32 v90, v90
	v_sub_f32_e32 v69, v69, v91
	v_sub_f32_e32 v68, v68, v91
	v_mul_f32_e32 v92, 0x45800000, v90
	v_cndmask_b32_e32 v90, v90, v92, vcc
	v_pk_mul_f32 v[68:69], v[68:69], v[90:91] op_sel_hi:[1,0]
	v_pk_mul_f32 v[70:71], v[70:71], v[90:91] op_sel_hi:[1,0]
	v_pk_fma_f32 v[68:69], v[72:73], v[68:69], v[76:77]
	v_pk_fma_f32 v[70:71], v[74:75], v[70:71], v[78:79]
	v_pk_fma_f32 v[60:61], v[68:69], s[24:25], v[60:61] op_sel_hi:[1,0,1]
	v_pk_fma_f32 v[62:63], v[70:71], s[24:25], v[62:63] op_sel_hi:[1,0,1]
	v_pk_add_f32 v[60:61], v[80:81], v[60:61]
	v_pk_add_f32 v[62:63], v[82:83], v[62:63]
	global_store_dwordx4 v[66:67], v[60:63], off
	v_lshlrev_b64 v[80:81], 11, v[88:89]
	v_lshl_add_u64 v[80:81], s[10:11], 0, v[80:81]
	v_lshl_add_u64 v[88:89], v[144:145], 1, v[80:81]
	v_sub_f32_e32 v81, v87, v91
	v_sub_f32_e32 v80, v86, v91
	v_sub_f32_e32 v83, v85, v91
	v_sub_f32_e32 v82, v84, v91
	v_pk_mul_f32 v[82:83], v[82:83], v[90:91] op_sel_hi:[1,0]
	v_pk_mul_f32 v[84:85], v[80:81], v[90:91] op_sel_hi:[1,0]
	v_cvt_pk_bf16_f32 v80, v60, v61
	v_cvt_pk_bf16_f32 v81, v62, v63
	v_pk_fma_f32 v[68:69], v[208:209], v[82:83], v[212:213]
	v_pk_fma_f32 v[70:71], v[210:211], v[84:85], v[214:215]
	v_pk_fma_f32 v[56:57], v[68:69], s[24:25], v[56:57] op_sel_hi:[1,0,1]
	v_pk_fma_f32 v[58:59], v[70:71], s[24:25], v[58:59] op_sel_hi:[1,0,1]
	v_pk_add_f32 v[56:57], v[250:251], v[56:57]
	v_pk_add_f32 v[58:59], v[252:253], v[58:59]
	global_store_dwordx4 v[66:67], v[56:59], off offset:16
	v_cvt_pk_bf16_f32 v82, v56, v57
	v_cvt_pk_bf16_f32 v83, v58, v59
	flat_store_dwordx4 v[88:89], v[80:83]
	global_load_dwordx4 v[68:71], v[66:67], off offset:512
	global_load_dwordx4 v[72:75], v[126:127], off
	global_load_dwordx4 v[76:79], v[158:159], off
	s_nop 0
	global_load_dwordx4 v[80:83], v[160:161], off
	global_load_dwordx4 v[84:87], v[66:67], off offset:528
	global_load_dwordx4 v[208:211], v[120:121], off
	global_load_dwordx4 v[212:215], v[122:123], off
	global_load_dwordx4 v[250:253], v[116:117], off
	s_waitcnt vmcnt(0)
	v_sub_f32_e32 v71, v71, v91
	v_sub_f32_e32 v70, v70, v91
	v_sub_f32_e32 v69, v69, v91
	v_sub_f32_e32 v68, v68, v91
	v_pk_mul_f32 v[68:69], v[90:91], v[68:69] op_sel_hi:[0,1]
	v_pk_mul_f32 v[70:71], v[90:91], v[70:71] op_sel_hi:[0,1]
	v_pk_fma_f32 v[70:71], v[74:75], v[70:71], v[78:79]
	v_pk_fma_f32 v[68:69], v[72:73], v[68:69], v[76:77]
	v_pk_fma_f32 v[54:55], v[70:71], s[24:25], v[54:55] op_sel_hi:[1,0,1]
	v_pk_fma_f32 v[52:53], v[68:69], s[24:25], v[52:53] op_sel_hi:[1,0,1]
	v_pk_add_f32 v[54:55], v[82:83], v[54:55]
	v_pk_add_f32 v[52:53], v[80:81], v[52:53]
	global_store_dwordx4 v[66:67], v[52:55], off offset:512
	v_add_f32_e32 v80, v60, v61
	v_mul_f32_e32 v61, v61, v61
	v_fmac_f32_e32 v61, v60, v60
	v_add_f32_e32 v80, v62, v80
	v_fmac_f32_e32 v61, v62, v62
	v_add_f32_e32 v62, v56, v57
	v_mul_f32_e32 v57, v57, v57
	v_fmac_f32_e32 v57, v56, v56
	v_add_f32_e32 v60, v63, v80
	v_add_f32_e32 v62, v58, v62
	v_fmac_f32_e32 v57, v58, v58
	v_add_f32_e32 v60, 0, v60
	v_fmac_f32_e32 v61, v63, v63
	v_add_f32_e32 v56, v59, v62
	v_fmac_f32_e32 v57, v59, v59
	v_sub_f32_e32 v59, v85, v91
	v_sub_f32_e32 v58, v84, v91
	v_add_f32_e32 v60, v56, v60
	v_add_f32_e32 v61, v61, v57
	v_sub_f32_e32 v57, v87, v91
	v_sub_f32_e32 v56, v86, v91
	v_pk_mul_f32 v[58:59], v[90:91], v[58:59] op_sel_hi:[0,1]
	v_pk_mul_f32 v[56:57], v[90:91], v[56:57] op_sel_hi:[0,1]
	v_mul_f32_e32 v63, v53, v53
	v_add_f32_e32 v62, v52, v53
	v_fmac_f32_e32 v63, v52, v52
	v_add_f32_e32 v62, v54, v62
	v_fmac_f32_e32 v63, v54, v54
	v_add_f32_e32 v62, v55, v62
	v_fmac_f32_e32 v63, v55, v55
	v_add_f32_e32 v60, v60, v62
	v_add_f32_e32 v61, v61, v63
	v_cvt_pk_bf16_f32 v52, v52, v53
	v_cvt_pk_bf16_f32 v53, v54, v55
	v_pk_fma_f32 v[58:59], v[208:209], v[58:59], v[212:213]
	v_pk_fma_f32 v[56:57], v[210:211], v[56:57], v[214:215]
	v_pk_fma_f32 v[48:49], v[58:59], s[24:25], v[48:49] op_sel_hi:[1,0,1]
	v_pk_fma_f32 v[50:51], v[56:57], s[24:25], v[50:51] op_sel_hi:[1,0,1]
	v_pk_add_f32 v[56:57], v[250:251], v[48:49]
	v_pk_add_f32 v[58:59], v[252:253], v[50:51]
	v_mul_f32_e32 v49, v57, v57
	v_add_f32_e32 v48, v56, v57
	v_fmac_f32_e32 v49, v56, v56
	v_add_f32_e32 v48, v58, v48
	v_fmac_f32_e32 v49, v58, v58
	v_add_f32_e32 v48, v59, v48
	v_fmac_f32_e32 v49, v59, v59
	v_add_f32_e32 v48, v60, v48
	v_add_f32_e32 v49, v61, v49
	ds_bpermute_b32 v50, v118, v48
	ds_bpermute_b32 v51, v118, v49
	global_store_dwordx4 v[66:67], v[56:59], off offset:528
	v_cvt_pk_bf16_f32 v54, v56, v57
	v_cvt_pk_bf16_f32 v55, v58, v59
	s_waitcnt lgkmcnt(0)
	v_add_f32_e32 v48, v48, v50
	v_add_f32_e32 v49, v49, v51
	ds_bpermute_b32 v50, v119, v48
	ds_bpermute_b32 v51, v119, v49
	flat_store_dwordx4 v[88:89], v[52:55] offset:256
	s_and_saveexec_b64 s[36:37], s[2:3]
	s_cbranch_execz .LBB0_2646
	v_lshl_add_u64 v[52:53], s[8:9], 0, v[64:65]
	s_waitcnt lgkmcnt(0)
	v_add_f32_e32 v48, v48, v50
	v_add_f32_e32 v49, v49, v51
	flat_atomic_add_f32 v[52:53], v48
	flat_atomic_add_f32 v[52:53], v49 offset:4
; DEVI unsigned pk2(float lo, float hi) { unsigned r; asm("v_cvt_pk_bf16_f32 %0, %1, %2" : "=v"(r) : "v"(lo), "v"(hi)); return r; }
; DEVI void row_stats(const float* stats, int row, float& mu, float& rs) {
;     if (stats) { const float2 st = *(const float2*)(stats + 2 * (size_t)row); mu = st.x * (1.0f / 1024.0f); const float var = st.y * (1.0f / 1024.0f) - mu * mu; rs = rsqrtf(fmaxf(var, 0.f) + LN_EPS); }
;     DEVI void operator()(const f32x4 (&acc)[2][2][4][2], const pg8::Unit& u, int wr, int wc, int fr, int fq) const {
;     ...
;                 const int row = row0 + ai * 128 + m * 16; float mu, rs; row_stats(stin, row, mu, rs);
;                 float sum = 0.f, sq = 0.f;
; #pragma unroll
;                 for (int bj = 0; bj < 2; ++bj) {
;                     f32x4 z[2];
; #pragma unroll
;                     for (int n = 0; n < 2; ++n) {
;                         const int col = colb + bj * 128 + 4 * n;
;                         f32x4 xv = *(const f32x4*)(zsrc + (size_t)row * DM + col);
;                         if (stin) { const f32x4 gv = *(const f32x4*)(gin + col), bv = *(const f32x4*)(bin + col); xv = (xv - mu) * rs * gv + bv; }
;                         f32x4 zz = ALPHA * xv + acc[ai][bj][m][n];
;                         if (bias) zz += *(const f32x4*)(bias + col);
;                         *(f32x4*)(zdst + (size_t)row * DM + col) = zz;
;                         sum += zz[0] + zz[1] + zz[2] + zz[3]; sq += zz[0] * zz[0] + zz[1] * zz[1] + zz[2] * zz[2] + zz[3] * zz[3];
;                         z[n] = zz;
;                     }
;                     u32x4 o; o.x = pk2(z[0][0], z[0][1]); o.y = pk2(z[0][2], z[0][3]); o.z = pk2(z[1][0], z[1][1]); o.w = pk2(z[1][2], z[1][3]);
;                     if (zb) *(u32x4*)(zb + (size_t)row * DM + colb + bj * 128) = o;
;                 }
;                 sum += __shfl_xor(sum, 16); sq += __shfl_xor(sq, 16);
;                 sum += __shfl_xor(sum, 32); sq += __shfl_xor(sq, 32);
;                 if (fq == 0) { atomicAdd(stout + 2 * (size_t)row, sum); atomicAdd(stout + 2 * (size_t)row + 1, sq); }
.LBB0_2646:
	s_or_b64 exec, exec, s[36:37]
	v_add_u32_e32 v72, 0x90, v154
	v_ashrrev_i32_e32 v73, 31, v72
	v_lshlrev_b64 v[48:49], 3, v[72:73]
	s_waitcnt lgkmcnt(0)
	v_lshl_add_u64 v[50:51], s[6:7], 0, v[48:49]
	flat_load_dwordx2 v[74:75], v[50:51]
	v_lshlrev_b64 v[50:51], 12, v[72:73]
	v_lshl_add_u64 v[50:51], s[46:47], 0, v[50:51]
	v_lshl_add_u64 v[50:51], v[144:145], 2, v[50:51]
	global_load_dwordx4 v[52:55], v[50:51], off
	global_load_dwordx4 v[56:59], v[150:151], off
	global_load_dwordx4 v[60:63], v[152:153], off
	global_load_dwordx4 v[64:67], v[156:157], off
	global_load_dwordx4 v[68:71], v[50:51], off offset:16
	global_load_dwordx4 v[208:211], v[146:147], off
	global_load_dwordx4 v[212:215], v[148:149], off
	global_load_dwordx4 v[250:253], v[124:125], off
	s_waitcnt vmcnt(0) lgkmcnt(0)
	v_pk_mul_f32 v[74:75], v[74:75], s[22:23] op_sel:[1,0] op_sel_hi:[0,0]
	v_fma_f32 v74, -v75, v75, v74
	v_max_f32_e32 v74, 0, v74
	v_add_f32_e32 v74, 0x3727c5ac, v74
	v_mul_f32_e32 v76, 0x4b800000, v74
	v_cmp_gt_f32_e32 vcc, s64, v74
	v_sub_f32_e32 v55, v55, v75
	v_sub_f32_e32 v54, v54, v75
	v_cndmask_b32_e32 v74, v74, v76, vcc
	v_rsq_f32_e32 v74, v74
	v_sub_f32_e32 v53, v53, v75
	v_sub_f32_e32 v52, v52, v75
	v_mul_f32_e32 v76, 0x45800000, v74
	v_cndmask_b32_e32 v74, v74, v76, vcc
	v_pk_mul_f32 v[52:53], v[52:53], v[74:75] op_sel_hi:[1,0]
	v_pk_mul_f32 v[54:55], v[54:55], v[74:75] op_sel_hi:[1,0]
	v_pk_fma_f32 v[52:53], v[56:57], v[52:53], v[60:61]
	v_pk_fma_f32 v[54:55], v[58:59], v[54:55], v[62:63]
	v_pk_fma_f32 v[44:45], v[52:53], s[24:25], v[44:45] op_sel_hi:[1,0,1]
	v_pk_fma_f32 v[46:47], v[54:55], s[24:25], v[46:47] op_sel_hi:[1,0,1]
	v_pk_add_f32 v[44:45], v[64:65], v[44:45]
	v_pk_add_f32 v[46:47], v[66:67], v[46:47]
	global_store_dwordx4 v[50:51], v[44:47], off
	v_lshlrev_b64 v[64:65], 11, v[72:73]
	v_lshl_add_u64 v[64:65], s[10:11], 0, v[64:65]
	v_lshl_add_u64 v[72:73], v[144:145], 1, v[64:65]
	v_sub_f32_e32 v65, v71, v75
	v_sub_f32_e32 v64, v70, v75
	v_sub_f32_e32 v67, v69, v75
	v_sub_f32_e32 v66, v68, v75
	v_pk_mul_f32 v[66:67], v[66:67], v[74:75] op_sel_hi:[1,0]
	v_pk_mul_f32 v[68:69], v[64:65], v[74:75] op_sel_hi:[1,0]
	v_cvt_pk_bf16_f32 v64, v44, v45
	v_cvt_pk_bf16_f32 v65, v46, v47
	v_pk_fma_f32 v[52:53], v[208:209], v[66:67], v[212:213]
	v_pk_fma_f32 v[54:55], v[210:211], v[68:69], v[214:215]
	v_pk_fma_f32 v[40:41], v[52:53], s[24:25], v[40:41] op_sel_hi:[1,0,1]
	v_pk_fma_f32 v[42:43], v[54:55], s[24:25], v[42:43] op_sel_hi:[1,0,1]
	v_pk_add_f32 v[40:41], v[250:251], v[40:41]
	v_pk_add_f32 v[42:43], v[252:253], v[42:43]
	global_store_dwordx4 v[50:51], v[40:43], off offset:16
	v_cvt_pk_bf16_f32 v66, v40, v41
	v_cvt_pk_bf16_f32 v67, v42, v43
	flat_store_dwordx4 v[72:73], v[64:67]
	global_load_dwordx4 v[52:55], v[50:51], off offset:512
	global_load_dwordx4 v[56:59], v[126:127], off
	global_load_dwordx4 v[60:63], v[158:159], off
	s_nop 0
	global_load_dwordx4 v[64:67], v[160:161], off
	global_load_dwordx4 v[68:71], v[50:51], off offset:528
	global_load_dwordx4 v[208:211], v[120:121], off
	global_load_dwordx4 v[212:215], v[122:123], off
	global_load_dwordx4 v[250:253], v[116:117], off
	s_waitcnt vmcnt(0)
	v_sub_f32_e32 v55, v55, v75
	v_sub_f32_e32 v54, v54, v75
	v_sub_f32_e32 v53, v53, v75
	v_sub_f32_e32 v52, v52, v75
	v_pk_mul_f32 v[52:53], v[74:75], v[52:53] op_sel_hi:[0,1]
	v_pk_mul_f32 v[54:55], v[74:75], v[54:55] op_sel_hi:[0,1]
	v_pk_fma_f32 v[54:55], v[58:59], v[54:55], v[62:63]
	v_pk_fma_f32 v[52:53], v[56:57], v[52:53], v[60:61]
	v_pk_fma_f32 v[38:39], v[54:55], s[24:25], v[38:39] op_sel_hi:[1,0,1]
	v_pk_fma_f32 v[36:37], v[52:53], s[24:25], v[36:37] op_sel_hi:[1,0,1]
	v_pk_add_f32 v[38:39], v[66:67], v[38:39]
	v_pk_add_f32 v[36:37], v[64:65], v[36:37]
	global_store_dwordx4 v[50:51], v[36:39], off offset:512
	v_add_f32_e32 v64, v44, v45
	v_mul_f32_e32 v45, v45, v45
	v_fmac_f32_e32 v45, v44, v44
	v_add_f32_e32 v64, v46, v64
	v_fmac_f32_e32 v45, v46, v46
	v_add_f32_e32 v46, v40, v41
	v_mul_f32_e32 v41, v41, v41
	v_fmac_f32_e32 v41, v40, v40
	v_add_f32_e32 v44, v47, v64
	v_add_f32_e32 v46, v42, v46
	v_fmac_f32_e32 v41, v42, v42
	v_add_f32_e32 v44, 0, v44
	v_fmac_f32_e32 v45, v47, v47
	v_add_f32_e32 v40, v43, v46
	v_fmac_f32_e32 v41, v43, v43
	v_sub_f32_e32 v43, v69, v75
	v_sub_f32_e32 v42, v68, v75
	v_add_f32_e32 v44, v40, v44
	v_add_f32_e32 v45, v45, v41
	v_sub_f32_e32 v41, v71, v75
	v_sub_f32_e32 v40, v70, v75
	v_pk_mul_f32 v[42:43], v[74:75], v[42:43] op_sel_hi:[0,1]
	v_pk_mul_f32 v[40:41], v[74:75], v[40:41] op_sel_hi:[0,1]
	v_mul_f32_e32 v47, v37, v37
	v_add_f32_e32 v46, v36, v37
	v_fmac_f32_e32 v47, v36, v36
	v_add_f32_e32 v46, v38, v46
	v_fmac_f32_e32 v47, v38, v38
	v_add_f32_e32 v46, v39, v46
	v_fmac_f32_e32 v47, v39, v39
	v_add_f32_e32 v44, v44, v46
	v_add_f32_e32 v45, v45, v47
	v_cvt_pk_bf16_f32 v36, v36, v37
	v_cvt_pk_bf16_f32 v37, v38, v39
	v_pk_fma_f32 v[42:43], v[208:209], v[42:43], v[212:213]
	v_pk_fma_f32 v[40:41], v[210:211], v[40:41], v[214:215]
	v_pk_fma_f32 v[32:33], v[42:43], s[24:25], v[32:33] op_sel_hi:[1,0,1]
	v_pk_fma_f32 v[34:35], v[40:41], s[24:25], v[34:35] op_sel_hi:[1,0,1]
	v_pk_add_f32 v[40:41], v[250:251], v[32:33]
	v_pk_add_f32 v[42:43], v[252:253], v[34:35]
	v_mul_f32_e32 v33, v41, v41
	v_add_f32_e32 v32, v40, v41
	v_fmac_f32_e32 v33, v40, v40
	v_add_f32_e32 v32, v42, v32
	v_fmac_f32_e32 v33, v42, v42
	v_add_f32_e32 v32, v43, v32
	v_fmac_f32_e32 v33, v43, v43
	v_add_f32_e32 v32, v44, v32
	v_add_f32_e32 v33, v45, v33
	ds_bpermute_b32 v34, v118, v32
	ds_bpermute_b32 v35, v118, v33
	global_store_dwordx4 v[50:51], v[40:43], off offset:528
	v_cvt_pk_bf16_f32 v38, v40, v41
	v_cvt_pk_bf16_f32 v39, v42, v43
	s_waitcnt lgkmcnt(0)
	v_add_f32_e32 v32, v32, v34
	v_add_f32_e32 v33, v33, v35
	ds_bpermute_b32 v34, v119, v32
	ds_bpermute_b32 v35, v119, v33
	flat_store_dwordx4 v[72:73], v[36:39] offset:256
	s_and_saveexec_b64 s[36:37], s[2:3]
	s_cbranch_execz .LBB0_2648
	v_lshl_add_u64 v[36:37], s[8:9], 0, v[48:49]
	s_waitcnt lgkmcnt(0)
	v_add_f32_e32 v32, v32, v34
	v_add_f32_e32 v33, v33, v35
	flat_atomic_add_f32 v[36:37], v32
	flat_atomic_add_f32 v[36:37], v33 offset:4
; DEVI unsigned pk2(float lo, float hi) { unsigned r; asm("v_cvt_pk_bf16_f32 %0, %1, %2" : "=v"(r) : "v"(lo), "v"(hi)); return r; }
; DEVI void row_stats(const float* stats, int row, float& mu, float& rs) {
;     if (stats) { const float2 st = *(const float2*)(stats + 2 * (size_t)row); mu = st.x * (1.0f / 1024.0f); const float var = st.y * (1.0f / 1024.0f) - mu * mu; rs = rsqrtf(fmaxf(var, 0.f) + LN_EPS); }
;     DEVI void operator()(const f32x4 (&acc)[2][2][4][2], const pg8::Unit& u, int wr, int wc, int fr, int fq) const {
;     ...
;                 const int row = row0 + ai * 128 + m * 16; float mu, rs; row_stats(stin, row, mu, rs);
;                 float sum = 0.f, sq = 0.f;
; #pragma unroll
;                 for (int bj = 0; bj < 2; ++bj) {
;                     f32x4 z[2];
; #pragma unroll
;                     for (int n = 0; n < 2; ++n) {
;                         const int col = colb + bj * 128 + 4 * n;
;                         f32x4 xv = *(const f32x4*)(zsrc + (size_t)row * DM + col);
;                         if (stin) { const f32x4 gv = *(const f32x4*)(gin + col), bv = *(const f32x4*)(bin + col); xv = (xv - mu) * rs * gv + bv; }
;                         f32x4 zz = ALPHA * xv + acc[ai][bj][m][n];
;                         if (bias) zz += *(const f32x4*)(bias + col);
;                         *(f32x4*)(zdst + (size_t)row * DM + col) = zz;
;                         sum += zz[0] + zz[1] + zz[2] + zz[3]; sq += zz[0] * zz[0] + zz[1] * zz[1] + zz[2] * zz[2] + zz[3] * zz[3];
;                         z[n] = zz;
;                     }
;                     u32x4 o; o.x = pk2(z[0][0], z[0][1]); o.y = pk2(z[0][2], z[0][3]); o.z = pk2(z[1][0], z[1][1]); o.w = pk2(z[1][2], z[1][3]);
;                     if (zb) *(u32x4*)(zb + (size_t)row * DM + colb + bj * 128) = o;
;                 }
;                 sum += __shfl_xor(sum, 16); sq += __shfl_xor(sq, 16);
;                 sum += __shfl_xor(sum, 32); sq += __shfl_xor(sq, 32);
;                 if (fq == 0) { atomicAdd(stout + 2 * (size_t)row, sum); atomicAdd(stout + 2 * (size_t)row + 1, sq); }
.LBB0_2648:
	s_or_b64 exec, exec, s[36:37]
	v_add_u32_e32 v56, 0xa0, v154
	v_ashrrev_i32_e32 v57, 31, v56
	v_lshlrev_b64 v[32:33], 3, v[56:57]
	s_waitcnt lgkmcnt(0)
	v_lshl_add_u64 v[34:35], s[6:7], 0, v[32:33]
	flat_load_dwordx2 v[58:59], v[34:35]
	v_lshlrev_b64 v[34:35], 12, v[56:57]
	v_lshl_add_u64 v[34:35], s[46:47], 0, v[34:35]
	v_lshl_add_u64 v[34:35], v[144:145], 2, v[34:35]
	global_load_dwordx4 v[36:39], v[34:35], off
	global_load_dwordx4 v[40:43], v[150:151], off
	global_load_dwordx4 v[44:47], v[152:153], off
	global_load_dwordx4 v[48:51], v[156:157], off
	global_load_dwordx4 v[52:55], v[34:35], off offset:16
	global_load_dwordx4 v[208:211], v[146:147], off
	global_load_dwordx4 v[212:215], v[148:149], off
	global_load_dwordx4 v[250:253], v[124:125], off
	s_waitcnt vmcnt(0) lgkmcnt(0)
	v_pk_mul_f32 v[58:59], v[58:59], s[22:23] op_sel:[1,0] op_sel_hi:[0,0]
	v_fma_f32 v58, -v59, v59, v58
	v_max_f32_e32 v58, 0, v58
	v_add_f32_e32 v58, 0x3727c5ac, v58
	v_mul_f32_e32 v60, 0x4b800000, v58
	v_cmp_gt_f32_e32 vcc, s64, v58
	v_sub_f32_e32 v39, v39, v59
	v_sub_f32_e32 v38, v38, v59
	v_cndmask_b32_e32 v58, v58, v60, vcc
	v_rsq_f32_e32 v58, v58
	v_sub_f32_e32 v37, v37, v59
	v_sub_f32_e32 v36, v36, v59
	v_mul_f32_e32 v60, 0x45800000, v58
	v_cndmask_b32_e32 v58, v58, v60, vcc
	v_pk_mul_f32 v[36:37], v[36:37], v[58:59] op_sel_hi:[1,0]
	v_pk_mul_f32 v[38:39], v[38:39], v[58:59] op_sel_hi:[1,0]
	v_pk_fma_f32 v[36:37], v[40:41], v[36:37], v[44:45]
	v_pk_fma_f32 v[38:39], v[42:43], v[38:39], v[46:47]
	v_pk_fma_f32 v[28:29], v[36:37], s[24:25], v[28:29] op_sel_hi:[1,0,1]
	v_pk_fma_f32 v[30:31], v[38:39], s[24:25], v[30:31] op_sel_hi:[1,0,1]
	v_pk_add_f32 v[28:29], v[48:49], v[28:29]
	v_pk_add_f32 v[30:31], v[50:51], v[30:31]
	global_store_dwordx4 v[34:35], v[28:31], off
	v_lshlrev_b64 v[48:49], 11, v[56:57]
	v_lshl_add_u64 v[48:49], s[10:11], 0, v[48:49]
	v_lshl_add_u64 v[56:57], v[144:145], 1, v[48:49]
	v_sub_f32_e32 v49, v55, v59
	v_sub_f32_e32 v48, v54, v59
	v_sub_f32_e32 v51, v53, v59
	v_sub_f32_e32 v50, v52, v59
	v_pk_mul_f32 v[50:51], v[50:51], v[58:59] op_sel_hi:[1,0]
	v_pk_mul_f32 v[52:53], v[48:49], v[58:59] op_sel_hi:[1,0]
	v_cvt_pk_bf16_f32 v48, v28, v29
	v_cvt_pk_bf16_f32 v49, v30, v31
	v_pk_fma_f32 v[36:37], v[208:209], v[50:51], v[212:213]
	v_pk_fma_f32 v[38:39], v[210:211], v[52:53], v[214:215]
	v_pk_fma_f32 v[24:25], v[36:37], s[24:25], v[24:25] op_sel_hi:[1,0,1]
	v_pk_fma_f32 v[26:27], v[38:39], s[24:25], v[26:27] op_sel_hi:[1,0,1]
	v_pk_add_f32 v[24:25], v[250:251], v[24:25]
	v_pk_add_f32 v[26:27], v[252:253], v[26:27]
	global_store_dwordx4 v[34:35], v[24:27], off offset:16
	v_cvt_pk_bf16_f32 v50, v24, v25
	v_cvt_pk_bf16_f32 v51, v26, v27
	flat_store_dwordx4 v[56:57], v[48:51]
	global_load_dwordx4 v[36:39], v[34:35], off offset:512
	global_load_dwordx4 v[40:43], v[126:127], off
	global_load_dwordx4 v[44:47], v[158:159], off
	s_nop 0
	global_load_dwordx4 v[48:51], v[160:161], off
	global_load_dwordx4 v[52:55], v[34:35], off offset:528
	global_load_dwordx4 v[208:211], v[120:121], off
	global_load_dwordx4 v[212:215], v[122:123], off
	global_load_dwordx4 v[250:253], v[116:117], off
	s_waitcnt vmcnt(0)
	v_sub_f32_e32 v39, v39, v59
	v_sub_f32_e32 v38, v38, v59
	v_sub_f32_e32 v37, v37, v59
	v_sub_f32_e32 v36, v36, v59
	v_pk_mul_f32 v[36:37], v[58:59], v[36:37] op_sel_hi:[0,1]
	v_pk_mul_f32 v[38:39], v[58:59], v[38:39] op_sel_hi:[0,1]
	v_pk_fma_f32 v[38:39], v[42:43], v[38:39], v[46:47]
	v_pk_fma_f32 v[36:37], v[40:41], v[36:37], v[44:45]
	v_pk_fma_f32 v[22:23], v[38:39], s[24:25], v[22:23] op_sel_hi:[1,0,1]
	v_pk_fma_f32 v[20:21], v[36:37], s[24:25], v[20:21] op_sel_hi:[1,0,1]
	v_pk_add_f32 v[22:23], v[50:51], v[22:23]
	v_pk_add_f32 v[20:21], v[48:49], v[20:21]
	global_store_dwordx4 v[34:35], v[20:23], off offset:512
	v_add_f32_e32 v48, v28, v29
	v_mul_f32_e32 v29, v29, v29
	v_fmac_f32_e32 v29, v28, v28
	v_add_f32_e32 v48, v30, v48
	v_fmac_f32_e32 v29, v30, v30
	v_add_f32_e32 v30, v24, v25
	v_mul_f32_e32 v25, v25, v25
	v_fmac_f32_e32 v25, v24, v24
	v_add_f32_e32 v28, v31, v48
	v_add_f32_e32 v30, v26, v30
	v_fmac_f32_e32 v25, v26, v26
	v_add_f32_e32 v28, 0, v28
	v_fmac_f32_e32 v29, v31, v31
	v_add_f32_e32 v24, v27, v30
	v_fmac_f32_e32 v25, v27, v27
	v_sub_f32_e32 v27, v53, v59
	v_sub_f32_e32 v26, v52, v59
	v_add_f32_e32 v28, v24, v28
	v_add_f32_e32 v29, v29, v25
	v_sub_f32_e32 v25, v55, v59
	v_sub_f32_e32 v24, v54, v59
	v_pk_mul_f32 v[26:27], v[58:59], v[26:27] op_sel_hi:[0,1]
	v_pk_mul_f32 v[24:25], v[58:59], v[24:25] op_sel_hi:[0,1]
	v_mul_f32_e32 v31, v21, v21
	v_add_f32_e32 v30, v20, v21
	v_fmac_f32_e32 v31, v20, v20
	v_add_f32_e32 v30, v22, v30
	v_fmac_f32_e32 v31, v22, v22
	v_add_f32_e32 v30, v23, v30
	v_fmac_f32_e32 v31, v23, v23
	v_add_f32_e32 v28, v28, v30
	v_add_f32_e32 v29, v29, v31
	v_cvt_pk_bf16_f32 v20, v20, v21
	v_cvt_pk_bf16_f32 v21, v22, v23
	v_pk_fma_f32 v[26:27], v[208:209], v[26:27], v[212:213]
	v_pk_fma_f32 v[24:25], v[210:211], v[24:25], v[214:215]
	v_pk_fma_f32 v[16:17], v[26:27], s[24:25], v[16:17] op_sel_hi:[1,0,1]
	v_pk_fma_f32 v[18:19], v[24:25], s[24:25], v[18:19] op_sel_hi:[1,0,1]
	v_pk_add_f32 v[24:25], v[250:251], v[16:17]
	v_pk_add_f32 v[26:27], v[252:253], v[18:19]
	v_mul_f32_e32 v17, v25, v25
	v_add_f32_e32 v16, v24, v25
	v_fmac_f32_e32 v17, v24, v24
	v_add_f32_e32 v16, v26, v16
	v_fmac_f32_e32 v17, v26, v26
	v_add_f32_e32 v16, v27, v16
	v_fmac_f32_e32 v17, v27, v27
	v_add_f32_e32 v16, v28, v16
	v_add_f32_e32 v17, v29, v17
	ds_bpermute_b32 v18, v118, v16
	ds_bpermute_b32 v19, v118, v17
	global_store_dwordx4 v[34:35], v[24:27], off offset:528
	v_cvt_pk_bf16_f32 v22, v24, v25
	v_cvt_pk_bf16_f32 v23, v26, v27
	s_waitcnt lgkmcnt(0)
	v_add_f32_e32 v16, v16, v18
	v_add_f32_e32 v17, v17, v19
	ds_bpermute_b32 v18, v119, v16
	ds_bpermute_b32 v19, v119, v17
	flat_store_dwordx4 v[56:57], v[20:23] offset:256
	s_and_saveexec_b64 s[36:37], s[2:3]
	s_cbranch_execz .LBB0_2650
	v_lshl_add_u64 v[20:21], s[8:9], 0, v[32:33]
	s_waitcnt lgkmcnt(0)
	v_add_f32_e32 v16, v16, v18
	v_add_f32_e32 v17, v17, v19
	flat_atomic_add_f32 v[20:21], v16
	flat_atomic_add_f32 v[20:21], v17 offset:4
; DEVI unsigned pk2(float lo, float hi) { unsigned r; asm("v_cvt_pk_bf16_f32 %0, %1, %2" : "=v"(r) : "v"(lo), "v"(hi)); return r; }
; DEVI void row_stats(const float* stats, int row, float& mu, float& rs) {
;     if (stats) { const float2 st = *(const float2*)(stats + 2 * (size_t)row); mu = st.x * (1.0f / 1024.0f); const float var = st.y * (1.0f / 1024.0f) - mu * mu; rs = rsqrtf(fmaxf(var, 0.f) + LN_EPS); }
;     DEVI void operator()(const f32x4 (&acc)[2][2][4][2], const pg8::Unit& u, int wr, int wc, int fr, int fq) const {
;     ...
;                 const int row = row0 + ai * 128 + m * 16; float mu, rs; row_stats(stin, row, mu, rs);
;                 float sum = 0.f, sq = 0.f;
; #pragma unroll
;                 for (int bj = 0; bj < 2; ++bj) {
;                     f32x4 z[2];
; #pragma unroll
;                     for (int n = 0; n < 2; ++n) {
;                         const int col = colb + bj * 128 + 4 * n;
;                         f32x4 xv = *(const f32x4*)(zsrc + (size_t)row * DM + col);
;                         if (stin) { const f32x4 gv = *(const f32x4*)(gin + col), bv = *(const f32x4*)(bin + col); xv = (xv - mu) * rs * gv + bv; }
;                         f32x4 zz = ALPHA * xv + acc[ai][bj][m][n];
;                         if (bias) zz += *(const f32x4*)(bias + col);
;                         *(f32x4*)(zdst + (size_t)row * DM + col) = zz;
;                         sum += zz[0] + zz[1] + zz[2] + zz[3]; sq += zz[0] * zz[0] + zz[1] * zz[1] + zz[2] * zz[2] + zz[3] * zz[3];
;                         z[n] = zz;
;                     }
;                     u32x4 o; o.x = pk2(z[0][0], z[0][1]); o.y = pk2(z[0][2], z[0][3]); o.z = pk2(z[1][0], z[1][1]); o.w = pk2(z[1][2], z[1][3]);
;                     if (zb) *(u32x4*)(zb + (size_t)row * DM + colb + bj * 128) = o;
;                 }
;                 sum += __shfl_xor(sum, 16); sq += __shfl_xor(sq, 16);
;                 sum += __shfl_xor(sum, 32); sq += __shfl_xor(sq, 32);
;                 if (fq == 0) { atomicAdd(stout + 2 * (size_t)row, sum); atomicAdd(stout + 2 * (size_t)row + 1, sq); }
.LBB0_2650:
	s_or_b64 exec, exec, s[36:37]
	v_add_u32_e32 v40, 0xb0, v154
	v_ashrrev_i32_e32 v41, 31, v40
	v_lshlrev_b64 v[16:17], 3, v[40:41]
	s_waitcnt lgkmcnt(0)
	v_lshl_add_u64 v[18:19], s[6:7], 0, v[16:17]
	flat_load_dwordx2 v[42:43], v[18:19]
	v_lshlrev_b64 v[18:19], 12, v[40:41]
	v_lshl_add_u64 v[18:19], s[46:47], 0, v[18:19]
	v_lshl_add_u64 v[18:19], v[144:145], 2, v[18:19]
	global_load_dwordx4 v[20:23], v[18:19], off
	global_load_dwordx4 v[24:27], v[150:151], off
	global_load_dwordx4 v[28:31], v[152:153], off
	global_load_dwordx4 v[32:35], v[156:157], off
	global_load_dwordx4 v[36:39], v[18:19], off offset:16
	global_load_dwordx4 v[208:211], v[146:147], off
	global_load_dwordx4 v[212:215], v[148:149], off
	global_load_dwordx4 v[250:253], v[124:125], off
	s_waitcnt vmcnt(0) lgkmcnt(0)
	v_pk_mul_f32 v[42:43], v[42:43], s[22:23] op_sel:[1,0] op_sel_hi:[0,0]
	v_fma_f32 v42, -v43, v43, v42
	v_max_f32_e32 v42, 0, v42
	v_add_f32_e32 v42, 0x3727c5ac, v42
	v_mul_f32_e32 v44, 0x4b800000, v42
	v_cmp_gt_f32_e32 vcc, s64, v42
	v_sub_f32_e32 v23, v23, v43
	v_sub_f32_e32 v22, v22, v43
	v_cndmask_b32_e32 v42, v42, v44, vcc
	v_rsq_f32_e32 v42, v42
	v_sub_f32_e32 v21, v21, v43
	v_sub_f32_e32 v20, v20, v43
	v_mul_f32_e32 v44, 0x45800000, v42
	v_cndmask_b32_e32 v42, v42, v44, vcc
	v_pk_mul_f32 v[20:21], v[20:21], v[42:43] op_sel_hi:[1,0]
	v_pk_mul_f32 v[22:23], v[22:23], v[42:43] op_sel_hi:[1,0]
	v_pk_fma_f32 v[20:21], v[24:25], v[20:21], v[28:29]
	v_pk_fma_f32 v[22:23], v[26:27], v[22:23], v[30:31]
	v_pk_fma_f32 v[12:13], v[20:21], s[24:25], v[12:13] op_sel_hi:[1,0,1]
	v_pk_fma_f32 v[14:15], v[22:23], s[24:25], v[14:15] op_sel_hi:[1,0,1]
	v_pk_add_f32 v[12:13], v[32:33], v[12:13]
	v_pk_add_f32 v[14:15], v[34:35], v[14:15]
	global_store_dwordx4 v[18:19], v[12:15], off
	v_lshlrev_b64 v[32:33], 11, v[40:41]
	v_lshl_add_u64 v[32:33], s[10:11], 0, v[32:33]
	v_lshl_add_u64 v[40:41], v[144:145], 1, v[32:33]
	v_sub_f32_e32 v33, v39, v43
	v_sub_f32_e32 v32, v38, v43
	v_sub_f32_e32 v35, v37, v43
	v_sub_f32_e32 v34, v36, v43
	v_pk_mul_f32 v[34:35], v[34:35], v[42:43] op_sel_hi:[1,0]
	v_pk_mul_f32 v[36:37], v[32:33], v[42:43] op_sel_hi:[1,0]
	v_cvt_pk_bf16_f32 v32, v12, v13
	v_cvt_pk_bf16_f32 v33, v14, v15
	v_pk_fma_f32 v[20:21], v[208:209], v[34:35], v[212:213]
	v_pk_fma_f32 v[22:23], v[210:211], v[36:37], v[214:215]
	v_pk_fma_f32 v[8:9], v[20:21], s[24:25], v[8:9] op_sel_hi:[1,0,1]
	v_pk_fma_f32 v[10:11], v[22:23], s[24:25], v[10:11] op_sel_hi:[1,0,1]
	v_pk_add_f32 v[8:9], v[250:251], v[8:9]
	v_pk_add_f32 v[10:11], v[252:253], v[10:11]
	global_store_dwordx4 v[18:19], v[8:11], off offset:16
	v_cvt_pk_bf16_f32 v34, v8, v9
	v_cvt_pk_bf16_f32 v35, v10, v11
	flat_store_dwordx4 v[40:41], v[32:35]
	global_load_dwordx4 v[20:23], v[18:19], off offset:512
	global_load_dwordx4 v[24:27], v[126:127], off
	global_load_dwordx4 v[28:31], v[158:159], off
	s_nop 0
	global_load_dwordx4 v[32:35], v[160:161], off
	global_load_dwordx4 v[36:39], v[18:19], off offset:528
	global_load_dwordx4 v[208:211], v[120:121], off
	global_load_dwordx4 v[212:215], v[122:123], off
	global_load_dwordx4 v[250:253], v[116:117], off
	s_waitcnt vmcnt(0)
	v_sub_f32_e32 v23, v23, v43
	v_sub_f32_e32 v22, v22, v43
	v_sub_f32_e32 v21, v21, v43
	v_sub_f32_e32 v20, v20, v43
	v_pk_mul_f32 v[20:21], v[42:43], v[20:21] op_sel_hi:[0,1]
	v_pk_mul_f32 v[22:23], v[42:43], v[22:23] op_sel_hi:[0,1]
	v_pk_fma_f32 v[22:23], v[26:27], v[22:23], v[30:31]
	v_pk_fma_f32 v[20:21], v[24:25], v[20:21], v[28:29]
	v_pk_fma_f32 v[6:7], v[22:23], s[24:25], v[6:7] op_sel_hi:[1,0,1]
	v_pk_fma_f32 v[4:5], v[20:21], s[24:25], v[4:5] op_sel_hi:[1,0,1]
	v_pk_add_f32 v[6:7], v[34:35], v[6:7]
	v_pk_add_f32 v[4:5], v[32:33], v[4:5]
	global_store_dwordx4 v[18:19], v[4:7], off offset:512
	v_add_f32_e32 v32, v12, v13
	v_mul_f32_e32 v13, v13, v13
	v_fmac_f32_e32 v13, v12, v12
	v_add_f32_e32 v32, v14, v32
	v_fmac_f32_e32 v13, v14, v14
	v_add_f32_e32 v14, v8, v9
	v_mul_f32_e32 v9, v9, v9
	v_fmac_f32_e32 v9, v8, v8
	v_add_f32_e32 v12, v15, v32
	v_add_f32_e32 v14, v10, v14
	v_fmac_f32_e32 v9, v10, v10
	v_add_f32_e32 v12, 0, v12
	v_fmac_f32_e32 v13, v15, v15
	v_add_f32_e32 v8, v11, v14
	v_fmac_f32_e32 v9, v11, v11
	v_sub_f32_e32 v11, v37, v43
	v_sub_f32_e32 v10, v36, v43
	v_add_f32_e32 v12, v8, v12
	v_add_f32_e32 v13, v13, v9
	v_sub_f32_e32 v9, v39, v43
	v_sub_f32_e32 v8, v38, v43
	v_pk_mul_f32 v[10:11], v[42:43], v[10:11] op_sel_hi:[0,1]
	v_pk_mul_f32 v[8:9], v[42:43], v[8:9] op_sel_hi:[0,1]
	v_mul_f32_e32 v15, v5, v5
	v_add_f32_e32 v14, v4, v5
	v_fmac_f32_e32 v15, v4, v4
	v_add_f32_e32 v14, v6, v14
	v_fmac_f32_e32 v15, v6, v6
	v_add_f32_e32 v14, v7, v14
	v_fmac_f32_e32 v15, v7, v7
	v_add_f32_e32 v12, v12, v14
	v_add_f32_e32 v13, v13, v15
	v_cvt_pk_bf16_f32 v4, v4, v5
	v_cvt_pk_bf16_f32 v5, v6, v7
	v_pk_fma_f32 v[10:11], v[208:209], v[10:11], v[212:213]
	v_pk_fma_f32 v[8:9], v[210:211], v[8:9], v[214:215]
	v_pk_fma_f32 v[0:1], v[10:11], s[24:25], v[0:1] op_sel_hi:[1,0,1]
	v_pk_fma_f32 v[2:3], v[8:9], s[24:25], v[2:3] op_sel_hi:[1,0,1]
	v_pk_add_f32 v[8:9], v[250:251], v[0:1]
	v_pk_add_f32 v[10:11], v[252:253], v[2:3]
	v_mul_f32_e32 v1, v9, v9
	v_add_f32_e32 v0, v8, v9
	v_fmac_f32_e32 v1, v8, v8
	v_add_f32_e32 v0, v10, v0
	v_fmac_f32_e32 v1, v10, v10
	v_add_f32_e32 v0, v11, v0
	v_fmac_f32_e32 v1, v11, v11
	v_add_f32_e32 v0, v12, v0
	v_add_f32_e32 v1, v13, v1
	ds_bpermute_b32 v2, v118, v0
	ds_bpermute_b32 v3, v118, v1
	global_store_dwordx4 v[18:19], v[8:11], off offset:528
	v_cvt_pk_bf16_f32 v6, v8, v9
	v_cvt_pk_bf16_f32 v7, v10, v11
	s_waitcnt lgkmcnt(0)
	v_add_f32_e32 v0, v0, v2
	v_add_f32_e32 v1, v1, v3
	ds_bpermute_b32 v2, v119, v0
	ds_bpermute_b32 v3, v119, v1
	flat_store_dwordx4 v[40:41], v[4:7] offset:256
	s_and_saveexec_b64 s[36:37], s[2:3]
	s_cbranch_execz .LBB0_2652
	v_lshl_add_u64 v[4:5], s[8:9], 0, v[16:17]
	s_waitcnt lgkmcnt(0)
	v_add_f32_e32 v0, v0, v2
	v_add_f32_e32 v1, v1, v3
	flat_atomic_add_f32 v[4:5], v0
	flat_atomic_add_f32 v[4:5], v1 offset:4
